# baseline (speedup 1.0000x reference)
; #define PG8_STAGE(bufoff, gbase, voff) do { _Pragma("unroll") for (int _i = 0; _i < 2; ++_i) \
;         __builtin_amdgcn_global_load_lds((const unsigned*)((const char*)(gbase) + (voff)[_i]), (PG8_LAS unsigned*)(lds + (bufoff) + ldsw + _i * 8192), 16, 0, 0); } while (0)
; #define PG8_LDA(dst, b, h) do { _Pragma("unroll") for (int m = 0; m < 4; ++m) _Pragma("unroll") for (int k = 0; k < 2; ++k) dst[m][k] = *(const PG8_LAS bf16x8*)(lds + PG8_SA(b, h) + aoff + m * 2048 + k * 1024); } while (0)
; #define PG8_LDB(dst, b, h) do { _Pragma("unroll") for (int n = 0; n < 2; ++n) _Pragma("unroll") for (int k = 0; k < 2; ++k) dst[n][k] = *(const PG8_LAS bf16x8*)(lds + PG8_SB(b, h) + boff + n * 2048 + k * 1024); } while (0)
; #define PG8_MMA(ai, bj, At, Bt) do { __builtin_amdgcn_s_setprio(1); _Pragma("unroll") for (int m = 0; m < 4; ++m) _Pragma("unroll") for (int n = 0; n < 2; ++n) _Pragma("unroll") for (int k = 0; k < 2; ++k) \
;         acc[ai][bj][m][n] = __builtin_amdgcn_mfma_f32_16x16x32_bf16(Bt[n][k], At[m][k], acc[ai][bj][m][n], 0, 0, 0); __builtin_amdgcn_s_setprio(0); } while (0)
; #define PG8_WAIT_V(n) asm volatile("s_waitcnt vmcnt(" #n ")" ::: "memory")
; #define PG8_WAIT_L(n) asm volatile("s_waitcnt lgkmcnt(" #n ")" ::: "memory")
; template <class Epi, class Sched, bool ALIGN_EPI = false, bool SP2 = false>
; __device__ __forceinline__ void gemm_phase(PG8_LAS unsigned char* lds, const Gemm g, const Sched& S, const Epi& E) {
;     ...
;             const bool last = (t == nt - 2);
;             const char* a1 = cA + (size_t)(t + 1) * kstep;
;             const char* a2 = last ? nA : cA + (size_t)(t + 2) * kstep; const char* b2 = last ? nB : cB + (size_t)(t + 2) * kstep;
;             const char* a3 = a2 + kstep; const char* b3 = b2 + kstep;
;             if (last && has_next) S.a_ready(nxt);
;             if constexpr (SP2) {
;             PG8_LDB(B0, 0, 0); PG8_LDB(B1, 0, 1); PG8_SCHED; PG8_LDA(At, 0, 0); PG8_STAGE(PG8_SA(1, 1), a1 + hstep, voffA);
;             PG8_WAIT_V(8); PG8_WAIT_L(0); PG8_BAR; PG8_MMA(0, 0, At, B0); PG8_MMA(0, 1, At, B1); PG8_BAR; PG8_SCHED;
;             PG8_LDA(At, 0, 1); PG8_STAGE(PG8_SB(0, 0), b2, voffB); PG8_STAGE(PG8_SB(0, 1), b2 + hstep, voffB); PG8_STAGE(PG8_SA(0, 0), a2, voffA);
;             PG8_WAIT_V(8); PG8_WAIT_L(0); PG8_BAR; PG8_MMA(1, 0, At, B0); PG8_MMA(1, 1, At, B1); PG8_BAR; PG8_SCHED;
.LBB0_121:
	ds_read_b128 v[148:151], v159
	ds_read_b128 v[168:171], v159 offset:1024
	ds_read_b128 v[172:175], v159 offset:2048
	ds_read_b128 v[176:179], v159 offset:3072
	ds_read_b128 v[180:183], v160
	ds_read_b128 v[184:187], v160 offset:1024
	ds_read_b128 v[188:191], v160 offset:2048
	ds_read_b128 v[192:195], v160 offset:3072
	s_add_i32 s46, s42, 2
	s_add_u32 s47, s6, 0x80
	s_addc_u32 s43, s7, 0
	s_cmp_eq_u32 s93, s42
	s_cselect_b32 s42, s38, s47
	s_cselect_b32 s43, s39, s43
	s_cselect_b32 s69, s41, vcc_lo
	s_cselect_b32 s68, s40, s0
	v_lshl_add_u64 v[152:153], s[6:7], 0, v[142:143]
	s_add_i32 m0, s64, 0xc000
	ds_read_b128 v[196:199], v161
	ds_read_b128 v[200:203], v161 offset:1024
	ds_read_b128 v[204:207], v161 offset:2048
	ds_read_b128 v[208:211], v161 offset:3072
	ds_read_b128 v[212:215], v161 offset:4096
	ds_read_b128 v[216:219], v161 offset:5120
	ds_read_b128 v[220:223], v161 offset:6144
	ds_read_b128 v[224:227], v161 offset:7168
	global_load_lds_dwordx4 v[152:153], off
	v_lshl_add_u64 v[152:153], s[6:7], 0, v[140:141]
	s_add_i32 m0, s64, 0xe000
	s_nop 0
	global_load_lds_dwordx4 v[152:153], off
	s_waitcnt vmcnt(8) lgkmcnt(0)
	s_barrier
	s_setprio 1
	v_mfma_f32_16x16x32_bf16 v[126:129], v[148:151], v[196:199], v[126:129]
	v_mfma_f32_16x16x32_bf16 v[122:125], v[172:175], v[196:199], v[122:125]
	v_mfma_f32_16x16x32_bf16 v[110:113], v[148:151], v[204:207], v[110:113]
	v_mfma_f32_16x16x32_bf16 v[106:109], v[172:175], v[204:207], v[106:109]
	v_mfma_f32_16x16x32_bf16 v[94:97], v[148:151], v[212:215], v[94:97]
	v_mfma_f32_16x16x32_bf16 v[90:93], v[172:175], v[212:215], v[90:93]
	v_mfma_f32_16x16x32_bf16 v[78:81], v[148:151], v[220:223], v[78:81]
	v_mfma_f32_16x16x32_bf16 v[74:77], v[172:175], v[220:223], v[74:77]
	v_mfma_f32_16x16x32_bf16 v[126:129], v[168:171], v[200:203], v[126:129]
	v_mfma_f32_16x16x32_bf16 v[122:125], v[176:179], v[200:203], v[122:125]
	v_mfma_f32_16x16x32_bf16 v[110:113], v[168:171], v[208:211], v[110:113]
	v_mfma_f32_16x16x32_bf16 v[106:109], v[176:179], v[208:211], v[106:109]
	v_mfma_f32_16x16x32_bf16 v[94:97], v[168:171], v[216:219], v[94:97]
	v_mfma_f32_16x16x32_bf16 v[90:93], v[176:179], v[216:219], v[90:93]
	v_mfma_f32_16x16x32_bf16 v[78:81], v[168:171], v[224:227], v[78:81]
	v_mfma_f32_16x16x32_bf16 v[74:77], v[176:179], v[224:227], v[74:77]
	v_mfma_f32_16x16x32_bf16 v[118:121], v[180:183], v[196:199], v[118:121]
	v_mfma_f32_16x16x32_bf16 v[114:117], v[188:191], v[196:199], v[114:117]
	v_mfma_f32_16x16x32_bf16 v[102:105], v[180:183], v[204:207], v[102:105]
	v_mfma_f32_16x16x32_bf16 v[98:101], v[188:191], v[204:207], v[98:101]
	v_mfma_f32_16x16x32_bf16 v[86:89], v[180:183], v[212:215], v[86:89]
	v_mfma_f32_16x16x32_bf16 v[82:85], v[188:191], v[212:215], v[82:85]
	v_mfma_f32_16x16x32_bf16 v[70:73], v[180:183], v[220:223], v[70:73]
	v_mfma_f32_16x16x32_bf16 v[66:69], v[188:191], v[220:223], v[66:69]
	v_mfma_f32_16x16x32_bf16 v[118:121], v[184:187], v[200:203], v[118:121]
	v_mfma_f32_16x16x32_bf16 v[114:117], v[192:195], v[200:203], v[114:117]
	v_mfma_f32_16x16x32_bf16 v[102:105], v[184:187], v[208:211], v[102:105]
	v_mfma_f32_16x16x32_bf16 v[98:101], v[192:195], v[208:211], v[98:101]
	v_mfma_f32_16x16x32_bf16 v[86:89], v[184:187], v[216:219], v[86:89]
	v_mfma_f32_16x16x32_bf16 v[82:85], v[192:195], v[216:219], v[82:85]
	v_mfma_f32_16x16x32_bf16 v[70:73], v[184:187], v[224:227], v[70:73]
	v_mfma_f32_16x16x32_bf16 v[66:69], v[192:195], v[224:227], v[66:69]
	s_setprio 0
	s_barrier
	s_add_i32 s47, s97, s55
	v_lshl_add_u64 v[152:153], s[68:69], 0, v[132:133]
	s_mov_b32 m0, s47
	ds_read_b128 v[196:199], v161 offset:16384
	ds_read_b128 v[200:203], v161 offset:17408
	ds_read_b128 v[204:207], v161 offset:18432
	ds_read_b128 v[208:211], v161 offset:19456
	ds_read_b128 v[212:215], v161 offset:20480
	ds_read_b128 v[216:219], v161 offset:21504
	ds_read_b128 v[220:223], v161 offset:22528
	ds_read_b128 v[224:227], v161 offset:23552
	global_load_lds_dwordx4 v[152:153], off
	s_add_i32 m0, s47, 0x2000
	v_lshl_add_u64 v[228:229], s[68:69], 0, v[136:137]
	s_add_u32 s68, s68, s10
	s_addc_u32 s69, s69, s11
	s_add_i32 s47, s80, s55
	global_load_lds_dwordx4 v[228:229], off
	v_lshl_add_u64 v[230:231], s[68:69], 0, v[132:133]
	s_mov_b32 m0, s47
	v_lshl_add_u64 v[232:233], s[68:69], 0, v[136:137]
	global_load_lds_dwordx4 v[230:231], off
	s_add_i32 m0, s47, 0x2000
	v_lshl_add_u64 v[234:235], s[42:43], 0, v[130:131]
	global_load_lds_dwordx4 v[232:233], off
	s_mov_b32 m0, s64
	v_lshl_add_u64 v[236:237], s[42:43], 0, v[134:135]
	global_load_lds_dwordx4 v[234:235], off
	s_mov_b32 m0, s65
	s_nop 0
	global_load_lds_dwordx4 v[236:237], off
	s_waitcnt vmcnt(8) lgkmcnt(0)
	s_barrier
; #define PG8_STAGE(bufoff, gbase, voff) do { _Pragma("unroll") for (int _i = 0; _i < 2; ++_i) \
;         __builtin_amdgcn_global_load_lds((const unsigned*)((const char*)(gbase) + (voff)[_i]), (PG8_LAS unsigned*)(lds + (bufoff) + ldsw + _i * 8192), 16, 0, 0); } while (0)
; #define PG8_LDA(dst, b, h) do { _Pragma("unroll") for (int m = 0; m < 4; ++m) _Pragma("unroll") for (int k = 0; k < 2; ++k) dst[m][k] = *(const PG8_LAS bf16x8*)(lds + PG8_SA(b, h) + aoff + m * 2048 + k * 1024); } while (0)
; #define PG8_LDB(dst, b, h) do { _Pragma("unroll") for (int n = 0; n < 2; ++n) _Pragma("unroll") for (int k = 0; k < 2; ++k) dst[n][k] = *(const PG8_LAS bf16x8*)(lds + PG8_SB(b, h) + boff + n * 2048 + k * 1024); } while (0)
; #define PG8_MMA(ai, bj, At, Bt) do { __builtin_amdgcn_s_setprio(1); _Pragma("unroll") for (int m = 0; m < 4; ++m) _Pragma("unroll") for (int n = 0; n < 2; ++n) _Pragma("unroll") for (int k = 0; k < 2; ++k) \
;         acc[ai][bj][m][n] = __builtin_amdgcn_mfma_f32_16x16x32_bf16(Bt[n][k], At[m][k], acc[ai][bj][m][n], 0, 0, 0); __builtin_amdgcn_s_setprio(0); } while (0)
; #define PG8_WAIT_V(n) asm volatile("s_waitcnt vmcnt(" #n ")" ::: "memory")
; #define PG8_WAIT_L(n) asm volatile("s_waitcnt lgkmcnt(" #n ")" ::: "memory")
; #define PG8_BAR __builtin_amdgcn_s_barrier()
; #define PG8_SCHED __builtin_amdgcn_sched_barrier(0)
; template <class Epi, class Sched, bool ALIGN_EPI = false, bool SP2 = false>
; __device__ __forceinline__ void gemm_phase(PG8_LAS unsigned char* lds, const Gemm g, const Sched& S, const Epi& E) {
;     ...
;             PG8_WAIT_V(8); PG8_WAIT_L(0); PG8_BAR; PG8_MMA(1, 0, At, B0); PG8_MMA(1, 1, At, B1); PG8_BAR; PG8_SCHED;
;             PG8_LDB(B0, 1, 0); PG8_LDB(B1, 1, 1); PG8_SCHED; PG8_LDA(At, 1, 0); PG8_STAGE(PG8_SA(0, 1), a2 + hstep, voffA);
;             PG8_WAIT_V(8); PG8_WAIT_L(0); PG8_BAR; PG8_MMA(0, 0, At, B0); PG8_MMA(0, 1, At, B1); PG8_BAR; PG8_SCHED;
	s_setprio 1
	v_mfma_f32_16x16x32_bf16 v[62:65], v[148:151], v[196:199], v[62:65]
	v_mfma_f32_16x16x32_bf16 v[58:61], v[172:175], v[196:199], v[58:61]
	v_mfma_f32_16x16x32_bf16 v[46:49], v[148:151], v[204:207], v[46:49]
	v_mfma_f32_16x16x32_bf16 v[42:45], v[172:175], v[204:207], v[42:45]
	v_mfma_f32_16x16x32_bf16 v[30:33], v[148:151], v[212:215], v[30:33]
	v_mfma_f32_16x16x32_bf16 v[26:29], v[172:175], v[212:215], v[26:29]
	v_mfma_f32_16x16x32_bf16 v[14:17], v[148:151], v[220:223], v[14:17]
	v_mfma_f32_16x16x32_bf16 v[10:13], v[172:175], v[220:223], v[10:13]
	v_mfma_f32_16x16x32_bf16 v[62:65], v[168:171], v[200:203], v[62:65]
	v_mfma_f32_16x16x32_bf16 v[58:61], v[176:179], v[200:203], v[58:61]
	v_mfma_f32_16x16x32_bf16 v[46:49], v[168:171], v[208:211], v[46:49]
	v_mfma_f32_16x16x32_bf16 v[42:45], v[176:179], v[208:211], v[42:45]
	v_mfma_f32_16x16x32_bf16 v[30:33], v[168:171], v[216:219], v[30:33]
	v_mfma_f32_16x16x32_bf16 v[26:29], v[176:179], v[216:219], v[26:29]
	v_mfma_f32_16x16x32_bf16 v[14:17], v[168:171], v[224:227], v[14:17]
	v_mfma_f32_16x16x32_bf16 v[10:13], v[176:179], v[224:227], v[10:13]
	v_mfma_f32_16x16x32_bf16 v[54:57], v[180:183], v[196:199], v[54:57]
	v_mfma_f32_16x16x32_bf16 v[50:53], v[188:191], v[196:199], v[50:53]
	v_mfma_f32_16x16x32_bf16 v[38:41], v[180:183], v[204:207], v[38:41]
	v_mfma_f32_16x16x32_bf16 v[34:37], v[188:191], v[204:207], v[34:37]
	v_mfma_f32_16x16x32_bf16 v[22:25], v[180:183], v[212:215], v[22:25]
	v_mfma_f32_16x16x32_bf16 v[18:21], v[188:191], v[212:215], v[18:21]
	v_mfma_f32_16x16x32_bf16 v[6:9], v[180:183], v[220:223], v[6:9]
	v_mfma_f32_16x16x32_bf16 v[2:5], v[188:191], v[220:223], v[2:5]
	v_mfma_f32_16x16x32_bf16 v[54:57], v[184:187], v[200:203], v[54:57]
	v_mfma_f32_16x16x32_bf16 v[50:53], v[192:195], v[200:203], v[50:53]
	v_mfma_f32_16x16x32_bf16 v[38:41], v[184:187], v[208:211], v[38:41]
	v_mfma_f32_16x16x32_bf16 v[34:37], v[192:195], v[208:211], v[34:37]
	v_mfma_f32_16x16x32_bf16 v[22:25], v[184:187], v[216:219], v[22:25]
	v_mfma_f32_16x16x32_bf16 v[18:21], v[192:195], v[216:219], v[18:21]
	v_mfma_f32_16x16x32_bf16 v[6:9], v[184:187], v[224:227], v[6:9]
	v_mfma_f32_16x16x32_bf16 v[2:5], v[192:195], v[224:227], v[2:5]
	s_setprio 0
	s_barrier
	s_add_i32 s47, 0, 0x18000
	v_add_u32_e32 v138, s47, v154
	s_add_i32 s68, 0, 0x1c000
	ds_read_b128 v[148:151], v138
	ds_read_b128 v[168:171], v138 offset:1024
	ds_read_b128 v[172:175], v138 offset:2048
	ds_read_b128 v[176:179], v138 offset:3072
	v_add_u32_e32 v138, s68, v154
	ds_read_b128 v[180:183], v138
	ds_read_b128 v[184:187], v138 offset:1024
	ds_read_b128 v[188:191], v138 offset:2048
	ds_read_b128 v[192:195], v138 offset:3072
	s_add_u32 s42, s42, s10
	s_addc_u32 s43, s43, s11
	s_mov_b32 m0, s66
	v_lshl_add_u64 v[238:239], s[42:43], 0, v[130:131]
	ds_read_b128 v[196:199], v161 offset:32768
	ds_read_b128 v[200:203], v161 offset:33792
	ds_read_b128 v[204:207], v161 offset:34816
	ds_read_b128 v[208:211], v161 offset:35840
	ds_read_b128 v[212:215], v161 offset:36864
	ds_read_b128 v[216:219], v161 offset:37888
	ds_read_b128 v[220:223], v161 offset:38912
	ds_read_b128 v[224:227], v161 offset:39936
	global_load_lds_dwordx4 v[238:239], off
	v_lshl_add_u64 v[238:239], s[42:43], 0, v[134:135]
	s_mov_b32 m0, s67
	s_nop 0
	global_load_lds_dwordx4 v[238:239], off
	s_waitcnt vmcnt(8) lgkmcnt(0)
	s_barrier
	s_setprio 1
	v_mfma_f32_16x16x32_bf16 v[126:129], v[148:151], v[196:199], v[126:129]
	v_mfma_f32_16x16x32_bf16 v[122:125], v[172:175], v[196:199], v[122:125]
	v_mfma_f32_16x16x32_bf16 v[110:113], v[148:151], v[204:207], v[110:113]
	v_mfma_f32_16x16x32_bf16 v[106:109], v[172:175], v[204:207], v[106:109]
	v_mfma_f32_16x16x32_bf16 v[94:97], v[148:151], v[212:215], v[94:97]
	v_mfma_f32_16x16x32_bf16 v[90:93], v[172:175], v[212:215], v[90:93]
	v_mfma_f32_16x16x32_bf16 v[78:81], v[148:151], v[220:223], v[78:81]
	v_mfma_f32_16x16x32_bf16 v[74:77], v[172:175], v[220:223], v[74:77]
	v_mfma_f32_16x16x32_bf16 v[126:129], v[168:171], v[200:203], v[126:129]
	v_mfma_f32_16x16x32_bf16 v[122:125], v[176:179], v[200:203], v[122:125]
	v_mfma_f32_16x16x32_bf16 v[110:113], v[168:171], v[208:211], v[110:113]
	v_mfma_f32_16x16x32_bf16 v[106:109], v[176:179], v[208:211], v[106:109]
	v_mfma_f32_16x16x32_bf16 v[94:97], v[168:171], v[216:219], v[94:97]
	v_mfma_f32_16x16x32_bf16 v[90:93], v[176:179], v[216:219], v[90:93]
	v_mfma_f32_16x16x32_bf16 v[78:81], v[168:171], v[224:227], v[78:81]
	v_mfma_f32_16x16x32_bf16 v[74:77], v[176:179], v[224:227], v[74:77]
	v_mfma_f32_16x16x32_bf16 v[118:121], v[180:183], v[196:199], v[118:121]
	v_mfma_f32_16x16x32_bf16 v[114:117], v[188:191], v[196:199], v[114:117]
	v_mfma_f32_16x16x32_bf16 v[102:105], v[180:183], v[204:207], v[102:105]
	v_mfma_f32_16x16x32_bf16 v[98:101], v[188:191], v[204:207], v[98:101]
	v_mfma_f32_16x16x32_bf16 v[86:89], v[180:183], v[212:215], v[86:89]
	v_mfma_f32_16x16x32_bf16 v[82:85], v[188:191], v[212:215], v[82:85]
	v_mfma_f32_16x16x32_bf16 v[70:73], v[180:183], v[220:223], v[70:73]
	v_mfma_f32_16x16x32_bf16 v[66:69], v[188:191], v[220:223], v[66:69]
	v_mfma_f32_16x16x32_bf16 v[118:121], v[184:187], v[200:203], v[118:121]
	v_mfma_f32_16x16x32_bf16 v[114:117], v[192:195], v[200:203], v[114:117]
	v_mfma_f32_16x16x32_bf16 v[102:105], v[184:187], v[208:211], v[102:105]
	v_mfma_f32_16x16x32_bf16 v[98:101], v[192:195], v[208:211], v[98:101]
	v_mfma_f32_16x16x32_bf16 v[86:89], v[184:187], v[216:219], v[86:89]
	v_mfma_f32_16x16x32_bf16 v[82:85], v[192:195], v[216:219], v[82:85]
	v_mfma_f32_16x16x32_bf16 v[70:73], v[184:187], v[224:227], v[70:73]
	v_mfma_f32_16x16x32_bf16 v[66:69], v[192:195], v[224:227], v[66:69]
	s_setprio 0
	s_barrier
; #define PG8_STAGE(bufoff, gbase, voff) do { _Pragma("unroll") for (int _i = 0; _i < 2; ++_i) \
;         __builtin_amdgcn_global_load_lds((const unsigned*)((const char*)(gbase) + (voff)[_i]), (PG8_LAS unsigned*)(lds + (bufoff) + ldsw + _i * 8192), 16, 0, 0); } while (0)
; #define PG8_LDA(dst, b, h) do { _Pragma("unroll") for (int m = 0; m < 4; ++m) _Pragma("unroll") for (int k = 0; k < 2; ++k) dst[m][k] = *(const PG8_LAS bf16x8*)(lds + PG8_SA(b, h) + aoff + m * 2048 + k * 1024); } while (0)
; #define PG8_MMA(ai, bj, At, Bt) do { __builtin_amdgcn_s_setprio(1); _Pragma("unroll") for (int m = 0; m < 4; ++m) _Pragma("unroll") for (int n = 0; n < 2; ++n) _Pragma("unroll") for (int k = 0; k < 2; ++k) \
;         acc[ai][bj][m][n] = __builtin_amdgcn_mfma_f32_16x16x32_bf16(Bt[n][k], At[m][k], acc[ai][bj][m][n], 0, 0, 0); __builtin_amdgcn_s_setprio(0); } while (0)
; #define PG8_WAIT_V(n) asm volatile("s_waitcnt vmcnt(" #n ")" ::: "memory")
; #define PG8_WAIT_L(n) asm volatile("s_waitcnt lgkmcnt(" #n ")" ::: "memory")
; #define PG8_BAR __builtin_amdgcn_s_barrier()
; #define PG8_SCHED __builtin_amdgcn_sched_barrier(0)
; template <class Epi, class Sched, bool ALIGN_EPI = false, bool SP2 = false>
; __device__ __forceinline__ void gemm_phase(PG8_LAS unsigned char* lds, const Gemm g, const Sched& S, const Epi& E) {
;     ...
;             PG8_LDA(At, 1, 1); PG8_STAGE(PG8_SB(1, 0), b3, voffB); PG8_STAGE(PG8_SB(1, 1), b3 + hstep, voffB); PG8_STAGE(PG8_SA(1, 0), a3, voffA);
;             PG8_WAIT_V(8); PG8_WAIT_L(0); PG8_BAR; PG8_MMA(1, 0, At, B0); PG8_MMA(1, 1, At, B1); PG8_BAR; PG8_SCHED;
	s_add_i32 s42, s47, s55
	v_lshl_add_u64 v[152:153], v[152:153], 0, s[30:31]
	s_mov_b32 m0, s42
	ds_read_b128 v[196:199], v161 offset:49152
	ds_read_b128 v[200:203], v161 offset:50176
	ds_read_b128 v[204:207], v161 offset:51200
	ds_read_b128 v[208:211], v161 offset:52224
	ds_read_b128 v[212:215], v161 offset:53248
	ds_read_b128 v[216:219], v161 offset:54272
	ds_read_b128 v[220:223], v161 offset:55296
	ds_read_b128 v[224:227], v161 offset:56320
	global_load_lds_dwordx4 v[152:153], off
	v_lshl_add_u64 v[152:153], v[228:229], 0, s[30:31]
	s_add_i32 m0, s42, 0x2000
	s_add_i32 s42, s68, s55
	global_load_lds_dwordx4 v[152:153], off
	v_lshl_add_u64 v[152:153], v[230:231], 0, s[30:31]
	s_mov_b32 m0, s42
	s_nop 0
	global_load_lds_dwordx4 v[152:153], off
	v_lshl_add_u64 v[152:153], v[232:233], 0, s[30:31]
	s_add_i32 m0, s42, 0x2000
	s_nop 0
	global_load_lds_dwordx4 v[152:153], off
	v_lshl_add_u64 v[152:153], v[234:235], 0, s[30:31]
	s_mov_b32 m0, s89
	s_nop 0
	global_load_lds_dwordx4 v[152:153], off
	v_lshl_add_u64 v[152:153], v[236:237], 0, s[30:31]
	s_mov_b32 m0, s90
	s_nop 0
	global_load_lds_dwordx4 v[152:153], off
	s_waitcnt vmcnt(8) lgkmcnt(0)
	s_barrier
	s_setprio 1
	v_mfma_f32_16x16x32_bf16 v[62:65], v[148:151], v[196:199], v[62:65]
	v_mfma_f32_16x16x32_bf16 v[58:61], v[172:175], v[196:199], v[58:61]
	v_mfma_f32_16x16x32_bf16 v[46:49], v[148:151], v[204:207], v[46:49]
	v_mfma_f32_16x16x32_bf16 v[42:45], v[172:175], v[204:207], v[42:45]
	v_mfma_f32_16x16x32_bf16 v[30:33], v[148:151], v[212:215], v[30:33]
	v_mfma_f32_16x16x32_bf16 v[26:29], v[172:175], v[212:215], v[26:29]
	v_mfma_f32_16x16x32_bf16 v[14:17], v[148:151], v[220:223], v[14:17]
	v_mfma_f32_16x16x32_bf16 v[10:13], v[172:175], v[220:223], v[10:13]
	v_mfma_f32_16x16x32_bf16 v[62:65], v[168:171], v[200:203], v[62:65]
	v_mfma_f32_16x16x32_bf16 v[58:61], v[176:179], v[200:203], v[58:61]
	v_mfma_f32_16x16x32_bf16 v[46:49], v[168:171], v[208:211], v[46:49]
	v_mfma_f32_16x16x32_bf16 v[42:45], v[176:179], v[208:211], v[42:45]
	v_mfma_f32_16x16x32_bf16 v[30:33], v[168:171], v[216:219], v[30:33]
	v_mfma_f32_16x16x32_bf16 v[26:29], v[176:179], v[216:219], v[26:29]
	v_mfma_f32_16x16x32_bf16 v[14:17], v[168:171], v[224:227], v[14:17]
	v_mfma_f32_16x16x32_bf16 v[10:13], v[176:179], v[224:227], v[10:13]
	v_mfma_f32_16x16x32_bf16 v[54:57], v[180:183], v[196:199], v[54:57]
	v_mfma_f32_16x16x32_bf16 v[50:53], v[188:191], v[196:199], v[50:53]
	v_mfma_f32_16x16x32_bf16 v[38:41], v[180:183], v[204:207], v[38:41]
	v_mfma_f32_16x16x32_bf16 v[34:37], v[188:191], v[204:207], v[34:37]
	v_mfma_f32_16x16x32_bf16 v[22:25], v[180:183], v[212:215], v[22:25]
	v_mfma_f32_16x16x32_bf16 v[18:21], v[188:191], v[212:215], v[18:21]
	v_mfma_f32_16x16x32_bf16 v[6:9], v[180:183], v[220:223], v[6:9]
	v_mfma_f32_16x16x32_bf16 v[2:5], v[188:191], v[220:223], v[2:5]
	v_mfma_f32_16x16x32_bf16 v[54:57], v[184:187], v[200:203], v[54:57]
	v_mfma_f32_16x16x32_bf16 v[50:53], v[192:195], v[200:203], v[50:53]
	v_mfma_f32_16x16x32_bf16 v[38:41], v[184:187], v[208:211], v[38:41]
	v_mfma_f32_16x16x32_bf16 v[34:37], v[192:195], v[208:211], v[34:37]
	v_mfma_f32_16x16x32_bf16 v[22:25], v[184:187], v[216:219], v[22:25]
	v_mfma_f32_16x16x32_bf16 v[18:21], v[192:195], v[216:219], v[18:21]
	v_mfma_f32_16x16x32_bf16 v[6:9], v[184:187], v[224:227], v[6:9]
	v_mfma_f32_16x16x32_bf16 v[2:5], v[192:195], v[224:227], v[2:5]
	s_setprio 0
	s_barrier
	s_add_u32 s0, s0, 0x100
	s_addc_u32 vcc_lo, vcc_lo, 0
	s_add_u32 s6, s6, 0x100
	s_addc_u32 s7, s7, 0
	s_cmp_ge_i32 s46, s91
	s_mov_b32 s42, s46
	s_cbranch_scc0 .LBB0_121

; #define PG8_STAGE(bufoff, gbase, voff) do { _Pragma("unroll") for (int _i = 0; _i < 2; ++_i) \
;         __builtin_amdgcn_global_load_lds((const unsigned*)((const char*)(gbase) + (voff)[_i]), (PG8_LAS unsigned*)(lds + (bufoff) + ldsw + _i * 8192), 16, 0, 0); } while (0)
; #define PG8_LDA(dst, b, h) do { _Pragma("unroll") for (int m = 0; m < 4; ++m) _Pragma("unroll") for (int k = 0; k < 2; ++k) dst[m][k] = *(const PG8_LAS bf16x8*)(lds + PG8_SA(b, h) + aoff + m * 2048 + k * 1024); } while (0)
; #define PG8_LDB(dst, b, h) do { _Pragma("unroll") for (int n = 0; n < 2; ++n) _Pragma("unroll") for (int k = 0; k < 2; ++k) dst[n][k] = *(const PG8_LAS bf16x8*)(lds + PG8_SB(b, h) + boff + n * 2048 + k * 1024); } while (0)
; #define PG8_MMA(ai, bj, At, Bt) do { __builtin_amdgcn_s_setprio(1); _Pragma("unroll") for (int m = 0; m < 4; ++m) _Pragma("unroll") for (int n = 0; n < 2; ++n) _Pragma("unroll") for (int k = 0; k < 2; ++k) \
;         acc[ai][bj][m][n] = __builtin_amdgcn_mfma_f32_16x16x32_bf16(Bt[n][k], At[m][k], acc[ai][bj][m][n], 0, 0, 0); __builtin_amdgcn_s_setprio(0); } while (0)
; #define PG8_WAIT_V(n) asm volatile("s_waitcnt vmcnt(" #n ")" ::: "memory")
; #define PG8_WAIT_L(n) asm volatile("s_waitcnt lgkmcnt(" #n ")" ::: "memory")
; template <class Epi, class Sched, bool ALIGN_EPI = false, bool SP2 = false>
; __device__ __forceinline__ void gemm_phase(PG8_LAS unsigned char* lds, const Gemm g, const Sched& S, const Epi& E) {
;     ...
;             const bool last = (t == nt - 2);
;             const char* a1 = cA + (size_t)(t + 1) * kstep;
;             const char* a2 = last ? nA : cA + (size_t)(t + 2) * kstep; const char* b2 = last ? nB : cB + (size_t)(t + 2) * kstep;
;             const char* a3 = a2 + kstep; const char* b3 = b2 + kstep;
;             if (last && has_next) S.a_ready(nxt);
;             if constexpr (SP2) {
;             PG8_LDB(B0, 0, 0); PG8_LDB(B1, 0, 1); PG8_SCHED; PG8_LDA(At, 0, 0); PG8_STAGE(PG8_SA(1, 1), a1 + hstep, voffA);
;             PG8_WAIT_V(8); PG8_WAIT_L(0); PG8_BAR; PG8_MMA(0, 0, At, B0); PG8_MMA(0, 1, At, B1); PG8_BAR; PG8_SCHED;
;             PG8_LDA(At, 0, 1); PG8_STAGE(PG8_SB(0, 0), b2, voffB); PG8_STAGE(PG8_SB(0, 1), b2 + hstep, voffB); PG8_STAGE(PG8_SA(0, 0), a2, voffA);
;             PG8_WAIT_V(8); PG8_WAIT_L(0); PG8_BAR; PG8_MMA(1, 0, At, B0); PG8_MMA(1, 1, At, B1); PG8_BAR; PG8_SCHED;
.LBB0_497:
	ds_read_b128 v[146:149], v152
	ds_read_b128 v[156:159], v152 offset:1024
	ds_read_b128 v[160:163], v152 offset:2048
	ds_read_b128 v[164:167], v152 offset:3072
	ds_read_b128 v[168:171], v153
	ds_read_b128 v[172:175], v153 offset:1024
	ds_read_b128 v[176:179], v153 offset:2048
	ds_read_b128 v[180:183], v153 offset:3072
	s_add_i32 s60, s34, 2
	s_add_u32 s61, s30, 0x80
	s_addc_u32 s35, s31, 0
	s_cmp_eq_u32 s44, s34
	s_cselect_b32 s34, s6, s61
	s_cselect_b32 s35, s7, s35
	s_cselect_b32 s63, s29, s59
	s_cselect_b32 s62, s28, s58
	v_lshl_add_u64 v[216:217], s[30:31], 0, v[140:141]
	s_add_i32 m0, s39, 0xc000
	ds_read_b128 v[184:187], v154
	ds_read_b128 v[188:191], v154 offset:1024
	ds_read_b128 v[192:195], v154 offset:2048
	ds_read_b128 v[196:199], v154 offset:3072
	ds_read_b128 v[200:203], v154 offset:4096
	ds_read_b128 v[204:207], v154 offset:5120
	ds_read_b128 v[208:211], v154 offset:6144
	ds_read_b128 v[212:215], v154 offset:7168
	global_load_lds_dwordx4 v[216:217], off
	v_lshl_add_u64 v[216:217], s[30:31], 0, v[138:139]
	s_add_i32 m0, s39, 0xe000
	s_nop 0
	global_load_lds_dwordx4 v[216:217], off
	s_waitcnt vmcnt(8) lgkmcnt(0)
	s_barrier
	s_setprio 1
	v_mfma_f32_16x16x32_bf16 v[126:129], v[146:149], v[184:187], v[126:129]
	v_mfma_f32_16x16x32_bf16 v[122:125], v[160:163], v[184:187], v[122:125]
	v_mfma_f32_16x16x32_bf16 v[110:113], v[146:149], v[192:195], v[110:113]
	v_mfma_f32_16x16x32_bf16 v[106:109], v[160:163], v[192:195], v[106:109]
	v_mfma_f32_16x16x32_bf16 v[94:97], v[146:149], v[200:203], v[94:97]
	v_mfma_f32_16x16x32_bf16 v[90:93], v[160:163], v[200:203], v[90:93]
	v_mfma_f32_16x16x32_bf16 v[78:81], v[146:149], v[208:211], v[78:81]
	v_mfma_f32_16x16x32_bf16 v[74:77], v[160:163], v[208:211], v[74:77]
	v_mfma_f32_16x16x32_bf16 v[126:129], v[156:159], v[188:191], v[126:129]
	v_mfma_f32_16x16x32_bf16 v[122:125], v[164:167], v[188:191], v[122:125]
	v_mfma_f32_16x16x32_bf16 v[110:113], v[156:159], v[196:199], v[110:113]
	v_mfma_f32_16x16x32_bf16 v[106:109], v[164:167], v[196:199], v[106:109]
	v_mfma_f32_16x16x32_bf16 v[94:97], v[156:159], v[204:207], v[94:97]
	v_mfma_f32_16x16x32_bf16 v[90:93], v[164:167], v[204:207], v[90:93]
	v_mfma_f32_16x16x32_bf16 v[78:81], v[156:159], v[212:215], v[78:81]
	v_mfma_f32_16x16x32_bf16 v[74:77], v[164:167], v[212:215], v[74:77]
	v_mfma_f32_16x16x32_bf16 v[118:121], v[168:171], v[184:187], v[118:121]
	v_mfma_f32_16x16x32_bf16 v[114:117], v[176:179], v[184:187], v[114:117]
	v_mfma_f32_16x16x32_bf16 v[102:105], v[168:171], v[192:195], v[102:105]
	v_mfma_f32_16x16x32_bf16 v[98:101], v[176:179], v[192:195], v[98:101]
	v_mfma_f32_16x16x32_bf16 v[86:89], v[168:171], v[200:203], v[86:89]
	v_mfma_f32_16x16x32_bf16 v[82:85], v[176:179], v[200:203], v[82:85]
	v_mfma_f32_16x16x32_bf16 v[70:73], v[168:171], v[208:211], v[70:73]
	v_mfma_f32_16x16x32_bf16 v[66:69], v[176:179], v[208:211], v[66:69]
	v_mfma_f32_16x16x32_bf16 v[118:121], v[172:175], v[188:191], v[118:121]
	v_mfma_f32_16x16x32_bf16 v[114:117], v[180:183], v[188:191], v[114:117]
	v_mfma_f32_16x16x32_bf16 v[102:105], v[172:175], v[196:199], v[102:105]
	v_mfma_f32_16x16x32_bf16 v[98:101], v[180:183], v[196:199], v[98:101]
	v_mfma_f32_16x16x32_bf16 v[86:89], v[172:175], v[204:207], v[86:89]
	v_mfma_f32_16x16x32_bf16 v[82:85], v[180:183], v[204:207], v[82:85]
	v_mfma_f32_16x16x32_bf16 v[70:73], v[172:175], v[212:215], v[70:73]
	v_mfma_f32_16x16x32_bf16 v[66:69], v[180:183], v[212:215], v[66:69]
	s_setprio 0
	s_barrier
	s_add_i32 s61, s54, s38
	v_lshl_add_u64 v[216:217], s[62:63], 0, v[132:133]
	s_mov_b32 m0, s61
	ds_read_b128 v[184:187], v154 offset:16384
	ds_read_b128 v[188:191], v154 offset:17408
	ds_read_b128 v[192:195], v154 offset:18432
	ds_read_b128 v[196:199], v154 offset:19456
	ds_read_b128 v[200:203], v154 offset:20480
	ds_read_b128 v[204:207], v154 offset:21504
	ds_read_b128 v[208:211], v154 offset:22528
	ds_read_b128 v[212:215], v154 offset:23552
	global_load_lds_dwordx4 v[216:217], off
	s_add_i32 m0, s61, 0x2000
	v_lshl_add_u64 v[218:219], s[62:63], 0, v[136:137]
	s_add_u32 s62, s62, s12
	s_addc_u32 s63, s63, s13
	s_add_i32 s61, s55, s38
	global_load_lds_dwordx4 v[218:219], off
	v_lshl_add_u64 v[220:221], s[62:63], 0, v[132:133]
	s_mov_b32 m0, s61
	v_lshl_add_u64 v[222:223], s[62:63], 0, v[136:137]
	global_load_lds_dwordx4 v[220:221], off
	s_add_i32 m0, s61, 0x2000
	v_lshl_add_u64 v[224:225], s[34:35], 0, v[130:131]
	global_load_lds_dwordx4 v[222:223], off
	s_mov_b32 m0, s39
	v_lshl_add_u64 v[226:227], s[34:35], 0, v[134:135]
	global_load_lds_dwordx4 v[224:225], off
	s_mov_b32 m0, s40
	s_nop 0
	global_load_lds_dwordx4 v[226:227], off
	s_waitcnt vmcnt(8) lgkmcnt(0)
	s_barrier
; #define PG8_STAGE(bufoff, gbase, voff) do { _Pragma("unroll") for (int _i = 0; _i < 2; ++_i) \
;         __builtin_amdgcn_global_load_lds((const unsigned*)((const char*)(gbase) + (voff)[_i]), (PG8_LAS unsigned*)(lds + (bufoff) + ldsw + _i * 8192), 16, 0, 0); } while (0)
; #define PG8_LDA(dst, b, h) do { _Pragma("unroll") for (int m = 0; m < 4; ++m) _Pragma("unroll") for (int k = 0; k < 2; ++k) dst[m][k] = *(const PG8_LAS bf16x8*)(lds + PG8_SA(b, h) + aoff + m * 2048 + k * 1024); } while (0)
; #define PG8_LDB(dst, b, h) do { _Pragma("unroll") for (int n = 0; n < 2; ++n) _Pragma("unroll") for (int k = 0; k < 2; ++k) dst[n][k] = *(const PG8_LAS bf16x8*)(lds + PG8_SB(b, h) + boff + n * 2048 + k * 1024); } while (0)
; #define PG8_MMA(ai, bj, At, Bt) do { __builtin_amdgcn_s_setprio(1); _Pragma("unroll") for (int m = 0; m < 4; ++m) _Pragma("unroll") for (int n = 0; n < 2; ++n) _Pragma("unroll") for (int k = 0; k < 2; ++k) \
;         acc[ai][bj][m][n] = __builtin_amdgcn_mfma_f32_16x16x32_bf16(Bt[n][k], At[m][k], acc[ai][bj][m][n], 0, 0, 0); __builtin_amdgcn_s_setprio(0); } while (0)
; #define PG8_WAIT_V(n) asm volatile("s_waitcnt vmcnt(" #n ")" ::: "memory")
; #define PG8_WAIT_L(n) asm volatile("s_waitcnt lgkmcnt(" #n ")" ::: "memory")
; #define PG8_BAR __builtin_amdgcn_s_barrier()
; #define PG8_SCHED __builtin_amdgcn_sched_barrier(0)
; template <class Epi, class Sched, bool ALIGN_EPI = false, bool SP2 = false>
; __device__ __forceinline__ void gemm_phase(PG8_LAS unsigned char* lds, const Gemm g, const Sched& S, const Epi& E) {
;     ...
;             PG8_WAIT_V(8); PG8_WAIT_L(0); PG8_BAR; PG8_MMA(1, 0, At, B0); PG8_MMA(1, 1, At, B1); PG8_BAR; PG8_SCHED;
;             PG8_LDB(B0, 1, 0); PG8_LDB(B1, 1, 1); PG8_SCHED; PG8_LDA(At, 1, 0); PG8_STAGE(PG8_SA(0, 1), a2 + hstep, voffA);
;             PG8_WAIT_V(8); PG8_WAIT_L(0); PG8_BAR; PG8_MMA(0, 0, At, B0); PG8_MMA(0, 1, At, B1); PG8_BAR; PG8_SCHED;
	s_setprio 1
	v_mfma_f32_16x16x32_bf16 v[62:65], v[146:149], v[184:187], v[62:65]
	v_mfma_f32_16x16x32_bf16 v[58:61], v[160:163], v[184:187], v[58:61]
	v_mfma_f32_16x16x32_bf16 v[46:49], v[146:149], v[192:195], v[46:49]
	v_mfma_f32_16x16x32_bf16 v[42:45], v[160:163], v[192:195], v[42:45]
	v_mfma_f32_16x16x32_bf16 v[30:33], v[146:149], v[200:203], v[30:33]
	v_mfma_f32_16x16x32_bf16 v[26:29], v[160:163], v[200:203], v[26:29]
	v_mfma_f32_16x16x32_bf16 v[14:17], v[146:149], v[208:211], v[14:17]
	v_mfma_f32_16x16x32_bf16 v[10:13], v[160:163], v[208:211], v[10:13]
	v_mfma_f32_16x16x32_bf16 v[62:65], v[156:159], v[188:191], v[62:65]
	v_mfma_f32_16x16x32_bf16 v[58:61], v[164:167], v[188:191], v[58:61]
	v_mfma_f32_16x16x32_bf16 v[46:49], v[156:159], v[196:199], v[46:49]
	v_mfma_f32_16x16x32_bf16 v[42:45], v[164:167], v[196:199], v[42:45]
	v_mfma_f32_16x16x32_bf16 v[30:33], v[156:159], v[204:207], v[30:33]
	v_mfma_f32_16x16x32_bf16 v[26:29], v[164:167], v[204:207], v[26:29]
	v_mfma_f32_16x16x32_bf16 v[14:17], v[156:159], v[212:215], v[14:17]
	v_mfma_f32_16x16x32_bf16 v[10:13], v[164:167], v[212:215], v[10:13]
	v_mfma_f32_16x16x32_bf16 v[54:57], v[168:171], v[184:187], v[54:57]
	v_mfma_f32_16x16x32_bf16 v[50:53], v[176:179], v[184:187], v[50:53]
	v_mfma_f32_16x16x32_bf16 v[38:41], v[168:171], v[192:195], v[38:41]
	v_mfma_f32_16x16x32_bf16 v[34:37], v[176:179], v[192:195], v[34:37]
	v_mfma_f32_16x16x32_bf16 v[22:25], v[168:171], v[200:203], v[22:25]
	v_mfma_f32_16x16x32_bf16 v[18:21], v[176:179], v[200:203], v[18:21]
	v_mfma_f32_16x16x32_bf16 v[6:9], v[168:171], v[208:211], v[6:9]
	v_mfma_f32_16x16x32_bf16 v[2:5], v[176:179], v[208:211], v[2:5]
	v_mfma_f32_16x16x32_bf16 v[54:57], v[172:175], v[188:191], v[54:57]
	v_mfma_f32_16x16x32_bf16 v[50:53], v[180:183], v[188:191], v[50:53]
	v_mfma_f32_16x16x32_bf16 v[38:41], v[172:175], v[196:199], v[38:41]
	v_mfma_f32_16x16x32_bf16 v[34:37], v[180:183], v[196:199], v[34:37]
	v_mfma_f32_16x16x32_bf16 v[22:25], v[172:175], v[204:207], v[22:25]
	v_mfma_f32_16x16x32_bf16 v[18:21], v[180:183], v[204:207], v[18:21]
	v_mfma_f32_16x16x32_bf16 v[6:9], v[172:175], v[212:215], v[6:9]
	v_mfma_f32_16x16x32_bf16 v[2:5], v[180:183], v[212:215], v[2:5]
	s_setprio 0
	s_barrier
	s_add_i32 s61, 0, 0x18000
	v_add_u32_e32 v155, s61, v150
	s_add_i32 s62, 0, 0x1c000
	ds_read_b128 v[146:149], v155
	ds_read_b128 v[156:159], v155 offset:1024
	ds_read_b128 v[160:163], v155 offset:2048
	ds_read_b128 v[164:167], v155 offset:3072
	v_add_u32_e32 v155, s62, v150
	ds_read_b128 v[168:171], v155
	ds_read_b128 v[172:175], v155 offset:1024
	ds_read_b128 v[176:179], v155 offset:2048
	ds_read_b128 v[180:183], v155 offset:3072
	s_add_u32 s34, s34, s12
	s_addc_u32 s35, s35, s13
	s_mov_b32 m0, s41
	v_lshl_add_u64 v[228:229], s[34:35], 0, v[130:131]
	ds_read_b128 v[184:187], v154 offset:32768
	ds_read_b128 v[188:191], v154 offset:33792
	ds_read_b128 v[192:195], v154 offset:34816
	ds_read_b128 v[196:199], v154 offset:35840
	ds_read_b128 v[200:203], v154 offset:36864
	ds_read_b128 v[204:207], v154 offset:37888
	ds_read_b128 v[208:211], v154 offset:38912
	ds_read_b128 v[212:215], v154 offset:39936
	global_load_lds_dwordx4 v[228:229], off
	v_lshl_add_u64 v[228:229], s[34:35], 0, v[134:135]
	s_mov_b32 m0, s42
	s_nop 0
	global_load_lds_dwordx4 v[228:229], off
	s_waitcnt vmcnt(8) lgkmcnt(0)
	s_barrier
	s_setprio 1
	v_mfma_f32_16x16x32_bf16 v[126:129], v[146:149], v[184:187], v[126:129]
	v_mfma_f32_16x16x32_bf16 v[122:125], v[160:163], v[184:187], v[122:125]
	v_mfma_f32_16x16x32_bf16 v[110:113], v[146:149], v[192:195], v[110:113]
	v_mfma_f32_16x16x32_bf16 v[106:109], v[160:163], v[192:195], v[106:109]
	v_mfma_f32_16x16x32_bf16 v[94:97], v[146:149], v[200:203], v[94:97]
	v_mfma_f32_16x16x32_bf16 v[90:93], v[160:163], v[200:203], v[90:93]
	v_mfma_f32_16x16x32_bf16 v[78:81], v[146:149], v[208:211], v[78:81]
	v_mfma_f32_16x16x32_bf16 v[74:77], v[160:163], v[208:211], v[74:77]
	v_mfma_f32_16x16x32_bf16 v[126:129], v[156:159], v[188:191], v[126:129]
	v_mfma_f32_16x16x32_bf16 v[122:125], v[164:167], v[188:191], v[122:125]
	v_mfma_f32_16x16x32_bf16 v[110:113], v[156:159], v[196:199], v[110:113]
	v_mfma_f32_16x16x32_bf16 v[106:109], v[164:167], v[196:199], v[106:109]
	v_mfma_f32_16x16x32_bf16 v[94:97], v[156:159], v[204:207], v[94:97]
	v_mfma_f32_16x16x32_bf16 v[90:93], v[164:167], v[204:207], v[90:93]
	v_mfma_f32_16x16x32_bf16 v[78:81], v[156:159], v[212:215], v[78:81]
	v_mfma_f32_16x16x32_bf16 v[74:77], v[164:167], v[212:215], v[74:77]
	v_mfma_f32_16x16x32_bf16 v[118:121], v[168:171], v[184:187], v[118:121]
	v_mfma_f32_16x16x32_bf16 v[114:117], v[176:179], v[184:187], v[114:117]
	v_mfma_f32_16x16x32_bf16 v[102:105], v[168:171], v[192:195], v[102:105]
	v_mfma_f32_16x16x32_bf16 v[98:101], v[176:179], v[192:195], v[98:101]
	v_mfma_f32_16x16x32_bf16 v[86:89], v[168:171], v[200:203], v[86:89]
	v_mfma_f32_16x16x32_bf16 v[82:85], v[176:179], v[200:203], v[82:85]
	v_mfma_f32_16x16x32_bf16 v[70:73], v[168:171], v[208:211], v[70:73]
	v_mfma_f32_16x16x32_bf16 v[66:69], v[176:179], v[208:211], v[66:69]
	v_mfma_f32_16x16x32_bf16 v[118:121], v[172:175], v[188:191], v[118:121]
	v_mfma_f32_16x16x32_bf16 v[114:117], v[180:183], v[188:191], v[114:117]
	v_mfma_f32_16x16x32_bf16 v[102:105], v[172:175], v[196:199], v[102:105]
	v_mfma_f32_16x16x32_bf16 v[98:101], v[180:183], v[196:199], v[98:101]
	v_mfma_f32_16x16x32_bf16 v[86:89], v[172:175], v[204:207], v[86:89]
	v_mfma_f32_16x16x32_bf16 v[82:85], v[180:183], v[204:207], v[82:85]
	v_mfma_f32_16x16x32_bf16 v[70:73], v[172:175], v[212:215], v[70:73]
	v_mfma_f32_16x16x32_bf16 v[66:69], v[180:183], v[212:215], v[66:69]
	s_setprio 0
	s_barrier
; #define PG8_STAGE(bufoff, gbase, voff) do { _Pragma("unroll") for (int _i = 0; _i < 2; ++_i) \
;         __builtin_amdgcn_global_load_lds((const unsigned*)((const char*)(gbase) + (voff)[_i]), (PG8_LAS unsigned*)(lds + (bufoff) + ldsw + _i * 8192), 16, 0, 0); } while (0)
; #define PG8_LDA(dst, b, h) do { _Pragma("unroll") for (int m = 0; m < 4; ++m) _Pragma("unroll") for (int k = 0; k < 2; ++k) dst[m][k] = *(const PG8_LAS bf16x8*)(lds + PG8_SA(b, h) + aoff + m * 2048 + k * 1024); } while (0)
; #define PG8_MMA(ai, bj, At, Bt) do { __builtin_amdgcn_s_setprio(1); _Pragma("unroll") for (int m = 0; m < 4; ++m) _Pragma("unroll") for (int n = 0; n < 2; ++n) _Pragma("unroll") for (int k = 0; k < 2; ++k) \
;         acc[ai][bj][m][n] = __builtin_amdgcn_mfma_f32_16x16x32_bf16(Bt[n][k], At[m][k], acc[ai][bj][m][n], 0, 0, 0); __builtin_amdgcn_s_setprio(0); } while (0)
; #define PG8_WAIT_V(n) asm volatile("s_waitcnt vmcnt(" #n ")" ::: "memory")
; #define PG8_WAIT_L(n) asm volatile("s_waitcnt lgkmcnt(" #n ")" ::: "memory")
; #define PG8_BAR __builtin_amdgcn_s_barrier()
; #define PG8_SCHED __builtin_amdgcn_sched_barrier(0)
; template <class Epi, class Sched, bool ALIGN_EPI = false, bool SP2 = false>
; __device__ __forceinline__ void gemm_phase(PG8_LAS unsigned char* lds, const Gemm g, const Sched& S, const Epi& E) {
;     ...
;             PG8_LDA(At, 1, 1); PG8_STAGE(PG8_SB(1, 0), b3, voffB); PG8_STAGE(PG8_SB(1, 1), b3 + hstep, voffB); PG8_STAGE(PG8_SA(1, 0), a3, voffA);
;             PG8_WAIT_V(8); PG8_WAIT_L(0); PG8_BAR; PG8_MMA(1, 0, At, B0); PG8_MMA(1, 1, At, B1); PG8_BAR; PG8_SCHED;
	s_add_i32 s34, s61, s38
	v_lshl_add_u64 v[216:217], v[216:217], 0, s[20:21]
	s_mov_b32 m0, s34
	ds_read_b128 v[184:187], v154 offset:49152
	ds_read_b128 v[188:191], v154 offset:50176
	ds_read_b128 v[192:195], v154 offset:51200
	ds_read_b128 v[196:199], v154 offset:52224
	ds_read_b128 v[200:203], v154 offset:53248
	ds_read_b128 v[204:207], v154 offset:54272
	ds_read_b128 v[208:211], v154 offset:55296
	ds_read_b128 v[212:215], v154 offset:56320
	global_load_lds_dwordx4 v[216:217], off
	v_lshl_add_u64 v[216:217], v[218:219], 0, s[20:21]
	s_add_i32 m0, s34, 0x2000
	s_add_i32 s34, s62, s38
	global_load_lds_dwordx4 v[216:217], off
	v_lshl_add_u64 v[216:217], v[220:221], 0, s[20:21]
	s_mov_b32 m0, s34
	s_nop 0
	global_load_lds_dwordx4 v[216:217], off
	v_lshl_add_u64 v[216:217], v[222:223], 0, s[20:21]
	s_add_i32 m0, s34, 0x2000
	s_nop 0
	global_load_lds_dwordx4 v[216:217], off
	v_lshl_add_u64 v[216:217], v[224:225], 0, s[20:21]
	s_mov_b32 m0, s46
	s_nop 0
	global_load_lds_dwordx4 v[216:217], off
	v_lshl_add_u64 v[216:217], v[226:227], 0, s[20:21]
	s_mov_b32 m0, s47
	s_nop 0
	global_load_lds_dwordx4 v[216:217], off
	s_waitcnt vmcnt(8) lgkmcnt(0)
	s_barrier
	s_setprio 1
	v_mfma_f32_16x16x32_bf16 v[62:65], v[146:149], v[184:187], v[62:65]
	v_mfma_f32_16x16x32_bf16 v[58:61], v[160:163], v[184:187], v[58:61]
	v_mfma_f32_16x16x32_bf16 v[46:49], v[146:149], v[192:195], v[46:49]
	v_mfma_f32_16x16x32_bf16 v[42:45], v[160:163], v[192:195], v[42:45]
	v_mfma_f32_16x16x32_bf16 v[30:33], v[146:149], v[200:203], v[30:33]
	v_mfma_f32_16x16x32_bf16 v[26:29], v[160:163], v[200:203], v[26:29]
	v_mfma_f32_16x16x32_bf16 v[14:17], v[146:149], v[208:211], v[14:17]
	v_mfma_f32_16x16x32_bf16 v[10:13], v[160:163], v[208:211], v[10:13]
	v_mfma_f32_16x16x32_bf16 v[62:65], v[156:159], v[188:191], v[62:65]
	v_mfma_f32_16x16x32_bf16 v[58:61], v[164:167], v[188:191], v[58:61]
	v_mfma_f32_16x16x32_bf16 v[46:49], v[156:159], v[196:199], v[46:49]
	v_mfma_f32_16x16x32_bf16 v[42:45], v[164:167], v[196:199], v[42:45]
	v_mfma_f32_16x16x32_bf16 v[30:33], v[156:159], v[204:207], v[30:33]
	v_mfma_f32_16x16x32_bf16 v[26:29], v[164:167], v[204:207], v[26:29]
	v_mfma_f32_16x16x32_bf16 v[14:17], v[156:159], v[212:215], v[14:17]
	v_mfma_f32_16x16x32_bf16 v[10:13], v[164:167], v[212:215], v[10:13]
	v_mfma_f32_16x16x32_bf16 v[54:57], v[168:171], v[184:187], v[54:57]
	v_mfma_f32_16x16x32_bf16 v[50:53], v[176:179], v[184:187], v[50:53]
	v_mfma_f32_16x16x32_bf16 v[38:41], v[168:171], v[192:195], v[38:41]
	v_mfma_f32_16x16x32_bf16 v[34:37], v[176:179], v[192:195], v[34:37]
	v_mfma_f32_16x16x32_bf16 v[22:25], v[168:171], v[200:203], v[22:25]
	v_mfma_f32_16x16x32_bf16 v[18:21], v[176:179], v[200:203], v[18:21]
	v_mfma_f32_16x16x32_bf16 v[6:9], v[168:171], v[208:211], v[6:9]
	v_mfma_f32_16x16x32_bf16 v[2:5], v[176:179], v[208:211], v[2:5]
	v_mfma_f32_16x16x32_bf16 v[54:57], v[172:175], v[188:191], v[54:57]
	v_mfma_f32_16x16x32_bf16 v[50:53], v[180:183], v[188:191], v[50:53]
	v_mfma_f32_16x16x32_bf16 v[38:41], v[172:175], v[196:199], v[38:41]
	v_mfma_f32_16x16x32_bf16 v[34:37], v[180:183], v[196:199], v[34:37]
	v_mfma_f32_16x16x32_bf16 v[22:25], v[172:175], v[204:207], v[22:25]
	v_mfma_f32_16x16x32_bf16 v[18:21], v[180:183], v[204:207], v[18:21]
	v_mfma_f32_16x16x32_bf16 v[6:9], v[172:175], v[212:215], v[6:9]
	v_mfma_f32_16x16x32_bf16 v[2:5], v[180:183], v[212:215], v[2:5]
	s_setprio 0
	s_barrier
	s_add_u32 s58, s58, 0x100
	s_addc_u32 s59, s59, 0
	s_add_u32 s30, s30, 0x100
	s_addc_u32 s31, s31, 0
	s_cmp_ge_i32 s60, s52
	s_mov_b32 s34, s60
	s_cbranch_scc0 .LBB0_497

; #define PG8_STAGE(bufoff, gbase, voff) do { _Pragma("unroll") for (int _i = 0; _i < 2; ++_i) \
;         __builtin_amdgcn_global_load_lds((const unsigned*)((const char*)(gbase) + (voff)[_i]), (PG8_LAS unsigned*)(lds + (bufoff) + ldsw + _i * 8192), 16, 0, 0); } while (0)
; #define PG8_LDA(dst, b, h) do { _Pragma("unroll") for (int m = 0; m < 4; ++m) _Pragma("unroll") for (int k = 0; k < 2; ++k) dst[m][k] = *(const PG8_LAS bf16x8*)(lds + PG8_SA(b, h) + aoff + m * 2048 + k * 1024); } while (0)
; #define PG8_LDB(dst, b, h) do { _Pragma("unroll") for (int n = 0; n < 2; ++n) _Pragma("unroll") for (int k = 0; k < 2; ++k) dst[n][k] = *(const PG8_LAS bf16x8*)(lds + PG8_SB(b, h) + boff + n * 2048 + k * 1024); } while (0)
; #define PG8_MMA(ai, bj, At, Bt) do { __builtin_amdgcn_s_setprio(1); _Pragma("unroll") for (int m = 0; m < 4; ++m) _Pragma("unroll") for (int n = 0; n < 2; ++n) _Pragma("unroll") for (int k = 0; k < 2; ++k) \
;         acc[ai][bj][m][n] = __builtin_amdgcn_mfma_f32_16x16x32_bf16(Bt[n][k], At[m][k], acc[ai][bj][m][n], 0, 0, 0); __builtin_amdgcn_s_setprio(0); } while (0)
; #define PG8_WAIT_V(n) asm volatile("s_waitcnt vmcnt(" #n ")" ::: "memory")
; #define PG8_WAIT_L(n) asm volatile("s_waitcnt lgkmcnt(" #n ")" ::: "memory")
; template <class Epi, class Sched, bool ALIGN_EPI = false, bool SP2 = false>
; __device__ __forceinline__ void gemm_phase(PG8_LAS unsigned char* lds, const Gemm g, const Sched& S, const Epi& E) {
;     ...
;             const bool last = (t == nt - 2);
;             const char* a1 = cA + (size_t)(t + 1) * kstep;
;             const char* a2 = last ? nA : cA + (size_t)(t + 2) * kstep; const char* b2 = last ? nB : cB + (size_t)(t + 2) * kstep;
;             const char* a3 = a2 + kstep; const char* b3 = b2 + kstep;
;             if (last && has_next) S.a_ready(nxt);
;             if constexpr (SP2) {
;             PG8_LDB(B0, 0, 0); PG8_LDB(B1, 0, 1); PG8_SCHED; PG8_LDA(At, 0, 0); PG8_STAGE(PG8_SA(1, 1), a1 + hstep, voffA);
;             PG8_WAIT_V(8); PG8_WAIT_L(0); PG8_BAR; PG8_MMA(0, 0, At, B0); PG8_MMA(0, 1, At, B1); PG8_BAR; PG8_SCHED;
;             PG8_LDA(At, 0, 1); PG8_STAGE(PG8_SB(0, 0), b2, voffB); PG8_STAGE(PG8_SB(0, 1), b2 + hstep, voffB); PG8_STAGE(PG8_SA(0, 0), a2, voffA);
;             PG8_WAIT_V(8); PG8_WAIT_L(0); PG8_BAR; PG8_MMA(1, 0, At, B0); PG8_MMA(1, 1, At, B1); PG8_BAR; PG8_SCHED;
.LBB0_582:
	ds_read_b128 v[152:155], v148
	ds_read_b128 v[156:159], v148 offset:1024
	ds_read_b128 v[160:163], v148 offset:2048
	ds_read_b128 v[164:167], v148 offset:3072
	ds_read_b128 v[168:171], v149
	ds_read_b128 v[172:175], v149 offset:1024
	ds_read_b128 v[176:179], v149 offset:2048
	ds_read_b128 v[180:183], v149 offset:3072
	s_add_i32 s60, s30, 2
	s_add_u32 s61, s28, 0x80
	s_addc_u32 s31, s29, 0
	s_cmp_eq_u32 s45, s30
	s_cselect_b32 s30, s6, s61
	s_cselect_b32 s31, s7, s31
	s_cselect_b32 s63, s25, s59
	s_cselect_b32 s62, s24, s58
	v_lshl_add_u64 v[216:217], s[28:29], 0, v[140:141]
	s_add_i32 m0, s0, 0xc000
	ds_read_b128 v[184:187], v150
	ds_read_b128 v[188:191], v150 offset:1024
	ds_read_b128 v[192:195], v150 offset:2048
	ds_read_b128 v[196:199], v150 offset:3072
	ds_read_b128 v[200:203], v150 offset:4096
	ds_read_b128 v[204:207], v150 offset:5120
	ds_read_b128 v[208:211], v150 offset:6144
	ds_read_b128 v[212:215], v150 offset:7168
	global_load_lds_dwordx4 v[216:217], off
	v_lshl_add_u64 v[216:217], s[28:29], 0, v[138:139]
	s_add_i32 m0, s0, 0xe000
	s_nop 0
	global_load_lds_dwordx4 v[216:217], off
	s_waitcnt vmcnt(8) lgkmcnt(0)
	s_barrier
	s_setprio 1
	v_mfma_f32_16x16x32_bf16 v[122:125], v[152:155], v[184:187], v[122:125]
	v_mfma_f32_16x16x32_bf16 v[126:129], v[160:163], v[184:187], v[126:129]
	v_mfma_f32_16x16x32_bf16 v[110:113], v[152:155], v[192:195], v[110:113]
	v_mfma_f32_16x16x32_bf16 v[106:109], v[160:163], v[192:195], v[106:109]
	v_mfma_f32_16x16x32_bf16 v[94:97], v[152:155], v[200:203], v[94:97]
	v_mfma_f32_16x16x32_bf16 v[90:93], v[160:163], v[200:203], v[90:93]
	v_mfma_f32_16x16x32_bf16 v[78:81], v[152:155], v[208:211], v[78:81]
	v_mfma_f32_16x16x32_bf16 v[74:77], v[160:163], v[208:211], v[74:77]
	v_mfma_f32_16x16x32_bf16 v[122:125], v[156:159], v[188:191], v[122:125]
	v_mfma_f32_16x16x32_bf16 v[126:129], v[164:167], v[188:191], v[126:129]
	v_mfma_f32_16x16x32_bf16 v[110:113], v[156:159], v[196:199], v[110:113]
	v_mfma_f32_16x16x32_bf16 v[106:109], v[164:167], v[196:199], v[106:109]
	v_mfma_f32_16x16x32_bf16 v[94:97], v[156:159], v[204:207], v[94:97]
	v_mfma_f32_16x16x32_bf16 v[90:93], v[164:167], v[204:207], v[90:93]
	v_mfma_f32_16x16x32_bf16 v[78:81], v[156:159], v[212:215], v[78:81]
	v_mfma_f32_16x16x32_bf16 v[74:77], v[164:167], v[212:215], v[74:77]
	v_mfma_f32_16x16x32_bf16 v[118:121], v[168:171], v[184:187], v[118:121]
	v_mfma_f32_16x16x32_bf16 v[114:117], v[176:179], v[184:187], v[114:117]
	v_mfma_f32_16x16x32_bf16 v[102:105], v[168:171], v[192:195], v[102:105]
	v_mfma_f32_16x16x32_bf16 v[98:101], v[176:179], v[192:195], v[98:101]
	v_mfma_f32_16x16x32_bf16 v[86:89], v[168:171], v[200:203], v[86:89]
	v_mfma_f32_16x16x32_bf16 v[82:85], v[176:179], v[200:203], v[82:85]
	v_mfma_f32_16x16x32_bf16 v[70:73], v[168:171], v[208:211], v[70:73]
	v_mfma_f32_16x16x32_bf16 v[66:69], v[176:179], v[208:211], v[66:69]
	v_mfma_f32_16x16x32_bf16 v[118:121], v[172:175], v[188:191], v[118:121]
	v_mfma_f32_16x16x32_bf16 v[114:117], v[180:183], v[188:191], v[114:117]
	v_mfma_f32_16x16x32_bf16 v[102:105], v[172:175], v[196:199], v[102:105]
	v_mfma_f32_16x16x32_bf16 v[98:101], v[180:183], v[196:199], v[98:101]
	v_mfma_f32_16x16x32_bf16 v[86:89], v[172:175], v[204:207], v[86:89]
	v_mfma_f32_16x16x32_bf16 v[82:85], v[180:183], v[204:207], v[82:85]
	v_mfma_f32_16x16x32_bf16 v[70:73], v[172:175], v[212:215], v[70:73]
	v_mfma_f32_16x16x32_bf16 v[66:69], v[180:183], v[212:215], v[66:69]
	s_setprio 0
	s_barrier
	s_add_i32 s61, s52, s38
	v_lshl_add_u64 v[216:217], s[62:63], 0, v[132:133]
	s_mov_b32 m0, s61
	ds_read_b128 v[184:187], v150 offset:16384
	ds_read_b128 v[188:191], v150 offset:17408
	ds_read_b128 v[192:195], v150 offset:18432
	ds_read_b128 v[196:199], v150 offset:19456
	ds_read_b128 v[200:203], v150 offset:20480
	ds_read_b128 v[204:207], v150 offset:21504
	ds_read_b128 v[208:211], v150 offset:22528
	ds_read_b128 v[212:215], v150 offset:23552
	global_load_lds_dwordx4 v[216:217], off
	s_add_i32 m0, s61, 0x2000
	v_lshl_add_u64 v[218:219], s[62:63], 0, v[136:137]
	s_add_u32 s62, s62, s10
	s_addc_u32 s63, s63, s11
	s_add_i32 s61, s53, s38
	global_load_lds_dwordx4 v[218:219], off
	v_lshl_add_u64 v[220:221], s[62:63], 0, v[132:133]
	s_mov_b32 m0, s61
	v_lshl_add_u64 v[222:223], s[62:63], 0, v[136:137]
	global_load_lds_dwordx4 v[220:221], off
	s_add_i32 m0, s61, 0x2000
	v_lshl_add_u64 v[224:225], s[30:31], 0, v[130:131]
	global_load_lds_dwordx4 v[222:223], off
	s_mov_b32 m0, s0
	v_lshl_add_u64 v[226:227], s[30:31], 0, v[134:135]
	global_load_lds_dwordx4 v[224:225], off
	s_mov_b32 m0, s1
	s_nop 0
	global_load_lds_dwordx4 v[226:227], off
	s_waitcnt vmcnt(8) lgkmcnt(0)
	s_barrier
; #define PG8_STAGE(bufoff, gbase, voff) do { _Pragma("unroll") for (int _i = 0; _i < 2; ++_i) \
;         __builtin_amdgcn_global_load_lds((const unsigned*)((const char*)(gbase) + (voff)[_i]), (PG8_LAS unsigned*)(lds + (bufoff) + ldsw + _i * 8192), 16, 0, 0); } while (0)
; #define PG8_LDA(dst, b, h) do { _Pragma("unroll") for (int m = 0; m < 4; ++m) _Pragma("unroll") for (int k = 0; k < 2; ++k) dst[m][k] = *(const PG8_LAS bf16x8*)(lds + PG8_SA(b, h) + aoff + m * 2048 + k * 1024); } while (0)
; #define PG8_LDB(dst, b, h) do { _Pragma("unroll") for (int n = 0; n < 2; ++n) _Pragma("unroll") for (int k = 0; k < 2; ++k) dst[n][k] = *(const PG8_LAS bf16x8*)(lds + PG8_SB(b, h) + boff + n * 2048 + k * 1024); } while (0)
; #define PG8_MMA(ai, bj, At, Bt) do { __builtin_amdgcn_s_setprio(1); _Pragma("unroll") for (int m = 0; m < 4; ++m) _Pragma("unroll") for (int n = 0; n < 2; ++n) _Pragma("unroll") for (int k = 0; k < 2; ++k) \
;         acc[ai][bj][m][n] = __builtin_amdgcn_mfma_f32_16x16x32_bf16(Bt[n][k], At[m][k], acc[ai][bj][m][n], 0, 0, 0); __builtin_amdgcn_s_setprio(0); } while (0)
; #define PG8_WAIT_V(n) asm volatile("s_waitcnt vmcnt(" #n ")" ::: "memory")
; #define PG8_WAIT_L(n) asm volatile("s_waitcnt lgkmcnt(" #n ")" ::: "memory")
; #define PG8_BAR __builtin_amdgcn_s_barrier()
; #define PG8_SCHED __builtin_amdgcn_sched_barrier(0)
; template <class Epi, class Sched, bool ALIGN_EPI = false, bool SP2 = false>
; __device__ __forceinline__ void gemm_phase(PG8_LAS unsigned char* lds, const Gemm g, const Sched& S, const Epi& E) {
;     ...
;             PG8_WAIT_V(8); PG8_WAIT_L(0); PG8_BAR; PG8_MMA(1, 0, At, B0); PG8_MMA(1, 1, At, B1); PG8_BAR; PG8_SCHED;
;             PG8_LDB(B0, 1, 0); PG8_LDB(B1, 1, 1); PG8_SCHED; PG8_LDA(At, 1, 0); PG8_STAGE(PG8_SA(0, 1), a2 + hstep, voffA);
;             PG8_WAIT_V(8); PG8_WAIT_L(0); PG8_BAR; PG8_MMA(0, 0, At, B0); PG8_MMA(0, 1, At, B1); PG8_BAR; PG8_SCHED;
	s_setprio 1
	v_mfma_f32_16x16x32_bf16 v[62:65], v[152:155], v[184:187], v[62:65]
	v_mfma_f32_16x16x32_bf16 v[58:61], v[160:163], v[184:187], v[58:61]
	v_mfma_f32_16x16x32_bf16 v[46:49], v[152:155], v[192:195], v[46:49]
	v_mfma_f32_16x16x32_bf16 v[42:45], v[160:163], v[192:195], v[42:45]
	v_mfma_f32_16x16x32_bf16 v[30:33], v[152:155], v[200:203], v[30:33]
	v_mfma_f32_16x16x32_bf16 v[26:29], v[160:163], v[200:203], v[26:29]
	v_mfma_f32_16x16x32_bf16 v[14:17], v[152:155], v[208:211], v[14:17]
	v_mfma_f32_16x16x32_bf16 v[10:13], v[160:163], v[208:211], v[10:13]
	v_mfma_f32_16x16x32_bf16 v[62:65], v[156:159], v[188:191], v[62:65]
	v_mfma_f32_16x16x32_bf16 v[58:61], v[164:167], v[188:191], v[58:61]
	v_mfma_f32_16x16x32_bf16 v[46:49], v[156:159], v[196:199], v[46:49]
	v_mfma_f32_16x16x32_bf16 v[42:45], v[164:167], v[196:199], v[42:45]
	v_mfma_f32_16x16x32_bf16 v[30:33], v[156:159], v[204:207], v[30:33]
	v_mfma_f32_16x16x32_bf16 v[26:29], v[164:167], v[204:207], v[26:29]
	v_mfma_f32_16x16x32_bf16 v[14:17], v[156:159], v[212:215], v[14:17]
	v_mfma_f32_16x16x32_bf16 v[10:13], v[164:167], v[212:215], v[10:13]
	v_mfma_f32_16x16x32_bf16 v[54:57], v[168:171], v[184:187], v[54:57]
	v_mfma_f32_16x16x32_bf16 v[50:53], v[176:179], v[184:187], v[50:53]
	v_mfma_f32_16x16x32_bf16 v[38:41], v[168:171], v[192:195], v[38:41]
	v_mfma_f32_16x16x32_bf16 v[34:37], v[176:179], v[192:195], v[34:37]
	v_mfma_f32_16x16x32_bf16 v[22:25], v[168:171], v[200:203], v[22:25]
	v_mfma_f32_16x16x32_bf16 v[18:21], v[176:179], v[200:203], v[18:21]
	v_mfma_f32_16x16x32_bf16 v[6:9], v[168:171], v[208:211], v[6:9]
	v_mfma_f32_16x16x32_bf16 v[2:5], v[176:179], v[208:211], v[2:5]
	v_mfma_f32_16x16x32_bf16 v[54:57], v[172:175], v[188:191], v[54:57]
	v_mfma_f32_16x16x32_bf16 v[50:53], v[180:183], v[188:191], v[50:53]
	v_mfma_f32_16x16x32_bf16 v[38:41], v[172:175], v[196:199], v[38:41]
	v_mfma_f32_16x16x32_bf16 v[34:37], v[180:183], v[196:199], v[34:37]
	v_mfma_f32_16x16x32_bf16 v[22:25], v[172:175], v[204:207], v[22:25]
	v_mfma_f32_16x16x32_bf16 v[18:21], v[180:183], v[204:207], v[18:21]
	v_mfma_f32_16x16x32_bf16 v[6:9], v[172:175], v[212:215], v[6:9]
	v_mfma_f32_16x16x32_bf16 v[2:5], v[180:183], v[212:215], v[2:5]
	s_setprio 0
	s_barrier
	s_add_i32 s61, 0, 0x18000
	v_add_u32_e32 v151, s61, v146
	s_add_i32 s62, 0, 0x1c000
	ds_read_b128 v[152:155], v151
	ds_read_b128 v[156:159], v151 offset:1024
	ds_read_b128 v[160:163], v151 offset:2048
	ds_read_b128 v[164:167], v151 offset:3072
	v_add_u32_e32 v151, s62, v146
	ds_read_b128 v[168:171], v151
	ds_read_b128 v[172:175], v151 offset:1024
	ds_read_b128 v[176:179], v151 offset:2048
	ds_read_b128 v[180:183], v151 offset:3072
	s_add_u32 s30, s30, s10
	s_addc_u32 s31, s31, s11
	s_mov_b32 m0, s39
	v_lshl_add_u64 v[228:229], s[30:31], 0, v[130:131]
	ds_read_b128 v[184:187], v150 offset:32768
	ds_read_b128 v[188:191], v150 offset:33792
	ds_read_b128 v[192:195], v150 offset:34816
	ds_read_b128 v[196:199], v150 offset:35840
	ds_read_b128 v[200:203], v150 offset:36864
	ds_read_b128 v[204:207], v150 offset:37888
	ds_read_b128 v[208:211], v150 offset:38912
	ds_read_b128 v[212:215], v150 offset:39936
	global_load_lds_dwordx4 v[228:229], off
	v_lshl_add_u64 v[228:229], s[30:31], 0, v[134:135]
	s_mov_b32 m0, s40
	s_nop 0
	global_load_lds_dwordx4 v[228:229], off
	s_waitcnt vmcnt(8) lgkmcnt(0)
	s_barrier
	s_setprio 1
	v_mfma_f32_16x16x32_bf16 v[122:125], v[152:155], v[184:187], v[122:125]
	v_mfma_f32_16x16x32_bf16 v[126:129], v[160:163], v[184:187], v[126:129]
	v_mfma_f32_16x16x32_bf16 v[110:113], v[152:155], v[192:195], v[110:113]
	v_mfma_f32_16x16x32_bf16 v[106:109], v[160:163], v[192:195], v[106:109]
	v_mfma_f32_16x16x32_bf16 v[94:97], v[152:155], v[200:203], v[94:97]
	v_mfma_f32_16x16x32_bf16 v[90:93], v[160:163], v[200:203], v[90:93]
	v_mfma_f32_16x16x32_bf16 v[78:81], v[152:155], v[208:211], v[78:81]
	v_mfma_f32_16x16x32_bf16 v[74:77], v[160:163], v[208:211], v[74:77]
	v_mfma_f32_16x16x32_bf16 v[122:125], v[156:159], v[188:191], v[122:125]
	v_mfma_f32_16x16x32_bf16 v[126:129], v[164:167], v[188:191], v[126:129]
	v_mfma_f32_16x16x32_bf16 v[110:113], v[156:159], v[196:199], v[110:113]
	v_mfma_f32_16x16x32_bf16 v[106:109], v[164:167], v[196:199], v[106:109]
	v_mfma_f32_16x16x32_bf16 v[94:97], v[156:159], v[204:207], v[94:97]
	v_mfma_f32_16x16x32_bf16 v[90:93], v[164:167], v[204:207], v[90:93]
	v_mfma_f32_16x16x32_bf16 v[78:81], v[156:159], v[212:215], v[78:81]
	v_mfma_f32_16x16x32_bf16 v[74:77], v[164:167], v[212:215], v[74:77]
	v_mfma_f32_16x16x32_bf16 v[118:121], v[168:171], v[184:187], v[118:121]
	v_mfma_f32_16x16x32_bf16 v[114:117], v[176:179], v[184:187], v[114:117]
	v_mfma_f32_16x16x32_bf16 v[102:105], v[168:171], v[192:195], v[102:105]
	v_mfma_f32_16x16x32_bf16 v[98:101], v[176:179], v[192:195], v[98:101]
	v_mfma_f32_16x16x32_bf16 v[86:89], v[168:171], v[200:203], v[86:89]
	v_mfma_f32_16x16x32_bf16 v[82:85], v[176:179], v[200:203], v[82:85]
	v_mfma_f32_16x16x32_bf16 v[70:73], v[168:171], v[208:211], v[70:73]
	v_mfma_f32_16x16x32_bf16 v[66:69], v[176:179], v[208:211], v[66:69]
	v_mfma_f32_16x16x32_bf16 v[118:121], v[172:175], v[188:191], v[118:121]
	v_mfma_f32_16x16x32_bf16 v[114:117], v[180:183], v[188:191], v[114:117]
	v_mfma_f32_16x16x32_bf16 v[102:105], v[172:175], v[196:199], v[102:105]
	v_mfma_f32_16x16x32_bf16 v[98:101], v[180:183], v[196:199], v[98:101]
	v_mfma_f32_16x16x32_bf16 v[86:89], v[172:175], v[204:207], v[86:89]
	v_mfma_f32_16x16x32_bf16 v[82:85], v[180:183], v[204:207], v[82:85]
	v_mfma_f32_16x16x32_bf16 v[70:73], v[172:175], v[212:215], v[70:73]
	v_mfma_f32_16x16x32_bf16 v[66:69], v[180:183], v[212:215], v[66:69]
	s_setprio 0
	s_barrier
; #define PG8_STAGE(bufoff, gbase, voff) do { _Pragma("unroll") for (int _i = 0; _i < 2; ++_i) \
;         __builtin_amdgcn_global_load_lds((const unsigned*)((const char*)(gbase) + (voff)[_i]), (PG8_LAS unsigned*)(lds + (bufoff) + ldsw + _i * 8192), 16, 0, 0); } while (0)
; #define PG8_LDA(dst, b, h) do { _Pragma("unroll") for (int m = 0; m < 4; ++m) _Pragma("unroll") for (int k = 0; k < 2; ++k) dst[m][k] = *(const PG8_LAS bf16x8*)(lds + PG8_SA(b, h) + aoff + m * 2048 + k * 1024); } while (0)
; #define PG8_MMA(ai, bj, At, Bt) do { __builtin_amdgcn_s_setprio(1); _Pragma("unroll") for (int m = 0; m < 4; ++m) _Pragma("unroll") for (int n = 0; n < 2; ++n) _Pragma("unroll") for (int k = 0; k < 2; ++k) \
;         acc[ai][bj][m][n] = __builtin_amdgcn_mfma_f32_16x16x32_bf16(Bt[n][k], At[m][k], acc[ai][bj][m][n], 0, 0, 0); __builtin_amdgcn_s_setprio(0); } while (0)
; #define PG8_WAIT_V(n) asm volatile("s_waitcnt vmcnt(" #n ")" ::: "memory")
; #define PG8_WAIT_L(n) asm volatile("s_waitcnt lgkmcnt(" #n ")" ::: "memory")
; #define PG8_BAR __builtin_amdgcn_s_barrier()
; #define PG8_SCHED __builtin_amdgcn_sched_barrier(0)
; template <class Epi, class Sched, bool ALIGN_EPI = false, bool SP2 = false>
; __device__ __forceinline__ void gemm_phase(PG8_LAS unsigned char* lds, const Gemm g, const Sched& S, const Epi& E) {
;     ...
;             PG8_LDA(At, 1, 1); PG8_STAGE(PG8_SB(1, 0), b3, voffB); PG8_STAGE(PG8_SB(1, 1), b3 + hstep, voffB); PG8_STAGE(PG8_SA(1, 0), a3, voffA);
;             PG8_WAIT_V(8); PG8_WAIT_L(0); PG8_BAR; PG8_MMA(1, 0, At, B0); PG8_MMA(1, 1, At, B1); PG8_BAR; PG8_SCHED;
	s_add_i32 s30, s61, s38
	v_lshl_add_u64 v[216:217], v[216:217], 0, s[18:19]
	s_mov_b32 m0, s30
	ds_read_b128 v[184:187], v150 offset:49152
	ds_read_b128 v[188:191], v150 offset:50176
	ds_read_b128 v[192:195], v150 offset:51200
	ds_read_b128 v[196:199], v150 offset:52224
	ds_read_b128 v[200:203], v150 offset:53248
	ds_read_b128 v[204:207], v150 offset:54272
	ds_read_b128 v[208:211], v150 offset:55296
	ds_read_b128 v[212:215], v150 offset:56320
	global_load_lds_dwordx4 v[216:217], off
	v_lshl_add_u64 v[216:217], v[218:219], 0, s[18:19]
	s_add_i32 m0, s30, 0x2000
	s_add_i32 s30, s62, s38
	global_load_lds_dwordx4 v[216:217], off
	v_lshl_add_u64 v[216:217], v[220:221], 0, s[18:19]
	s_mov_b32 m0, s30
	s_nop 0
	global_load_lds_dwordx4 v[216:217], off
	v_lshl_add_u64 v[216:217], v[222:223], 0, s[18:19]
	s_add_i32 m0, s30, 0x2000
	s_nop 0
	global_load_lds_dwordx4 v[216:217], off
	v_lshl_add_u64 v[216:217], v[224:225], 0, s[18:19]
	s_mov_b32 m0, s42
	s_nop 0
	global_load_lds_dwordx4 v[216:217], off
	v_lshl_add_u64 v[216:217], v[226:227], 0, s[18:19]
	s_mov_b32 m0, s43
	s_nop 0
	global_load_lds_dwordx4 v[216:217], off
	s_waitcnt vmcnt(8) lgkmcnt(0)
	s_barrier
	s_setprio 1
	v_mfma_f32_16x16x32_bf16 v[62:65], v[152:155], v[184:187], v[62:65]
	v_mfma_f32_16x16x32_bf16 v[58:61], v[160:163], v[184:187], v[58:61]
	v_mfma_f32_16x16x32_bf16 v[46:49], v[152:155], v[192:195], v[46:49]
	v_mfma_f32_16x16x32_bf16 v[42:45], v[160:163], v[192:195], v[42:45]
	v_mfma_f32_16x16x32_bf16 v[30:33], v[152:155], v[200:203], v[30:33]
	v_mfma_f32_16x16x32_bf16 v[26:29], v[160:163], v[200:203], v[26:29]
	v_mfma_f32_16x16x32_bf16 v[14:17], v[152:155], v[208:211], v[14:17]
	v_mfma_f32_16x16x32_bf16 v[10:13], v[160:163], v[208:211], v[10:13]
	v_mfma_f32_16x16x32_bf16 v[62:65], v[156:159], v[188:191], v[62:65]
	v_mfma_f32_16x16x32_bf16 v[58:61], v[164:167], v[188:191], v[58:61]
	v_mfma_f32_16x16x32_bf16 v[46:49], v[156:159], v[196:199], v[46:49]
	v_mfma_f32_16x16x32_bf16 v[42:45], v[164:167], v[196:199], v[42:45]
	v_mfma_f32_16x16x32_bf16 v[30:33], v[156:159], v[204:207], v[30:33]
	v_mfma_f32_16x16x32_bf16 v[26:29], v[164:167], v[204:207], v[26:29]
	v_mfma_f32_16x16x32_bf16 v[14:17], v[156:159], v[212:215], v[14:17]
	v_mfma_f32_16x16x32_bf16 v[10:13], v[164:167], v[212:215], v[10:13]
	v_mfma_f32_16x16x32_bf16 v[54:57], v[168:171], v[184:187], v[54:57]
	v_mfma_f32_16x16x32_bf16 v[50:53], v[176:179], v[184:187], v[50:53]
	v_mfma_f32_16x16x32_bf16 v[38:41], v[168:171], v[192:195], v[38:41]
	v_mfma_f32_16x16x32_bf16 v[34:37], v[176:179], v[192:195], v[34:37]
	v_mfma_f32_16x16x32_bf16 v[22:25], v[168:171], v[200:203], v[22:25]
	v_mfma_f32_16x16x32_bf16 v[18:21], v[176:179], v[200:203], v[18:21]
	v_mfma_f32_16x16x32_bf16 v[6:9], v[168:171], v[208:211], v[6:9]
	v_mfma_f32_16x16x32_bf16 v[2:5], v[176:179], v[208:211], v[2:5]
	v_mfma_f32_16x16x32_bf16 v[54:57], v[172:175], v[188:191], v[54:57]
	v_mfma_f32_16x16x32_bf16 v[50:53], v[180:183], v[188:191], v[50:53]
	v_mfma_f32_16x16x32_bf16 v[38:41], v[172:175], v[196:199], v[38:41]
	v_mfma_f32_16x16x32_bf16 v[34:37], v[180:183], v[196:199], v[34:37]
	v_mfma_f32_16x16x32_bf16 v[22:25], v[172:175], v[204:207], v[22:25]
	v_mfma_f32_16x16x32_bf16 v[18:21], v[180:183], v[204:207], v[18:21]
	v_mfma_f32_16x16x32_bf16 v[6:9], v[172:175], v[212:215], v[6:9]
	v_mfma_f32_16x16x32_bf16 v[2:5], v[180:183], v[212:215], v[2:5]
	s_setprio 0
	s_barrier
	s_add_u32 s58, s58, 0x100
	s_addc_u32 s59, s59, 0
	s_add_u32 s28, s28, 0x100
	s_addc_u32 s29, s29, 0
	s_cmp_ge_i32 s60, s44
	s_mov_b32 s30, s60
	s_cbranch_scc0 .LBB0_582

; #define PG8_STAGE(bufoff, gbase, voff) do { _Pragma("unroll") for (int _i = 0; _i < 2; ++_i) \
;         __builtin_amdgcn_global_load_lds((const unsigned*)((const char*)(gbase) + (voff)[_i]), (PG8_LAS unsigned*)(lds + (bufoff) + ldsw + _i * 8192), 16, 0, 0); } while (0)
; #define PG8_LDA(dst, b, h) do { _Pragma("unroll") for (int m = 0; m < 4; ++m) _Pragma("unroll") for (int k = 0; k < 2; ++k) dst[m][k] = *(const PG8_LAS bf16x8*)(lds + PG8_SA(b, h) + aoff + m * 2048 + k * 1024); } while (0)
; #define PG8_LDB(dst, b, h) do { _Pragma("unroll") for (int n = 0; n < 2; ++n) _Pragma("unroll") for (int k = 0; k < 2; ++k) dst[n][k] = *(const PG8_LAS bf16x8*)(lds + PG8_SB(b, h) + boff + n * 2048 + k * 1024); } while (0)
; #define PG8_MMA(ai, bj, At, Bt) do { __builtin_amdgcn_s_setprio(1); _Pragma("unroll") for (int m = 0; m < 4; ++m) _Pragma("unroll") for (int n = 0; n < 2; ++n) _Pragma("unroll") for (int k = 0; k < 2; ++k) \
;         acc[ai][bj][m][n] = __builtin_amdgcn_mfma_f32_16x16x32_bf16(Bt[n][k], At[m][k], acc[ai][bj][m][n], 0, 0, 0); __builtin_amdgcn_s_setprio(0); } while (0)
; #define PG8_WAIT_V(n) asm volatile("s_waitcnt vmcnt(" #n ")" ::: "memory")
; #define PG8_WAIT_L(n) asm volatile("s_waitcnt lgkmcnt(" #n ")" ::: "memory")
; template <class Epi, class Sched, bool ALIGN_EPI = false, bool SP2 = false>
; __device__ __forceinline__ void gemm_phase(PG8_LAS unsigned char* lds, const Gemm g, const Sched& S, const Epi& E) {
;     ...
;             const bool last = (t == nt - 2);
;             const char* a1 = cA + (size_t)(t + 1) * kstep;
;             const char* a2 = last ? nA : cA + (size_t)(t + 2) * kstep; const char* b2 = last ? nB : cB + (size_t)(t + 2) * kstep;
;             const char* a3 = a2 + kstep; const char* b3 = b2 + kstep;
;             if (last && has_next) S.a_ready(nxt);
;             if constexpr (SP2) {
;             PG8_LDB(B0, 0, 0); PG8_LDB(B1, 0, 1); PG8_SCHED; PG8_LDA(At, 0, 0); PG8_STAGE(PG8_SA(1, 1), a1 + hstep, voffA);
;             PG8_WAIT_V(8); PG8_WAIT_L(0); PG8_BAR; PG8_MMA(0, 0, At, B0); PG8_MMA(0, 1, At, B1); PG8_BAR; PG8_SCHED;
;             PG8_LDA(At, 0, 1); PG8_STAGE(PG8_SB(0, 0), b2, voffB); PG8_STAGE(PG8_SB(0, 1), b2 + hstep, voffB); PG8_STAGE(PG8_SA(0, 0), a2, voffA);
;             PG8_WAIT_V(8); PG8_WAIT_L(0); PG8_BAR; PG8_MMA(1, 0, At, B0); PG8_MMA(1, 1, At, B1); PG8_BAR; PG8_SCHED;
.LBB0_749:
	ds_read_b128 v[152:155], v148
	ds_read_b128 v[156:159], v148 offset:1024
	ds_read_b128 v[160:163], v148 offset:2048
	ds_read_b128 v[164:167], v148 offset:3072
	ds_read_b128 v[168:171], v149
	ds_read_b128 v[172:175], v149 offset:1024
	ds_read_b128 v[176:179], v149 offset:2048
	ds_read_b128 v[180:183], v149 offset:3072
	s_add_i32 s60, s30, 2
	s_add_u32 s61, s28, 0x80
	s_addc_u32 s31, s29, 0
	s_cmp_eq_u32 s48, s30
	s_cselect_b32 s30, s6, s61
	s_cselect_b32 s31, s7, s31
	s_cselect_b32 s63, s25, s59
	s_cselect_b32 s62, s24, s58
	v_lshl_add_u64 v[216:217], s[28:29], 0, v[140:141]
	s_add_i32 m0, s40, 0xc000
	ds_read_b128 v[184:187], v150
	ds_read_b128 v[188:191], v150 offset:1024
	ds_read_b128 v[192:195], v150 offset:2048
	ds_read_b128 v[196:199], v150 offset:3072
	ds_read_b128 v[200:203], v150 offset:4096
	ds_read_b128 v[204:207], v150 offset:5120
	ds_read_b128 v[208:211], v150 offset:6144
	ds_read_b128 v[212:215], v150 offset:7168
	global_load_lds_dwordx4 v[216:217], off
	v_lshl_add_u64 v[216:217], s[28:29], 0, v[138:139]
	s_add_i32 m0, s40, 0xe000
	s_nop 0
	global_load_lds_dwordx4 v[216:217], off
	s_waitcnt vmcnt(8) lgkmcnt(0)
	s_barrier
	s_setprio 1
	v_mfma_f32_16x16x32_bf16 v[122:125], v[152:155], v[184:187], v[122:125]
	v_mfma_f32_16x16x32_bf16 v[118:121], v[160:163], v[184:187], v[118:121]
	v_mfma_f32_16x16x32_bf16 v[110:113], v[152:155], v[192:195], v[110:113]
	v_mfma_f32_16x16x32_bf16 v[102:105], v[160:163], v[192:195], v[102:105]
	v_mfma_f32_16x16x32_bf16 v[94:97], v[152:155], v[200:203], v[94:97]
	v_mfma_f32_16x16x32_bf16 v[86:89], v[160:163], v[200:203], v[86:89]
	v_mfma_f32_16x16x32_bf16 v[78:81], v[152:155], v[208:211], v[78:81]
	v_mfma_f32_16x16x32_bf16 v[70:73], v[160:163], v[208:211], v[70:73]
	v_mfma_f32_16x16x32_bf16 v[122:125], v[156:159], v[188:191], v[122:125]
	v_mfma_f32_16x16x32_bf16 v[118:121], v[164:167], v[188:191], v[118:121]
	v_mfma_f32_16x16x32_bf16 v[110:113], v[156:159], v[196:199], v[110:113]
	v_mfma_f32_16x16x32_bf16 v[102:105], v[164:167], v[196:199], v[102:105]
	v_mfma_f32_16x16x32_bf16 v[94:97], v[156:159], v[204:207], v[94:97]
	v_mfma_f32_16x16x32_bf16 v[86:89], v[164:167], v[204:207], v[86:89]
	v_mfma_f32_16x16x32_bf16 v[78:81], v[156:159], v[212:215], v[78:81]
	v_mfma_f32_16x16x32_bf16 v[70:73], v[164:167], v[212:215], v[70:73]
	v_mfma_f32_16x16x32_bf16 v[126:129], v[168:171], v[184:187], v[126:129]
	v_mfma_f32_16x16x32_bf16 v[114:117], v[176:179], v[184:187], v[114:117]
	v_mfma_f32_16x16x32_bf16 v[106:109], v[168:171], v[192:195], v[106:109]
	v_mfma_f32_16x16x32_bf16 v[98:101], v[176:179], v[192:195], v[98:101]
	v_mfma_f32_16x16x32_bf16 v[90:93], v[168:171], v[200:203], v[90:93]
	v_mfma_f32_16x16x32_bf16 v[82:85], v[176:179], v[200:203], v[82:85]
	v_mfma_f32_16x16x32_bf16 v[74:77], v[168:171], v[208:211], v[74:77]
	v_mfma_f32_16x16x32_bf16 v[66:69], v[176:179], v[208:211], v[66:69]
	v_mfma_f32_16x16x32_bf16 v[126:129], v[172:175], v[188:191], v[126:129]
	v_mfma_f32_16x16x32_bf16 v[114:117], v[180:183], v[188:191], v[114:117]
	v_mfma_f32_16x16x32_bf16 v[106:109], v[172:175], v[196:199], v[106:109]
	v_mfma_f32_16x16x32_bf16 v[98:101], v[180:183], v[196:199], v[98:101]
	v_mfma_f32_16x16x32_bf16 v[90:93], v[172:175], v[204:207], v[90:93]
	v_mfma_f32_16x16x32_bf16 v[82:85], v[180:183], v[204:207], v[82:85]
	v_mfma_f32_16x16x32_bf16 v[74:77], v[172:175], v[212:215], v[74:77]
	v_mfma_f32_16x16x32_bf16 v[66:69], v[180:183], v[212:215], v[66:69]
	s_setprio 0
	s_barrier
	s_add_i32 s61, s53, s37
	v_lshl_add_u64 v[216:217], s[62:63], 0, v[134:135]
	s_mov_b32 m0, s61
	ds_read_b128 v[184:187], v150 offset:16384
	ds_read_b128 v[188:191], v150 offset:17408
	ds_read_b128 v[192:195], v150 offset:18432
	ds_read_b128 v[196:199], v150 offset:19456
	ds_read_b128 v[200:203], v150 offset:20480
	ds_read_b128 v[204:207], v150 offset:21504
	ds_read_b128 v[208:211], v150 offset:22528
	ds_read_b128 v[212:215], v150 offset:23552
	global_load_lds_dwordx4 v[216:217], off
	s_add_i32 m0, s61, 0x2000
	v_lshl_add_u64 v[218:219], s[62:63], 0, v[130:131]
	s_add_u32 s62, s62, s10
	s_addc_u32 s63, s63, s11
	s_add_i32 s61, s54, s37
	global_load_lds_dwordx4 v[218:219], off
	v_lshl_add_u64 v[220:221], s[62:63], 0, v[134:135]
	s_mov_b32 m0, s61
	v_lshl_add_u64 v[222:223], s[62:63], 0, v[130:131]
	global_load_lds_dwordx4 v[220:221], off
	s_add_i32 m0, s61, 0x2000
	v_lshl_add_u64 v[224:225], s[30:31], 0, v[136:137]
	global_load_lds_dwordx4 v[222:223], off
	s_mov_b32 m0, s40
	v_lshl_add_u64 v[226:227], s[30:31], 0, v[132:133]
	global_load_lds_dwordx4 v[224:225], off
	s_mov_b32 m0, s41
	s_nop 0
	global_load_lds_dwordx4 v[226:227], off
	s_waitcnt vmcnt(8) lgkmcnt(0)
	s_barrier
; #define PG8_STAGE(bufoff, gbase, voff) do { _Pragma("unroll") for (int _i = 0; _i < 2; ++_i) \
;         __builtin_amdgcn_global_load_lds((const unsigned*)((const char*)(gbase) + (voff)[_i]), (PG8_LAS unsigned*)(lds + (bufoff) + ldsw + _i * 8192), 16, 0, 0); } while (0)
; #define PG8_LDA(dst, b, h) do { _Pragma("unroll") for (int m = 0; m < 4; ++m) _Pragma("unroll") for (int k = 0; k < 2; ++k) dst[m][k] = *(const PG8_LAS bf16x8*)(lds + PG8_SA(b, h) + aoff + m * 2048 + k * 1024); } while (0)
; #define PG8_LDB(dst, b, h) do { _Pragma("unroll") for (int n = 0; n < 2; ++n) _Pragma("unroll") for (int k = 0; k < 2; ++k) dst[n][k] = *(const PG8_LAS bf16x8*)(lds + PG8_SB(b, h) + boff + n * 2048 + k * 1024); } while (0)
; #define PG8_MMA(ai, bj, At, Bt) do { __builtin_amdgcn_s_setprio(1); _Pragma("unroll") for (int m = 0; m < 4; ++m) _Pragma("unroll") for (int n = 0; n < 2; ++n) _Pragma("unroll") for (int k = 0; k < 2; ++k) \
;         acc[ai][bj][m][n] = __builtin_amdgcn_mfma_f32_16x16x32_bf16(Bt[n][k], At[m][k], acc[ai][bj][m][n], 0, 0, 0); __builtin_amdgcn_s_setprio(0); } while (0)
; #define PG8_WAIT_V(n) asm volatile("s_waitcnt vmcnt(" #n ")" ::: "memory")
; #define PG8_WAIT_L(n) asm volatile("s_waitcnt lgkmcnt(" #n ")" ::: "memory")
; #define PG8_BAR __builtin_amdgcn_s_barrier()
; #define PG8_SCHED __builtin_amdgcn_sched_barrier(0)
; template <class Epi, class Sched, bool ALIGN_EPI = false, bool SP2 = false>
; __device__ __forceinline__ void gemm_phase(PG8_LAS unsigned char* lds, const Gemm g, const Sched& S, const Epi& E) {
;     ...
;             PG8_WAIT_V(8); PG8_WAIT_L(0); PG8_BAR; PG8_MMA(1, 0, At, B0); PG8_MMA(1, 1, At, B1); PG8_BAR; PG8_SCHED;
;             PG8_LDB(B0, 1, 0); PG8_LDB(B1, 1, 1); PG8_SCHED; PG8_LDA(At, 1, 0); PG8_STAGE(PG8_SA(0, 1), a2 + hstep, voffA);
;             PG8_WAIT_V(8); PG8_WAIT_L(0); PG8_BAR; PG8_MMA(0, 0, At, B0); PG8_MMA(0, 1, At, B1); PG8_BAR; PG8_SCHED;
	s_setprio 1
	v_mfma_f32_16x16x32_bf16 v[62:65], v[152:155], v[184:187], v[62:65]
	v_mfma_f32_16x16x32_bf16 v[54:57], v[160:163], v[184:187], v[54:57]
	v_mfma_f32_16x16x32_bf16 v[46:49], v[152:155], v[192:195], v[46:49]
	v_mfma_f32_16x16x32_bf16 v[38:41], v[160:163], v[192:195], v[38:41]
	v_mfma_f32_16x16x32_bf16 v[30:33], v[152:155], v[200:203], v[30:33]
	v_mfma_f32_16x16x32_bf16 v[22:25], v[160:163], v[200:203], v[22:25]
	v_mfma_f32_16x16x32_bf16 v[14:17], v[152:155], v[208:211], v[14:17]
	v_mfma_f32_16x16x32_bf16 v[6:9], v[160:163], v[208:211], v[6:9]
	v_mfma_f32_16x16x32_bf16 v[62:65], v[156:159], v[188:191], v[62:65]
	v_mfma_f32_16x16x32_bf16 v[54:57], v[164:167], v[188:191], v[54:57]
	v_mfma_f32_16x16x32_bf16 v[46:49], v[156:159], v[196:199], v[46:49]
	v_mfma_f32_16x16x32_bf16 v[38:41], v[164:167], v[196:199], v[38:41]
	v_mfma_f32_16x16x32_bf16 v[30:33], v[156:159], v[204:207], v[30:33]
	v_mfma_f32_16x16x32_bf16 v[22:25], v[164:167], v[204:207], v[22:25]
	v_mfma_f32_16x16x32_bf16 v[14:17], v[156:159], v[212:215], v[14:17]
	v_mfma_f32_16x16x32_bf16 v[6:9], v[164:167], v[212:215], v[6:9]
	v_mfma_f32_16x16x32_bf16 v[58:61], v[168:171], v[184:187], v[58:61]
	v_mfma_f32_16x16x32_bf16 v[50:53], v[176:179], v[184:187], v[50:53]
	v_mfma_f32_16x16x32_bf16 v[42:45], v[168:171], v[192:195], v[42:45]
	v_mfma_f32_16x16x32_bf16 v[34:37], v[176:179], v[192:195], v[34:37]
	v_mfma_f32_16x16x32_bf16 v[26:29], v[168:171], v[200:203], v[26:29]
	v_mfma_f32_16x16x32_bf16 v[18:21], v[176:179], v[200:203], v[18:21]
	v_mfma_f32_16x16x32_bf16 v[10:13], v[168:171], v[208:211], v[10:13]
	v_mfma_f32_16x16x32_bf16 v[2:5], v[176:179], v[208:211], v[2:5]
	v_mfma_f32_16x16x32_bf16 v[58:61], v[172:175], v[188:191], v[58:61]
	v_mfma_f32_16x16x32_bf16 v[50:53], v[180:183], v[188:191], v[50:53]
	v_mfma_f32_16x16x32_bf16 v[42:45], v[172:175], v[196:199], v[42:45]
	v_mfma_f32_16x16x32_bf16 v[34:37], v[180:183], v[196:199], v[34:37]
	v_mfma_f32_16x16x32_bf16 v[26:29], v[172:175], v[204:207], v[26:29]
	v_mfma_f32_16x16x32_bf16 v[18:21], v[180:183], v[204:207], v[18:21]
	v_mfma_f32_16x16x32_bf16 v[10:13], v[172:175], v[212:215], v[10:13]
	v_mfma_f32_16x16x32_bf16 v[2:5], v[180:183], v[212:215], v[2:5]
	s_setprio 0
	s_barrier
	s_add_i32 s61, 0, 0x18000
	v_add_u32_e32 v151, s61, v146
	s_add_i32 s62, 0, 0x1c000
	ds_read_b128 v[152:155], v151
	ds_read_b128 v[156:159], v151 offset:1024
	ds_read_b128 v[160:163], v151 offset:2048
	ds_read_b128 v[164:167], v151 offset:3072
	v_add_u32_e32 v151, s62, v146
	ds_read_b128 v[168:171], v151
	ds_read_b128 v[172:175], v151 offset:1024
	ds_read_b128 v[176:179], v151 offset:2048
	ds_read_b128 v[180:183], v151 offset:3072
	s_add_u32 s30, s30, s10
	s_addc_u32 s31, s31, s11
	s_mov_b32 m0, s42
	v_lshl_add_u64 v[228:229], s[30:31], 0, v[136:137]
	ds_read_b128 v[184:187], v150 offset:32768
	ds_read_b128 v[188:191], v150 offset:33792
	ds_read_b128 v[192:195], v150 offset:34816
	ds_read_b128 v[196:199], v150 offset:35840
	ds_read_b128 v[200:203], v150 offset:36864
	ds_read_b128 v[204:207], v150 offset:37888
	ds_read_b128 v[208:211], v150 offset:38912
	ds_read_b128 v[212:215], v150 offset:39936
	global_load_lds_dwordx4 v[228:229], off
	v_lshl_add_u64 v[228:229], s[30:31], 0, v[132:133]
	s_mov_b32 m0, s43
	s_nop 0
	global_load_lds_dwordx4 v[228:229], off
	s_waitcnt vmcnt(8) lgkmcnt(0)
	s_barrier
	s_setprio 1
	v_mfma_f32_16x16x32_bf16 v[122:125], v[152:155], v[184:187], v[122:125]
	v_mfma_f32_16x16x32_bf16 v[118:121], v[160:163], v[184:187], v[118:121]
	v_mfma_f32_16x16x32_bf16 v[110:113], v[152:155], v[192:195], v[110:113]
	v_mfma_f32_16x16x32_bf16 v[102:105], v[160:163], v[192:195], v[102:105]
	v_mfma_f32_16x16x32_bf16 v[94:97], v[152:155], v[200:203], v[94:97]
	v_mfma_f32_16x16x32_bf16 v[86:89], v[160:163], v[200:203], v[86:89]
	v_mfma_f32_16x16x32_bf16 v[78:81], v[152:155], v[208:211], v[78:81]
	v_mfma_f32_16x16x32_bf16 v[70:73], v[160:163], v[208:211], v[70:73]
	v_mfma_f32_16x16x32_bf16 v[122:125], v[156:159], v[188:191], v[122:125]
	v_mfma_f32_16x16x32_bf16 v[118:121], v[164:167], v[188:191], v[118:121]
	v_mfma_f32_16x16x32_bf16 v[110:113], v[156:159], v[196:199], v[110:113]
	v_mfma_f32_16x16x32_bf16 v[102:105], v[164:167], v[196:199], v[102:105]
	v_mfma_f32_16x16x32_bf16 v[94:97], v[156:159], v[204:207], v[94:97]
	v_mfma_f32_16x16x32_bf16 v[86:89], v[164:167], v[204:207], v[86:89]
	v_mfma_f32_16x16x32_bf16 v[78:81], v[156:159], v[212:215], v[78:81]
	v_mfma_f32_16x16x32_bf16 v[70:73], v[164:167], v[212:215], v[70:73]
	v_mfma_f32_16x16x32_bf16 v[126:129], v[168:171], v[184:187], v[126:129]
	v_mfma_f32_16x16x32_bf16 v[114:117], v[176:179], v[184:187], v[114:117]
	v_mfma_f32_16x16x32_bf16 v[106:109], v[168:171], v[192:195], v[106:109]
	v_mfma_f32_16x16x32_bf16 v[98:101], v[176:179], v[192:195], v[98:101]
	v_mfma_f32_16x16x32_bf16 v[90:93], v[168:171], v[200:203], v[90:93]
	v_mfma_f32_16x16x32_bf16 v[82:85], v[176:179], v[200:203], v[82:85]
	v_mfma_f32_16x16x32_bf16 v[74:77], v[168:171], v[208:211], v[74:77]
	v_mfma_f32_16x16x32_bf16 v[66:69], v[176:179], v[208:211], v[66:69]
	v_mfma_f32_16x16x32_bf16 v[126:129], v[172:175], v[188:191], v[126:129]
	v_mfma_f32_16x16x32_bf16 v[114:117], v[180:183], v[188:191], v[114:117]
	v_mfma_f32_16x16x32_bf16 v[106:109], v[172:175], v[196:199], v[106:109]
	v_mfma_f32_16x16x32_bf16 v[98:101], v[180:183], v[196:199], v[98:101]
	v_mfma_f32_16x16x32_bf16 v[90:93], v[172:175], v[204:207], v[90:93]
	v_mfma_f32_16x16x32_bf16 v[82:85], v[180:183], v[204:207], v[82:85]
	v_mfma_f32_16x16x32_bf16 v[74:77], v[172:175], v[212:215], v[74:77]
	v_mfma_f32_16x16x32_bf16 v[66:69], v[180:183], v[212:215], v[66:69]
	s_setprio 0
	s_barrier
; #define PG8_STAGE(bufoff, gbase, voff) do { _Pragma("unroll") for (int _i = 0; _i < 2; ++_i) \
;         __builtin_amdgcn_global_load_lds((const unsigned*)((const char*)(gbase) + (voff)[_i]), (PG8_LAS unsigned*)(lds + (bufoff) + ldsw + _i * 8192), 16, 0, 0); } while (0)
; #define PG8_LDA(dst, b, h) do { _Pragma("unroll") for (int m = 0; m < 4; ++m) _Pragma("unroll") for (int k = 0; k < 2; ++k) dst[m][k] = *(const PG8_LAS bf16x8*)(lds + PG8_SA(b, h) + aoff + m * 2048 + k * 1024); } while (0)
; #define PG8_MMA(ai, bj, At, Bt) do { __builtin_amdgcn_s_setprio(1); _Pragma("unroll") for (int m = 0; m < 4; ++m) _Pragma("unroll") for (int n = 0; n < 2; ++n) _Pragma("unroll") for (int k = 0; k < 2; ++k) \
;         acc[ai][bj][m][n] = __builtin_amdgcn_mfma_f32_16x16x32_bf16(Bt[n][k], At[m][k], acc[ai][bj][m][n], 0, 0, 0); __builtin_amdgcn_s_setprio(0); } while (0)
; #define PG8_WAIT_V(n) asm volatile("s_waitcnt vmcnt(" #n ")" ::: "memory")
; #define PG8_WAIT_L(n) asm volatile("s_waitcnt lgkmcnt(" #n ")" ::: "memory")
; #define PG8_BAR __builtin_amdgcn_s_barrier()
; #define PG8_SCHED __builtin_amdgcn_sched_barrier(0)
; template <class Epi, class Sched, bool ALIGN_EPI = false, bool SP2 = false>
; __device__ __forceinline__ void gemm_phase(PG8_LAS unsigned char* lds, const Gemm g, const Sched& S, const Epi& E) {
;     ...
;             PG8_LDA(At, 1, 1); PG8_STAGE(PG8_SB(1, 0), b3, voffB); PG8_STAGE(PG8_SB(1, 1), b3 + hstep, voffB); PG8_STAGE(PG8_SA(1, 0), a3, voffA);
;             PG8_WAIT_V(8); PG8_WAIT_L(0); PG8_BAR; PG8_MMA(1, 0, At, B0); PG8_MMA(1, 1, At, B1); PG8_BAR; PG8_SCHED;
	s_add_i32 s30, s61, s37
	v_lshl_add_u64 v[216:217], v[216:217], 0, s[18:19]
	s_mov_b32 m0, s30
	ds_read_b128 v[184:187], v150 offset:49152
	ds_read_b128 v[188:191], v150 offset:50176
	ds_read_b128 v[192:195], v150 offset:51200
	ds_read_b128 v[196:199], v150 offset:52224
	ds_read_b128 v[200:203], v150 offset:53248
	ds_read_b128 v[204:207], v150 offset:54272
	ds_read_b128 v[208:211], v150 offset:55296
	ds_read_b128 v[212:215], v150 offset:56320
	global_load_lds_dwordx4 v[216:217], off
	v_lshl_add_u64 v[216:217], v[218:219], 0, s[18:19]
	s_add_i32 m0, s30, 0x2000
	s_add_i32 s30, s62, s37
	global_load_lds_dwordx4 v[216:217], off
	v_lshl_add_u64 v[216:217], v[220:221], 0, s[18:19]
	s_mov_b32 m0, s30
	s_nop 0
	global_load_lds_dwordx4 v[216:217], off
	v_lshl_add_u64 v[216:217], v[222:223], 0, s[18:19]
	s_add_i32 m0, s30, 0x2000
	s_nop 0
	global_load_lds_dwordx4 v[216:217], off
	v_lshl_add_u64 v[216:217], v[224:225], 0, s[18:19]
	s_mov_b32 m0, s45
	s_nop 0
	global_load_lds_dwordx4 v[216:217], off
	v_lshl_add_u64 v[216:217], v[226:227], 0, s[18:19]
	s_mov_b32 m0, s46
	s_nop 0
	global_load_lds_dwordx4 v[216:217], off
	s_waitcnt vmcnt(8) lgkmcnt(0)
	s_barrier
	s_setprio 1
	v_mfma_f32_16x16x32_bf16 v[62:65], v[152:155], v[184:187], v[62:65]
	v_mfma_f32_16x16x32_bf16 v[54:57], v[160:163], v[184:187], v[54:57]
	v_mfma_f32_16x16x32_bf16 v[46:49], v[152:155], v[192:195], v[46:49]
	v_mfma_f32_16x16x32_bf16 v[38:41], v[160:163], v[192:195], v[38:41]
	v_mfma_f32_16x16x32_bf16 v[30:33], v[152:155], v[200:203], v[30:33]
	v_mfma_f32_16x16x32_bf16 v[22:25], v[160:163], v[200:203], v[22:25]
	v_mfma_f32_16x16x32_bf16 v[14:17], v[152:155], v[208:211], v[14:17]
	v_mfma_f32_16x16x32_bf16 v[6:9], v[160:163], v[208:211], v[6:9]
	v_mfma_f32_16x16x32_bf16 v[62:65], v[156:159], v[188:191], v[62:65]
	v_mfma_f32_16x16x32_bf16 v[54:57], v[164:167], v[188:191], v[54:57]
	v_mfma_f32_16x16x32_bf16 v[46:49], v[156:159], v[196:199], v[46:49]
	v_mfma_f32_16x16x32_bf16 v[38:41], v[164:167], v[196:199], v[38:41]
	v_mfma_f32_16x16x32_bf16 v[30:33], v[156:159], v[204:207], v[30:33]
	v_mfma_f32_16x16x32_bf16 v[22:25], v[164:167], v[204:207], v[22:25]
	v_mfma_f32_16x16x32_bf16 v[14:17], v[156:159], v[212:215], v[14:17]
	v_mfma_f32_16x16x32_bf16 v[6:9], v[164:167], v[212:215], v[6:9]
	v_mfma_f32_16x16x32_bf16 v[58:61], v[168:171], v[184:187], v[58:61]
	v_mfma_f32_16x16x32_bf16 v[50:53], v[176:179], v[184:187], v[50:53]
	v_mfma_f32_16x16x32_bf16 v[42:45], v[168:171], v[192:195], v[42:45]
	v_mfma_f32_16x16x32_bf16 v[34:37], v[176:179], v[192:195], v[34:37]
	v_mfma_f32_16x16x32_bf16 v[26:29], v[168:171], v[200:203], v[26:29]
	v_mfma_f32_16x16x32_bf16 v[18:21], v[176:179], v[200:203], v[18:21]
	v_mfma_f32_16x16x32_bf16 v[10:13], v[168:171], v[208:211], v[10:13]
	v_mfma_f32_16x16x32_bf16 v[2:5], v[176:179], v[208:211], v[2:5]
	v_mfma_f32_16x16x32_bf16 v[58:61], v[172:175], v[188:191], v[58:61]
	v_mfma_f32_16x16x32_bf16 v[50:53], v[180:183], v[188:191], v[50:53]
	v_mfma_f32_16x16x32_bf16 v[42:45], v[172:175], v[196:199], v[42:45]
	v_mfma_f32_16x16x32_bf16 v[34:37], v[180:183], v[196:199], v[34:37]
	v_mfma_f32_16x16x32_bf16 v[26:29], v[172:175], v[204:207], v[26:29]
	v_mfma_f32_16x16x32_bf16 v[18:21], v[180:183], v[204:207], v[18:21]
	v_mfma_f32_16x16x32_bf16 v[10:13], v[172:175], v[212:215], v[10:13]
	v_mfma_f32_16x16x32_bf16 v[2:5], v[180:183], v[212:215], v[2:5]
	s_setprio 0
	s_barrier
	s_add_u32 s58, s58, 0x100
	s_addc_u32 s59, s59, 0
	s_add_u32 s28, s28, 0x100
	s_addc_u32 s29, s29, 0
	s_cmp_ge_i32 s60, s47
	s_mov_b32 s30, s60
	s_cbranch_scc0 .LBB0_749

; #define PG8_STAGE(bufoff, gbase, voff) do { _Pragma("unroll") for (int _i = 0; _i < 2; ++_i) \
;         __builtin_amdgcn_global_load_lds((const unsigned*)((const char*)(gbase) + (voff)[_i]), (PG8_LAS unsigned*)(lds + (bufoff) + ldsw + _i * 8192), 16, 0, 0); } while (0)
; #define PG8_LDA(dst, b, h) do { _Pragma("unroll") for (int m = 0; m < 4; ++m) _Pragma("unroll") for (int k = 0; k < 2; ++k) dst[m][k] = *(const PG8_LAS bf16x8*)(lds + PG8_SA(b, h) + aoff + m * 2048 + k * 1024); } while (0)
; #define PG8_LDB(dst, b, h) do { _Pragma("unroll") for (int n = 0; n < 2; ++n) _Pragma("unroll") for (int k = 0; k < 2; ++k) dst[n][k] = *(const PG8_LAS bf16x8*)(lds + PG8_SB(b, h) + boff + n * 2048 + k * 1024); } while (0)
; #define PG8_MMA(ai, bj, At, Bt) do { __builtin_amdgcn_s_setprio(1); _Pragma("unroll") for (int m = 0; m < 4; ++m) _Pragma("unroll") for (int n = 0; n < 2; ++n) _Pragma("unroll") for (int k = 0; k < 2; ++k) \
;         acc[ai][bj][m][n] = __builtin_amdgcn_mfma_f32_16x16x32_bf16(Bt[n][k], At[m][k], acc[ai][bj][m][n], 0, 0, 0); __builtin_amdgcn_s_setprio(0); } while (0)
; #define PG8_WAIT_V(n) asm volatile("s_waitcnt vmcnt(" #n ")" ::: "memory")
; #define PG8_WAIT_L(n) asm volatile("s_waitcnt lgkmcnt(" #n ")" ::: "memory")
; template <class Epi, class Sched, bool ALIGN_EPI = false, bool SP2 = false>
; __device__ __forceinline__ void gemm_phase(PG8_LAS unsigned char* lds, const Gemm g, const Sched& S, const Epi& E) {
;     ...
;             const bool last = (t == nt - 2);
;             const char* a1 = cA + (size_t)(t + 1) * kstep;
;             const char* a2 = last ? nA : cA + (size_t)(t + 2) * kstep; const char* b2 = last ? nB : cB + (size_t)(t + 2) * kstep;
;             const char* a3 = a2 + kstep; const char* b3 = b2 + kstep;
;             if (last && has_next) S.a_ready(nxt);
;             if constexpr (SP2) {
;             PG8_LDB(B0, 0, 0); PG8_LDB(B1, 0, 1); PG8_SCHED; PG8_LDA(At, 0, 0); PG8_STAGE(PG8_SA(1, 1), a1 + hstep, voffA);
;             PG8_WAIT_V(8); PG8_WAIT_L(0); PG8_BAR; PG8_MMA(0, 0, At, B0); PG8_MMA(0, 1, At, B1); PG8_BAR; PG8_SCHED;
;             PG8_LDA(At, 0, 1); PG8_STAGE(PG8_SB(0, 0), b2, voffB); PG8_STAGE(PG8_SB(0, 1), b2 + hstep, voffB); PG8_STAGE(PG8_SA(0, 0), a2, voffA);
;             PG8_WAIT_V(8); PG8_WAIT_L(0); PG8_BAR; PG8_MMA(1, 0, At, B0); PG8_MMA(1, 1, At, B1); PG8_BAR; PG8_SCHED;
.LBB0_834:
	ds_read_b128 v[152:155], v148
	ds_read_b128 v[156:159], v148 offset:1024
	ds_read_b128 v[160:163], v148 offset:2048
	ds_read_b128 v[164:167], v148 offset:3072
	ds_read_b128 v[168:171], v149
	ds_read_b128 v[172:175], v149 offset:1024
	ds_read_b128 v[176:179], v149 offset:2048
	ds_read_b128 v[180:183], v149 offset:3072
	s_add_i32 s58, s30, 2
	s_add_u32 s59, s28, 0x80
	s_addc_u32 s31, s29, 0
	s_cmp_eq_u32 s45, s30
	s_cselect_b32 s30, s6, s59
	s_cselect_b32 s31, s7, s31
	s_cselect_b32 s61, s25, s57
	s_cselect_b32 s60, s24, s56
	v_lshl_add_u64 v[216:217], s[28:29], 0, v[140:141]
	s_add_i32 m0, s0, 0xc000
	ds_read_b128 v[184:187], v150
	ds_read_b128 v[188:191], v150 offset:1024
	ds_read_b128 v[192:195], v150 offset:2048
	ds_read_b128 v[196:199], v150 offset:3072
	ds_read_b128 v[200:203], v150 offset:4096
	ds_read_b128 v[204:207], v150 offset:5120
	ds_read_b128 v[208:211], v150 offset:6144
	ds_read_b128 v[212:215], v150 offset:7168
	global_load_lds_dwordx4 v[216:217], off
	v_lshl_add_u64 v[216:217], s[28:29], 0, v[138:139]
	s_add_i32 m0, s0, 0xe000
	s_nop 0
	global_load_lds_dwordx4 v[216:217], off
	s_waitcnt vmcnt(8) lgkmcnt(0)
	s_barrier
	s_setprio 1
	v_mfma_f32_16x16x32_bf16 v[122:125], v[152:155], v[184:187], v[122:125]
	v_mfma_f32_16x16x32_bf16 v[126:129], v[160:163], v[184:187], v[126:129]
	v_mfma_f32_16x16x32_bf16 v[110:113], v[152:155], v[192:195], v[110:113]
	v_mfma_f32_16x16x32_bf16 v[106:109], v[160:163], v[192:195], v[106:109]
	v_mfma_f32_16x16x32_bf16 v[94:97], v[152:155], v[200:203], v[94:97]
	v_mfma_f32_16x16x32_bf16 v[90:93], v[160:163], v[200:203], v[90:93]
	v_mfma_f32_16x16x32_bf16 v[78:81], v[152:155], v[208:211], v[78:81]
	v_mfma_f32_16x16x32_bf16 v[74:77], v[160:163], v[208:211], v[74:77]
	v_mfma_f32_16x16x32_bf16 v[122:125], v[156:159], v[188:191], v[122:125]
	v_mfma_f32_16x16x32_bf16 v[126:129], v[164:167], v[188:191], v[126:129]
	v_mfma_f32_16x16x32_bf16 v[110:113], v[156:159], v[196:199], v[110:113]
	v_mfma_f32_16x16x32_bf16 v[106:109], v[164:167], v[196:199], v[106:109]
	v_mfma_f32_16x16x32_bf16 v[94:97], v[156:159], v[204:207], v[94:97]
	v_mfma_f32_16x16x32_bf16 v[90:93], v[164:167], v[204:207], v[90:93]
	v_mfma_f32_16x16x32_bf16 v[78:81], v[156:159], v[212:215], v[78:81]
	v_mfma_f32_16x16x32_bf16 v[74:77], v[164:167], v[212:215], v[74:77]
	v_mfma_f32_16x16x32_bf16 v[118:121], v[168:171], v[184:187], v[118:121]
	v_mfma_f32_16x16x32_bf16 v[114:117], v[176:179], v[184:187], v[114:117]
	v_mfma_f32_16x16x32_bf16 v[102:105], v[168:171], v[192:195], v[102:105]
	v_mfma_f32_16x16x32_bf16 v[98:101], v[176:179], v[192:195], v[98:101]
	v_mfma_f32_16x16x32_bf16 v[86:89], v[168:171], v[200:203], v[86:89]
	v_mfma_f32_16x16x32_bf16 v[82:85], v[176:179], v[200:203], v[82:85]
	v_mfma_f32_16x16x32_bf16 v[70:73], v[168:171], v[208:211], v[70:73]
	v_mfma_f32_16x16x32_bf16 v[66:69], v[176:179], v[208:211], v[66:69]
	v_mfma_f32_16x16x32_bf16 v[118:121], v[172:175], v[188:191], v[118:121]
	v_mfma_f32_16x16x32_bf16 v[114:117], v[180:183], v[188:191], v[114:117]
	v_mfma_f32_16x16x32_bf16 v[102:105], v[172:175], v[196:199], v[102:105]
	v_mfma_f32_16x16x32_bf16 v[98:101], v[180:183], v[196:199], v[98:101]
	v_mfma_f32_16x16x32_bf16 v[86:89], v[172:175], v[204:207], v[86:89]
	v_mfma_f32_16x16x32_bf16 v[82:85], v[180:183], v[204:207], v[82:85]
	v_mfma_f32_16x16x32_bf16 v[70:73], v[172:175], v[212:215], v[70:73]
	v_mfma_f32_16x16x32_bf16 v[66:69], v[180:183], v[212:215], v[66:69]
	s_setprio 0
	s_barrier
	s_add_i32 s59, s48, s38
	v_lshl_add_u64 v[216:217], s[60:61], 0, v[132:133]
	s_mov_b32 m0, s59
	ds_read_b128 v[184:187], v150 offset:16384
	ds_read_b128 v[188:191], v150 offset:17408
	ds_read_b128 v[192:195], v150 offset:18432
	ds_read_b128 v[196:199], v150 offset:19456
	ds_read_b128 v[200:203], v150 offset:20480
	ds_read_b128 v[204:207], v150 offset:21504
	ds_read_b128 v[208:211], v150 offset:22528
	ds_read_b128 v[212:215], v150 offset:23552
	global_load_lds_dwordx4 v[216:217], off
	s_add_i32 m0, s59, 0x2000
	v_lshl_add_u64 v[218:219], s[60:61], 0, v[136:137]
	s_add_u32 s60, s60, s10
	s_addc_u32 s61, s61, s11
	s_add_i32 s59, s49, s38
	global_load_lds_dwordx4 v[218:219], off
	v_lshl_add_u64 v[220:221], s[60:61], 0, v[132:133]
	s_mov_b32 m0, s59
	v_lshl_add_u64 v[222:223], s[60:61], 0, v[136:137]
	global_load_lds_dwordx4 v[220:221], off
	s_add_i32 m0, s59, 0x2000
	v_lshl_add_u64 v[224:225], s[30:31], 0, v[130:131]
	global_load_lds_dwordx4 v[222:223], off
	s_mov_b32 m0, s0
	v_lshl_add_u64 v[226:227], s[30:31], 0, v[134:135]
	global_load_lds_dwordx4 v[224:225], off
	s_mov_b32 m0, s1
	s_nop 0
	global_load_lds_dwordx4 v[226:227], off
	s_waitcnt vmcnt(8) lgkmcnt(0)
	s_barrier
; #define PG8_STAGE(bufoff, gbase, voff) do { _Pragma("unroll") for (int _i = 0; _i < 2; ++_i) \
;         __builtin_amdgcn_global_load_lds((const unsigned*)((const char*)(gbase) + (voff)[_i]), (PG8_LAS unsigned*)(lds + (bufoff) + ldsw + _i * 8192), 16, 0, 0); } while (0)
; #define PG8_LDA(dst, b, h) do { _Pragma("unroll") for (int m = 0; m < 4; ++m) _Pragma("unroll") for (int k = 0; k < 2; ++k) dst[m][k] = *(const PG8_LAS bf16x8*)(lds + PG8_SA(b, h) + aoff + m * 2048 + k * 1024); } while (0)
; #define PG8_LDB(dst, b, h) do { _Pragma("unroll") for (int n = 0; n < 2; ++n) _Pragma("unroll") for (int k = 0; k < 2; ++k) dst[n][k] = *(const PG8_LAS bf16x8*)(lds + PG8_SB(b, h) + boff + n * 2048 + k * 1024); } while (0)
; #define PG8_MMA(ai, bj, At, Bt) do { __builtin_amdgcn_s_setprio(1); _Pragma("unroll") for (int m = 0; m < 4; ++m) _Pragma("unroll") for (int n = 0; n < 2; ++n) _Pragma("unroll") for (int k = 0; k < 2; ++k) \
;         acc[ai][bj][m][n] = __builtin_amdgcn_mfma_f32_16x16x32_bf16(Bt[n][k], At[m][k], acc[ai][bj][m][n], 0, 0, 0); __builtin_amdgcn_s_setprio(0); } while (0)
; #define PG8_WAIT_V(n) asm volatile("s_waitcnt vmcnt(" #n ")" ::: "memory")
; #define PG8_WAIT_L(n) asm volatile("s_waitcnt lgkmcnt(" #n ")" ::: "memory")
; #define PG8_BAR __builtin_amdgcn_s_barrier()
; #define PG8_SCHED __builtin_amdgcn_sched_barrier(0)
; template <class Epi, class Sched, bool ALIGN_EPI = false, bool SP2 = false>
; __device__ __forceinline__ void gemm_phase(PG8_LAS unsigned char* lds, const Gemm g, const Sched& S, const Epi& E) {
;     ...
;             PG8_WAIT_V(8); PG8_WAIT_L(0); PG8_BAR; PG8_MMA(1, 0, At, B0); PG8_MMA(1, 1, At, B1); PG8_BAR; PG8_SCHED;
;             PG8_LDB(B0, 1, 0); PG8_LDB(B1, 1, 1); PG8_SCHED; PG8_LDA(At, 1, 0); PG8_STAGE(PG8_SA(0, 1), a2 + hstep, voffA);
;             PG8_WAIT_V(8); PG8_WAIT_L(0); PG8_BAR; PG8_MMA(0, 0, At, B0); PG8_MMA(0, 1, At, B1); PG8_BAR; PG8_SCHED;
	s_setprio 1
	v_mfma_f32_16x16x32_bf16 v[62:65], v[152:155], v[184:187], v[62:65]
	v_mfma_f32_16x16x32_bf16 v[58:61], v[160:163], v[184:187], v[58:61]
	v_mfma_f32_16x16x32_bf16 v[46:49], v[152:155], v[192:195], v[46:49]
	v_mfma_f32_16x16x32_bf16 v[42:45], v[160:163], v[192:195], v[42:45]
	v_mfma_f32_16x16x32_bf16 v[30:33], v[152:155], v[200:203], v[30:33]
	v_mfma_f32_16x16x32_bf16 v[26:29], v[160:163], v[200:203], v[26:29]
	v_mfma_f32_16x16x32_bf16 v[14:17], v[152:155], v[208:211], v[14:17]
	v_mfma_f32_16x16x32_bf16 v[10:13], v[160:163], v[208:211], v[10:13]
	v_mfma_f32_16x16x32_bf16 v[62:65], v[156:159], v[188:191], v[62:65]
	v_mfma_f32_16x16x32_bf16 v[58:61], v[164:167], v[188:191], v[58:61]
	v_mfma_f32_16x16x32_bf16 v[46:49], v[156:159], v[196:199], v[46:49]
	v_mfma_f32_16x16x32_bf16 v[42:45], v[164:167], v[196:199], v[42:45]
	v_mfma_f32_16x16x32_bf16 v[30:33], v[156:159], v[204:207], v[30:33]
	v_mfma_f32_16x16x32_bf16 v[26:29], v[164:167], v[204:207], v[26:29]
	v_mfma_f32_16x16x32_bf16 v[14:17], v[156:159], v[212:215], v[14:17]
	v_mfma_f32_16x16x32_bf16 v[10:13], v[164:167], v[212:215], v[10:13]
	v_mfma_f32_16x16x32_bf16 v[54:57], v[168:171], v[184:187], v[54:57]
	v_mfma_f32_16x16x32_bf16 v[50:53], v[176:179], v[184:187], v[50:53]
	v_mfma_f32_16x16x32_bf16 v[38:41], v[168:171], v[192:195], v[38:41]
	v_mfma_f32_16x16x32_bf16 v[34:37], v[176:179], v[192:195], v[34:37]
	v_mfma_f32_16x16x32_bf16 v[22:25], v[168:171], v[200:203], v[22:25]
	v_mfma_f32_16x16x32_bf16 v[18:21], v[176:179], v[200:203], v[18:21]
	v_mfma_f32_16x16x32_bf16 v[6:9], v[168:171], v[208:211], v[6:9]
	v_mfma_f32_16x16x32_bf16 v[2:5], v[176:179], v[208:211], v[2:5]
	v_mfma_f32_16x16x32_bf16 v[54:57], v[172:175], v[188:191], v[54:57]
	v_mfma_f32_16x16x32_bf16 v[50:53], v[180:183], v[188:191], v[50:53]
	v_mfma_f32_16x16x32_bf16 v[38:41], v[172:175], v[196:199], v[38:41]
	v_mfma_f32_16x16x32_bf16 v[34:37], v[180:183], v[196:199], v[34:37]
	v_mfma_f32_16x16x32_bf16 v[22:25], v[172:175], v[204:207], v[22:25]
	v_mfma_f32_16x16x32_bf16 v[18:21], v[180:183], v[204:207], v[18:21]
	v_mfma_f32_16x16x32_bf16 v[6:9], v[172:175], v[212:215], v[6:9]
	v_mfma_f32_16x16x32_bf16 v[2:5], v[180:183], v[212:215], v[2:5]
	s_setprio 0
	s_barrier
	s_add_i32 s59, 0, 0x18000
	v_add_u32_e32 v151, s59, v146
	s_add_i32 s60, 0, 0x1c000
	ds_read_b128 v[152:155], v151
	ds_read_b128 v[156:159], v151 offset:1024
	ds_read_b128 v[160:163], v151 offset:2048
	ds_read_b128 v[164:167], v151 offset:3072
	v_add_u32_e32 v151, s60, v146
	ds_read_b128 v[168:171], v151
	ds_read_b128 v[172:175], v151 offset:1024
	ds_read_b128 v[176:179], v151 offset:2048
	ds_read_b128 v[180:183], v151 offset:3072
	s_add_u32 s30, s30, s10
	s_addc_u32 s31, s31, s11
	s_mov_b32 m0, s39
	v_lshl_add_u64 v[228:229], s[30:31], 0, v[130:131]
	ds_read_b128 v[184:187], v150 offset:32768
	ds_read_b128 v[188:191], v150 offset:33792
	ds_read_b128 v[192:195], v150 offset:34816
	ds_read_b128 v[196:199], v150 offset:35840
	ds_read_b128 v[200:203], v150 offset:36864
	ds_read_b128 v[204:207], v150 offset:37888
	ds_read_b128 v[208:211], v150 offset:38912
	ds_read_b128 v[212:215], v150 offset:39936
	global_load_lds_dwordx4 v[228:229], off
	v_lshl_add_u64 v[228:229], s[30:31], 0, v[134:135]
	s_mov_b32 m0, s40
	s_nop 0
	global_load_lds_dwordx4 v[228:229], off
	s_waitcnt vmcnt(8) lgkmcnt(0)
	s_barrier
	s_setprio 1
	v_mfma_f32_16x16x32_bf16 v[122:125], v[152:155], v[184:187], v[122:125]
	v_mfma_f32_16x16x32_bf16 v[126:129], v[160:163], v[184:187], v[126:129]
	v_mfma_f32_16x16x32_bf16 v[110:113], v[152:155], v[192:195], v[110:113]
	v_mfma_f32_16x16x32_bf16 v[106:109], v[160:163], v[192:195], v[106:109]
	v_mfma_f32_16x16x32_bf16 v[94:97], v[152:155], v[200:203], v[94:97]
	v_mfma_f32_16x16x32_bf16 v[90:93], v[160:163], v[200:203], v[90:93]
	v_mfma_f32_16x16x32_bf16 v[78:81], v[152:155], v[208:211], v[78:81]
	v_mfma_f32_16x16x32_bf16 v[74:77], v[160:163], v[208:211], v[74:77]
	v_mfma_f32_16x16x32_bf16 v[122:125], v[156:159], v[188:191], v[122:125]
	v_mfma_f32_16x16x32_bf16 v[126:129], v[164:167], v[188:191], v[126:129]
	v_mfma_f32_16x16x32_bf16 v[110:113], v[156:159], v[196:199], v[110:113]
	v_mfma_f32_16x16x32_bf16 v[106:109], v[164:167], v[196:199], v[106:109]
	v_mfma_f32_16x16x32_bf16 v[94:97], v[156:159], v[204:207], v[94:97]
	v_mfma_f32_16x16x32_bf16 v[90:93], v[164:167], v[204:207], v[90:93]
	v_mfma_f32_16x16x32_bf16 v[78:81], v[156:159], v[212:215], v[78:81]
	v_mfma_f32_16x16x32_bf16 v[74:77], v[164:167], v[212:215], v[74:77]
	v_mfma_f32_16x16x32_bf16 v[118:121], v[168:171], v[184:187], v[118:121]
	v_mfma_f32_16x16x32_bf16 v[114:117], v[176:179], v[184:187], v[114:117]
	v_mfma_f32_16x16x32_bf16 v[102:105], v[168:171], v[192:195], v[102:105]
	v_mfma_f32_16x16x32_bf16 v[98:101], v[176:179], v[192:195], v[98:101]
	v_mfma_f32_16x16x32_bf16 v[86:89], v[168:171], v[200:203], v[86:89]
	v_mfma_f32_16x16x32_bf16 v[82:85], v[176:179], v[200:203], v[82:85]
	v_mfma_f32_16x16x32_bf16 v[70:73], v[168:171], v[208:211], v[70:73]
	v_mfma_f32_16x16x32_bf16 v[66:69], v[176:179], v[208:211], v[66:69]
	v_mfma_f32_16x16x32_bf16 v[118:121], v[172:175], v[188:191], v[118:121]
	v_mfma_f32_16x16x32_bf16 v[114:117], v[180:183], v[188:191], v[114:117]
	v_mfma_f32_16x16x32_bf16 v[102:105], v[172:175], v[196:199], v[102:105]
	v_mfma_f32_16x16x32_bf16 v[98:101], v[180:183], v[196:199], v[98:101]
	v_mfma_f32_16x16x32_bf16 v[86:89], v[172:175], v[204:207], v[86:89]
	v_mfma_f32_16x16x32_bf16 v[82:85], v[180:183], v[204:207], v[82:85]
	v_mfma_f32_16x16x32_bf16 v[70:73], v[172:175], v[212:215], v[70:73]
	v_mfma_f32_16x16x32_bf16 v[66:69], v[180:183], v[212:215], v[66:69]
	s_setprio 0
	s_barrier
; #define PG8_STAGE(bufoff, gbase, voff) do { _Pragma("unroll") for (int _i = 0; _i < 2; ++_i) \
;         __builtin_amdgcn_global_load_lds((const unsigned*)((const char*)(gbase) + (voff)[_i]), (PG8_LAS unsigned*)(lds + (bufoff) + ldsw + _i * 8192), 16, 0, 0); } while (0)
; #define PG8_LDA(dst, b, h) do { _Pragma("unroll") for (int m = 0; m < 4; ++m) _Pragma("unroll") for (int k = 0; k < 2; ++k) dst[m][k] = *(const PG8_LAS bf16x8*)(lds + PG8_SA(b, h) + aoff + m * 2048 + k * 1024); } while (0)
; #define PG8_MMA(ai, bj, At, Bt) do { __builtin_amdgcn_s_setprio(1); _Pragma("unroll") for (int m = 0; m < 4; ++m) _Pragma("unroll") for (int n = 0; n < 2; ++n) _Pragma("unroll") for (int k = 0; k < 2; ++k) \
;         acc[ai][bj][m][n] = __builtin_amdgcn_mfma_f32_16x16x32_bf16(Bt[n][k], At[m][k], acc[ai][bj][m][n], 0, 0, 0); __builtin_amdgcn_s_setprio(0); } while (0)
; #define PG8_WAIT_V(n) asm volatile("s_waitcnt vmcnt(" #n ")" ::: "memory")
; #define PG8_WAIT_L(n) asm volatile("s_waitcnt lgkmcnt(" #n ")" ::: "memory")
; #define PG8_BAR __builtin_amdgcn_s_barrier()
; #define PG8_SCHED __builtin_amdgcn_sched_barrier(0)
; template <class Epi, class Sched, bool ALIGN_EPI = false, bool SP2 = false>
; __device__ __forceinline__ void gemm_phase(PG8_LAS unsigned char* lds, const Gemm g, const Sched& S, const Epi& E) {
;     ...
;             PG8_LDA(At, 1, 1); PG8_STAGE(PG8_SB(1, 0), b3, voffB); PG8_STAGE(PG8_SB(1, 1), b3 + hstep, voffB); PG8_STAGE(PG8_SA(1, 0), a3, voffA);
;             PG8_WAIT_V(8); PG8_WAIT_L(0); PG8_BAR; PG8_MMA(1, 0, At, B0); PG8_MMA(1, 1, At, B1); PG8_BAR; PG8_SCHED;
	s_add_i32 s30, s59, s38
	v_lshl_add_u64 v[216:217], v[216:217], 0, s[18:19]
	s_mov_b32 m0, s30
	ds_read_b128 v[184:187], v150 offset:49152
	ds_read_b128 v[188:191], v150 offset:50176
	ds_read_b128 v[192:195], v150 offset:51200
	ds_read_b128 v[196:199], v150 offset:52224
	ds_read_b128 v[200:203], v150 offset:53248
	ds_read_b128 v[204:207], v150 offset:54272
	ds_read_b128 v[208:211], v150 offset:55296
	ds_read_b128 v[212:215], v150 offset:56320
	global_load_lds_dwordx4 v[216:217], off
	v_lshl_add_u64 v[216:217], v[218:219], 0, s[18:19]
	s_add_i32 m0, s30, 0x2000
	s_add_i32 s30, s60, s38
	global_load_lds_dwordx4 v[216:217], off
	v_lshl_add_u64 v[216:217], v[220:221], 0, s[18:19]
	s_mov_b32 m0, s30
	s_nop 0
	global_load_lds_dwordx4 v[216:217], off
	v_lshl_add_u64 v[216:217], v[222:223], 0, s[18:19]
	s_add_i32 m0, s30, 0x2000
	s_nop 0
	global_load_lds_dwordx4 v[216:217], off
	v_lshl_add_u64 v[216:217], v[224:225], 0, s[18:19]
	s_mov_b32 m0, s42
	s_nop 0
	global_load_lds_dwordx4 v[216:217], off
	v_lshl_add_u64 v[216:217], v[226:227], 0, s[18:19]
	s_mov_b32 m0, s43
	s_nop 0
	global_load_lds_dwordx4 v[216:217], off
	s_waitcnt vmcnt(8) lgkmcnt(0)
	s_barrier
	s_setprio 1
	v_mfma_f32_16x16x32_bf16 v[62:65], v[152:155], v[184:187], v[62:65]
	v_mfma_f32_16x16x32_bf16 v[58:61], v[160:163], v[184:187], v[58:61]
	v_mfma_f32_16x16x32_bf16 v[46:49], v[152:155], v[192:195], v[46:49]
	v_mfma_f32_16x16x32_bf16 v[42:45], v[160:163], v[192:195], v[42:45]
	v_mfma_f32_16x16x32_bf16 v[30:33], v[152:155], v[200:203], v[30:33]
	v_mfma_f32_16x16x32_bf16 v[26:29], v[160:163], v[200:203], v[26:29]
	v_mfma_f32_16x16x32_bf16 v[14:17], v[152:155], v[208:211], v[14:17]
	v_mfma_f32_16x16x32_bf16 v[10:13], v[160:163], v[208:211], v[10:13]
	v_mfma_f32_16x16x32_bf16 v[62:65], v[156:159], v[188:191], v[62:65]
	v_mfma_f32_16x16x32_bf16 v[58:61], v[164:167], v[188:191], v[58:61]
	v_mfma_f32_16x16x32_bf16 v[46:49], v[156:159], v[196:199], v[46:49]
	v_mfma_f32_16x16x32_bf16 v[42:45], v[164:167], v[196:199], v[42:45]
	v_mfma_f32_16x16x32_bf16 v[30:33], v[156:159], v[204:207], v[30:33]
	v_mfma_f32_16x16x32_bf16 v[26:29], v[164:167], v[204:207], v[26:29]
	v_mfma_f32_16x16x32_bf16 v[14:17], v[156:159], v[212:215], v[14:17]
	v_mfma_f32_16x16x32_bf16 v[10:13], v[164:167], v[212:215], v[10:13]
	v_mfma_f32_16x16x32_bf16 v[54:57], v[168:171], v[184:187], v[54:57]
	v_mfma_f32_16x16x32_bf16 v[50:53], v[176:179], v[184:187], v[50:53]
	v_mfma_f32_16x16x32_bf16 v[38:41], v[168:171], v[192:195], v[38:41]
	v_mfma_f32_16x16x32_bf16 v[34:37], v[176:179], v[192:195], v[34:37]
	v_mfma_f32_16x16x32_bf16 v[22:25], v[168:171], v[200:203], v[22:25]
	v_mfma_f32_16x16x32_bf16 v[18:21], v[176:179], v[200:203], v[18:21]
	v_mfma_f32_16x16x32_bf16 v[6:9], v[168:171], v[208:211], v[6:9]
	v_mfma_f32_16x16x32_bf16 v[2:5], v[176:179], v[208:211], v[2:5]
	v_mfma_f32_16x16x32_bf16 v[54:57], v[172:175], v[188:191], v[54:57]
	v_mfma_f32_16x16x32_bf16 v[50:53], v[180:183], v[188:191], v[50:53]
	v_mfma_f32_16x16x32_bf16 v[38:41], v[172:175], v[196:199], v[38:41]
	v_mfma_f32_16x16x32_bf16 v[34:37], v[180:183], v[196:199], v[34:37]
	v_mfma_f32_16x16x32_bf16 v[22:25], v[172:175], v[204:207], v[22:25]
	v_mfma_f32_16x16x32_bf16 v[18:21], v[180:183], v[204:207], v[18:21]
	v_mfma_f32_16x16x32_bf16 v[6:9], v[172:175], v[212:215], v[6:9]
	v_mfma_f32_16x16x32_bf16 v[2:5], v[180:183], v[212:215], v[2:5]
	s_setprio 0
	s_barrier
	s_add_u32 s56, s56, 0x100
	s_addc_u32 s57, s57, 0
	s_add_u32 s28, s28, 0x100
	s_addc_u32 s29, s29, 0
	s_cmp_ge_i32 s58, s44
	s_mov_b32 s30, s58
	s_cbranch_scc0 .LBB0_834

; #define PG8_STAGE(bufoff, gbase, voff) do { _Pragma("unroll") for (int _i = 0; _i < 2; ++_i) \
;         __builtin_amdgcn_global_load_lds((const unsigned*)((const char*)(gbase) + (voff)[_i]), (PG8_LAS unsigned*)(lds + (bufoff) + ldsw + _i * 8192), 16, 0, 0); } while (0)
; #define PG8_LDA(dst, b, h) do { _Pragma("unroll") for (int m = 0; m < 4; ++m) _Pragma("unroll") for (int k = 0; k < 2; ++k) dst[m][k] = *(const PG8_LAS bf16x8*)(lds + PG8_SA(b, h) + aoff + m * 2048 + k * 1024); } while (0)
; #define PG8_LDB(dst, b, h) do { _Pragma("unroll") for (int n = 0; n < 2; ++n) _Pragma("unroll") for (int k = 0; k < 2; ++k) dst[n][k] = *(const PG8_LAS bf16x8*)(lds + PG8_SB(b, h) + boff + n * 2048 + k * 1024); } while (0)
; #define PG8_MMA(ai, bj, At, Bt) do { __builtin_amdgcn_s_setprio(1); _Pragma("unroll") for (int m = 0; m < 4; ++m) _Pragma("unroll") for (int n = 0; n < 2; ++n) _Pragma("unroll") for (int k = 0; k < 2; ++k) \
;         acc[ai][bj][m][n] = __builtin_amdgcn_mfma_f32_16x16x32_bf16(Bt[n][k], At[m][k], acc[ai][bj][m][n], 0, 0, 0); __builtin_amdgcn_s_setprio(0); } while (0)
; #define PG8_WAIT_V(n) asm volatile("s_waitcnt vmcnt(" #n ")" ::: "memory")
; #define PG8_WAIT_L(n) asm volatile("s_waitcnt lgkmcnt(" #n ")" ::: "memory")
; template <class Epi, class Sched, bool ALIGN_EPI = false, bool SP2 = false>
; __device__ __forceinline__ void gemm_phase(PG8_LAS unsigned char* lds, const Gemm g, const Sched& S, const Epi& E) {
;     ...
;             const bool last = (t == nt - 2);
;             const char* a1 = cA + (size_t)(t + 1) * kstep;
;             const char* a2 = last ? nA : cA + (size_t)(t + 2) * kstep; const char* b2 = last ? nB : cB + (size_t)(t + 2) * kstep;
;             const char* a3 = a2 + kstep; const char* b3 = b2 + kstep;
;             if (last && has_next) S.a_ready(nxt);
;             if constexpr (SP2) {
;             PG8_LDB(B0, 0, 0); PG8_LDB(B1, 0, 1); PG8_SCHED; PG8_LDA(At, 0, 0); PG8_STAGE(PG8_SA(1, 1), a1 + hstep, voffA);
;             PG8_WAIT_V(8); PG8_WAIT_L(0); PG8_BAR; PG8_MMA(0, 0, At, B0); PG8_MMA(0, 1, At, B1); PG8_BAR; PG8_SCHED;
;             PG8_LDA(At, 0, 1); PG8_STAGE(PG8_SB(0, 0), b2, voffB); PG8_STAGE(PG8_SB(0, 1), b2 + hstep, voffB); PG8_STAGE(PG8_SA(0, 0), a2, voffA);
;             PG8_WAIT_V(8); PG8_WAIT_L(0); PG8_BAR; PG8_MMA(1, 0, At, B0); PG8_MMA(1, 1, At, B1); PG8_BAR; PG8_SCHED;
.LBB0_1154:
	ds_read_b128 v[130:133], v160
	ds_read_b128 v[134:137], v160 offset:1024
	ds_read_b128 v[164:167], v160 offset:2048
	ds_read_b128 v[168:171], v160 offset:3072
	ds_read_b128 v[172:175], v161
	ds_read_b128 v[176:179], v161 offset:1024
	ds_read_b128 v[180:183], v161 offset:2048
	ds_read_b128 v[184:187], v161 offset:3072
	s_add_i32 s81, s36, 2
	s_add_u32 s70, s34, 0x80
	s_addc_u32 s37, s35, 0
	s_cmp_eq_u32 s55, s36
	s_cselect_b32 s36, s4, s70
	s_cselect_b32 s37, s5, s37
	s_cselect_b32 s71, s31, s80
	s_cselect_b32 s70, s30, s45
	v_lshl_add_u64 v[158:159], s[34:35], 0, v[152:153]
	s_add_i32 m0, s42, 0xc000
	ds_read_b128 v[188:191], v162
	ds_read_b128 v[192:195], v162 offset:1024
	ds_read_b128 v[196:199], v162 offset:2048
	ds_read_b128 v[200:203], v162 offset:3072
	ds_read_b128 v[204:207], v162 offset:4096
	ds_read_b128 v[208:211], v162 offset:5120
	ds_read_b128 v[212:215], v162 offset:6144
	ds_read_b128 v[216:219], v162 offset:7168
	global_load_lds_dwordx4 v[158:159], off
	v_lshl_add_u64 v[158:159], s[34:35], 0, v[150:151]
	s_add_i32 m0, s42, 0xe000
	s_nop 0
	global_load_lds_dwordx4 v[158:159], off
	s_waitcnt vmcnt(8) lgkmcnt(0)
	s_barrier
	s_setprio 1
	v_mfma_f32_16x16x32_bf16 v[126:129], v[130:133], v[188:191], v[126:129]
	v_mfma_f32_16x16x32_bf16 v[122:125], v[164:167], v[188:191], v[122:125]
	v_mfma_f32_16x16x32_bf16 v[110:113], v[130:133], v[196:199], v[110:113]
	v_mfma_f32_16x16x32_bf16 v[106:109], v[164:167], v[196:199], v[106:109]
	v_mfma_f32_16x16x32_bf16 v[94:97], v[130:133], v[204:207], v[94:97]
	v_mfma_f32_16x16x32_bf16 v[90:93], v[164:167], v[204:207], v[90:93]
	v_mfma_f32_16x16x32_bf16 v[78:81], v[130:133], v[212:215], v[78:81]
	v_mfma_f32_16x16x32_bf16 v[74:77], v[164:167], v[212:215], v[74:77]
	v_mfma_f32_16x16x32_bf16 v[126:129], v[134:137], v[192:195], v[126:129]
	v_mfma_f32_16x16x32_bf16 v[122:125], v[168:171], v[192:195], v[122:125]
	v_mfma_f32_16x16x32_bf16 v[110:113], v[134:137], v[200:203], v[110:113]
	v_mfma_f32_16x16x32_bf16 v[106:109], v[168:171], v[200:203], v[106:109]
	v_mfma_f32_16x16x32_bf16 v[94:97], v[134:137], v[208:211], v[94:97]
	v_mfma_f32_16x16x32_bf16 v[90:93], v[168:171], v[208:211], v[90:93]
	v_mfma_f32_16x16x32_bf16 v[78:81], v[134:137], v[216:219], v[78:81]
	v_mfma_f32_16x16x32_bf16 v[74:77], v[168:171], v[216:219], v[74:77]
	v_mfma_f32_16x16x32_bf16 v[118:121], v[172:175], v[188:191], v[118:121]
	v_mfma_f32_16x16x32_bf16 v[114:117], v[180:183], v[188:191], v[114:117]
	v_mfma_f32_16x16x32_bf16 v[102:105], v[172:175], v[196:199], v[102:105]
	v_mfma_f32_16x16x32_bf16 v[98:101], v[180:183], v[196:199], v[98:101]
	v_mfma_f32_16x16x32_bf16 v[86:89], v[172:175], v[204:207], v[86:89]
	v_mfma_f32_16x16x32_bf16 v[82:85], v[180:183], v[204:207], v[82:85]
	v_mfma_f32_16x16x32_bf16 v[70:73], v[172:175], v[212:215], v[70:73]
	v_mfma_f32_16x16x32_bf16 v[66:69], v[180:183], v[212:215], v[66:69]
	v_mfma_f32_16x16x32_bf16 v[118:121], v[176:179], v[192:195], v[118:121]
	v_mfma_f32_16x16x32_bf16 v[114:117], v[184:187], v[192:195], v[114:117]
	v_mfma_f32_16x16x32_bf16 v[102:105], v[176:179], v[200:203], v[102:105]
	v_mfma_f32_16x16x32_bf16 v[98:101], v[184:187], v[200:203], v[98:101]
	v_mfma_f32_16x16x32_bf16 v[86:89], v[176:179], v[208:211], v[86:89]
	v_mfma_f32_16x16x32_bf16 v[82:85], v[184:187], v[208:211], v[82:85]
	v_mfma_f32_16x16x32_bf16 v[70:73], v[176:179], v[216:219], v[70:73]
	v_mfma_f32_16x16x32_bf16 v[66:69], v[184:187], v[216:219], v[66:69]
	s_setprio 0
	s_barrier
	s_add_i32 s72, s69, s41
	v_lshl_add_u64 v[158:159], s[70:71], 0, v[140:141]
	s_mov_b32 m0, s72
	ds_read_b128 v[188:191], v162 offset:16384
	ds_read_b128 v[192:195], v162 offset:17408
	ds_read_b128 v[196:199], v162 offset:18432
	ds_read_b128 v[200:203], v162 offset:19456
	ds_read_b128 v[204:207], v162 offset:20480
	ds_read_b128 v[208:211], v162 offset:21504
	ds_read_b128 v[212:215], v162 offset:22528
	ds_read_b128 v[216:219], v162 offset:23552
	global_load_lds_dwordx4 v[158:159], off
	s_add_i32 m0, s72, 0x2000
	v_lshl_add_u64 v[220:221], s[70:71], 0, v[144:145]
	s_add_u32 s70, s70, s8
	s_addc_u32 s71, s71, s9
	s_add_i32 s72, s86, s41
	global_load_lds_dwordx4 v[220:221], off
	v_lshl_add_u64 v[222:223], s[70:71], 0, v[140:141]
	s_mov_b32 m0, s72
	v_lshl_add_u64 v[224:225], s[70:71], 0, v[144:145]
	global_load_lds_dwordx4 v[222:223], off
	s_add_i32 m0, s72, 0x2000
	v_lshl_add_u64 v[226:227], s[36:37], 0, v[138:139]
	global_load_lds_dwordx4 v[224:225], off
	s_mov_b32 m0, s42
	v_lshl_add_u64 v[228:229], s[36:37], 0, v[142:143]
	global_load_lds_dwordx4 v[226:227], off
	s_mov_b32 m0, s46
	s_nop 0
	global_load_lds_dwordx4 v[228:229], off
	s_waitcnt vmcnt(8) lgkmcnt(0)
	s_barrier
; #define PG8_STAGE(bufoff, gbase, voff) do { _Pragma("unroll") for (int _i = 0; _i < 2; ++_i) \
;         __builtin_amdgcn_global_load_lds((const unsigned*)((const char*)(gbase) + (voff)[_i]), (PG8_LAS unsigned*)(lds + (bufoff) + ldsw + _i * 8192), 16, 0, 0); } while (0)
; #define PG8_LDA(dst, b, h) do { _Pragma("unroll") for (int m = 0; m < 4; ++m) _Pragma("unroll") for (int k = 0; k < 2; ++k) dst[m][k] = *(const PG8_LAS bf16x8*)(lds + PG8_SA(b, h) + aoff + m * 2048 + k * 1024); } while (0)
; #define PG8_LDB(dst, b, h) do { _Pragma("unroll") for (int n = 0; n < 2; ++n) _Pragma("unroll") for (int k = 0; k < 2; ++k) dst[n][k] = *(const PG8_LAS bf16x8*)(lds + PG8_SB(b, h) + boff + n * 2048 + k * 1024); } while (0)
; #define PG8_MMA(ai, bj, At, Bt) do { __builtin_amdgcn_s_setprio(1); _Pragma("unroll") for (int m = 0; m < 4; ++m) _Pragma("unroll") for (int n = 0; n < 2; ++n) _Pragma("unroll") for (int k = 0; k < 2; ++k) \
;         acc[ai][bj][m][n] = __builtin_amdgcn_mfma_f32_16x16x32_bf16(Bt[n][k], At[m][k], acc[ai][bj][m][n], 0, 0, 0); __builtin_amdgcn_s_setprio(0); } while (0)
; #define PG8_WAIT_V(n) asm volatile("s_waitcnt vmcnt(" #n ")" ::: "memory")
; #define PG8_WAIT_L(n) asm volatile("s_waitcnt lgkmcnt(" #n ")" ::: "memory")
; #define PG8_BAR __builtin_amdgcn_s_barrier()
; #define PG8_SCHED __builtin_amdgcn_sched_barrier(0)
; template <class Epi, class Sched, bool ALIGN_EPI = false, bool SP2 = false>
; __device__ __forceinline__ void gemm_phase(PG8_LAS unsigned char* lds, const Gemm g, const Sched& S, const Epi& E) {
;     ...
;             PG8_WAIT_V(8); PG8_WAIT_L(0); PG8_BAR; PG8_MMA(1, 0, At, B0); PG8_MMA(1, 1, At, B1); PG8_BAR; PG8_SCHED;
;             PG8_LDB(B0, 1, 0); PG8_LDB(B1, 1, 1); PG8_SCHED; PG8_LDA(At, 1, 0); PG8_STAGE(PG8_SA(0, 1), a2 + hstep, voffA);
;             PG8_WAIT_V(8); PG8_WAIT_L(0); PG8_BAR; PG8_MMA(0, 0, At, B0); PG8_MMA(0, 1, At, B1); PG8_BAR; PG8_SCHED;
	s_setprio 1
	v_mfma_f32_16x16x32_bf16 v[62:65], v[130:133], v[188:191], v[62:65]
	v_mfma_f32_16x16x32_bf16 v[58:61], v[164:167], v[188:191], v[58:61]
	v_mfma_f32_16x16x32_bf16 v[46:49], v[130:133], v[196:199], v[46:49]
	v_mfma_f32_16x16x32_bf16 v[42:45], v[164:167], v[196:199], v[42:45]
	v_mfma_f32_16x16x32_bf16 v[30:33], v[130:133], v[204:207], v[30:33]
	v_mfma_f32_16x16x32_bf16 v[26:29], v[164:167], v[204:207], v[26:29]
	v_mfma_f32_16x16x32_bf16 v[14:17], v[130:133], v[212:215], v[14:17]
	v_mfma_f32_16x16x32_bf16 v[10:13], v[164:167], v[212:215], v[10:13]
	v_mfma_f32_16x16x32_bf16 v[62:65], v[134:137], v[192:195], v[62:65]
	v_mfma_f32_16x16x32_bf16 v[58:61], v[168:171], v[192:195], v[58:61]
	v_mfma_f32_16x16x32_bf16 v[46:49], v[134:137], v[200:203], v[46:49]
	v_mfma_f32_16x16x32_bf16 v[42:45], v[168:171], v[200:203], v[42:45]
	v_mfma_f32_16x16x32_bf16 v[30:33], v[134:137], v[208:211], v[30:33]
	v_mfma_f32_16x16x32_bf16 v[26:29], v[168:171], v[208:211], v[26:29]
	v_mfma_f32_16x16x32_bf16 v[14:17], v[134:137], v[216:219], v[14:17]
	v_mfma_f32_16x16x32_bf16 v[10:13], v[168:171], v[216:219], v[10:13]
	v_mfma_f32_16x16x32_bf16 v[54:57], v[172:175], v[188:191], v[54:57]
	v_mfma_f32_16x16x32_bf16 v[50:53], v[180:183], v[188:191], v[50:53]
	v_mfma_f32_16x16x32_bf16 v[38:41], v[172:175], v[196:199], v[38:41]
	v_mfma_f32_16x16x32_bf16 v[34:37], v[180:183], v[196:199], v[34:37]
	v_mfma_f32_16x16x32_bf16 v[22:25], v[172:175], v[204:207], v[22:25]
	v_mfma_f32_16x16x32_bf16 v[18:21], v[180:183], v[204:207], v[18:21]
	v_mfma_f32_16x16x32_bf16 v[6:9], v[172:175], v[212:215], v[6:9]
	v_mfma_f32_16x16x32_bf16 v[2:5], v[180:183], v[212:215], v[2:5]
	v_mfma_f32_16x16x32_bf16 v[54:57], v[176:179], v[192:195], v[54:57]
	v_mfma_f32_16x16x32_bf16 v[50:53], v[184:187], v[192:195], v[50:53]
	v_mfma_f32_16x16x32_bf16 v[38:41], v[176:179], v[200:203], v[38:41]
	v_mfma_f32_16x16x32_bf16 v[34:37], v[184:187], v[200:203], v[34:37]
	v_mfma_f32_16x16x32_bf16 v[22:25], v[176:179], v[208:211], v[22:25]
	v_mfma_f32_16x16x32_bf16 v[18:21], v[184:187], v[208:211], v[18:21]
	v_mfma_f32_16x16x32_bf16 v[6:9], v[176:179], v[216:219], v[6:9]
	v_mfma_f32_16x16x32_bf16 v[2:5], v[184:187], v[216:219], v[2:5]
	s_setprio 0
	s_barrier
	s_add_i32 s70, 0, 0x18000
	v_add_u32_e32 v146, s70, v149
	s_add_i32 s71, 0, 0x1c000
	ds_read_b128 v[130:133], v146
	ds_read_b128 v[134:137], v146 offset:1024
	ds_read_b128 v[164:167], v146 offset:2048
	ds_read_b128 v[168:171], v146 offset:3072
	v_add_u32_e32 v146, s71, v149
	ds_read_b128 v[172:175], v146
	ds_read_b128 v[176:179], v146 offset:1024
	ds_read_b128 v[180:183], v146 offset:2048
	ds_read_b128 v[184:187], v146 offset:3072
	s_add_u32 s36, s36, s8
	s_addc_u32 s37, s37, s9
	s_mov_b32 m0, s47
	v_lshl_add_u64 v[230:231], s[36:37], 0, v[138:139]
	ds_read_b128 v[188:191], v162 offset:32768
	ds_read_b128 v[192:195], v162 offset:33792
	ds_read_b128 v[196:199], v162 offset:34816
	ds_read_b128 v[200:203], v162 offset:35840
	ds_read_b128 v[204:207], v162 offset:36864
	ds_read_b128 v[208:211], v162 offset:37888
	ds_read_b128 v[212:215], v162 offset:38912
	ds_read_b128 v[216:219], v162 offset:39936
	global_load_lds_dwordx4 v[230:231], off
	v_lshl_add_u64 v[230:231], s[36:37], 0, v[142:143]
	s_mov_b32 m0, s48
	s_nop 0
	global_load_lds_dwordx4 v[230:231], off
	s_waitcnt vmcnt(8) lgkmcnt(0)
	s_barrier
	s_setprio 1
	v_mfma_f32_16x16x32_bf16 v[126:129], v[130:133], v[188:191], v[126:129]
	v_mfma_f32_16x16x32_bf16 v[122:125], v[164:167], v[188:191], v[122:125]
	v_mfma_f32_16x16x32_bf16 v[110:113], v[130:133], v[196:199], v[110:113]
	v_mfma_f32_16x16x32_bf16 v[106:109], v[164:167], v[196:199], v[106:109]
	v_mfma_f32_16x16x32_bf16 v[94:97], v[130:133], v[204:207], v[94:97]
	v_mfma_f32_16x16x32_bf16 v[90:93], v[164:167], v[204:207], v[90:93]
	v_mfma_f32_16x16x32_bf16 v[78:81], v[130:133], v[212:215], v[78:81]
	v_mfma_f32_16x16x32_bf16 v[74:77], v[164:167], v[212:215], v[74:77]
	v_mfma_f32_16x16x32_bf16 v[126:129], v[134:137], v[192:195], v[126:129]
	v_mfma_f32_16x16x32_bf16 v[122:125], v[168:171], v[192:195], v[122:125]
	v_mfma_f32_16x16x32_bf16 v[110:113], v[134:137], v[200:203], v[110:113]
	v_mfma_f32_16x16x32_bf16 v[106:109], v[168:171], v[200:203], v[106:109]
	v_mfma_f32_16x16x32_bf16 v[94:97], v[134:137], v[208:211], v[94:97]
	v_mfma_f32_16x16x32_bf16 v[90:93], v[168:171], v[208:211], v[90:93]
	v_mfma_f32_16x16x32_bf16 v[78:81], v[134:137], v[216:219], v[78:81]
	v_mfma_f32_16x16x32_bf16 v[74:77], v[168:171], v[216:219], v[74:77]
	v_mfma_f32_16x16x32_bf16 v[118:121], v[172:175], v[188:191], v[118:121]
	v_mfma_f32_16x16x32_bf16 v[114:117], v[180:183], v[188:191], v[114:117]
	v_mfma_f32_16x16x32_bf16 v[102:105], v[172:175], v[196:199], v[102:105]
	v_mfma_f32_16x16x32_bf16 v[98:101], v[180:183], v[196:199], v[98:101]
	v_mfma_f32_16x16x32_bf16 v[86:89], v[172:175], v[204:207], v[86:89]
	v_mfma_f32_16x16x32_bf16 v[82:85], v[180:183], v[204:207], v[82:85]
	v_mfma_f32_16x16x32_bf16 v[70:73], v[172:175], v[212:215], v[70:73]
	v_mfma_f32_16x16x32_bf16 v[66:69], v[180:183], v[212:215], v[66:69]
	v_mfma_f32_16x16x32_bf16 v[118:121], v[176:179], v[192:195], v[118:121]
	v_mfma_f32_16x16x32_bf16 v[114:117], v[184:187], v[192:195], v[114:117]
	v_mfma_f32_16x16x32_bf16 v[102:105], v[176:179], v[200:203], v[102:105]
	v_mfma_f32_16x16x32_bf16 v[98:101], v[184:187], v[200:203], v[98:101]
	v_mfma_f32_16x16x32_bf16 v[86:89], v[176:179], v[208:211], v[86:89]
	v_mfma_f32_16x16x32_bf16 v[82:85], v[184:187], v[208:211], v[82:85]
	v_mfma_f32_16x16x32_bf16 v[70:73], v[176:179], v[216:219], v[70:73]
	v_mfma_f32_16x16x32_bf16 v[66:69], v[184:187], v[216:219], v[66:69]
	s_setprio 0
	s_barrier
; #define PG8_STAGE(bufoff, gbase, voff) do { _Pragma("unroll") for (int _i = 0; _i < 2; ++_i) \
;         __builtin_amdgcn_global_load_lds((const unsigned*)((const char*)(gbase) + (voff)[_i]), (PG8_LAS unsigned*)(lds + (bufoff) + ldsw + _i * 8192), 16, 0, 0); } while (0)
; #define PG8_LDA(dst, b, h) do { _Pragma("unroll") for (int m = 0; m < 4; ++m) _Pragma("unroll") for (int k = 0; k < 2; ++k) dst[m][k] = *(const PG8_LAS bf16x8*)(lds + PG8_SA(b, h) + aoff + m * 2048 + k * 1024); } while (0)
; #define PG8_MMA(ai, bj, At, Bt) do { __builtin_amdgcn_s_setprio(1); _Pragma("unroll") for (int m = 0; m < 4; ++m) _Pragma("unroll") for (int n = 0; n < 2; ++n) _Pragma("unroll") for (int k = 0; k < 2; ++k) \
;         acc[ai][bj][m][n] = __builtin_amdgcn_mfma_f32_16x16x32_bf16(Bt[n][k], At[m][k], acc[ai][bj][m][n], 0, 0, 0); __builtin_amdgcn_s_setprio(0); } while (0)
; #define PG8_WAIT_V(n) asm volatile("s_waitcnt vmcnt(" #n ")" ::: "memory")
; #define PG8_WAIT_L(n) asm volatile("s_waitcnt lgkmcnt(" #n ")" ::: "memory")
; #define PG8_BAR __builtin_amdgcn_s_barrier()
; #define PG8_SCHED __builtin_amdgcn_sched_barrier(0)
; template <class Epi, class Sched, bool ALIGN_EPI = false, bool SP2 = false>
; __device__ __forceinline__ void gemm_phase(PG8_LAS unsigned char* lds, const Gemm g, const Sched& S, const Epi& E) {
;     ...
;             PG8_LDA(At, 1, 1); PG8_STAGE(PG8_SB(1, 0), b3, voffB); PG8_STAGE(PG8_SB(1, 1), b3 + hstep, voffB); PG8_STAGE(PG8_SA(1, 0), a3, voffA);
;             PG8_WAIT_V(8); PG8_WAIT_L(0); PG8_BAR; PG8_MMA(1, 0, At, B0); PG8_MMA(1, 1, At, B1); PG8_BAR; PG8_SCHED;
	s_add_i32 s36, s70, s41
	v_lshl_add_u64 v[158:159], v[158:159], 0, s[24:25]
	s_mov_b32 m0, s36
	ds_read_b128 v[188:191], v162 offset:49152
	ds_read_b128 v[192:195], v162 offset:50176
	ds_read_b128 v[196:199], v162 offset:51200
	ds_read_b128 v[200:203], v162 offset:52224
	ds_read_b128 v[204:207], v162 offset:53248
	ds_read_b128 v[208:211], v162 offset:54272
	ds_read_b128 v[212:215], v162 offset:55296
	ds_read_b128 v[216:219], v162 offset:56320
	global_load_lds_dwordx4 v[158:159], off
	v_lshl_add_u64 v[158:159], v[220:221], 0, s[24:25]
	s_add_i32 m0, s36, 0x2000
	s_add_i32 s36, s71, s41
	global_load_lds_dwordx4 v[158:159], off
	v_lshl_add_u64 v[158:159], v[222:223], 0, s[24:25]
	s_mov_b32 m0, s36
	s_nop 0
	global_load_lds_dwordx4 v[158:159], off
	v_lshl_add_u64 v[158:159], v[224:225], 0, s[24:25]
	s_add_i32 m0, s36, 0x2000
	s_nop 0
	global_load_lds_dwordx4 v[158:159], off
	v_lshl_add_u64 v[158:159], v[226:227], 0, s[24:25]
	s_mov_b32 m0, s52
	s_nop 0
	global_load_lds_dwordx4 v[158:159], off
	v_lshl_add_u64 v[158:159], v[228:229], 0, s[24:25]
	s_mov_b32 m0, s53
	s_nop 0
	global_load_lds_dwordx4 v[158:159], off
	s_waitcnt vmcnt(8) lgkmcnt(0)
	s_barrier
	s_setprio 1
	v_mfma_f32_16x16x32_bf16 v[62:65], v[130:133], v[188:191], v[62:65]
	v_mfma_f32_16x16x32_bf16 v[58:61], v[164:167], v[188:191], v[58:61]
	v_mfma_f32_16x16x32_bf16 v[46:49], v[130:133], v[196:199], v[46:49]
	v_mfma_f32_16x16x32_bf16 v[42:45], v[164:167], v[196:199], v[42:45]
	v_mfma_f32_16x16x32_bf16 v[30:33], v[130:133], v[204:207], v[30:33]
	v_mfma_f32_16x16x32_bf16 v[26:29], v[164:167], v[204:207], v[26:29]
	v_mfma_f32_16x16x32_bf16 v[14:17], v[130:133], v[212:215], v[14:17]
	v_mfma_f32_16x16x32_bf16 v[10:13], v[164:167], v[212:215], v[10:13]
	v_mfma_f32_16x16x32_bf16 v[62:65], v[134:137], v[192:195], v[62:65]
	v_mfma_f32_16x16x32_bf16 v[58:61], v[168:171], v[192:195], v[58:61]
	v_mfma_f32_16x16x32_bf16 v[46:49], v[134:137], v[200:203], v[46:49]
	v_mfma_f32_16x16x32_bf16 v[42:45], v[168:171], v[200:203], v[42:45]
	v_mfma_f32_16x16x32_bf16 v[30:33], v[134:137], v[208:211], v[30:33]
	v_mfma_f32_16x16x32_bf16 v[26:29], v[168:171], v[208:211], v[26:29]
	v_mfma_f32_16x16x32_bf16 v[14:17], v[134:137], v[216:219], v[14:17]
	v_mfma_f32_16x16x32_bf16 v[10:13], v[168:171], v[216:219], v[10:13]
	v_mfma_f32_16x16x32_bf16 v[54:57], v[172:175], v[188:191], v[54:57]
	v_mfma_f32_16x16x32_bf16 v[50:53], v[180:183], v[188:191], v[50:53]
	v_mfma_f32_16x16x32_bf16 v[38:41], v[172:175], v[196:199], v[38:41]
	v_mfma_f32_16x16x32_bf16 v[34:37], v[180:183], v[196:199], v[34:37]
	v_mfma_f32_16x16x32_bf16 v[22:25], v[172:175], v[204:207], v[22:25]
	v_mfma_f32_16x16x32_bf16 v[18:21], v[180:183], v[204:207], v[18:21]
	v_mfma_f32_16x16x32_bf16 v[6:9], v[172:175], v[212:215], v[6:9]
	v_mfma_f32_16x16x32_bf16 v[2:5], v[180:183], v[212:215], v[2:5]
	v_mfma_f32_16x16x32_bf16 v[54:57], v[176:179], v[192:195], v[54:57]
	v_mfma_f32_16x16x32_bf16 v[50:53], v[184:187], v[192:195], v[50:53]
	v_mfma_f32_16x16x32_bf16 v[38:41], v[176:179], v[200:203], v[38:41]
	v_mfma_f32_16x16x32_bf16 v[34:37], v[184:187], v[200:203], v[34:37]
	v_mfma_f32_16x16x32_bf16 v[22:25], v[176:179], v[208:211], v[22:25]
	v_mfma_f32_16x16x32_bf16 v[18:21], v[184:187], v[208:211], v[18:21]
	v_mfma_f32_16x16x32_bf16 v[6:9], v[176:179], v[216:219], v[6:9]
	v_mfma_f32_16x16x32_bf16 v[2:5], v[184:187], v[216:219], v[2:5]
	s_setprio 0
	s_barrier
	s_add_u32 s45, s45, 0x100
	s_addc_u32 s80, s80, 0
	s_add_u32 s34, s34, 0x100
	s_addc_u32 s35, s35, 0
	s_cmp_ge_i32 s81, s54
	s_mov_b32 s36, s81
	s_cbranch_scc0 .LBB0_1154

; #define PG8_STAGE(bufoff, gbase, voff) do { _Pragma("unroll") for (int _i = 0; _i < 2; ++_i) \
;         __builtin_amdgcn_global_load_lds((const unsigned*)((const char*)(gbase) + (voff)[_i]), (PG8_LAS unsigned*)(lds + (bufoff) + ldsw + _i * 8192), 16, 0, 0); } while (0)
; #define PG8_LDA(dst, b, h) do { _Pragma("unroll") for (int m = 0; m < 4; ++m) _Pragma("unroll") for (int k = 0; k < 2; ++k) dst[m][k] = *(const PG8_LAS bf16x8*)(lds + PG8_SA(b, h) + aoff + m * 2048 + k * 1024); } while (0)
; #define PG8_LDB(dst, b, h) do { _Pragma("unroll") for (int n = 0; n < 2; ++n) _Pragma("unroll") for (int k = 0; k < 2; ++k) dst[n][k] = *(const PG8_LAS bf16x8*)(lds + PG8_SB(b, h) + boff + n * 2048 + k * 1024); } while (0)
; #define PG8_MMA(ai, bj, At, Bt) do { __builtin_amdgcn_s_setprio(1); _Pragma("unroll") for (int m = 0; m < 4; ++m) _Pragma("unroll") for (int n = 0; n < 2; ++n) _Pragma("unroll") for (int k = 0; k < 2; ++k) \
;         acc[ai][bj][m][n] = __builtin_amdgcn_mfma_f32_16x16x32_bf16(Bt[n][k], At[m][k], acc[ai][bj][m][n], 0, 0, 0); __builtin_amdgcn_s_setprio(0); } while (0)
; #define PG8_WAIT_V(n) asm volatile("s_waitcnt vmcnt(" #n ")" ::: "memory")
; #define PG8_WAIT_L(n) asm volatile("s_waitcnt lgkmcnt(" #n ")" ::: "memory")
; template <class Epi, class Sched, bool ALIGN_EPI = false, bool SP2 = false>
; __device__ __forceinline__ void gemm_phase(PG8_LAS unsigned char* lds, const Gemm g, const Sched& S, const Epi& E) {
;     ...
;             const bool last = (t == nt - 2);
;             const char* a1 = cA + (size_t)(t + 1) * kstep;
;             const char* a2 = last ? nA : cA + (size_t)(t + 2) * kstep; const char* b2 = last ? nB : cB + (size_t)(t + 2) * kstep;
;             const char* a3 = a2 + kstep; const char* b3 = b2 + kstep;
;             if (last && has_next) S.a_ready(nxt);
;             if constexpr (SP2) {
;             PG8_LDB(B0, 0, 0); PG8_LDB(B1, 0, 1); PG8_SCHED; PG8_LDA(At, 0, 0); PG8_STAGE(PG8_SA(1, 1), a1 + hstep, voffA);
;             PG8_WAIT_V(8); PG8_WAIT_L(0); PG8_BAR; PG8_MMA(0, 0, At, B0); PG8_MMA(0, 1, At, B1); PG8_BAR; PG8_SCHED;
;             PG8_LDA(At, 0, 1); PG8_STAGE(PG8_SB(0, 0), b2, voffB); PG8_STAGE(PG8_SB(0, 1), b2 + hstep, voffB); PG8_STAGE(PG8_SA(0, 0), a2, voffA);
;             PG8_WAIT_V(8); PG8_WAIT_L(0); PG8_BAR; PG8_MMA(1, 0, At, B0); PG8_MMA(1, 1, At, B1); PG8_BAR; PG8_SCHED;
.LBB0_1375:
	ds_read_b128 v[166:169], v162
	ds_read_b128 v[170:173], v162 offset:1024
	ds_read_b128 v[174:177], v162 offset:2048
	ds_read_b128 v[178:181], v162 offset:3072
	ds_read_b128 v[182:185], v163
	ds_read_b128 v[186:189], v163 offset:1024
	ds_read_b128 v[190:193], v163 offset:2048
	ds_read_b128 v[194:197], v163 offset:3072
	s_add_i32 s87, s36, 2
	s_add_u32 s70, s34, 0x80
	s_addc_u32 s37, s35, 0
	s_cmp_eq_u32 s52, s36
	s_cselect_b32 s36, s4, s70
	s_cselect_b32 s37, s5, s37
	s_cselect_b32 s71, s31, s86
	s_cselect_b32 s70, s30, s81
	v_lshl_add_u64 v[230:231], s[34:35], 0, v[140:141]
	s_add_i32 m0, s42, 0xc000
	ds_read_b128 v[198:201], v164
	ds_read_b128 v[202:205], v164 offset:1024
	ds_read_b128 v[206:209], v164 offset:2048
	ds_read_b128 v[210:213], v164 offset:3072
	ds_read_b128 v[214:217], v164 offset:4096
	ds_read_b128 v[218:221], v164 offset:5120
	ds_read_b128 v[222:225], v164 offset:6144
	ds_read_b128 v[226:229], v164 offset:7168
	global_load_lds_dwordx4 v[230:231], off
	v_lshl_add_u64 v[230:231], s[34:35], 0, v[138:139]
	s_add_i32 m0, s42, 0xe000
	s_nop 0
	global_load_lds_dwordx4 v[230:231], off
	s_waitcnt vmcnt(8) lgkmcnt(0)
	s_barrier
	s_setprio 1
	v_mfma_f32_16x16x32_bf16 v[122:125], v[166:169], v[198:201], v[122:125]
	v_mfma_f32_16x16x32_bf16 v[126:129], v[174:177], v[198:201], v[126:129]
	v_mfma_f32_16x16x32_bf16 v[110:113], v[166:169], v[206:209], v[110:113]
	v_mfma_f32_16x16x32_bf16 v[106:109], v[174:177], v[206:209], v[106:109]
	v_mfma_f32_16x16x32_bf16 v[94:97], v[166:169], v[214:217], v[94:97]
	v_mfma_f32_16x16x32_bf16 v[90:93], v[174:177], v[214:217], v[90:93]
	v_mfma_f32_16x16x32_bf16 v[78:81], v[166:169], v[222:225], v[78:81]
	v_mfma_f32_16x16x32_bf16 v[74:77], v[174:177], v[222:225], v[74:77]
	v_mfma_f32_16x16x32_bf16 v[122:125], v[170:173], v[202:205], v[122:125]
	v_mfma_f32_16x16x32_bf16 v[126:129], v[178:181], v[202:205], v[126:129]
	v_mfma_f32_16x16x32_bf16 v[110:113], v[170:173], v[210:213], v[110:113]
	v_mfma_f32_16x16x32_bf16 v[106:109], v[178:181], v[210:213], v[106:109]
	v_mfma_f32_16x16x32_bf16 v[94:97], v[170:173], v[218:221], v[94:97]
	v_mfma_f32_16x16x32_bf16 v[90:93], v[178:181], v[218:221], v[90:93]
	v_mfma_f32_16x16x32_bf16 v[78:81], v[170:173], v[226:229], v[78:81]
	v_mfma_f32_16x16x32_bf16 v[74:77], v[178:181], v[226:229], v[74:77]
	v_mfma_f32_16x16x32_bf16 v[118:121], v[182:185], v[198:201], v[118:121]
	v_mfma_f32_16x16x32_bf16 v[114:117], v[190:193], v[198:201], v[114:117]
	v_mfma_f32_16x16x32_bf16 v[102:105], v[182:185], v[206:209], v[102:105]
	v_mfma_f32_16x16x32_bf16 v[98:101], v[190:193], v[206:209], v[98:101]
	v_mfma_f32_16x16x32_bf16 v[86:89], v[182:185], v[214:217], v[86:89]
	v_mfma_f32_16x16x32_bf16 v[82:85], v[190:193], v[214:217], v[82:85]
	v_mfma_f32_16x16x32_bf16 v[70:73], v[182:185], v[222:225], v[70:73]
	v_mfma_f32_16x16x32_bf16 v[66:69], v[190:193], v[222:225], v[66:69]
	v_mfma_f32_16x16x32_bf16 v[118:121], v[186:189], v[202:205], v[118:121]
	v_mfma_f32_16x16x32_bf16 v[114:117], v[194:197], v[202:205], v[114:117]
	v_mfma_f32_16x16x32_bf16 v[102:105], v[186:189], v[210:213], v[102:105]
	v_mfma_f32_16x16x32_bf16 v[98:101], v[194:197], v[210:213], v[98:101]
	v_mfma_f32_16x16x32_bf16 v[86:89], v[186:189], v[218:221], v[86:89]
	v_mfma_f32_16x16x32_bf16 v[82:85], v[194:197], v[218:221], v[82:85]
	v_mfma_f32_16x16x32_bf16 v[70:73], v[186:189], v[226:229], v[70:73]
	v_mfma_f32_16x16x32_bf16 v[66:69], v[194:197], v[226:229], v[66:69]
	s_setprio 0
	s_barrier
	s_add_i32 s72, s55, s41
	v_lshl_add_u64 v[230:231], s[70:71], 0, v[132:133]
	s_mov_b32 m0, s72
	ds_read_b128 v[198:201], v164 offset:16384
	ds_read_b128 v[202:205], v164 offset:17408
	ds_read_b128 v[206:209], v164 offset:18432
	ds_read_b128 v[210:213], v164 offset:19456
	ds_read_b128 v[214:217], v164 offset:20480
	ds_read_b128 v[218:221], v164 offset:21504
	ds_read_b128 v[222:225], v164 offset:22528
	ds_read_b128 v[226:229], v164 offset:23552
	global_load_lds_dwordx4 v[230:231], off
	s_add_i32 m0, s72, 0x2000
	v_lshl_add_u64 v[232:233], s[70:71], 0, v[136:137]
	s_add_u32 s70, s70, s14
	s_addc_u32 s71, s71, s15
	s_add_i32 s72, s56, s41
	global_load_lds_dwordx4 v[232:233], off
	v_lshl_add_u64 v[234:235], s[70:71], 0, v[132:133]
	s_mov_b32 m0, s72
	v_lshl_add_u64 v[236:237], s[70:71], 0, v[136:137]
	global_load_lds_dwordx4 v[234:235], off
	s_add_i32 m0, s72, 0x2000
	v_lshl_add_u64 v[238:239], s[36:37], 0, v[130:131]
	global_load_lds_dwordx4 v[236:237], off
	s_mov_b32 m0, s42
	v_lshl_add_u64 v[240:241], s[36:37], 0, v[134:135]
	global_load_lds_dwordx4 v[238:239], off
	s_mov_b32 m0, s43
	s_nop 0
	global_load_lds_dwordx4 v[240:241], off
	s_waitcnt vmcnt(8) lgkmcnt(0)
	s_barrier
; #define PG8_STAGE(bufoff, gbase, voff) do { _Pragma("unroll") for (int _i = 0; _i < 2; ++_i) \
;         __builtin_amdgcn_global_load_lds((const unsigned*)((const char*)(gbase) + (voff)[_i]), (PG8_LAS unsigned*)(lds + (bufoff) + ldsw + _i * 8192), 16, 0, 0); } while (0)
; #define PG8_LDA(dst, b, h) do { _Pragma("unroll") for (int m = 0; m < 4; ++m) _Pragma("unroll") for (int k = 0; k < 2; ++k) dst[m][k] = *(const PG8_LAS bf16x8*)(lds + PG8_SA(b, h) + aoff + m * 2048 + k * 1024); } while (0)
; #define PG8_LDB(dst, b, h) do { _Pragma("unroll") for (int n = 0; n < 2; ++n) _Pragma("unroll") for (int k = 0; k < 2; ++k) dst[n][k] = *(const PG8_LAS bf16x8*)(lds + PG8_SB(b, h) + boff + n * 2048 + k * 1024); } while (0)
; #define PG8_MMA(ai, bj, At, Bt) do { __builtin_amdgcn_s_setprio(1); _Pragma("unroll") for (int m = 0; m < 4; ++m) _Pragma("unroll") for (int n = 0; n < 2; ++n) _Pragma("unroll") for (int k = 0; k < 2; ++k) \
;         acc[ai][bj][m][n] = __builtin_amdgcn_mfma_f32_16x16x32_bf16(Bt[n][k], At[m][k], acc[ai][bj][m][n], 0, 0, 0); __builtin_amdgcn_s_setprio(0); } while (0)
; #define PG8_WAIT_V(n) asm volatile("s_waitcnt vmcnt(" #n ")" ::: "memory")
; #define PG8_WAIT_L(n) asm volatile("s_waitcnt lgkmcnt(" #n ")" ::: "memory")
; #define PG8_BAR __builtin_amdgcn_s_barrier()
; #define PG8_SCHED __builtin_amdgcn_sched_barrier(0)
; template <class Epi, class Sched, bool ALIGN_EPI = false, bool SP2 = false>
; __device__ __forceinline__ void gemm_phase(PG8_LAS unsigned char* lds, const Gemm g, const Sched& S, const Epi& E) {
;     ...
;             PG8_WAIT_V(8); PG8_WAIT_L(0); PG8_BAR; PG8_MMA(1, 0, At, B0); PG8_MMA(1, 1, At, B1); PG8_BAR; PG8_SCHED;
;             PG8_LDB(B0, 1, 0); PG8_LDB(B1, 1, 1); PG8_SCHED; PG8_LDA(At, 1, 0); PG8_STAGE(PG8_SA(0, 1), a2 + hstep, voffA);
;             PG8_WAIT_V(8); PG8_WAIT_L(0); PG8_BAR; PG8_MMA(0, 0, At, B0); PG8_MMA(0, 1, At, B1); PG8_BAR; PG8_SCHED;
	s_setprio 1
	v_mfma_f32_16x16x32_bf16 v[62:65], v[166:169], v[198:201], v[62:65]
	v_mfma_f32_16x16x32_bf16 v[58:61], v[174:177], v[198:201], v[58:61]
	v_mfma_f32_16x16x32_bf16 v[46:49], v[166:169], v[206:209], v[46:49]
	v_mfma_f32_16x16x32_bf16 v[42:45], v[174:177], v[206:209], v[42:45]
	v_mfma_f32_16x16x32_bf16 v[30:33], v[166:169], v[214:217], v[30:33]
	v_mfma_f32_16x16x32_bf16 v[26:29], v[174:177], v[214:217], v[26:29]
	v_mfma_f32_16x16x32_bf16 v[14:17], v[166:169], v[222:225], v[14:17]
	v_mfma_f32_16x16x32_bf16 v[10:13], v[174:177], v[222:225], v[10:13]
	v_mfma_f32_16x16x32_bf16 v[62:65], v[170:173], v[202:205], v[62:65]
	v_mfma_f32_16x16x32_bf16 v[58:61], v[178:181], v[202:205], v[58:61]
	v_mfma_f32_16x16x32_bf16 v[46:49], v[170:173], v[210:213], v[46:49]
	v_mfma_f32_16x16x32_bf16 v[42:45], v[178:181], v[210:213], v[42:45]
	v_mfma_f32_16x16x32_bf16 v[30:33], v[170:173], v[218:221], v[30:33]
	v_mfma_f32_16x16x32_bf16 v[26:29], v[178:181], v[218:221], v[26:29]
	v_mfma_f32_16x16x32_bf16 v[14:17], v[170:173], v[226:229], v[14:17]
	v_mfma_f32_16x16x32_bf16 v[10:13], v[178:181], v[226:229], v[10:13]
	v_mfma_f32_16x16x32_bf16 v[54:57], v[182:185], v[198:201], v[54:57]
	v_mfma_f32_16x16x32_bf16 v[50:53], v[190:193], v[198:201], v[50:53]
	v_mfma_f32_16x16x32_bf16 v[38:41], v[182:185], v[206:209], v[38:41]
	v_mfma_f32_16x16x32_bf16 v[34:37], v[190:193], v[206:209], v[34:37]
	v_mfma_f32_16x16x32_bf16 v[22:25], v[182:185], v[214:217], v[22:25]
	v_mfma_f32_16x16x32_bf16 v[18:21], v[190:193], v[214:217], v[18:21]
	v_mfma_f32_16x16x32_bf16 v[6:9], v[182:185], v[222:225], v[6:9]
	v_mfma_f32_16x16x32_bf16 v[2:5], v[190:193], v[222:225], v[2:5]
	v_mfma_f32_16x16x32_bf16 v[54:57], v[186:189], v[202:205], v[54:57]
	v_mfma_f32_16x16x32_bf16 v[50:53], v[194:197], v[202:205], v[50:53]
	v_mfma_f32_16x16x32_bf16 v[38:41], v[186:189], v[210:213], v[38:41]
	v_mfma_f32_16x16x32_bf16 v[34:37], v[194:197], v[210:213], v[34:37]
	v_mfma_f32_16x16x32_bf16 v[22:25], v[186:189], v[218:221], v[22:25]
	v_mfma_f32_16x16x32_bf16 v[18:21], v[194:197], v[218:221], v[18:21]
	v_mfma_f32_16x16x32_bf16 v[6:9], v[186:189], v[226:229], v[6:9]
	v_mfma_f32_16x16x32_bf16 v[2:5], v[194:197], v[226:229], v[2:5]
	s_setprio 0
	s_barrier
	s_add_i32 s70, 0, 0x18000
	v_add_u32_e32 v165, s70, v160
	s_add_i32 s71, 0, 0x1c000
	ds_read_b128 v[166:169], v165
	ds_read_b128 v[170:173], v165 offset:1024
	ds_read_b128 v[174:177], v165 offset:2048
	ds_read_b128 v[178:181], v165 offset:3072
	v_add_u32_e32 v165, s71, v160
	ds_read_b128 v[182:185], v165
	ds_read_b128 v[186:189], v165 offset:1024
	ds_read_b128 v[190:193], v165 offset:2048
	ds_read_b128 v[194:197], v165 offset:3072
	s_add_u32 s36, s36, s14
	s_addc_u32 s37, s37, s15
	s_mov_b32 m0, s44
	v_lshl_add_u64 v[242:243], s[36:37], 0, v[130:131]
	ds_read_b128 v[198:201], v164 offset:32768
	ds_read_b128 v[202:205], v164 offset:33792
	ds_read_b128 v[206:209], v164 offset:34816
	ds_read_b128 v[210:213], v164 offset:35840
	ds_read_b128 v[214:217], v164 offset:36864
	ds_read_b128 v[218:221], v164 offset:37888
	ds_read_b128 v[222:225], v164 offset:38912
	ds_read_b128 v[226:229], v164 offset:39936
	global_load_lds_dwordx4 v[242:243], off
	v_lshl_add_u64 v[242:243], s[36:37], 0, v[134:135]
	s_mov_b32 m0, s45
	s_nop 0
	global_load_lds_dwordx4 v[242:243], off
	s_waitcnt vmcnt(8) lgkmcnt(0)
	s_barrier
	s_setprio 1
	v_mfma_f32_16x16x32_bf16 v[122:125], v[166:169], v[198:201], v[122:125]
	v_mfma_f32_16x16x32_bf16 v[126:129], v[174:177], v[198:201], v[126:129]
	v_mfma_f32_16x16x32_bf16 v[110:113], v[166:169], v[206:209], v[110:113]
	v_mfma_f32_16x16x32_bf16 v[106:109], v[174:177], v[206:209], v[106:109]
	v_mfma_f32_16x16x32_bf16 v[94:97], v[166:169], v[214:217], v[94:97]
	v_mfma_f32_16x16x32_bf16 v[90:93], v[174:177], v[214:217], v[90:93]
	v_mfma_f32_16x16x32_bf16 v[78:81], v[166:169], v[222:225], v[78:81]
	v_mfma_f32_16x16x32_bf16 v[74:77], v[174:177], v[222:225], v[74:77]
	v_mfma_f32_16x16x32_bf16 v[122:125], v[170:173], v[202:205], v[122:125]
	v_mfma_f32_16x16x32_bf16 v[126:129], v[178:181], v[202:205], v[126:129]
	v_mfma_f32_16x16x32_bf16 v[110:113], v[170:173], v[210:213], v[110:113]
	v_mfma_f32_16x16x32_bf16 v[106:109], v[178:181], v[210:213], v[106:109]
	v_mfma_f32_16x16x32_bf16 v[94:97], v[170:173], v[218:221], v[94:97]
	v_mfma_f32_16x16x32_bf16 v[90:93], v[178:181], v[218:221], v[90:93]
	v_mfma_f32_16x16x32_bf16 v[78:81], v[170:173], v[226:229], v[78:81]
	v_mfma_f32_16x16x32_bf16 v[74:77], v[178:181], v[226:229], v[74:77]
	v_mfma_f32_16x16x32_bf16 v[118:121], v[182:185], v[198:201], v[118:121]
	v_mfma_f32_16x16x32_bf16 v[114:117], v[190:193], v[198:201], v[114:117]
	v_mfma_f32_16x16x32_bf16 v[102:105], v[182:185], v[206:209], v[102:105]
	v_mfma_f32_16x16x32_bf16 v[98:101], v[190:193], v[206:209], v[98:101]
	v_mfma_f32_16x16x32_bf16 v[86:89], v[182:185], v[214:217], v[86:89]
	v_mfma_f32_16x16x32_bf16 v[82:85], v[190:193], v[214:217], v[82:85]
	v_mfma_f32_16x16x32_bf16 v[70:73], v[182:185], v[222:225], v[70:73]
	v_mfma_f32_16x16x32_bf16 v[66:69], v[190:193], v[222:225], v[66:69]
	v_mfma_f32_16x16x32_bf16 v[118:121], v[186:189], v[202:205], v[118:121]
	v_mfma_f32_16x16x32_bf16 v[114:117], v[194:197], v[202:205], v[114:117]
	v_mfma_f32_16x16x32_bf16 v[102:105], v[186:189], v[210:213], v[102:105]
	v_mfma_f32_16x16x32_bf16 v[98:101], v[194:197], v[210:213], v[98:101]
	v_mfma_f32_16x16x32_bf16 v[86:89], v[186:189], v[218:221], v[86:89]
	v_mfma_f32_16x16x32_bf16 v[82:85], v[194:197], v[218:221], v[82:85]
	v_mfma_f32_16x16x32_bf16 v[70:73], v[186:189], v[226:229], v[70:73]
	v_mfma_f32_16x16x32_bf16 v[66:69], v[194:197], v[226:229], v[66:69]
	s_setprio 0
	s_barrier
; #define PG8_STAGE(bufoff, gbase, voff) do { _Pragma("unroll") for (int _i = 0; _i < 2; ++_i) \
;         __builtin_amdgcn_global_load_lds((const unsigned*)((const char*)(gbase) + (voff)[_i]), (PG8_LAS unsigned*)(lds + (bufoff) + ldsw + _i * 8192), 16, 0, 0); } while (0)
; #define PG8_LDA(dst, b, h) do { _Pragma("unroll") for (int m = 0; m < 4; ++m) _Pragma("unroll") for (int k = 0; k < 2; ++k) dst[m][k] = *(const PG8_LAS bf16x8*)(lds + PG8_SA(b, h) + aoff + m * 2048 + k * 1024); } while (0)
; #define PG8_MMA(ai, bj, At, Bt) do { __builtin_amdgcn_s_setprio(1); _Pragma("unroll") for (int m = 0; m < 4; ++m) _Pragma("unroll") for (int n = 0; n < 2; ++n) _Pragma("unroll") for (int k = 0; k < 2; ++k) \
;         acc[ai][bj][m][n] = __builtin_amdgcn_mfma_f32_16x16x32_bf16(Bt[n][k], At[m][k], acc[ai][bj][m][n], 0, 0, 0); __builtin_amdgcn_s_setprio(0); } while (0)
; #define PG8_WAIT_V(n) asm volatile("s_waitcnt vmcnt(" #n ")" ::: "memory")
; #define PG8_WAIT_L(n) asm volatile("s_waitcnt lgkmcnt(" #n ")" ::: "memory")
; #define PG8_BAR __builtin_amdgcn_s_barrier()
; #define PG8_SCHED __builtin_amdgcn_sched_barrier(0)
; template <class Epi, class Sched, bool ALIGN_EPI = false, bool SP2 = false>
; __device__ __forceinline__ void gemm_phase(PG8_LAS unsigned char* lds, const Gemm g, const Sched& S, const Epi& E) {
;     ...
;             PG8_LDA(At, 1, 1); PG8_STAGE(PG8_SB(1, 0), b3, voffB); PG8_STAGE(PG8_SB(1, 1), b3 + hstep, voffB); PG8_STAGE(PG8_SA(1, 0), a3, voffA);
;             PG8_WAIT_V(8); PG8_WAIT_L(0); PG8_BAR; PG8_MMA(1, 0, At, B0); PG8_MMA(1, 1, At, B1); PG8_BAR; PG8_SCHED;
	s_add_i32 s36, s70, s41
	v_lshl_add_u64 v[230:231], v[230:231], 0, s[24:25]
	s_mov_b32 m0, s36
	ds_read_b128 v[198:201], v164 offset:49152
	ds_read_b128 v[202:205], v164 offset:50176
	ds_read_b128 v[206:209], v164 offset:51200
	ds_read_b128 v[210:213], v164 offset:52224
	ds_read_b128 v[214:217], v164 offset:53248
	ds_read_b128 v[218:221], v164 offset:54272
	ds_read_b128 v[222:225], v164 offset:55296
	ds_read_b128 v[226:229], v164 offset:56320
	global_load_lds_dwordx4 v[230:231], off
	v_lshl_add_u64 v[230:231], v[232:233], 0, s[24:25]
	s_add_i32 m0, s36, 0x2000
	s_add_i32 s36, s71, s41
	global_load_lds_dwordx4 v[230:231], off
	v_lshl_add_u64 v[230:231], v[234:235], 0, s[24:25]
	s_mov_b32 m0, s36
	s_nop 0
	global_load_lds_dwordx4 v[230:231], off
	v_lshl_add_u64 v[230:231], v[236:237], 0, s[24:25]
	s_add_i32 m0, s36, 0x2000
	s_nop 0
	global_load_lds_dwordx4 v[230:231], off
	v_lshl_add_u64 v[230:231], v[238:239], 0, s[24:25]
	s_mov_b32 m0, s47
	s_nop 0
	global_load_lds_dwordx4 v[230:231], off
	v_lshl_add_u64 v[230:231], v[240:241], 0, s[24:25]
	s_mov_b32 m0, s48
	s_nop 0
	global_load_lds_dwordx4 v[230:231], off
	s_waitcnt vmcnt(8) lgkmcnt(0)
	s_barrier
	s_setprio 1
	v_mfma_f32_16x16x32_bf16 v[62:65], v[166:169], v[198:201], v[62:65]
	v_mfma_f32_16x16x32_bf16 v[58:61], v[174:177], v[198:201], v[58:61]
	v_mfma_f32_16x16x32_bf16 v[46:49], v[166:169], v[206:209], v[46:49]
	v_mfma_f32_16x16x32_bf16 v[42:45], v[174:177], v[206:209], v[42:45]
	v_mfma_f32_16x16x32_bf16 v[30:33], v[166:169], v[214:217], v[30:33]
	v_mfma_f32_16x16x32_bf16 v[26:29], v[174:177], v[214:217], v[26:29]
	v_mfma_f32_16x16x32_bf16 v[14:17], v[166:169], v[222:225], v[14:17]
	v_mfma_f32_16x16x32_bf16 v[10:13], v[174:177], v[222:225], v[10:13]
	v_mfma_f32_16x16x32_bf16 v[62:65], v[170:173], v[202:205], v[62:65]
	v_mfma_f32_16x16x32_bf16 v[58:61], v[178:181], v[202:205], v[58:61]
	v_mfma_f32_16x16x32_bf16 v[46:49], v[170:173], v[210:213], v[46:49]
	v_mfma_f32_16x16x32_bf16 v[42:45], v[178:181], v[210:213], v[42:45]
	v_mfma_f32_16x16x32_bf16 v[30:33], v[170:173], v[218:221], v[30:33]
	v_mfma_f32_16x16x32_bf16 v[26:29], v[178:181], v[218:221], v[26:29]
	v_mfma_f32_16x16x32_bf16 v[14:17], v[170:173], v[226:229], v[14:17]
	v_mfma_f32_16x16x32_bf16 v[10:13], v[178:181], v[226:229], v[10:13]
	v_mfma_f32_16x16x32_bf16 v[54:57], v[182:185], v[198:201], v[54:57]
	v_mfma_f32_16x16x32_bf16 v[50:53], v[190:193], v[198:201], v[50:53]
	v_mfma_f32_16x16x32_bf16 v[38:41], v[182:185], v[206:209], v[38:41]
	v_mfma_f32_16x16x32_bf16 v[34:37], v[190:193], v[206:209], v[34:37]
	v_mfma_f32_16x16x32_bf16 v[22:25], v[182:185], v[214:217], v[22:25]
	v_mfma_f32_16x16x32_bf16 v[18:21], v[190:193], v[214:217], v[18:21]
	v_mfma_f32_16x16x32_bf16 v[6:9], v[182:185], v[222:225], v[6:9]
	v_mfma_f32_16x16x32_bf16 v[2:5], v[190:193], v[222:225], v[2:5]
	v_mfma_f32_16x16x32_bf16 v[54:57], v[186:189], v[202:205], v[54:57]
	v_mfma_f32_16x16x32_bf16 v[50:53], v[194:197], v[202:205], v[50:53]
	v_mfma_f32_16x16x32_bf16 v[38:41], v[186:189], v[210:213], v[38:41]
	v_mfma_f32_16x16x32_bf16 v[34:37], v[194:197], v[210:213], v[34:37]
	v_mfma_f32_16x16x32_bf16 v[22:25], v[186:189], v[218:221], v[22:25]
	v_mfma_f32_16x16x32_bf16 v[18:21], v[194:197], v[218:221], v[18:21]
	v_mfma_f32_16x16x32_bf16 v[6:9], v[186:189], v[226:229], v[6:9]
	v_mfma_f32_16x16x32_bf16 v[2:5], v[194:197], v[226:229], v[2:5]
	s_setprio 0
	s_barrier
	s_add_u32 s81, s81, 0x100
	s_addc_u32 s86, s86, 0
	s_add_u32 s34, s34, 0x100
	s_addc_u32 s35, s35, 0
	s_cmp_ge_i32 s87, s49
	s_mov_b32 s36, s87
	s_cbranch_scc0 .LBB0_1375

; #define PG8_STAGE(bufoff, gbase, voff) do { _Pragma("unroll") for (int _i = 0; _i < 2; ++_i) \
;         __builtin_amdgcn_global_load_lds((const unsigned*)((const char*)(gbase) + (voff)[_i]), (PG8_LAS unsigned*)(lds + (bufoff) + ldsw + _i * 8192), 16, 0, 0); } while (0)
; #define PG8_LDA(dst, b, h) do { _Pragma("unroll") for (int m = 0; m < 4; ++m) _Pragma("unroll") for (int k = 0; k < 2; ++k) dst[m][k] = *(const PG8_LAS bf16x8*)(lds + PG8_SA(b, h) + aoff + m * 2048 + k * 1024); } while (0)
; #define PG8_LDB(dst, b, h) do { _Pragma("unroll") for (int n = 0; n < 2; ++n) _Pragma("unroll") for (int k = 0; k < 2; ++k) dst[n][k] = *(const PG8_LAS bf16x8*)(lds + PG8_SB(b, h) + boff + n * 2048 + k * 1024); } while (0)
; #define PG8_MMA(ai, bj, At, Bt) do { __builtin_amdgcn_s_setprio(1); _Pragma("unroll") for (int m = 0; m < 4; ++m) _Pragma("unroll") for (int n = 0; n < 2; ++n) _Pragma("unroll") for (int k = 0; k < 2; ++k) \
;         acc[ai][bj][m][n] = __builtin_amdgcn_mfma_f32_16x16x32_bf16(Bt[n][k], At[m][k], acc[ai][bj][m][n], 0, 0, 0); __builtin_amdgcn_s_setprio(0); } while (0)
; #define PG8_WAIT_V(n) asm volatile("s_waitcnt vmcnt(" #n ")" ::: "memory")
; #define PG8_WAIT_L(n) asm volatile("s_waitcnt lgkmcnt(" #n ")" ::: "memory")
; template <class Epi, class Sched, bool ALIGN_EPI = false, bool SP2 = false>
; __device__ __forceinline__ void gemm_phase(PG8_LAS unsigned char* lds, const Gemm g, const Sched& S, const Epi& E) {
;     ...
;             const bool last = (t == nt - 2);
;             const char* a1 = cA + (size_t)(t + 1) * kstep;
;             const char* a2 = last ? nA : cA + (size_t)(t + 2) * kstep; const char* b2 = last ? nB : cB + (size_t)(t + 2) * kstep;
;             const char* a3 = a2 + kstep; const char* b3 = b2 + kstep;
;             if (last && has_next) S.a_ready(nxt);
;             if constexpr (SP2) {
;             PG8_LDB(B0, 0, 0); PG8_LDB(B1, 0, 1); PG8_SCHED; PG8_LDA(At, 0, 0); PG8_STAGE(PG8_SA(1, 1), a1 + hstep, voffA);
;             PG8_WAIT_V(8); PG8_WAIT_L(0); PG8_BAR; PG8_MMA(0, 0, At, B0); PG8_MMA(0, 1, At, B1); PG8_BAR; PG8_SCHED;
;             PG8_LDA(At, 0, 1); PG8_STAGE(PG8_SB(0, 0), b2, voffB); PG8_STAGE(PG8_SB(0, 1), b2 + hstep, voffB); PG8_STAGE(PG8_SA(0, 0), a2, voffA);
;             PG8_WAIT_V(8); PG8_WAIT_L(0); PG8_BAR; PG8_MMA(1, 0, At, B0); PG8_MMA(1, 1, At, B1); PG8_BAR; PG8_SCHED;
.LBB0_1404:
	ds_read_b128 v[166:169], v162
	ds_read_b128 v[170:173], v162 offset:1024
	ds_read_b128 v[174:177], v162 offset:2048
	ds_read_b128 v[178:181], v162 offset:3072
	ds_read_b128 v[182:185], v163
	ds_read_b128 v[186:189], v163 offset:1024
	ds_read_b128 v[190:193], v163 offset:2048
	ds_read_b128 v[194:197], v163 offset:3072
	s_add_i32 s86, s34, 2
	s_add_u32 s70, s30, 0x80
	s_addc_u32 s35, s31, 0
	s_cmp_eq_u32 s49, s34
	s_cselect_b32 s34, s6, s70
	s_cselect_b32 s35, s7, s35
	s_cselect_b32 s71, s29, s81
	s_cselect_b32 s70, s28, s80
	v_lshl_add_u64 v[230:231], s[30:31], 0, v[140:141]
	s_add_i32 m0, s41, 0xc000
	ds_read_b128 v[198:201], v164
	ds_read_b128 v[202:205], v164 offset:1024
	ds_read_b128 v[206:209], v164 offset:2048
	ds_read_b128 v[210:213], v164 offset:3072
	ds_read_b128 v[214:217], v164 offset:4096
	ds_read_b128 v[218:221], v164 offset:5120
	ds_read_b128 v[222:225], v164 offset:6144
	ds_read_b128 v[226:229], v164 offset:7168
	global_load_lds_dwordx4 v[230:231], off
	v_lshl_add_u64 v[230:231], s[30:31], 0, v[138:139]
	s_add_i32 m0, s41, 0xe000
	s_nop 0
	global_load_lds_dwordx4 v[230:231], off
	s_waitcnt vmcnt(8) lgkmcnt(0)
	s_barrier
	s_setprio 1
	v_mfma_f32_16x16x32_bf16 v[122:125], v[166:169], v[198:201], v[122:125]
	v_mfma_f32_16x16x32_bf16 v[126:129], v[174:177], v[198:201], v[126:129]
	v_mfma_f32_16x16x32_bf16 v[110:113], v[166:169], v[206:209], v[110:113]
	v_mfma_f32_16x16x32_bf16 v[106:109], v[174:177], v[206:209], v[106:109]
	v_mfma_f32_16x16x32_bf16 v[94:97], v[166:169], v[214:217], v[94:97]
	v_mfma_f32_16x16x32_bf16 v[90:93], v[174:177], v[214:217], v[90:93]
	v_mfma_f32_16x16x32_bf16 v[78:81], v[166:169], v[222:225], v[78:81]
	v_mfma_f32_16x16x32_bf16 v[74:77], v[174:177], v[222:225], v[74:77]
	v_mfma_f32_16x16x32_bf16 v[122:125], v[170:173], v[202:205], v[122:125]
	v_mfma_f32_16x16x32_bf16 v[126:129], v[178:181], v[202:205], v[126:129]
	v_mfma_f32_16x16x32_bf16 v[110:113], v[170:173], v[210:213], v[110:113]
	v_mfma_f32_16x16x32_bf16 v[106:109], v[178:181], v[210:213], v[106:109]
	v_mfma_f32_16x16x32_bf16 v[94:97], v[170:173], v[218:221], v[94:97]
	v_mfma_f32_16x16x32_bf16 v[90:93], v[178:181], v[218:221], v[90:93]
	v_mfma_f32_16x16x32_bf16 v[78:81], v[170:173], v[226:229], v[78:81]
	v_mfma_f32_16x16x32_bf16 v[74:77], v[178:181], v[226:229], v[74:77]
	v_mfma_f32_16x16x32_bf16 v[118:121], v[182:185], v[198:201], v[118:121]
	v_mfma_f32_16x16x32_bf16 v[114:117], v[190:193], v[198:201], v[114:117]
	v_mfma_f32_16x16x32_bf16 v[102:105], v[182:185], v[206:209], v[102:105]
	v_mfma_f32_16x16x32_bf16 v[98:101], v[190:193], v[206:209], v[98:101]
	v_mfma_f32_16x16x32_bf16 v[86:89], v[182:185], v[214:217], v[86:89]
	v_mfma_f32_16x16x32_bf16 v[82:85], v[190:193], v[214:217], v[82:85]
	v_mfma_f32_16x16x32_bf16 v[70:73], v[182:185], v[222:225], v[70:73]
	v_mfma_f32_16x16x32_bf16 v[66:69], v[190:193], v[222:225], v[66:69]
	v_mfma_f32_16x16x32_bf16 v[118:121], v[186:189], v[202:205], v[118:121]
	v_mfma_f32_16x16x32_bf16 v[114:117], v[194:197], v[202:205], v[114:117]
	v_mfma_f32_16x16x32_bf16 v[102:105], v[186:189], v[210:213], v[102:105]
	v_mfma_f32_16x16x32_bf16 v[98:101], v[194:197], v[210:213], v[98:101]
	v_mfma_f32_16x16x32_bf16 v[86:89], v[186:189], v[218:221], v[86:89]
	v_mfma_f32_16x16x32_bf16 v[82:85], v[194:197], v[218:221], v[82:85]
	v_mfma_f32_16x16x32_bf16 v[70:73], v[186:189], v[226:229], v[70:73]
	v_mfma_f32_16x16x32_bf16 v[66:69], v[194:197], v[226:229], v[66:69]
	s_setprio 0
	s_barrier
	s_add_i32 s72, s54, s40
	v_lshl_add_u64 v[230:231], s[70:71], 0, v[132:133]
	s_mov_b32 m0, s72
	ds_read_b128 v[198:201], v164 offset:16384
	ds_read_b128 v[202:205], v164 offset:17408
	ds_read_b128 v[206:209], v164 offset:18432
	ds_read_b128 v[210:213], v164 offset:19456
	ds_read_b128 v[214:217], v164 offset:20480
	ds_read_b128 v[218:221], v164 offset:21504
	ds_read_b128 v[222:225], v164 offset:22528
	ds_read_b128 v[226:229], v164 offset:23552
	global_load_lds_dwordx4 v[230:231], off
	s_add_i32 m0, s72, 0x2000
	v_lshl_add_u64 v[232:233], s[70:71], 0, v[136:137]
	s_add_u32 s70, s70, s12
	s_addc_u32 s71, s71, s13
	s_add_i32 s72, s55, s40
	global_load_lds_dwordx4 v[232:233], off
	v_lshl_add_u64 v[234:235], s[70:71], 0, v[132:133]
	s_mov_b32 m0, s72
	v_lshl_add_u64 v[236:237], s[70:71], 0, v[136:137]
	global_load_lds_dwordx4 v[234:235], off
	s_add_i32 m0, s72, 0x2000
	v_lshl_add_u64 v[238:239], s[34:35], 0, v[130:131]
	global_load_lds_dwordx4 v[236:237], off
	s_mov_b32 m0, s41
	v_lshl_add_u64 v[240:241], s[34:35], 0, v[134:135]
	global_load_lds_dwordx4 v[238:239], off
	s_mov_b32 m0, s42
	s_nop 0
	global_load_lds_dwordx4 v[240:241], off
	s_waitcnt vmcnt(8) lgkmcnt(0)
	s_barrier
; #define PG8_STAGE(bufoff, gbase, voff) do { _Pragma("unroll") for (int _i = 0; _i < 2; ++_i) \
;         __builtin_amdgcn_global_load_lds((const unsigned*)((const char*)(gbase) + (voff)[_i]), (PG8_LAS unsigned*)(lds + (bufoff) + ldsw + _i * 8192), 16, 0, 0); } while (0)
; #define PG8_LDA(dst, b, h) do { _Pragma("unroll") for (int m = 0; m < 4; ++m) _Pragma("unroll") for (int k = 0; k < 2; ++k) dst[m][k] = *(const PG8_LAS bf16x8*)(lds + PG8_SA(b, h) + aoff + m * 2048 + k * 1024); } while (0)
; #define PG8_LDB(dst, b, h) do { _Pragma("unroll") for (int n = 0; n < 2; ++n) _Pragma("unroll") for (int k = 0; k < 2; ++k) dst[n][k] = *(const PG8_LAS bf16x8*)(lds + PG8_SB(b, h) + boff + n * 2048 + k * 1024); } while (0)
; #define PG8_MMA(ai, bj, At, Bt) do { __builtin_amdgcn_s_setprio(1); _Pragma("unroll") for (int m = 0; m < 4; ++m) _Pragma("unroll") for (int n = 0; n < 2; ++n) _Pragma("unroll") for (int k = 0; k < 2; ++k) \
;         acc[ai][bj][m][n] = __builtin_amdgcn_mfma_f32_16x16x32_bf16(Bt[n][k], At[m][k], acc[ai][bj][m][n], 0, 0, 0); __builtin_amdgcn_s_setprio(0); } while (0)
; #define PG8_WAIT_V(n) asm volatile("s_waitcnt vmcnt(" #n ")" ::: "memory")
; #define PG8_WAIT_L(n) asm volatile("s_waitcnt lgkmcnt(" #n ")" ::: "memory")
; #define PG8_BAR __builtin_amdgcn_s_barrier()
; #define PG8_SCHED __builtin_amdgcn_sched_barrier(0)
; template <class Epi, class Sched, bool ALIGN_EPI = false, bool SP2 = false>
; __device__ __forceinline__ void gemm_phase(PG8_LAS unsigned char* lds, const Gemm g, const Sched& S, const Epi& E) {
;     ...
;             PG8_WAIT_V(8); PG8_WAIT_L(0); PG8_BAR; PG8_MMA(1, 0, At, B0); PG8_MMA(1, 1, At, B1); PG8_BAR; PG8_SCHED;
;             PG8_LDB(B0, 1, 0); PG8_LDB(B1, 1, 1); PG8_SCHED; PG8_LDA(At, 1, 0); PG8_STAGE(PG8_SA(0, 1), a2 + hstep, voffA);
;             PG8_WAIT_V(8); PG8_WAIT_L(0); PG8_BAR; PG8_MMA(0, 0, At, B0); PG8_MMA(0, 1, At, B1); PG8_BAR; PG8_SCHED;
	s_setprio 1
	v_mfma_f32_16x16x32_bf16 v[62:65], v[166:169], v[198:201], v[62:65]
	v_mfma_f32_16x16x32_bf16 v[58:61], v[174:177], v[198:201], v[58:61]
	v_mfma_f32_16x16x32_bf16 v[46:49], v[166:169], v[206:209], v[46:49]
	v_mfma_f32_16x16x32_bf16 v[42:45], v[174:177], v[206:209], v[42:45]
	v_mfma_f32_16x16x32_bf16 v[30:33], v[166:169], v[214:217], v[30:33]
	v_mfma_f32_16x16x32_bf16 v[26:29], v[174:177], v[214:217], v[26:29]
	v_mfma_f32_16x16x32_bf16 v[14:17], v[166:169], v[222:225], v[14:17]
	v_mfma_f32_16x16x32_bf16 v[10:13], v[174:177], v[222:225], v[10:13]
	v_mfma_f32_16x16x32_bf16 v[62:65], v[170:173], v[202:205], v[62:65]
	v_mfma_f32_16x16x32_bf16 v[58:61], v[178:181], v[202:205], v[58:61]
	v_mfma_f32_16x16x32_bf16 v[46:49], v[170:173], v[210:213], v[46:49]
	v_mfma_f32_16x16x32_bf16 v[42:45], v[178:181], v[210:213], v[42:45]
	v_mfma_f32_16x16x32_bf16 v[30:33], v[170:173], v[218:221], v[30:33]
	v_mfma_f32_16x16x32_bf16 v[26:29], v[178:181], v[218:221], v[26:29]
	v_mfma_f32_16x16x32_bf16 v[14:17], v[170:173], v[226:229], v[14:17]
	v_mfma_f32_16x16x32_bf16 v[10:13], v[178:181], v[226:229], v[10:13]
	v_mfma_f32_16x16x32_bf16 v[54:57], v[182:185], v[198:201], v[54:57]
	v_mfma_f32_16x16x32_bf16 v[50:53], v[190:193], v[198:201], v[50:53]
	v_mfma_f32_16x16x32_bf16 v[38:41], v[182:185], v[206:209], v[38:41]
	v_mfma_f32_16x16x32_bf16 v[34:37], v[190:193], v[206:209], v[34:37]
	v_mfma_f32_16x16x32_bf16 v[22:25], v[182:185], v[214:217], v[22:25]
	v_mfma_f32_16x16x32_bf16 v[18:21], v[190:193], v[214:217], v[18:21]
	v_mfma_f32_16x16x32_bf16 v[6:9], v[182:185], v[222:225], v[6:9]
	v_mfma_f32_16x16x32_bf16 v[2:5], v[190:193], v[222:225], v[2:5]
	v_mfma_f32_16x16x32_bf16 v[54:57], v[186:189], v[202:205], v[54:57]
	v_mfma_f32_16x16x32_bf16 v[50:53], v[194:197], v[202:205], v[50:53]
	v_mfma_f32_16x16x32_bf16 v[38:41], v[186:189], v[210:213], v[38:41]
	v_mfma_f32_16x16x32_bf16 v[34:37], v[194:197], v[210:213], v[34:37]
	v_mfma_f32_16x16x32_bf16 v[22:25], v[186:189], v[218:221], v[22:25]
	v_mfma_f32_16x16x32_bf16 v[18:21], v[194:197], v[218:221], v[18:21]
	v_mfma_f32_16x16x32_bf16 v[6:9], v[186:189], v[226:229], v[6:9]
	v_mfma_f32_16x16x32_bf16 v[2:5], v[194:197], v[226:229], v[2:5]
	s_setprio 0
	s_barrier
	s_add_i32 s70, 0, 0x18000
	v_add_u32_e32 v165, s70, v160
	s_add_i32 s71, 0, 0x1c000
	ds_read_b128 v[166:169], v165
	ds_read_b128 v[170:173], v165 offset:1024
	ds_read_b128 v[174:177], v165 offset:2048
	ds_read_b128 v[178:181], v165 offset:3072
	v_add_u32_e32 v165, s71, v160
	ds_read_b128 v[182:185], v165
	ds_read_b128 v[186:189], v165 offset:1024
	ds_read_b128 v[190:193], v165 offset:2048
	ds_read_b128 v[194:197], v165 offset:3072
	s_add_u32 s34, s34, s12
	s_addc_u32 s35, s35, s13
	s_mov_b32 m0, s43
	v_lshl_add_u64 v[242:243], s[34:35], 0, v[130:131]
	ds_read_b128 v[198:201], v164 offset:32768
	ds_read_b128 v[202:205], v164 offset:33792
	ds_read_b128 v[206:209], v164 offset:34816
	ds_read_b128 v[210:213], v164 offset:35840
	ds_read_b128 v[214:217], v164 offset:36864
	ds_read_b128 v[218:221], v164 offset:37888
	ds_read_b128 v[222:225], v164 offset:38912
	ds_read_b128 v[226:229], v164 offset:39936
	global_load_lds_dwordx4 v[242:243], off
	v_lshl_add_u64 v[242:243], s[34:35], 0, v[134:135]
	s_mov_b32 m0, s44
	s_nop 0
	global_load_lds_dwordx4 v[242:243], off
	s_waitcnt vmcnt(8) lgkmcnt(0)
	s_barrier
	s_setprio 1
	v_mfma_f32_16x16x32_bf16 v[122:125], v[166:169], v[198:201], v[122:125]
	v_mfma_f32_16x16x32_bf16 v[126:129], v[174:177], v[198:201], v[126:129]
	v_mfma_f32_16x16x32_bf16 v[110:113], v[166:169], v[206:209], v[110:113]
	v_mfma_f32_16x16x32_bf16 v[106:109], v[174:177], v[206:209], v[106:109]
	v_mfma_f32_16x16x32_bf16 v[94:97], v[166:169], v[214:217], v[94:97]
	v_mfma_f32_16x16x32_bf16 v[90:93], v[174:177], v[214:217], v[90:93]
	v_mfma_f32_16x16x32_bf16 v[78:81], v[166:169], v[222:225], v[78:81]
	v_mfma_f32_16x16x32_bf16 v[74:77], v[174:177], v[222:225], v[74:77]
	v_mfma_f32_16x16x32_bf16 v[122:125], v[170:173], v[202:205], v[122:125]
	v_mfma_f32_16x16x32_bf16 v[126:129], v[178:181], v[202:205], v[126:129]
	v_mfma_f32_16x16x32_bf16 v[110:113], v[170:173], v[210:213], v[110:113]
	v_mfma_f32_16x16x32_bf16 v[106:109], v[178:181], v[210:213], v[106:109]
	v_mfma_f32_16x16x32_bf16 v[94:97], v[170:173], v[218:221], v[94:97]
	v_mfma_f32_16x16x32_bf16 v[90:93], v[178:181], v[218:221], v[90:93]
	v_mfma_f32_16x16x32_bf16 v[78:81], v[170:173], v[226:229], v[78:81]
	v_mfma_f32_16x16x32_bf16 v[74:77], v[178:181], v[226:229], v[74:77]
	v_mfma_f32_16x16x32_bf16 v[118:121], v[182:185], v[198:201], v[118:121]
	v_mfma_f32_16x16x32_bf16 v[114:117], v[190:193], v[198:201], v[114:117]
	v_mfma_f32_16x16x32_bf16 v[102:105], v[182:185], v[206:209], v[102:105]
	v_mfma_f32_16x16x32_bf16 v[98:101], v[190:193], v[206:209], v[98:101]
	v_mfma_f32_16x16x32_bf16 v[86:89], v[182:185], v[214:217], v[86:89]
	v_mfma_f32_16x16x32_bf16 v[82:85], v[190:193], v[214:217], v[82:85]
	v_mfma_f32_16x16x32_bf16 v[70:73], v[182:185], v[222:225], v[70:73]
	v_mfma_f32_16x16x32_bf16 v[66:69], v[190:193], v[222:225], v[66:69]
	v_mfma_f32_16x16x32_bf16 v[118:121], v[186:189], v[202:205], v[118:121]
	v_mfma_f32_16x16x32_bf16 v[114:117], v[194:197], v[202:205], v[114:117]
	v_mfma_f32_16x16x32_bf16 v[102:105], v[186:189], v[210:213], v[102:105]
	v_mfma_f32_16x16x32_bf16 v[98:101], v[194:197], v[210:213], v[98:101]
	v_mfma_f32_16x16x32_bf16 v[86:89], v[186:189], v[218:221], v[86:89]
	v_mfma_f32_16x16x32_bf16 v[82:85], v[194:197], v[218:221], v[82:85]
	v_mfma_f32_16x16x32_bf16 v[70:73], v[186:189], v[226:229], v[70:73]
	v_mfma_f32_16x16x32_bf16 v[66:69], v[194:197], v[226:229], v[66:69]
	s_setprio 0
	s_barrier
; #define PG8_STAGE(bufoff, gbase, voff) do { _Pragma("unroll") for (int _i = 0; _i < 2; ++_i) \
;         __builtin_amdgcn_global_load_lds((const unsigned*)((const char*)(gbase) + (voff)[_i]), (PG8_LAS unsigned*)(lds + (bufoff) + ldsw + _i * 8192), 16, 0, 0); } while (0)
; #define PG8_LDA(dst, b, h) do { _Pragma("unroll") for (int m = 0; m < 4; ++m) _Pragma("unroll") for (int k = 0; k < 2; ++k) dst[m][k] = *(const PG8_LAS bf16x8*)(lds + PG8_SA(b, h) + aoff + m * 2048 + k * 1024); } while (0)
; #define PG8_MMA(ai, bj, At, Bt) do { __builtin_amdgcn_s_setprio(1); _Pragma("unroll") for (int m = 0; m < 4; ++m) _Pragma("unroll") for (int n = 0; n < 2; ++n) _Pragma("unroll") for (int k = 0; k < 2; ++k) \
;         acc[ai][bj][m][n] = __builtin_amdgcn_mfma_f32_16x16x32_bf16(Bt[n][k], At[m][k], acc[ai][bj][m][n], 0, 0, 0); __builtin_amdgcn_s_setprio(0); } while (0)
; #define PG8_WAIT_V(n) asm volatile("s_waitcnt vmcnt(" #n ")" ::: "memory")
; #define PG8_WAIT_L(n) asm volatile("s_waitcnt lgkmcnt(" #n ")" ::: "memory")
; #define PG8_BAR __builtin_amdgcn_s_barrier()
; #define PG8_SCHED __builtin_amdgcn_sched_barrier(0)
; template <class Epi, class Sched, bool ALIGN_EPI = false, bool SP2 = false>
; __device__ __forceinline__ void gemm_phase(PG8_LAS unsigned char* lds, const Gemm g, const Sched& S, const Epi& E) {
;     ...
;             PG8_LDA(At, 1, 1); PG8_STAGE(PG8_SB(1, 0), b3, voffB); PG8_STAGE(PG8_SB(1, 1), b3 + hstep, voffB); PG8_STAGE(PG8_SA(1, 0), a3, voffA);
;             PG8_WAIT_V(8); PG8_WAIT_L(0); PG8_BAR; PG8_MMA(1, 0, At, B0); PG8_MMA(1, 1, At, B1); PG8_BAR; PG8_SCHED;
	s_add_i32 s34, s70, s40
	v_lshl_add_u64 v[230:231], v[230:231], 0, s[22:23]
	s_mov_b32 m0, s34
	ds_read_b128 v[198:201], v164 offset:49152
	ds_read_b128 v[202:205], v164 offset:50176
	ds_read_b128 v[206:209], v164 offset:51200
	ds_read_b128 v[210:213], v164 offset:52224
	ds_read_b128 v[214:217], v164 offset:53248
	ds_read_b128 v[218:221], v164 offset:54272
	ds_read_b128 v[222:225], v164 offset:55296
	ds_read_b128 v[226:229], v164 offset:56320
	global_load_lds_dwordx4 v[230:231], off
	v_lshl_add_u64 v[230:231], v[232:233], 0, s[22:23]
	s_add_i32 m0, s34, 0x2000
	s_add_i32 s34, s71, s40
	global_load_lds_dwordx4 v[230:231], off
	v_lshl_add_u64 v[230:231], v[234:235], 0, s[22:23]
	s_mov_b32 m0, s34
	s_nop 0
	global_load_lds_dwordx4 v[230:231], off
	v_lshl_add_u64 v[230:231], v[236:237], 0, s[22:23]
	s_add_i32 m0, s34, 0x2000
	s_nop 0
	global_load_lds_dwordx4 v[230:231], off
	v_lshl_add_u64 v[230:231], v[238:239], 0, s[22:23]
	s_mov_b32 m0, s46
	s_nop 0
	global_load_lds_dwordx4 v[230:231], off
	v_lshl_add_u64 v[230:231], v[240:241], 0, s[22:23]
	s_mov_b32 m0, s47
	s_nop 0
	global_load_lds_dwordx4 v[230:231], off
	s_waitcnt vmcnt(8) lgkmcnt(0)
	s_barrier
	s_setprio 1
	v_mfma_f32_16x16x32_bf16 v[62:65], v[166:169], v[198:201], v[62:65]
	v_mfma_f32_16x16x32_bf16 v[58:61], v[174:177], v[198:201], v[58:61]
	v_mfma_f32_16x16x32_bf16 v[46:49], v[166:169], v[206:209], v[46:49]
	v_mfma_f32_16x16x32_bf16 v[42:45], v[174:177], v[206:209], v[42:45]
	v_mfma_f32_16x16x32_bf16 v[30:33], v[166:169], v[214:217], v[30:33]
	v_mfma_f32_16x16x32_bf16 v[26:29], v[174:177], v[214:217], v[26:29]
	v_mfma_f32_16x16x32_bf16 v[14:17], v[166:169], v[222:225], v[14:17]
	v_mfma_f32_16x16x32_bf16 v[10:13], v[174:177], v[222:225], v[10:13]
	v_mfma_f32_16x16x32_bf16 v[62:65], v[170:173], v[202:205], v[62:65]
	v_mfma_f32_16x16x32_bf16 v[58:61], v[178:181], v[202:205], v[58:61]
	v_mfma_f32_16x16x32_bf16 v[46:49], v[170:173], v[210:213], v[46:49]
	v_mfma_f32_16x16x32_bf16 v[42:45], v[178:181], v[210:213], v[42:45]
	v_mfma_f32_16x16x32_bf16 v[30:33], v[170:173], v[218:221], v[30:33]
	v_mfma_f32_16x16x32_bf16 v[26:29], v[178:181], v[218:221], v[26:29]
	v_mfma_f32_16x16x32_bf16 v[14:17], v[170:173], v[226:229], v[14:17]
	v_mfma_f32_16x16x32_bf16 v[10:13], v[178:181], v[226:229], v[10:13]
	v_mfma_f32_16x16x32_bf16 v[54:57], v[182:185], v[198:201], v[54:57]
	v_mfma_f32_16x16x32_bf16 v[50:53], v[190:193], v[198:201], v[50:53]
	v_mfma_f32_16x16x32_bf16 v[38:41], v[182:185], v[206:209], v[38:41]
	v_mfma_f32_16x16x32_bf16 v[34:37], v[190:193], v[206:209], v[34:37]
	v_mfma_f32_16x16x32_bf16 v[22:25], v[182:185], v[214:217], v[22:25]
	v_mfma_f32_16x16x32_bf16 v[18:21], v[190:193], v[214:217], v[18:21]
	v_mfma_f32_16x16x32_bf16 v[6:9], v[182:185], v[222:225], v[6:9]
	v_mfma_f32_16x16x32_bf16 v[2:5], v[190:193], v[222:225], v[2:5]
	v_mfma_f32_16x16x32_bf16 v[54:57], v[186:189], v[202:205], v[54:57]
	v_mfma_f32_16x16x32_bf16 v[50:53], v[194:197], v[202:205], v[50:53]
	v_mfma_f32_16x16x32_bf16 v[38:41], v[186:189], v[210:213], v[38:41]
	v_mfma_f32_16x16x32_bf16 v[34:37], v[194:197], v[210:213], v[34:37]
	v_mfma_f32_16x16x32_bf16 v[22:25], v[186:189], v[218:221], v[22:25]
	v_mfma_f32_16x16x32_bf16 v[18:21], v[194:197], v[218:221], v[18:21]
	v_mfma_f32_16x16x32_bf16 v[6:9], v[186:189], v[226:229], v[6:9]
	v_mfma_f32_16x16x32_bf16 v[2:5], v[194:197], v[226:229], v[2:5]
	s_setprio 0
	s_barrier
	s_add_u32 s80, s80, 0x100
	s_addc_u32 s81, s81, 0
	s_add_u32 s30, s30, 0x100
	s_addc_u32 s31, s31, 0
	s_cmp_ge_i32 s86, s48
	s_mov_b32 s34, s86
	s_cbranch_scc0 .LBB0_1404

; #define PG8_STAGE(bufoff, gbase, voff) do { _Pragma("unroll") for (int _i = 0; _i < 2; ++_i) \
;         __builtin_amdgcn_global_load_lds((const unsigned*)((const char*)(gbase) + (voff)[_i]), (PG8_LAS unsigned*)(lds + (bufoff) + ldsw + _i * 8192), 16, 0, 0); } while (0)
; #define PG8_LDA(dst, b, h) do { _Pragma("unroll") for (int m = 0; m < 4; ++m) _Pragma("unroll") for (int k = 0; k < 2; ++k) dst[m][k] = *(const PG8_LAS bf16x8*)(lds + PG8_SA(b, h) + aoff + m * 2048 + k * 1024); } while (0)
; #define PG8_LDB(dst, b, h) do { _Pragma("unroll") for (int n = 0; n < 2; ++n) _Pragma("unroll") for (int k = 0; k < 2; ++k) dst[n][k] = *(const PG8_LAS bf16x8*)(lds + PG8_SB(b, h) + boff + n * 2048 + k * 1024); } while (0)
; #define PG8_MMA(ai, bj, At, Bt) do { __builtin_amdgcn_s_setprio(1); _Pragma("unroll") for (int m = 0; m < 4; ++m) _Pragma("unroll") for (int n = 0; n < 2; ++n) _Pragma("unroll") for (int k = 0; k < 2; ++k) \
;         acc[ai][bj][m][n] = __builtin_amdgcn_mfma_f32_16x16x32_bf16(Bt[n][k], At[m][k], acc[ai][bj][m][n], 0, 0, 0); __builtin_amdgcn_s_setprio(0); } while (0)
; #define PG8_WAIT_V(n) asm volatile("s_waitcnt vmcnt(" #n ")" ::: "memory")
; #define PG8_WAIT_L(n) asm volatile("s_waitcnt lgkmcnt(" #n ")" ::: "memory")
; template <class Epi, class Sched, bool ALIGN_EPI = false, bool SP2 = false>
; __device__ __forceinline__ void gemm_phase(PG8_LAS unsigned char* lds, const Gemm g, const Sched& S, const Epi& E) {
;     ...
;             const bool last = (t == nt - 2);
;             const char* a1 = cA + (size_t)(t + 1) * kstep;
;             const char* a2 = last ? nA : cA + (size_t)(t + 2) * kstep; const char* b2 = last ? nB : cB + (size_t)(t + 2) * kstep;
;             const char* a3 = a2 + kstep; const char* b3 = b2 + kstep;
;             if (last && has_next) S.a_ready(nxt);
;             if constexpr (SP2) {
;             PG8_LDB(B0, 0, 0); PG8_LDB(B1, 0, 1); PG8_SCHED; PG8_LDA(At, 0, 0); PG8_STAGE(PG8_SA(1, 1), a1 + hstep, voffA);
;             PG8_WAIT_V(8); PG8_WAIT_L(0); PG8_BAR; PG8_MMA(0, 0, At, B0); PG8_MMA(0, 1, At, B1); PG8_BAR; PG8_SCHED;
;             PG8_LDA(At, 0, 1); PG8_STAGE(PG8_SB(0, 0), b2, voffB); PG8_STAGE(PG8_SB(0, 1), b2 + hstep, voffB); PG8_STAGE(PG8_SA(0, 0), a2, voffA);
;             PG8_WAIT_V(8); PG8_WAIT_L(0); PG8_BAR; PG8_MMA(1, 0, At, B0); PG8_MMA(1, 1, At, B1); PG8_BAR; PG8_SCHED;
.LBB0_1433:
	ds_read_b128 v[156:159], v1
	ds_read_b128 v[160:163], v1 offset:1024
	ds_read_b128 v[164:167], v1 offset:2048
	ds_read_b128 v[168:171], v1 offset:3072
	ds_read_b128 v[172:175], v146
	ds_read_b128 v[176:179], v146 offset:1024
	ds_read_b128 v[180:183], v146 offset:2048
	ds_read_b128 v[184:187], v146 offset:3072
	s_add_i32 s80, s30, 2
	s_add_u32 s70, s28, 0x80
	s_addc_u32 s31, s29, 0
	s_cmp_eq_u32 s47, s30
	s_cselect_b32 s30, s4, s70
	s_cselect_b32 s31, s5, s31
	s_cselect_b32 s71, s27, s69
	s_cselect_b32 s70, s26, s68
	v_lshl_add_u64 v[152:153], s[28:29], 0, v[140:141]
	s_add_i32 m0, s39, 0xc000
	ds_read_b128 v[188:191], v147
	ds_read_b128 v[192:195], v147 offset:1024
	ds_read_b128 v[196:199], v147 offset:2048
	ds_read_b128 v[200:203], v147 offset:3072
	ds_read_b128 v[204:207], v147 offset:4096
	ds_read_b128 v[208:211], v147 offset:5120
	ds_read_b128 v[212:215], v147 offset:6144
	ds_read_b128 v[216:219], v147 offset:7168
	global_load_lds_dwordx4 v[152:153], off
	v_lshl_add_u64 v[152:153], s[28:29], 0, v[138:139]
	s_add_i32 m0, s39, 0xe000
	s_nop 0
	global_load_lds_dwordx4 v[152:153], off
	s_waitcnt vmcnt(8) lgkmcnt(0)
	s_barrier
	s_setprio 1
	v_mfma_f32_16x16x32_bf16 v[122:125], v[156:159], v[188:191], v[122:125]
	v_mfma_f32_16x16x32_bf16 v[126:129], v[164:167], v[188:191], v[126:129]
	v_mfma_f32_16x16x32_bf16 v[110:113], v[156:159], v[196:199], v[110:113]
	v_mfma_f32_16x16x32_bf16 v[106:109], v[164:167], v[196:199], v[106:109]
	v_mfma_f32_16x16x32_bf16 v[94:97], v[156:159], v[204:207], v[94:97]
	v_mfma_f32_16x16x32_bf16 v[90:93], v[164:167], v[204:207], v[90:93]
	v_mfma_f32_16x16x32_bf16 v[78:81], v[156:159], v[212:215], v[78:81]
	v_mfma_f32_16x16x32_bf16 v[74:77], v[164:167], v[212:215], v[74:77]
	v_mfma_f32_16x16x32_bf16 v[122:125], v[160:163], v[192:195], v[122:125]
	v_mfma_f32_16x16x32_bf16 v[126:129], v[168:171], v[192:195], v[126:129]
	v_mfma_f32_16x16x32_bf16 v[110:113], v[160:163], v[200:203], v[110:113]
	v_mfma_f32_16x16x32_bf16 v[106:109], v[168:171], v[200:203], v[106:109]
	v_mfma_f32_16x16x32_bf16 v[94:97], v[160:163], v[208:211], v[94:97]
	v_mfma_f32_16x16x32_bf16 v[90:93], v[168:171], v[208:211], v[90:93]
	v_mfma_f32_16x16x32_bf16 v[78:81], v[160:163], v[216:219], v[78:81]
	v_mfma_f32_16x16x32_bf16 v[74:77], v[168:171], v[216:219], v[74:77]
	v_mfma_f32_16x16x32_bf16 v[118:121], v[172:175], v[188:191], v[118:121]
	v_mfma_f32_16x16x32_bf16 v[114:117], v[180:183], v[188:191], v[114:117]
	v_mfma_f32_16x16x32_bf16 v[102:105], v[172:175], v[196:199], v[102:105]
	v_mfma_f32_16x16x32_bf16 v[98:101], v[180:183], v[196:199], v[98:101]
	v_mfma_f32_16x16x32_bf16 v[86:89], v[172:175], v[204:207], v[86:89]
	v_mfma_f32_16x16x32_bf16 v[82:85], v[180:183], v[204:207], v[82:85]
	v_mfma_f32_16x16x32_bf16 v[70:73], v[172:175], v[212:215], v[70:73]
	v_mfma_f32_16x16x32_bf16 v[66:69], v[180:183], v[212:215], v[66:69]
	v_mfma_f32_16x16x32_bf16 v[118:121], v[176:179], v[192:195], v[118:121]
	v_mfma_f32_16x16x32_bf16 v[114:117], v[184:187], v[192:195], v[114:117]
	v_mfma_f32_16x16x32_bf16 v[102:105], v[176:179], v[200:203], v[102:105]
	v_mfma_f32_16x16x32_bf16 v[98:101], v[184:187], v[200:203], v[98:101]
	v_mfma_f32_16x16x32_bf16 v[86:89], v[176:179], v[208:211], v[86:89]
	v_mfma_f32_16x16x32_bf16 v[82:85], v[184:187], v[208:211], v[82:85]
	v_mfma_f32_16x16x32_bf16 v[70:73], v[176:179], v[216:219], v[70:73]
	v_mfma_f32_16x16x32_bf16 v[66:69], v[184:187], v[216:219], v[66:69]
	s_setprio 0
	s_barrier
	s_add_i32 s72, s52, s38
	v_lshl_add_u64 v[152:153], s[70:71], 0, v[132:133]
	s_mov_b32 m0, s72
	ds_read_b128 v[188:191], v147 offset:16384
	ds_read_b128 v[192:195], v147 offset:17408
	ds_read_b128 v[196:199], v147 offset:18432
	ds_read_b128 v[200:203], v147 offset:19456
	ds_read_b128 v[204:207], v147 offset:20480
	ds_read_b128 v[208:211], v147 offset:21504
	ds_read_b128 v[212:215], v147 offset:22528
	ds_read_b128 v[216:219], v147 offset:23552
	global_load_lds_dwordx4 v[152:153], off
	s_add_i32 m0, s72, 0x2000
	v_lshl_add_u64 v[220:221], s[70:71], 0, v[136:137]
	s_add_u32 s70, s70, s6
	s_addc_u32 s71, s71, s7
	s_add_i32 s72, s53, s38
	global_load_lds_dwordx4 v[220:221], off
	v_lshl_add_u64 v[222:223], s[70:71], 0, v[132:133]
	s_mov_b32 m0, s72
	v_lshl_add_u64 v[224:225], s[70:71], 0, v[136:137]
	global_load_lds_dwordx4 v[222:223], off
	s_add_i32 m0, s72, 0x2000
	v_lshl_add_u64 v[226:227], s[30:31], 0, v[130:131]
	global_load_lds_dwordx4 v[224:225], off
	s_mov_b32 m0, s39
	v_lshl_add_u64 v[228:229], s[30:31], 0, v[134:135]
	global_load_lds_dwordx4 v[226:227], off
	s_mov_b32 m0, s40
	s_nop 0
	global_load_lds_dwordx4 v[228:229], off
	s_waitcnt vmcnt(8) lgkmcnt(0)
	s_barrier
; #define PG8_STAGE(bufoff, gbase, voff) do { _Pragma("unroll") for (int _i = 0; _i < 2; ++_i) \
;         __builtin_amdgcn_global_load_lds((const unsigned*)((const char*)(gbase) + (voff)[_i]), (PG8_LAS unsigned*)(lds + (bufoff) + ldsw + _i * 8192), 16, 0, 0); } while (0)
; #define PG8_LDA(dst, b, h) do { _Pragma("unroll") for (int m = 0; m < 4; ++m) _Pragma("unroll") for (int k = 0; k < 2; ++k) dst[m][k] = *(const PG8_LAS bf16x8*)(lds + PG8_SA(b, h) + aoff + m * 2048 + k * 1024); } while (0)
; #define PG8_LDB(dst, b, h) do { _Pragma("unroll") for (int n = 0; n < 2; ++n) _Pragma("unroll") for (int k = 0; k < 2; ++k) dst[n][k] = *(const PG8_LAS bf16x8*)(lds + PG8_SB(b, h) + boff + n * 2048 + k * 1024); } while (0)
; #define PG8_MMA(ai, bj, At, Bt) do { __builtin_amdgcn_s_setprio(1); _Pragma("unroll") for (int m = 0; m < 4; ++m) _Pragma("unroll") for (int n = 0; n < 2; ++n) _Pragma("unroll") for (int k = 0; k < 2; ++k) \
;         acc[ai][bj][m][n] = __builtin_amdgcn_mfma_f32_16x16x32_bf16(Bt[n][k], At[m][k], acc[ai][bj][m][n], 0, 0, 0); __builtin_amdgcn_s_setprio(0); } while (0)
; #define PG8_WAIT_V(n) asm volatile("s_waitcnt vmcnt(" #n ")" ::: "memory")
; #define PG8_WAIT_L(n) asm volatile("s_waitcnt lgkmcnt(" #n ")" ::: "memory")
; #define PG8_BAR __builtin_amdgcn_s_barrier()
; #define PG8_SCHED __builtin_amdgcn_sched_barrier(0)
; template <class Epi, class Sched, bool ALIGN_EPI = false, bool SP2 = false>
; __device__ __forceinline__ void gemm_phase(PG8_LAS unsigned char* lds, const Gemm g, const Sched& S, const Epi& E) {
;     ...
;             PG8_WAIT_V(8); PG8_WAIT_L(0); PG8_BAR; PG8_MMA(1, 0, At, B0); PG8_MMA(1, 1, At, B1); PG8_BAR; PG8_SCHED;
;             PG8_LDB(B0, 1, 0); PG8_LDB(B1, 1, 1); PG8_SCHED; PG8_LDA(At, 1, 0); PG8_STAGE(PG8_SA(0, 1), a2 + hstep, voffA);
;             PG8_WAIT_V(8); PG8_WAIT_L(0); PG8_BAR; PG8_MMA(0, 0, At, B0); PG8_MMA(0, 1, At, B1); PG8_BAR; PG8_SCHED;
	s_setprio 1
	v_mfma_f32_16x16x32_bf16 v[62:65], v[156:159], v[188:191], v[62:65]
	v_mfma_f32_16x16x32_bf16 v[58:61], v[164:167], v[188:191], v[58:61]
	v_mfma_f32_16x16x32_bf16 v[46:49], v[156:159], v[196:199], v[46:49]
	v_mfma_f32_16x16x32_bf16 v[42:45], v[164:167], v[196:199], v[42:45]
	v_mfma_f32_16x16x32_bf16 v[30:33], v[156:159], v[204:207], v[30:33]
	v_mfma_f32_16x16x32_bf16 v[26:29], v[164:167], v[204:207], v[26:29]
	v_mfma_f32_16x16x32_bf16 v[14:17], v[156:159], v[212:215], v[14:17]
	v_mfma_f32_16x16x32_bf16 v[10:13], v[164:167], v[212:215], v[10:13]
	v_mfma_f32_16x16x32_bf16 v[62:65], v[160:163], v[192:195], v[62:65]
	v_mfma_f32_16x16x32_bf16 v[58:61], v[168:171], v[192:195], v[58:61]
	v_mfma_f32_16x16x32_bf16 v[46:49], v[160:163], v[200:203], v[46:49]
	v_mfma_f32_16x16x32_bf16 v[42:45], v[168:171], v[200:203], v[42:45]
	v_mfma_f32_16x16x32_bf16 v[30:33], v[160:163], v[208:211], v[30:33]
	v_mfma_f32_16x16x32_bf16 v[26:29], v[168:171], v[208:211], v[26:29]
	v_mfma_f32_16x16x32_bf16 v[14:17], v[160:163], v[216:219], v[14:17]
	v_mfma_f32_16x16x32_bf16 v[10:13], v[168:171], v[216:219], v[10:13]
	v_mfma_f32_16x16x32_bf16 v[54:57], v[172:175], v[188:191], v[54:57]
	v_mfma_f32_16x16x32_bf16 v[50:53], v[180:183], v[188:191], v[50:53]
	v_mfma_f32_16x16x32_bf16 v[38:41], v[172:175], v[196:199], v[38:41]
	v_mfma_f32_16x16x32_bf16 v[34:37], v[180:183], v[196:199], v[34:37]
	v_mfma_f32_16x16x32_bf16 v[22:25], v[172:175], v[204:207], v[22:25]
	v_mfma_f32_16x16x32_bf16 v[18:21], v[180:183], v[204:207], v[18:21]
	v_mfma_f32_16x16x32_bf16 v[6:9], v[172:175], v[212:215], v[6:9]
	v_mfma_f32_16x16x32_bf16 v[2:5], v[180:183], v[212:215], v[2:5]
	v_mfma_f32_16x16x32_bf16 v[54:57], v[176:179], v[192:195], v[54:57]
	v_mfma_f32_16x16x32_bf16 v[50:53], v[184:187], v[192:195], v[50:53]
	v_mfma_f32_16x16x32_bf16 v[38:41], v[176:179], v[200:203], v[38:41]
	v_mfma_f32_16x16x32_bf16 v[34:37], v[184:187], v[200:203], v[34:37]
	v_mfma_f32_16x16x32_bf16 v[22:25], v[176:179], v[208:211], v[22:25]
	v_mfma_f32_16x16x32_bf16 v[18:21], v[184:187], v[208:211], v[18:21]
	v_mfma_f32_16x16x32_bf16 v[6:9], v[176:179], v[216:219], v[6:9]
	v_mfma_f32_16x16x32_bf16 v[2:5], v[184:187], v[216:219], v[2:5]
	s_setprio 0
	s_barrier
	s_add_i32 s70, 0, 0x18000
	v_add_u32_e32 v148, s70, v150
	s_add_i32 s71, 0, 0x1c000
	ds_read_b128 v[156:159], v148
	ds_read_b128 v[160:163], v148 offset:1024
	ds_read_b128 v[164:167], v148 offset:2048
	ds_read_b128 v[168:171], v148 offset:3072
	v_add_u32_e32 v148, s71, v150
	ds_read_b128 v[172:175], v148
	ds_read_b128 v[176:179], v148 offset:1024
	ds_read_b128 v[180:183], v148 offset:2048
	ds_read_b128 v[184:187], v148 offset:3072
	s_add_u32 s30, s30, s6
	s_addc_u32 s31, s31, s7
	s_mov_b32 m0, s41
	v_lshl_add_u64 v[230:231], s[30:31], 0, v[130:131]
	ds_read_b128 v[188:191], v147 offset:32768
	ds_read_b128 v[192:195], v147 offset:33792
	ds_read_b128 v[196:199], v147 offset:34816
	ds_read_b128 v[200:203], v147 offset:35840
	ds_read_b128 v[204:207], v147 offset:36864
	ds_read_b128 v[208:211], v147 offset:37888
	ds_read_b128 v[212:215], v147 offset:38912
	ds_read_b128 v[216:219], v147 offset:39936
	global_load_lds_dwordx4 v[230:231], off
	v_lshl_add_u64 v[230:231], s[30:31], 0, v[134:135]
	s_mov_b32 m0, s42
	s_nop 0
	global_load_lds_dwordx4 v[230:231], off
	s_waitcnt vmcnt(8) lgkmcnt(0)
	s_barrier
	s_setprio 1
	v_mfma_f32_16x16x32_bf16 v[122:125], v[156:159], v[188:191], v[122:125]
	v_mfma_f32_16x16x32_bf16 v[126:129], v[164:167], v[188:191], v[126:129]
	v_mfma_f32_16x16x32_bf16 v[110:113], v[156:159], v[196:199], v[110:113]
	v_mfma_f32_16x16x32_bf16 v[106:109], v[164:167], v[196:199], v[106:109]
	v_mfma_f32_16x16x32_bf16 v[94:97], v[156:159], v[204:207], v[94:97]
	v_mfma_f32_16x16x32_bf16 v[90:93], v[164:167], v[204:207], v[90:93]
	v_mfma_f32_16x16x32_bf16 v[78:81], v[156:159], v[212:215], v[78:81]
	v_mfma_f32_16x16x32_bf16 v[74:77], v[164:167], v[212:215], v[74:77]
	v_mfma_f32_16x16x32_bf16 v[122:125], v[160:163], v[192:195], v[122:125]
	v_mfma_f32_16x16x32_bf16 v[126:129], v[168:171], v[192:195], v[126:129]
	v_mfma_f32_16x16x32_bf16 v[110:113], v[160:163], v[200:203], v[110:113]
	v_mfma_f32_16x16x32_bf16 v[106:109], v[168:171], v[200:203], v[106:109]
	v_mfma_f32_16x16x32_bf16 v[94:97], v[160:163], v[208:211], v[94:97]
	v_mfma_f32_16x16x32_bf16 v[90:93], v[168:171], v[208:211], v[90:93]
	v_mfma_f32_16x16x32_bf16 v[78:81], v[160:163], v[216:219], v[78:81]
	v_mfma_f32_16x16x32_bf16 v[74:77], v[168:171], v[216:219], v[74:77]
	v_mfma_f32_16x16x32_bf16 v[118:121], v[172:175], v[188:191], v[118:121]
	v_mfma_f32_16x16x32_bf16 v[114:117], v[180:183], v[188:191], v[114:117]
	v_mfma_f32_16x16x32_bf16 v[102:105], v[172:175], v[196:199], v[102:105]
	v_mfma_f32_16x16x32_bf16 v[98:101], v[180:183], v[196:199], v[98:101]
	v_mfma_f32_16x16x32_bf16 v[86:89], v[172:175], v[204:207], v[86:89]
	v_mfma_f32_16x16x32_bf16 v[82:85], v[180:183], v[204:207], v[82:85]
	v_mfma_f32_16x16x32_bf16 v[70:73], v[172:175], v[212:215], v[70:73]
	v_mfma_f32_16x16x32_bf16 v[66:69], v[180:183], v[212:215], v[66:69]
	v_mfma_f32_16x16x32_bf16 v[118:121], v[176:179], v[192:195], v[118:121]
	v_mfma_f32_16x16x32_bf16 v[114:117], v[184:187], v[192:195], v[114:117]
	v_mfma_f32_16x16x32_bf16 v[102:105], v[176:179], v[200:203], v[102:105]
	v_mfma_f32_16x16x32_bf16 v[98:101], v[184:187], v[200:203], v[98:101]
	v_mfma_f32_16x16x32_bf16 v[86:89], v[176:179], v[208:211], v[86:89]
	v_mfma_f32_16x16x32_bf16 v[82:85], v[184:187], v[208:211], v[82:85]
	v_mfma_f32_16x16x32_bf16 v[70:73], v[176:179], v[216:219], v[70:73]
	v_mfma_f32_16x16x32_bf16 v[66:69], v[184:187], v[216:219], v[66:69]
	s_setprio 0
	s_barrier
; #define PG8_STAGE(bufoff, gbase, voff) do { _Pragma("unroll") for (int _i = 0; _i < 2; ++_i) \
;         __builtin_amdgcn_global_load_lds((const unsigned*)((const char*)(gbase) + (voff)[_i]), (PG8_LAS unsigned*)(lds + (bufoff) + ldsw + _i * 8192), 16, 0, 0); } while (0)
; #define PG8_LDA(dst, b, h) do { _Pragma("unroll") for (int m = 0; m < 4; ++m) _Pragma("unroll") for (int k = 0; k < 2; ++k) dst[m][k] = *(const PG8_LAS bf16x8*)(lds + PG8_SA(b, h) + aoff + m * 2048 + k * 1024); } while (0)
; #define PG8_MMA(ai, bj, At, Bt) do { __builtin_amdgcn_s_setprio(1); _Pragma("unroll") for (int m = 0; m < 4; ++m) _Pragma("unroll") for (int n = 0; n < 2; ++n) _Pragma("unroll") for (int k = 0; k < 2; ++k) \
;         acc[ai][bj][m][n] = __builtin_amdgcn_mfma_f32_16x16x32_bf16(Bt[n][k], At[m][k], acc[ai][bj][m][n], 0, 0, 0); __builtin_amdgcn_s_setprio(0); } while (0)
; #define PG8_WAIT_V(n) asm volatile("s_waitcnt vmcnt(" #n ")" ::: "memory")
; #define PG8_WAIT_L(n) asm volatile("s_waitcnt lgkmcnt(" #n ")" ::: "memory")
; #define PG8_BAR __builtin_amdgcn_s_barrier()
; #define PG8_SCHED __builtin_amdgcn_sched_barrier(0)
; template <class Epi, class Sched, bool ALIGN_EPI = false, bool SP2 = false>
; __device__ __forceinline__ void gemm_phase(PG8_LAS unsigned char* lds, const Gemm g, const Sched& S, const Epi& E) {
;     ...
;             PG8_LDA(At, 1, 1); PG8_STAGE(PG8_SB(1, 0), b3, voffB); PG8_STAGE(PG8_SB(1, 1), b3 + hstep, voffB); PG8_STAGE(PG8_SA(1, 0), a3, voffA);
;             PG8_WAIT_V(8); PG8_WAIT_L(0); PG8_BAR; PG8_MMA(1, 0, At, B0); PG8_MMA(1, 1, At, B1); PG8_BAR; PG8_SCHED;
	s_add_i32 s30, s70, s38
	v_lshl_add_u64 v[152:153], v[152:153], 0, s[20:21]
	s_mov_b32 m0, s30
	ds_read_b128 v[188:191], v147 offset:49152
	ds_read_b128 v[192:195], v147 offset:50176
	ds_read_b128 v[196:199], v147 offset:51200
	ds_read_b128 v[200:203], v147 offset:52224
	ds_read_b128 v[204:207], v147 offset:53248
	ds_read_b128 v[208:211], v147 offset:54272
	ds_read_b128 v[212:215], v147 offset:55296
	ds_read_b128 v[216:219], v147 offset:56320
	global_load_lds_dwordx4 v[152:153], off
	v_lshl_add_u64 v[152:153], v[220:221], 0, s[20:21]
	s_add_i32 m0, s30, 0x2000
	s_add_i32 s30, s71, s38
	global_load_lds_dwordx4 v[152:153], off
	v_lshl_add_u64 v[152:153], v[222:223], 0, s[20:21]
	s_mov_b32 m0, s30
	s_nop 0
	global_load_lds_dwordx4 v[152:153], off
	v_lshl_add_u64 v[152:153], v[224:225], 0, s[20:21]
	s_add_i32 m0, s30, 0x2000
	s_nop 0
	global_load_lds_dwordx4 v[152:153], off
	v_lshl_add_u64 v[152:153], v[226:227], 0, s[20:21]
	s_mov_b32 m0, s44
	s_nop 0
	global_load_lds_dwordx4 v[152:153], off
	v_lshl_add_u64 v[152:153], v[228:229], 0, s[20:21]
	s_mov_b32 m0, s45
	s_nop 0
	global_load_lds_dwordx4 v[152:153], off
	s_waitcnt vmcnt(8) lgkmcnt(0)
	s_barrier
	s_setprio 1
	v_mfma_f32_16x16x32_bf16 v[62:65], v[156:159], v[188:191], v[62:65]
	v_mfma_f32_16x16x32_bf16 v[58:61], v[164:167], v[188:191], v[58:61]
	v_mfma_f32_16x16x32_bf16 v[46:49], v[156:159], v[196:199], v[46:49]
	v_mfma_f32_16x16x32_bf16 v[42:45], v[164:167], v[196:199], v[42:45]
	v_mfma_f32_16x16x32_bf16 v[30:33], v[156:159], v[204:207], v[30:33]
	v_mfma_f32_16x16x32_bf16 v[26:29], v[164:167], v[204:207], v[26:29]
	v_mfma_f32_16x16x32_bf16 v[14:17], v[156:159], v[212:215], v[14:17]
	v_mfma_f32_16x16x32_bf16 v[10:13], v[164:167], v[212:215], v[10:13]
	v_mfma_f32_16x16x32_bf16 v[62:65], v[160:163], v[192:195], v[62:65]
	v_mfma_f32_16x16x32_bf16 v[58:61], v[168:171], v[192:195], v[58:61]
	v_mfma_f32_16x16x32_bf16 v[46:49], v[160:163], v[200:203], v[46:49]
	v_mfma_f32_16x16x32_bf16 v[42:45], v[168:171], v[200:203], v[42:45]
	v_mfma_f32_16x16x32_bf16 v[30:33], v[160:163], v[208:211], v[30:33]
	v_mfma_f32_16x16x32_bf16 v[26:29], v[168:171], v[208:211], v[26:29]
	v_mfma_f32_16x16x32_bf16 v[14:17], v[160:163], v[216:219], v[14:17]
	v_mfma_f32_16x16x32_bf16 v[10:13], v[168:171], v[216:219], v[10:13]
	v_mfma_f32_16x16x32_bf16 v[54:57], v[172:175], v[188:191], v[54:57]
	v_mfma_f32_16x16x32_bf16 v[50:53], v[180:183], v[188:191], v[50:53]
	v_mfma_f32_16x16x32_bf16 v[38:41], v[172:175], v[196:199], v[38:41]
	v_mfma_f32_16x16x32_bf16 v[34:37], v[180:183], v[196:199], v[34:37]
	v_mfma_f32_16x16x32_bf16 v[22:25], v[172:175], v[204:207], v[22:25]
	v_mfma_f32_16x16x32_bf16 v[18:21], v[180:183], v[204:207], v[18:21]
	v_mfma_f32_16x16x32_bf16 v[6:9], v[172:175], v[212:215], v[6:9]
	v_mfma_f32_16x16x32_bf16 v[2:5], v[180:183], v[212:215], v[2:5]
	v_mfma_f32_16x16x32_bf16 v[54:57], v[176:179], v[192:195], v[54:57]
	v_mfma_f32_16x16x32_bf16 v[50:53], v[184:187], v[192:195], v[50:53]
	v_mfma_f32_16x16x32_bf16 v[38:41], v[176:179], v[200:203], v[38:41]
	v_mfma_f32_16x16x32_bf16 v[34:37], v[184:187], v[200:203], v[34:37]
	v_mfma_f32_16x16x32_bf16 v[22:25], v[176:179], v[208:211], v[22:25]
	v_mfma_f32_16x16x32_bf16 v[18:21], v[184:187], v[208:211], v[18:21]
	v_mfma_f32_16x16x32_bf16 v[6:9], v[176:179], v[216:219], v[6:9]
	v_mfma_f32_16x16x32_bf16 v[2:5], v[184:187], v[216:219], v[2:5]
	s_setprio 0
	s_barrier
	s_add_u32 s68, s68, 0x100
	s_addc_u32 s69, s69, 0
	s_add_u32 s28, s28, 0x100
	s_addc_u32 s29, s29, 0
	s_cmp_ge_i32 s80, s46
	s_mov_b32 s30, s80
	s_cbranch_scc0 .LBB0_1433

; #define PG8_STAGE(bufoff, gbase, voff) do { _Pragma("unroll") for (int _i = 0; _i < 2; ++_i) \
;         __builtin_amdgcn_global_load_lds((const unsigned*)((const char*)(gbase) + (voff)[_i]), (PG8_LAS unsigned*)(lds + (bufoff) + ldsw + _i * 8192), 16, 0, 0); } while (0)
; #define PG8_LDA(dst, b, h) do { _Pragma("unroll") for (int m = 0; m < 4; ++m) _Pragma("unroll") for (int k = 0; k < 2; ++k) dst[m][k] = *(const PG8_LAS bf16x8*)(lds + PG8_SA(b, h) + aoff + m * 2048 + k * 1024); } while (0)
; #define PG8_LDB(dst, b, h) do { _Pragma("unroll") for (int n = 0; n < 2; ++n) _Pragma("unroll") for (int k = 0; k < 2; ++k) dst[n][k] = *(const PG8_LAS bf16x8*)(lds + PG8_SB(b, h) + boff + n * 2048 + k * 1024); } while (0)
; #define PG8_MMA(ai, bj, At, Bt) do { __builtin_amdgcn_s_setprio(1); _Pragma("unroll") for (int m = 0; m < 4; ++m) _Pragma("unroll") for (int n = 0; n < 2; ++n) _Pragma("unroll") for (int k = 0; k < 2; ++k) \
;         acc[ai][bj][m][n] = __builtin_amdgcn_mfma_f32_16x16x32_bf16(Bt[n][k], At[m][k], acc[ai][bj][m][n], 0, 0, 0); __builtin_amdgcn_s_setprio(0); } while (0)
; #define PG8_WAIT_V(n) asm volatile("s_waitcnt vmcnt(" #n ")" ::: "memory")
; #define PG8_WAIT_L(n) asm volatile("s_waitcnt lgkmcnt(" #n ")" ::: "memory")
; template <class Epi, class Sched, bool ALIGN_EPI = false, bool SP2 = false>
; __device__ __forceinline__ void gemm_phase(PG8_LAS unsigned char* lds, const Gemm g, const Sched& S, const Epi& E) {
;     ...
;             const bool last = (t == nt - 2);
;             const char* a1 = cA + (size_t)(t + 1) * kstep;
;             const char* a2 = last ? nA : cA + (size_t)(t + 2) * kstep; const char* b2 = last ? nB : cB + (size_t)(t + 2) * kstep;
;             const char* a3 = a2 + kstep; const char* b3 = b2 + kstep;
;             if (last && has_next) S.a_ready(nxt);
;             if constexpr (SP2) {
;             PG8_LDB(B0, 0, 0); PG8_LDB(B1, 0, 1); PG8_SCHED; PG8_LDA(At, 0, 0); PG8_STAGE(PG8_SA(1, 1), a1 + hstep, voffA);
;             PG8_WAIT_V(8); PG8_WAIT_L(0); PG8_BAR; PG8_MMA(0, 0, At, B0); PG8_MMA(0, 1, At, B1); PG8_BAR; PG8_SCHED;
;             PG8_LDA(At, 0, 1); PG8_STAGE(PG8_SB(0, 0), b2, voffB); PG8_STAGE(PG8_SB(0, 1), b2 + hstep, voffB); PG8_STAGE(PG8_SA(0, 0), a2, voffA);
;             PG8_WAIT_V(8); PG8_WAIT_L(0); PG8_BAR; PG8_MMA(1, 0, At, B0); PG8_MMA(1, 1, At, B1); PG8_BAR; PG8_SCHED;
.LBB0_1518:
	ds_read_b128 v[146:149], v168
	ds_read_b128 v[172:175], v168 offset:1024
	ds_read_b128 v[176:179], v168 offset:2048
	ds_read_b128 v[180:183], v168 offset:3072
	ds_read_b128 v[184:187], v169
	ds_read_b128 v[188:191], v169 offset:1024
	ds_read_b128 v[192:195], v169 offset:2048
	ds_read_b128 v[196:199], v169 offset:3072
	s_add_i32 s88, s38, 2
	s_add_u32 s70, s36, 0x80
	s_addc_u32 s39, s37, 0
	s_cmp_eq_u32 s53, s38
	s_cselect_b32 s38, s4, s70
	s_cselect_b32 s39, s5, s39
	s_cselect_b32 s71, s35, s87
	s_cselect_b32 s70, s34, s86
	v_lshl_add_u64 v[150:151], s[36:37], 0, v[140:141]
	s_add_i32 m0, s43, 0xc000
	ds_read_b128 v[200:203], v170
	ds_read_b128 v[204:207], v170 offset:1024
	ds_read_b128 v[208:211], v170 offset:2048
	ds_read_b128 v[212:215], v170 offset:3072
	ds_read_b128 v[216:219], v170 offset:4096
	ds_read_b128 v[220:223], v170 offset:5120
	ds_read_b128 v[224:227], v170 offset:6144
	ds_read_b128 v[228:231], v170 offset:7168
	global_load_lds_dwordx4 v[150:151], off
	v_lshl_add_u64 v[150:151], s[36:37], 0, v[138:139]
	s_add_i32 m0, s43, 0xe000
	s_nop 0
	global_load_lds_dwordx4 v[150:151], off
	s_waitcnt vmcnt(8) lgkmcnt(0)
	s_barrier
	s_setprio 1
	v_mfma_f32_16x16x32_bf16 v[122:125], v[146:149], v[200:203], v[122:125]
	v_mfma_f32_16x16x32_bf16 v[126:129], v[176:179], v[200:203], v[126:129]
	v_mfma_f32_16x16x32_bf16 v[110:113], v[146:149], v[208:211], v[110:113]
	v_mfma_f32_16x16x32_bf16 v[106:109], v[176:179], v[208:211], v[106:109]
	v_mfma_f32_16x16x32_bf16 v[94:97], v[146:149], v[216:219], v[94:97]
	v_mfma_f32_16x16x32_bf16 v[90:93], v[176:179], v[216:219], v[90:93]
	v_mfma_f32_16x16x32_bf16 v[78:81], v[146:149], v[224:227], v[78:81]
	v_mfma_f32_16x16x32_bf16 v[74:77], v[176:179], v[224:227], v[74:77]
	v_mfma_f32_16x16x32_bf16 v[122:125], v[172:175], v[204:207], v[122:125]
	v_mfma_f32_16x16x32_bf16 v[126:129], v[180:183], v[204:207], v[126:129]
	v_mfma_f32_16x16x32_bf16 v[110:113], v[172:175], v[212:215], v[110:113]
	v_mfma_f32_16x16x32_bf16 v[106:109], v[180:183], v[212:215], v[106:109]
	v_mfma_f32_16x16x32_bf16 v[94:97], v[172:175], v[220:223], v[94:97]
	v_mfma_f32_16x16x32_bf16 v[90:93], v[180:183], v[220:223], v[90:93]
	v_mfma_f32_16x16x32_bf16 v[78:81], v[172:175], v[228:231], v[78:81]
	v_mfma_f32_16x16x32_bf16 v[74:77], v[180:183], v[228:231], v[74:77]
	v_mfma_f32_16x16x32_bf16 v[118:121], v[184:187], v[200:203], v[118:121]
	v_mfma_f32_16x16x32_bf16 v[114:117], v[192:195], v[200:203], v[114:117]
	v_mfma_f32_16x16x32_bf16 v[102:105], v[184:187], v[208:211], v[102:105]
	v_mfma_f32_16x16x32_bf16 v[98:101], v[192:195], v[208:211], v[98:101]
	v_mfma_f32_16x16x32_bf16 v[86:89], v[184:187], v[216:219], v[86:89]
	v_mfma_f32_16x16x32_bf16 v[82:85], v[192:195], v[216:219], v[82:85]
	v_mfma_f32_16x16x32_bf16 v[70:73], v[184:187], v[224:227], v[70:73]
	v_mfma_f32_16x16x32_bf16 v[66:69], v[192:195], v[224:227], v[66:69]
	v_mfma_f32_16x16x32_bf16 v[118:121], v[188:191], v[204:207], v[118:121]
	v_mfma_f32_16x16x32_bf16 v[114:117], v[196:199], v[204:207], v[114:117]
	v_mfma_f32_16x16x32_bf16 v[102:105], v[188:191], v[212:215], v[102:105]
	v_mfma_f32_16x16x32_bf16 v[98:101], v[196:199], v[212:215], v[98:101]
	v_mfma_f32_16x16x32_bf16 v[86:89], v[188:191], v[220:223], v[86:89]
	v_mfma_f32_16x16x32_bf16 v[82:85], v[196:199], v[220:223], v[82:85]
	v_mfma_f32_16x16x32_bf16 v[70:73], v[188:191], v[228:231], v[70:73]
	v_mfma_f32_16x16x32_bf16 v[66:69], v[196:199], v[228:231], v[66:69]
	s_setprio 0
	s_barrier
	s_add_i32 s72, s56, s42
	v_lshl_add_u64 v[150:151], s[70:71], 0, v[132:133]
	s_mov_b32 m0, s72
	ds_read_b128 v[200:203], v170 offset:16384
	ds_read_b128 v[204:207], v170 offset:17408
	ds_read_b128 v[208:211], v170 offset:18432
	ds_read_b128 v[212:215], v170 offset:19456
	ds_read_b128 v[216:219], v170 offset:20480
	ds_read_b128 v[220:223], v170 offset:21504
	ds_read_b128 v[224:227], v170 offset:22528
	ds_read_b128 v[228:231], v170 offset:23552
	global_load_lds_dwordx4 v[150:151], off
	s_add_i32 m0, s72, 0x2000
	v_lshl_add_u64 v[232:233], s[70:71], 0, v[136:137]
	s_add_u32 s70, s70, s14
	s_addc_u32 s71, s71, s15
	s_add_i32 s72, s57, s42
	global_load_lds_dwordx4 v[232:233], off
	v_lshl_add_u64 v[234:235], s[70:71], 0, v[132:133]
	s_mov_b32 m0, s72
	v_lshl_add_u64 v[236:237], s[70:71], 0, v[136:137]
	global_load_lds_dwordx4 v[234:235], off
	s_add_i32 m0, s72, 0x2000
	v_lshl_add_u64 v[238:239], s[38:39], 0, v[130:131]
	global_load_lds_dwordx4 v[236:237], off
	s_mov_b32 m0, s43
	v_lshl_add_u64 v[240:241], s[38:39], 0, v[134:135]
	global_load_lds_dwordx4 v[238:239], off
	s_mov_b32 m0, s44
	s_nop 0
	global_load_lds_dwordx4 v[240:241], off
	s_waitcnt vmcnt(8) lgkmcnt(0)
	s_barrier
; #define PG8_STAGE(bufoff, gbase, voff) do { _Pragma("unroll") for (int _i = 0; _i < 2; ++_i) \
;         __builtin_amdgcn_global_load_lds((const unsigned*)((const char*)(gbase) + (voff)[_i]), (PG8_LAS unsigned*)(lds + (bufoff) + ldsw + _i * 8192), 16, 0, 0); } while (0)
; #define PG8_LDA(dst, b, h) do { _Pragma("unroll") for (int m = 0; m < 4; ++m) _Pragma("unroll") for (int k = 0; k < 2; ++k) dst[m][k] = *(const PG8_LAS bf16x8*)(lds + PG8_SA(b, h) + aoff + m * 2048 + k * 1024); } while (0)
; #define PG8_LDB(dst, b, h) do { _Pragma("unroll") for (int n = 0; n < 2; ++n) _Pragma("unroll") for (int k = 0; k < 2; ++k) dst[n][k] = *(const PG8_LAS bf16x8*)(lds + PG8_SB(b, h) + boff + n * 2048 + k * 1024); } while (0)
; #define PG8_MMA(ai, bj, At, Bt) do { __builtin_amdgcn_s_setprio(1); _Pragma("unroll") for (int m = 0; m < 4; ++m) _Pragma("unroll") for (int n = 0; n < 2; ++n) _Pragma("unroll") for (int k = 0; k < 2; ++k) \
;         acc[ai][bj][m][n] = __builtin_amdgcn_mfma_f32_16x16x32_bf16(Bt[n][k], At[m][k], acc[ai][bj][m][n], 0, 0, 0); __builtin_amdgcn_s_setprio(0); } while (0)
; #define PG8_WAIT_V(n) asm volatile("s_waitcnt vmcnt(" #n ")" ::: "memory")
; #define PG8_WAIT_L(n) asm volatile("s_waitcnt lgkmcnt(" #n ")" ::: "memory")
; #define PG8_BAR __builtin_amdgcn_s_barrier()
; #define PG8_SCHED __builtin_amdgcn_sched_barrier(0)
; template <class Epi, class Sched, bool ALIGN_EPI = false, bool SP2 = false>
; __device__ __forceinline__ void gemm_phase(PG8_LAS unsigned char* lds, const Gemm g, const Sched& S, const Epi& E) {
;     ...
;             PG8_WAIT_V(8); PG8_WAIT_L(0); PG8_BAR; PG8_MMA(1, 0, At, B0); PG8_MMA(1, 1, At, B1); PG8_BAR; PG8_SCHED;
;             PG8_LDB(B0, 1, 0); PG8_LDB(B1, 1, 1); PG8_SCHED; PG8_LDA(At, 1, 0); PG8_STAGE(PG8_SA(0, 1), a2 + hstep, voffA);
;             PG8_WAIT_V(8); PG8_WAIT_L(0); PG8_BAR; PG8_MMA(0, 0, At, B0); PG8_MMA(0, 1, At, B1); PG8_BAR; PG8_SCHED;
	s_setprio 1
	v_mfma_f32_16x16x32_bf16 v[62:65], v[146:149], v[200:203], v[62:65]
	v_mfma_f32_16x16x32_bf16 v[58:61], v[176:179], v[200:203], v[58:61]
	v_mfma_f32_16x16x32_bf16 v[46:49], v[146:149], v[208:211], v[46:49]
	v_mfma_f32_16x16x32_bf16 v[42:45], v[176:179], v[208:211], v[42:45]
	v_mfma_f32_16x16x32_bf16 v[30:33], v[146:149], v[216:219], v[30:33]
	v_mfma_f32_16x16x32_bf16 v[26:29], v[176:179], v[216:219], v[26:29]
	v_mfma_f32_16x16x32_bf16 v[14:17], v[146:149], v[224:227], v[14:17]
	v_mfma_f32_16x16x32_bf16 v[10:13], v[176:179], v[224:227], v[10:13]
	v_mfma_f32_16x16x32_bf16 v[62:65], v[172:175], v[204:207], v[62:65]
	v_mfma_f32_16x16x32_bf16 v[58:61], v[180:183], v[204:207], v[58:61]
	v_mfma_f32_16x16x32_bf16 v[46:49], v[172:175], v[212:215], v[46:49]
	v_mfma_f32_16x16x32_bf16 v[42:45], v[180:183], v[212:215], v[42:45]
	v_mfma_f32_16x16x32_bf16 v[30:33], v[172:175], v[220:223], v[30:33]
	v_mfma_f32_16x16x32_bf16 v[26:29], v[180:183], v[220:223], v[26:29]
	v_mfma_f32_16x16x32_bf16 v[14:17], v[172:175], v[228:231], v[14:17]
	v_mfma_f32_16x16x32_bf16 v[10:13], v[180:183], v[228:231], v[10:13]
	v_mfma_f32_16x16x32_bf16 v[54:57], v[184:187], v[200:203], v[54:57]
	v_mfma_f32_16x16x32_bf16 v[50:53], v[192:195], v[200:203], v[50:53]
	v_mfma_f32_16x16x32_bf16 v[38:41], v[184:187], v[208:211], v[38:41]
	v_mfma_f32_16x16x32_bf16 v[34:37], v[192:195], v[208:211], v[34:37]
	v_mfma_f32_16x16x32_bf16 v[22:25], v[184:187], v[216:219], v[22:25]
	v_mfma_f32_16x16x32_bf16 v[18:21], v[192:195], v[216:219], v[18:21]
	v_mfma_f32_16x16x32_bf16 v[6:9], v[184:187], v[224:227], v[6:9]
	v_mfma_f32_16x16x32_bf16 v[2:5], v[192:195], v[224:227], v[2:5]
	v_mfma_f32_16x16x32_bf16 v[54:57], v[188:191], v[204:207], v[54:57]
	v_mfma_f32_16x16x32_bf16 v[50:53], v[196:199], v[204:207], v[50:53]
	v_mfma_f32_16x16x32_bf16 v[38:41], v[188:191], v[212:215], v[38:41]
	v_mfma_f32_16x16x32_bf16 v[34:37], v[196:199], v[212:215], v[34:37]
	v_mfma_f32_16x16x32_bf16 v[22:25], v[188:191], v[220:223], v[22:25]
	v_mfma_f32_16x16x32_bf16 v[18:21], v[196:199], v[220:223], v[18:21]
	v_mfma_f32_16x16x32_bf16 v[6:9], v[188:191], v[228:231], v[6:9]
	v_mfma_f32_16x16x32_bf16 v[2:5], v[196:199], v[228:231], v[2:5]
	s_setprio 0
	s_barrier
	s_add_i32 s70, 0, 0x18000
	v_add_u32_e32 v171, s70, v166
	s_add_i32 s71, 0, 0x1c000
	ds_read_b128 v[146:149], v171
	ds_read_b128 v[172:175], v171 offset:1024
	ds_read_b128 v[176:179], v171 offset:2048
	ds_read_b128 v[180:183], v171 offset:3072
	v_add_u32_e32 v171, s71, v166
	ds_read_b128 v[184:187], v171
	ds_read_b128 v[188:191], v171 offset:1024
	ds_read_b128 v[192:195], v171 offset:2048
	ds_read_b128 v[196:199], v171 offset:3072
	s_add_u32 s38, s38, s14
	s_addc_u32 s39, s39, s15
	s_mov_b32 m0, s45
	v_lshl_add_u64 v[242:243], s[38:39], 0, v[130:131]
	ds_read_b128 v[200:203], v170 offset:32768
	ds_read_b128 v[204:207], v170 offset:33792
	ds_read_b128 v[208:211], v170 offset:34816
	ds_read_b128 v[212:215], v170 offset:35840
	ds_read_b128 v[216:219], v170 offset:36864
	ds_read_b128 v[220:223], v170 offset:37888
	ds_read_b128 v[224:227], v170 offset:38912
	ds_read_b128 v[228:231], v170 offset:39936
	global_load_lds_dwordx4 v[242:243], off
	v_lshl_add_u64 v[242:243], s[38:39], 0, v[134:135]
	s_mov_b32 m0, s46
	s_nop 0
	global_load_lds_dwordx4 v[242:243], off
	s_waitcnt vmcnt(8) lgkmcnt(0)
	s_barrier
	s_setprio 1
	v_mfma_f32_16x16x32_bf16 v[122:125], v[146:149], v[200:203], v[122:125]
	v_mfma_f32_16x16x32_bf16 v[126:129], v[176:179], v[200:203], v[126:129]
	v_mfma_f32_16x16x32_bf16 v[110:113], v[146:149], v[208:211], v[110:113]
	v_mfma_f32_16x16x32_bf16 v[106:109], v[176:179], v[208:211], v[106:109]
	v_mfma_f32_16x16x32_bf16 v[94:97], v[146:149], v[216:219], v[94:97]
	v_mfma_f32_16x16x32_bf16 v[90:93], v[176:179], v[216:219], v[90:93]
	v_mfma_f32_16x16x32_bf16 v[78:81], v[146:149], v[224:227], v[78:81]
	v_mfma_f32_16x16x32_bf16 v[74:77], v[176:179], v[224:227], v[74:77]
	v_mfma_f32_16x16x32_bf16 v[122:125], v[172:175], v[204:207], v[122:125]
	v_mfma_f32_16x16x32_bf16 v[126:129], v[180:183], v[204:207], v[126:129]
	v_mfma_f32_16x16x32_bf16 v[110:113], v[172:175], v[212:215], v[110:113]
	v_mfma_f32_16x16x32_bf16 v[106:109], v[180:183], v[212:215], v[106:109]
	v_mfma_f32_16x16x32_bf16 v[94:97], v[172:175], v[220:223], v[94:97]
	v_mfma_f32_16x16x32_bf16 v[90:93], v[180:183], v[220:223], v[90:93]
	v_mfma_f32_16x16x32_bf16 v[78:81], v[172:175], v[228:231], v[78:81]
	v_mfma_f32_16x16x32_bf16 v[74:77], v[180:183], v[228:231], v[74:77]
	v_mfma_f32_16x16x32_bf16 v[118:121], v[184:187], v[200:203], v[118:121]
	v_mfma_f32_16x16x32_bf16 v[114:117], v[192:195], v[200:203], v[114:117]
	v_mfma_f32_16x16x32_bf16 v[102:105], v[184:187], v[208:211], v[102:105]
	v_mfma_f32_16x16x32_bf16 v[98:101], v[192:195], v[208:211], v[98:101]
	v_mfma_f32_16x16x32_bf16 v[86:89], v[184:187], v[216:219], v[86:89]
	v_mfma_f32_16x16x32_bf16 v[82:85], v[192:195], v[216:219], v[82:85]
	v_mfma_f32_16x16x32_bf16 v[70:73], v[184:187], v[224:227], v[70:73]
	v_mfma_f32_16x16x32_bf16 v[66:69], v[192:195], v[224:227], v[66:69]
	v_mfma_f32_16x16x32_bf16 v[118:121], v[188:191], v[204:207], v[118:121]
	v_mfma_f32_16x16x32_bf16 v[114:117], v[196:199], v[204:207], v[114:117]
	v_mfma_f32_16x16x32_bf16 v[102:105], v[188:191], v[212:215], v[102:105]
	v_mfma_f32_16x16x32_bf16 v[98:101], v[196:199], v[212:215], v[98:101]
	v_mfma_f32_16x16x32_bf16 v[86:89], v[188:191], v[220:223], v[86:89]
	v_mfma_f32_16x16x32_bf16 v[82:85], v[196:199], v[220:223], v[82:85]
	v_mfma_f32_16x16x32_bf16 v[70:73], v[188:191], v[228:231], v[70:73]
	v_mfma_f32_16x16x32_bf16 v[66:69], v[196:199], v[228:231], v[66:69]
	s_setprio 0
	s_barrier
; #define PG8_STAGE(bufoff, gbase, voff) do { _Pragma("unroll") for (int _i = 0; _i < 2; ++_i) \
;         __builtin_amdgcn_global_load_lds((const unsigned*)((const char*)(gbase) + (voff)[_i]), (PG8_LAS unsigned*)(lds + (bufoff) + ldsw + _i * 8192), 16, 0, 0); } while (0)
; #define PG8_LDA(dst, b, h) do { _Pragma("unroll") for (int m = 0; m < 4; ++m) _Pragma("unroll") for (int k = 0; k < 2; ++k) dst[m][k] = *(const PG8_LAS bf16x8*)(lds + PG8_SA(b, h) + aoff + m * 2048 + k * 1024); } while (0)
; #define PG8_MMA(ai, bj, At, Bt) do { __builtin_amdgcn_s_setprio(1); _Pragma("unroll") for (int m = 0; m < 4; ++m) _Pragma("unroll") for (int n = 0; n < 2; ++n) _Pragma("unroll") for (int k = 0; k < 2; ++k) \
;         acc[ai][bj][m][n] = __builtin_amdgcn_mfma_f32_16x16x32_bf16(Bt[n][k], At[m][k], acc[ai][bj][m][n], 0, 0, 0); __builtin_amdgcn_s_setprio(0); } while (0)
; #define PG8_WAIT_V(n) asm volatile("s_waitcnt vmcnt(" #n ")" ::: "memory")
; #define PG8_WAIT_L(n) asm volatile("s_waitcnt lgkmcnt(" #n ")" ::: "memory")
; #define PG8_BAR __builtin_amdgcn_s_barrier()
; #define PG8_SCHED __builtin_amdgcn_sched_barrier(0)
; template <class Epi, class Sched, bool ALIGN_EPI = false, bool SP2 = false>
; __device__ __forceinline__ void gemm_phase(PG8_LAS unsigned char* lds, const Gemm g, const Sched& S, const Epi& E) {
;     ...
;             PG8_LDA(At, 1, 1); PG8_STAGE(PG8_SB(1, 0), b3, voffB); PG8_STAGE(PG8_SB(1, 1), b3 + hstep, voffB); PG8_STAGE(PG8_SA(1, 0), a3, voffA);
;             PG8_WAIT_V(8); PG8_WAIT_L(0); PG8_BAR; PG8_MMA(1, 0, At, B0); PG8_MMA(1, 1, At, B1); PG8_BAR; PG8_SCHED;
	s_add_i32 s38, s70, s42
	v_lshl_add_u64 v[150:151], v[150:151], 0, s[24:25]
	s_mov_b32 m0, s38
	ds_read_b128 v[200:203], v170 offset:49152
	ds_read_b128 v[204:207], v170 offset:50176
	ds_read_b128 v[208:211], v170 offset:51200
	ds_read_b128 v[212:215], v170 offset:52224
	ds_read_b128 v[216:219], v170 offset:53248
	ds_read_b128 v[220:223], v170 offset:54272
	ds_read_b128 v[224:227], v170 offset:55296
	ds_read_b128 v[228:231], v170 offset:56320
	global_load_lds_dwordx4 v[150:151], off
	v_lshl_add_u64 v[150:151], v[232:233], 0, s[24:25]
	s_add_i32 m0, s38, 0x2000
	s_add_i32 s38, s71, s42
	global_load_lds_dwordx4 v[150:151], off
	v_lshl_add_u64 v[150:151], v[234:235], 0, s[24:25]
	s_mov_b32 m0, s38
	s_nop 0
	global_load_lds_dwordx4 v[150:151], off
	v_lshl_add_u64 v[150:151], v[236:237], 0, s[24:25]
	s_add_i32 m0, s38, 0x2000
	s_nop 0
	global_load_lds_dwordx4 v[150:151], off
	v_lshl_add_u64 v[150:151], v[238:239], 0, s[24:25]
	s_mov_b32 m0, s48
	s_nop 0
	global_load_lds_dwordx4 v[150:151], off
	v_lshl_add_u64 v[150:151], v[240:241], 0, s[24:25]
	s_mov_b32 m0, s49
	s_nop 0
	global_load_lds_dwordx4 v[150:151], off
	s_waitcnt vmcnt(8) lgkmcnt(0)
	s_barrier
	s_setprio 1
	v_mfma_f32_16x16x32_bf16 v[62:65], v[146:149], v[200:203], v[62:65]
	v_mfma_f32_16x16x32_bf16 v[58:61], v[176:179], v[200:203], v[58:61]
	v_mfma_f32_16x16x32_bf16 v[46:49], v[146:149], v[208:211], v[46:49]
	v_mfma_f32_16x16x32_bf16 v[42:45], v[176:179], v[208:211], v[42:45]
	v_mfma_f32_16x16x32_bf16 v[30:33], v[146:149], v[216:219], v[30:33]
	v_mfma_f32_16x16x32_bf16 v[26:29], v[176:179], v[216:219], v[26:29]
	v_mfma_f32_16x16x32_bf16 v[14:17], v[146:149], v[224:227], v[14:17]
	v_mfma_f32_16x16x32_bf16 v[10:13], v[176:179], v[224:227], v[10:13]
	v_mfma_f32_16x16x32_bf16 v[62:65], v[172:175], v[204:207], v[62:65]
	v_mfma_f32_16x16x32_bf16 v[58:61], v[180:183], v[204:207], v[58:61]
	v_mfma_f32_16x16x32_bf16 v[46:49], v[172:175], v[212:215], v[46:49]
	v_mfma_f32_16x16x32_bf16 v[42:45], v[180:183], v[212:215], v[42:45]
	v_mfma_f32_16x16x32_bf16 v[30:33], v[172:175], v[220:223], v[30:33]
	v_mfma_f32_16x16x32_bf16 v[26:29], v[180:183], v[220:223], v[26:29]
	v_mfma_f32_16x16x32_bf16 v[14:17], v[172:175], v[228:231], v[14:17]
	v_mfma_f32_16x16x32_bf16 v[10:13], v[180:183], v[228:231], v[10:13]
	v_mfma_f32_16x16x32_bf16 v[54:57], v[184:187], v[200:203], v[54:57]
	v_mfma_f32_16x16x32_bf16 v[50:53], v[192:195], v[200:203], v[50:53]
	v_mfma_f32_16x16x32_bf16 v[38:41], v[184:187], v[208:211], v[38:41]
	v_mfma_f32_16x16x32_bf16 v[34:37], v[192:195], v[208:211], v[34:37]
	v_mfma_f32_16x16x32_bf16 v[22:25], v[184:187], v[216:219], v[22:25]
	v_mfma_f32_16x16x32_bf16 v[18:21], v[192:195], v[216:219], v[18:21]
	v_mfma_f32_16x16x32_bf16 v[6:9], v[184:187], v[224:227], v[6:9]
	v_mfma_f32_16x16x32_bf16 v[2:5], v[192:195], v[224:227], v[2:5]
	v_mfma_f32_16x16x32_bf16 v[54:57], v[188:191], v[204:207], v[54:57]
	v_mfma_f32_16x16x32_bf16 v[50:53], v[196:199], v[204:207], v[50:53]
	v_mfma_f32_16x16x32_bf16 v[38:41], v[188:191], v[212:215], v[38:41]
	v_mfma_f32_16x16x32_bf16 v[34:37], v[196:199], v[212:215], v[34:37]
	v_mfma_f32_16x16x32_bf16 v[22:25], v[188:191], v[220:223], v[22:25]
	v_mfma_f32_16x16x32_bf16 v[18:21], v[196:199], v[220:223], v[18:21]
	v_mfma_f32_16x16x32_bf16 v[6:9], v[188:191], v[228:231], v[6:9]
	v_mfma_f32_16x16x32_bf16 v[2:5], v[196:199], v[228:231], v[2:5]
	s_setprio 0
	s_barrier
	s_add_u32 s86, s86, 0x100
	s_addc_u32 s87, s87, 0
	s_add_u32 s36, s36, 0x100
	s_addc_u32 s37, s37, 0
	s_cmp_ge_i32 s88, s52
	s_mov_b32 s38, s88
	s_cbranch_scc0 .LBB0_1518
	v_readlane_b32 s74, v244, 3
	v_readlane_b32 s88, v244, 5
	v_readlane_b32 s75, v244, 4
	v_readlane_b32 s90, v244, 7
	v_readlane_b32 s91, v244, 8
	v_readlane_b32 s92, v244, 9
	v_readlane_b32 s93, v244, 10
	v_readlane_b32 s94, v244, 11
	v_readlane_b32 s95, v244, 12
	v_readlane_b32 s89, v244, 6

; #define PG8_STAGE(bufoff, gbase, voff) do { _Pragma("unroll") for (int _i = 0; _i < 2; ++_i) \
;         __builtin_amdgcn_global_load_lds((const unsigned*)((const char*)(gbase) + (voff)[_i]), (PG8_LAS unsigned*)(lds + (bufoff) + ldsw + _i * 8192), 16, 0, 0); } while (0)
; #define PG8_LDA(dst, b, h) do { _Pragma("unroll") for (int m = 0; m < 4; ++m) _Pragma("unroll") for (int k = 0; k < 2; ++k) dst[m][k] = *(const PG8_LAS bf16x8*)(lds + PG8_SA(b, h) + aoff + m * 2048 + k * 1024); } while (0)
; #define PG8_LDB(dst, b, h) do { _Pragma("unroll") for (int n = 0; n < 2; ++n) _Pragma("unroll") for (int k = 0; k < 2; ++k) dst[n][k] = *(const PG8_LAS bf16x8*)(lds + PG8_SB(b, h) + boff + n * 2048 + k * 1024); } while (0)
; #define PG8_MMA(ai, bj, At, Bt) do { __builtin_amdgcn_s_setprio(1); _Pragma("unroll") for (int m = 0; m < 4; ++m) _Pragma("unroll") for (int n = 0; n < 2; ++n) _Pragma("unroll") for (int k = 0; k < 2; ++k) \
;         acc[ai][bj][m][n] = __builtin_amdgcn_mfma_f32_16x16x32_bf16(Bt[n][k], At[m][k], acc[ai][bj][m][n], 0, 0, 0); __builtin_amdgcn_s_setprio(0); } while (0)
; #define PG8_WAIT_V(n) asm volatile("s_waitcnt vmcnt(" #n ")" ::: "memory")
; #define PG8_WAIT_L(n) asm volatile("s_waitcnt lgkmcnt(" #n ")" ::: "memory")
; #define PG8_BAR __builtin_amdgcn_s_barrier()
; #define PG8_SCHED __builtin_amdgcn_sched_barrier(0)
; template <class Epi, class Sched, bool ALIGN_EPI = false, bool SP2 = false>
; __device__ __forceinline__ void gemm_phase(PG8_LAS unsigned char* lds, const Gemm g, const Sched& S, const Epi& E) {
;     ...
;             const bool last = (t == nt - 2);
;             const char* a1 = cA + (size_t)(t + 1) * kstep;
;             const char* a2 = last ? nA : cA + (size_t)(t + 2) * kstep; const char* b2 = last ? nB : cB + (size_t)(t + 2) * kstep;
;             const char* a3 = a2 + kstep; const char* b3 = b2 + kstep;
;             if (last && has_next) S.a_ready(nxt);
;             if constexpr (SP2) {
;             PG8_LDB(B0, 0, 0); PG8_LDB(B1, 0, 1); PG8_SCHED; PG8_LDA(At, 0, 0); PG8_STAGE(PG8_SA(1, 1), a1 + hstep, voffA);
;             PG8_WAIT_V(8); PG8_WAIT_L(0); PG8_BAR; PG8_MMA(0, 0, At, B0); PG8_MMA(0, 1, At, B1); PG8_BAR; PG8_SCHED;
;             PG8_LDA(At, 0, 1); PG8_STAGE(PG8_SB(0, 0), b2, voffB); PG8_STAGE(PG8_SB(0, 1), b2 + hstep, voffB); PG8_STAGE(PG8_SA(0, 0), a2, voffA);
.LBB0_1548:
	ds_read_b128 v[146:149], v1
	ds_read_b128 v[162:165], v1 offset:1024
	ds_read_b128 v[166:169], v1 offset:2048
	ds_read_b128 v[170:173], v1 offset:3072
	ds_read_b128 v[174:177], v152
	ds_read_b128 v[178:181], v152 offset:1024
	ds_read_b128 v[182:185], v152 offset:2048
	ds_read_b128 v[186:189], v152 offset:3072
	s_add_i32 s68, s28, 2
	s_add_u32 s69, s26, 0x80
	s_addc_u32 s29, s27, 0
	s_cmp_eq_u32 s45, s28
	s_cselect_b32 s28, s4, s69
	s_cselect_b32 s29, s5, s29
	s_cselect_b32 s71, s9, s57
	s_cselect_b32 s70, s8, s56
	v_lshl_add_u64 v[150:151], s[26:27], 0, v[140:141]
	s_add_i32 m0, s37, 0xc000
	ds_read_b128 v[190:193], v153
	ds_read_b128 v[194:197], v153 offset:1024
	ds_read_b128 v[198:201], v153 offset:2048
	ds_read_b128 v[202:205], v153 offset:3072
	ds_read_b128 v[206:209], v153 offset:4096
	ds_read_b128 v[210:213], v153 offset:5120
	ds_read_b128 v[214:217], v153 offset:6144
	ds_read_b128 v[218:221], v153 offset:7168
	global_load_lds_dwordx4 v[150:151], off
	v_lshl_add_u64 v[150:151], s[26:27], 0, v[138:139]
	s_add_i32 m0, s37, 0xe000
	s_nop 0
	global_load_lds_dwordx4 v[150:151], off
	s_waitcnt vmcnt(8) lgkmcnt(0)
	s_barrier
	s_setprio 1
	v_mfma_f32_16x16x32_bf16 v[122:125], v[146:149], v[190:193], v[122:125]
	v_mfma_f32_16x16x32_bf16 v[126:129], v[166:169], v[190:193], v[126:129]
	v_mfma_f32_16x16x32_bf16 v[110:113], v[146:149], v[198:201], v[110:113]
	v_mfma_f32_16x16x32_bf16 v[106:109], v[166:169], v[198:201], v[106:109]
	v_mfma_f32_16x16x32_bf16 v[94:97], v[146:149], v[206:209], v[94:97]
	v_mfma_f32_16x16x32_bf16 v[90:93], v[166:169], v[206:209], v[90:93]
	v_mfma_f32_16x16x32_bf16 v[78:81], v[146:149], v[214:217], v[78:81]
	v_mfma_f32_16x16x32_bf16 v[74:77], v[166:169], v[214:217], v[74:77]
	v_mfma_f32_16x16x32_bf16 v[122:125], v[162:165], v[194:197], v[122:125]
	v_mfma_f32_16x16x32_bf16 v[126:129], v[170:173], v[194:197], v[126:129]
	v_mfma_f32_16x16x32_bf16 v[110:113], v[162:165], v[202:205], v[110:113]
	v_mfma_f32_16x16x32_bf16 v[106:109], v[170:173], v[202:205], v[106:109]
	v_mfma_f32_16x16x32_bf16 v[94:97], v[162:165], v[210:213], v[94:97]
	v_mfma_f32_16x16x32_bf16 v[90:93], v[170:173], v[210:213], v[90:93]
	v_mfma_f32_16x16x32_bf16 v[78:81], v[162:165], v[218:221], v[78:81]
	v_mfma_f32_16x16x32_bf16 v[74:77], v[170:173], v[218:221], v[74:77]
	v_mfma_f32_16x16x32_bf16 v[118:121], v[174:177], v[190:193], v[118:121]
	v_mfma_f32_16x16x32_bf16 v[114:117], v[182:185], v[190:193], v[114:117]
	v_mfma_f32_16x16x32_bf16 v[102:105], v[174:177], v[198:201], v[102:105]
	v_mfma_f32_16x16x32_bf16 v[98:101], v[182:185], v[198:201], v[98:101]
	v_mfma_f32_16x16x32_bf16 v[86:89], v[174:177], v[206:209], v[86:89]
	v_mfma_f32_16x16x32_bf16 v[82:85], v[182:185], v[206:209], v[82:85]
	v_mfma_f32_16x16x32_bf16 v[70:73], v[174:177], v[214:217], v[70:73]
	v_mfma_f32_16x16x32_bf16 v[66:69], v[182:185], v[214:217], v[66:69]
	v_mfma_f32_16x16x32_bf16 v[118:121], v[178:181], v[194:197], v[118:121]
	v_mfma_f32_16x16x32_bf16 v[114:117], v[186:189], v[194:197], v[114:117]
	v_mfma_f32_16x16x32_bf16 v[102:105], v[178:181], v[202:205], v[102:105]
	v_mfma_f32_16x16x32_bf16 v[98:101], v[186:189], v[202:205], v[98:101]
	v_mfma_f32_16x16x32_bf16 v[86:89], v[178:181], v[210:213], v[86:89]
	v_mfma_f32_16x16x32_bf16 v[82:85], v[186:189], v[210:213], v[82:85]
	v_mfma_f32_16x16x32_bf16 v[70:73], v[178:181], v[218:221], v[70:73]
	v_mfma_f32_16x16x32_bf16 v[66:69], v[186:189], v[218:221], v[66:69]
	s_setprio 0
	s_barrier
	s_add_i32 s69, s48, s36
	v_lshl_add_u64 v[150:151], s[70:71], 0, v[132:133]
	s_mov_b32 m0, s69
	ds_read_b128 v[190:193], v153 offset:16384
	ds_read_b128 v[194:197], v153 offset:17408
	ds_read_b128 v[198:201], v153 offset:18432
	ds_read_b128 v[202:205], v153 offset:19456
	ds_read_b128 v[206:209], v153 offset:20480
	ds_read_b128 v[210:213], v153 offset:21504
	ds_read_b128 v[214:217], v153 offset:22528
	ds_read_b128 v[218:221], v153 offset:23552
	global_load_lds_dwordx4 v[150:151], off
	s_add_i32 m0, s69, 0x2000
	v_lshl_add_u64 v[158:159], s[70:71], 0, v[136:137]
	s_add_u32 s70, s70, s10
	s_addc_u32 s71, s71, s11
	s_add_i32 s69, s49, s36
	global_load_lds_dwordx4 v[158:159], off
	v_lshl_add_u64 v[222:223], s[70:71], 0, v[132:133]
	s_mov_b32 m0, s69
	v_lshl_add_u64 v[224:225], s[70:71], 0, v[136:137]
	global_load_lds_dwordx4 v[222:223], off
	s_add_i32 m0, s69, 0x2000
	v_lshl_add_u64 v[226:227], s[28:29], 0, v[130:131]
	global_load_lds_dwordx4 v[224:225], off
	s_mov_b32 m0, s37
	v_lshl_add_u64 v[228:229], s[28:29], 0, v[134:135]
	global_load_lds_dwordx4 v[226:227], off
	s_mov_b32 m0, s38
	s_nop 0
	global_load_lds_dwordx4 v[228:229], off
	s_waitcnt vmcnt(8) lgkmcnt(0)
	s_barrier
; #define PG8_STAGE(bufoff, gbase, voff) do { _Pragma("unroll") for (int _i = 0; _i < 2; ++_i) \
;         __builtin_amdgcn_global_load_lds((const unsigned*)((const char*)(gbase) + (voff)[_i]), (PG8_LAS unsigned*)(lds + (bufoff) + ldsw + _i * 8192), 16, 0, 0); } while (0)
; #define PG8_LDA(dst, b, h) do { _Pragma("unroll") for (int m = 0; m < 4; ++m) _Pragma("unroll") for (int k = 0; k < 2; ++k) dst[m][k] = *(const PG8_LAS bf16x8*)(lds + PG8_SA(b, h) + aoff + m * 2048 + k * 1024); } while (0)
; #define PG8_LDB(dst, b, h) do { _Pragma("unroll") for (int n = 0; n < 2; ++n) _Pragma("unroll") for (int k = 0; k < 2; ++k) dst[n][k] = *(const PG8_LAS bf16x8*)(lds + PG8_SB(b, h) + boff + n * 2048 + k * 1024); } while (0)
; #define PG8_MMA(ai, bj, At, Bt) do { __builtin_amdgcn_s_setprio(1); _Pragma("unroll") for (int m = 0; m < 4; ++m) _Pragma("unroll") for (int n = 0; n < 2; ++n) _Pragma("unroll") for (int k = 0; k < 2; ++k) \
;         acc[ai][bj][m][n] = __builtin_amdgcn_mfma_f32_16x16x32_bf16(Bt[n][k], At[m][k], acc[ai][bj][m][n], 0, 0, 0); __builtin_amdgcn_s_setprio(0); } while (0)
; #define PG8_WAIT_V(n) asm volatile("s_waitcnt vmcnt(" #n ")" ::: "memory")
; #define PG8_WAIT_L(n) asm volatile("s_waitcnt lgkmcnt(" #n ")" ::: "memory")
; #define PG8_BAR __builtin_amdgcn_s_barrier()
; #define PG8_SCHED __builtin_amdgcn_sched_barrier(0)
; template <class Epi, class Sched, bool ALIGN_EPI = false, bool SP2 = false>
; __device__ __forceinline__ void gemm_phase(PG8_LAS unsigned char* lds, const Gemm g, const Sched& S, const Epi& E) {
;     ...
;             PG8_WAIT_V(8); PG8_WAIT_L(0); PG8_BAR; PG8_MMA(1, 0, At, B0); PG8_MMA(1, 1, At, B1); PG8_BAR; PG8_SCHED;
;             PG8_LDB(B0, 1, 0); PG8_LDB(B1, 1, 1); PG8_SCHED; PG8_LDA(At, 1, 0); PG8_STAGE(PG8_SA(0, 1), a2 + hstep, voffA);
;             PG8_WAIT_V(8); PG8_WAIT_L(0); PG8_BAR; PG8_MMA(0, 0, At, B0); PG8_MMA(0, 1, At, B1); PG8_BAR; PG8_SCHED;
	s_setprio 1
	v_mfma_f32_16x16x32_bf16 v[62:65], v[146:149], v[190:193], v[62:65]
	v_mfma_f32_16x16x32_bf16 v[58:61], v[166:169], v[190:193], v[58:61]
	v_mfma_f32_16x16x32_bf16 v[46:49], v[146:149], v[198:201], v[46:49]
	v_mfma_f32_16x16x32_bf16 v[42:45], v[166:169], v[198:201], v[42:45]
	v_mfma_f32_16x16x32_bf16 v[30:33], v[146:149], v[206:209], v[30:33]
	v_mfma_f32_16x16x32_bf16 v[26:29], v[166:169], v[206:209], v[26:29]
	v_mfma_f32_16x16x32_bf16 v[14:17], v[146:149], v[214:217], v[14:17]
	v_mfma_f32_16x16x32_bf16 v[10:13], v[166:169], v[214:217], v[10:13]
	v_mfma_f32_16x16x32_bf16 v[62:65], v[162:165], v[194:197], v[62:65]
	v_mfma_f32_16x16x32_bf16 v[58:61], v[170:173], v[194:197], v[58:61]
	v_mfma_f32_16x16x32_bf16 v[46:49], v[162:165], v[202:205], v[46:49]
	v_mfma_f32_16x16x32_bf16 v[42:45], v[170:173], v[202:205], v[42:45]
	v_mfma_f32_16x16x32_bf16 v[30:33], v[162:165], v[210:213], v[30:33]
	v_mfma_f32_16x16x32_bf16 v[26:29], v[170:173], v[210:213], v[26:29]
	v_mfma_f32_16x16x32_bf16 v[14:17], v[162:165], v[218:221], v[14:17]
	v_mfma_f32_16x16x32_bf16 v[10:13], v[170:173], v[218:221], v[10:13]
	v_mfma_f32_16x16x32_bf16 v[54:57], v[174:177], v[190:193], v[54:57]
	v_mfma_f32_16x16x32_bf16 v[50:53], v[182:185], v[190:193], v[50:53]
	v_mfma_f32_16x16x32_bf16 v[38:41], v[174:177], v[198:201], v[38:41]
	v_mfma_f32_16x16x32_bf16 v[34:37], v[182:185], v[198:201], v[34:37]
	v_mfma_f32_16x16x32_bf16 v[22:25], v[174:177], v[206:209], v[22:25]
	v_mfma_f32_16x16x32_bf16 v[18:21], v[182:185], v[206:209], v[18:21]
	v_mfma_f32_16x16x32_bf16 v[6:9], v[174:177], v[214:217], v[6:9]
	v_mfma_f32_16x16x32_bf16 v[2:5], v[182:185], v[214:217], v[2:5]
	v_mfma_f32_16x16x32_bf16 v[54:57], v[178:181], v[194:197], v[54:57]
	v_mfma_f32_16x16x32_bf16 v[50:53], v[186:189], v[194:197], v[50:53]
	v_mfma_f32_16x16x32_bf16 v[38:41], v[178:181], v[202:205], v[38:41]
	v_mfma_f32_16x16x32_bf16 v[34:37], v[186:189], v[202:205], v[34:37]
	v_mfma_f32_16x16x32_bf16 v[22:25], v[178:181], v[210:213], v[22:25]
	v_mfma_f32_16x16x32_bf16 v[18:21], v[186:189], v[210:213], v[18:21]
	v_mfma_f32_16x16x32_bf16 v[6:9], v[178:181], v[218:221], v[6:9]
	v_mfma_f32_16x16x32_bf16 v[2:5], v[186:189], v[218:221], v[2:5]
	s_setprio 0
	s_barrier
	s_add_i32 s69, 0, 0x18000
	v_add_u32_e32 v154, s69, v156
	s_add_i32 s70, 0, 0x1c000
	ds_read_b128 v[146:149], v154
	ds_read_b128 v[162:165], v154 offset:1024
	ds_read_b128 v[166:169], v154 offset:2048
	ds_read_b128 v[170:173], v154 offset:3072
	v_add_u32_e32 v154, s70, v156
	ds_read_b128 v[174:177], v154
	ds_read_b128 v[178:181], v154 offset:1024
	ds_read_b128 v[182:185], v154 offset:2048
	ds_read_b128 v[186:189], v154 offset:3072
	s_add_u32 s28, s28, s10
	s_addc_u32 s29, s29, s11
	s_mov_b32 m0, s39
	v_lshl_add_u64 v[230:231], s[28:29], 0, v[130:131]
	ds_read_b128 v[190:193], v153 offset:32768
	ds_read_b128 v[194:197], v153 offset:33792
	ds_read_b128 v[198:201], v153 offset:34816
	ds_read_b128 v[202:205], v153 offset:35840
	ds_read_b128 v[206:209], v153 offset:36864
	ds_read_b128 v[210:213], v153 offset:37888
	ds_read_b128 v[214:217], v153 offset:38912
	ds_read_b128 v[218:221], v153 offset:39936
	global_load_lds_dwordx4 v[230:231], off
	v_lshl_add_u64 v[230:231], s[28:29], 0, v[134:135]
	s_mov_b32 m0, s40
	s_nop 0
	global_load_lds_dwordx4 v[230:231], off
	s_waitcnt vmcnt(8) lgkmcnt(0)
	s_barrier
	s_setprio 1
	v_mfma_f32_16x16x32_bf16 v[122:125], v[146:149], v[190:193], v[122:125]
	v_mfma_f32_16x16x32_bf16 v[126:129], v[166:169], v[190:193], v[126:129]
	v_mfma_f32_16x16x32_bf16 v[110:113], v[146:149], v[198:201], v[110:113]
	v_mfma_f32_16x16x32_bf16 v[106:109], v[166:169], v[198:201], v[106:109]
	v_mfma_f32_16x16x32_bf16 v[94:97], v[146:149], v[206:209], v[94:97]
	v_mfma_f32_16x16x32_bf16 v[90:93], v[166:169], v[206:209], v[90:93]
	v_mfma_f32_16x16x32_bf16 v[78:81], v[146:149], v[214:217], v[78:81]
	v_mfma_f32_16x16x32_bf16 v[74:77], v[166:169], v[214:217], v[74:77]
	v_mfma_f32_16x16x32_bf16 v[122:125], v[162:165], v[194:197], v[122:125]
	v_mfma_f32_16x16x32_bf16 v[126:129], v[170:173], v[194:197], v[126:129]
	v_mfma_f32_16x16x32_bf16 v[110:113], v[162:165], v[202:205], v[110:113]
	v_mfma_f32_16x16x32_bf16 v[106:109], v[170:173], v[202:205], v[106:109]
	v_mfma_f32_16x16x32_bf16 v[94:97], v[162:165], v[210:213], v[94:97]
	v_mfma_f32_16x16x32_bf16 v[90:93], v[170:173], v[210:213], v[90:93]
	v_mfma_f32_16x16x32_bf16 v[78:81], v[162:165], v[218:221], v[78:81]
	v_mfma_f32_16x16x32_bf16 v[74:77], v[170:173], v[218:221], v[74:77]
	v_mfma_f32_16x16x32_bf16 v[118:121], v[174:177], v[190:193], v[118:121]
	v_mfma_f32_16x16x32_bf16 v[114:117], v[182:185], v[190:193], v[114:117]
	v_mfma_f32_16x16x32_bf16 v[102:105], v[174:177], v[198:201], v[102:105]
	v_mfma_f32_16x16x32_bf16 v[98:101], v[182:185], v[198:201], v[98:101]
	v_mfma_f32_16x16x32_bf16 v[86:89], v[174:177], v[206:209], v[86:89]
	v_mfma_f32_16x16x32_bf16 v[82:85], v[182:185], v[206:209], v[82:85]
	v_mfma_f32_16x16x32_bf16 v[70:73], v[174:177], v[214:217], v[70:73]
	v_mfma_f32_16x16x32_bf16 v[66:69], v[182:185], v[214:217], v[66:69]
	v_mfma_f32_16x16x32_bf16 v[118:121], v[178:181], v[194:197], v[118:121]
	v_mfma_f32_16x16x32_bf16 v[114:117], v[186:189], v[194:197], v[114:117]
	v_mfma_f32_16x16x32_bf16 v[102:105], v[178:181], v[202:205], v[102:105]
	v_mfma_f32_16x16x32_bf16 v[98:101], v[186:189], v[202:205], v[98:101]
	v_mfma_f32_16x16x32_bf16 v[86:89], v[178:181], v[210:213], v[86:89]
	v_mfma_f32_16x16x32_bf16 v[82:85], v[186:189], v[210:213], v[82:85]
	v_mfma_f32_16x16x32_bf16 v[70:73], v[178:181], v[218:221], v[70:73]
	v_mfma_f32_16x16x32_bf16 v[66:69], v[186:189], v[218:221], v[66:69]
	s_setprio 0
	s_barrier
; #define PG8_STAGE(bufoff, gbase, voff) do { _Pragma("unroll") for (int _i = 0; _i < 2; ++_i) \
;         __builtin_amdgcn_global_load_lds((const unsigned*)((const char*)(gbase) + (voff)[_i]), (PG8_LAS unsigned*)(lds + (bufoff) + ldsw + _i * 8192), 16, 0, 0); } while (0)
; #define PG8_LDA(dst, b, h) do { _Pragma("unroll") for (int m = 0; m < 4; ++m) _Pragma("unroll") for (int k = 0; k < 2; ++k) dst[m][k] = *(const PG8_LAS bf16x8*)(lds + PG8_SA(b, h) + aoff + m * 2048 + k * 1024); } while (0)
; #define PG8_MMA(ai, bj, At, Bt) do { __builtin_amdgcn_s_setprio(1); _Pragma("unroll") for (int m = 0; m < 4; ++m) _Pragma("unroll") for (int n = 0; n < 2; ++n) _Pragma("unroll") for (int k = 0; k < 2; ++k) \
;         acc[ai][bj][m][n] = __builtin_amdgcn_mfma_f32_16x16x32_bf16(Bt[n][k], At[m][k], acc[ai][bj][m][n], 0, 0, 0); __builtin_amdgcn_s_setprio(0); } while (0)
; #define PG8_WAIT_V(n) asm volatile("s_waitcnt vmcnt(" #n ")" ::: "memory")
; #define PG8_WAIT_L(n) asm volatile("s_waitcnt lgkmcnt(" #n ")" ::: "memory")
; #define PG8_BAR __builtin_amdgcn_s_barrier()
; #define PG8_SCHED __builtin_amdgcn_sched_barrier(0)
; template <class Epi, class Sched, bool ALIGN_EPI = false, bool SP2 = false>
; __device__ __forceinline__ void gemm_phase(PG8_LAS unsigned char* lds, const Gemm g, const Sched& S, const Epi& E) {
;     ...
;             PG8_LDA(At, 1, 1); PG8_STAGE(PG8_SB(1, 0), b3, voffB); PG8_STAGE(PG8_SB(1, 1), b3 + hstep, voffB); PG8_STAGE(PG8_SA(1, 0), a3, voffA);
;             PG8_WAIT_V(8); PG8_WAIT_L(0); PG8_BAR; PG8_MMA(1, 0, At, B0); PG8_MMA(1, 1, At, B1); PG8_BAR; PG8_SCHED;
	s_add_i32 s28, s69, s36
	v_lshl_add_u64 v[150:151], v[150:151], 0, s[20:21]
	s_mov_b32 m0, s28
	ds_read_b128 v[190:193], v153 offset:49152
	ds_read_b128 v[194:197], v153 offset:50176
	ds_read_b128 v[198:201], v153 offset:51200
	ds_read_b128 v[202:205], v153 offset:52224
	ds_read_b128 v[206:209], v153 offset:53248
	ds_read_b128 v[210:213], v153 offset:54272
	ds_read_b128 v[214:217], v153 offset:55296
	ds_read_b128 v[218:221], v153 offset:56320
	global_load_lds_dwordx4 v[150:151], off
	v_lshl_add_u64 v[150:151], v[158:159], 0, s[20:21]
	s_add_i32 m0, s28, 0x2000
	s_add_i32 s28, s70, s36
	global_load_lds_dwordx4 v[150:151], off
	v_lshl_add_u64 v[150:151], v[222:223], 0, s[20:21]
	s_mov_b32 m0, s28
	s_nop 0
	global_load_lds_dwordx4 v[150:151], off
	v_lshl_add_u64 v[150:151], v[224:225], 0, s[20:21]
	s_add_i32 m0, s28, 0x2000
	s_nop 0
	global_load_lds_dwordx4 v[150:151], off
	v_lshl_add_u64 v[150:151], v[226:227], 0, s[20:21]
	s_mov_b32 m0, s42
	s_nop 0
	global_load_lds_dwordx4 v[150:151], off
	v_lshl_add_u64 v[150:151], v[228:229], 0, s[20:21]
	s_mov_b32 m0, s43
	s_nop 0
	global_load_lds_dwordx4 v[150:151], off
	s_waitcnt vmcnt(8) lgkmcnt(0)
	s_barrier
	s_setprio 1
	v_mfma_f32_16x16x32_bf16 v[62:65], v[146:149], v[190:193], v[62:65]
	v_mfma_f32_16x16x32_bf16 v[58:61], v[166:169], v[190:193], v[58:61]
	v_mfma_f32_16x16x32_bf16 v[46:49], v[146:149], v[198:201], v[46:49]
	v_mfma_f32_16x16x32_bf16 v[42:45], v[166:169], v[198:201], v[42:45]
	v_mfma_f32_16x16x32_bf16 v[30:33], v[146:149], v[206:209], v[30:33]
	v_mfma_f32_16x16x32_bf16 v[26:29], v[166:169], v[206:209], v[26:29]
	v_mfma_f32_16x16x32_bf16 v[14:17], v[146:149], v[214:217], v[14:17]
	v_mfma_f32_16x16x32_bf16 v[10:13], v[166:169], v[214:217], v[10:13]
	v_mfma_f32_16x16x32_bf16 v[62:65], v[162:165], v[194:197], v[62:65]
	v_mfma_f32_16x16x32_bf16 v[58:61], v[170:173], v[194:197], v[58:61]
	v_mfma_f32_16x16x32_bf16 v[46:49], v[162:165], v[202:205], v[46:49]
	v_mfma_f32_16x16x32_bf16 v[42:45], v[170:173], v[202:205], v[42:45]
	v_mfma_f32_16x16x32_bf16 v[30:33], v[162:165], v[210:213], v[30:33]
	v_mfma_f32_16x16x32_bf16 v[26:29], v[170:173], v[210:213], v[26:29]
	v_mfma_f32_16x16x32_bf16 v[14:17], v[162:165], v[218:221], v[14:17]
	v_mfma_f32_16x16x32_bf16 v[10:13], v[170:173], v[218:221], v[10:13]
	v_mfma_f32_16x16x32_bf16 v[54:57], v[174:177], v[190:193], v[54:57]
	v_mfma_f32_16x16x32_bf16 v[50:53], v[182:185], v[190:193], v[50:53]
	v_mfma_f32_16x16x32_bf16 v[38:41], v[174:177], v[198:201], v[38:41]
	v_mfma_f32_16x16x32_bf16 v[34:37], v[182:185], v[198:201], v[34:37]
	v_mfma_f32_16x16x32_bf16 v[22:25], v[174:177], v[206:209], v[22:25]
	v_mfma_f32_16x16x32_bf16 v[18:21], v[182:185], v[206:209], v[18:21]
	v_mfma_f32_16x16x32_bf16 v[6:9], v[174:177], v[214:217], v[6:9]
	v_mfma_f32_16x16x32_bf16 v[2:5], v[182:185], v[214:217], v[2:5]
	v_mfma_f32_16x16x32_bf16 v[54:57], v[178:181], v[194:197], v[54:57]
	v_mfma_f32_16x16x32_bf16 v[50:53], v[186:189], v[194:197], v[50:53]
	v_mfma_f32_16x16x32_bf16 v[38:41], v[178:181], v[202:205], v[38:41]
	v_mfma_f32_16x16x32_bf16 v[34:37], v[186:189], v[202:205], v[34:37]
	v_mfma_f32_16x16x32_bf16 v[22:25], v[178:181], v[210:213], v[22:25]
	v_mfma_f32_16x16x32_bf16 v[18:21], v[186:189], v[210:213], v[18:21]
	v_mfma_f32_16x16x32_bf16 v[6:9], v[178:181], v[218:221], v[6:9]
	v_mfma_f32_16x16x32_bf16 v[2:5], v[186:189], v[218:221], v[2:5]
	s_setprio 0
	s_barrier
	s_add_u32 s56, s56, 0x100
	s_addc_u32 s57, s57, 0
	s_add_u32 s26, s26, 0x100
	s_addc_u32 s27, s27, 0
	s_cmp_ge_i32 s68, s44
	s_mov_b32 s28, s68
	s_cbranch_scc0 .LBB0_1548

; #define PG8_STAGE(bufoff, gbase, voff) do { _Pragma("unroll") for (int _i = 0; _i < 2; ++_i) \
;         __builtin_amdgcn_global_load_lds((const unsigned*)((const char*)(gbase) + (voff)[_i]), (PG8_LAS unsigned*)(lds + (bufoff) + ldsw + _i * 8192), 16, 0, 0); } while (0)
; #define PG8_LDA(dst, b, h) do { _Pragma("unroll") for (int m = 0; m < 4; ++m) _Pragma("unroll") for (int k = 0; k < 2; ++k) dst[m][k] = *(const PG8_LAS bf16x8*)(lds + PG8_SA(b, h) + aoff + m * 2048 + k * 1024); } while (0)
; #define PG8_LDB(dst, b, h) do { _Pragma("unroll") for (int n = 0; n < 2; ++n) _Pragma("unroll") for (int k = 0; k < 2; ++k) dst[n][k] = *(const PG8_LAS bf16x8*)(lds + PG8_SB(b, h) + boff + n * 2048 + k * 1024); } while (0)
; #define PG8_MMA(ai, bj, At, Bt) do { __builtin_amdgcn_s_setprio(1); _Pragma("unroll") for (int m = 0; m < 4; ++m) _Pragma("unroll") for (int n = 0; n < 2; ++n) _Pragma("unroll") for (int k = 0; k < 2; ++k) \
;         acc[ai][bj][m][n] = __builtin_amdgcn_mfma_f32_16x16x32_bf16(Bt[n][k], At[m][k], acc[ai][bj][m][n], 0, 0, 0); __builtin_amdgcn_s_setprio(0); } while (0)
; #define PG8_WAIT_V(n) asm volatile("s_waitcnt vmcnt(" #n ")" ::: "memory")
; #define PG8_WAIT_L(n) asm volatile("s_waitcnt lgkmcnt(" #n ")" ::: "memory")
; #define PG8_BAR __builtin_amdgcn_s_barrier()
; #define PG8_SCHED __builtin_amdgcn_sched_barrier(0)
; template <class Epi, class Sched, bool ALIGN_EPI = false, bool SP2 = false>
; __device__ __forceinline__ void gemm_phase(PG8_LAS unsigned char* lds, const Gemm g, const Sched& S, const Epi& E) {
;     ...
;             const bool last = (t == nt - 2);
;             const char* a1 = cA + (size_t)(t + 1) * kstep;
;             const char* a2 = last ? nA : cA + (size_t)(t + 2) * kstep; const char* b2 = last ? nB : cB + (size_t)(t + 2) * kstep;
;             const char* a3 = a2 + kstep; const char* b3 = b2 + kstep;
;             if (last && has_next) S.a_ready(nxt);
;             if constexpr (SP2) {
;             PG8_LDB(B0, 0, 0); PG8_LDB(B1, 0, 1); PG8_SCHED; PG8_LDA(At, 0, 0); PG8_STAGE(PG8_SA(1, 1), a1 + hstep, voffA);
;             PG8_WAIT_V(8); PG8_WAIT_L(0); PG8_BAR; PG8_MMA(0, 0, At, B0); PG8_MMA(0, 1, At, B1); PG8_BAR; PG8_SCHED;
;             PG8_LDA(At, 0, 1); PG8_STAGE(PG8_SB(0, 0), b2, voffB); PG8_STAGE(PG8_SB(0, 1), b2 + hstep, voffB); PG8_STAGE(PG8_SA(0, 0), a2, voffA);
.LBB0_1724:
	ds_read_b128 v[148:151], v157
	ds_read_b128 v[152:155], v157 offset:1024
	ds_read_b128 v[160:163], v157 offset:2048
	ds_read_b128 v[164:167], v157 offset:3072
	ds_read_b128 v[168:171], v158
	ds_read_b128 v[172:175], v158 offset:1024
	ds_read_b128 v[176:179], v158 offset:2048
	ds_read_b128 v[180:183], v158 offset:3072
	s_add_i32 s80, s38, 2
	s_add_u32 s70, s36, 0x80
	s_addc_u32 s39, s37, 0
	s_cmp_eq_u32 s59, s38
	s_cselect_b32 s38, s4, s70
	s_cselect_b32 s39, s5, s39
	s_cselect_b32 s71, s35, s45
	s_cselect_b32 s70, s34, s44
	v_lshl_add_u64 v[216:217], s[36:37], 0, v[142:143]
	s_add_i32 m0, s48, 0xc000
	ds_read_b128 v[184:187], v159
	ds_read_b128 v[188:191], v159 offset:1024
	ds_read_b128 v[192:195], v159 offset:2048
	ds_read_b128 v[196:199], v159 offset:3072
	ds_read_b128 v[200:203], v159 offset:4096
	ds_read_b128 v[204:207], v159 offset:5120
	ds_read_b128 v[208:211], v159 offset:6144
	ds_read_b128 v[212:215], v159 offset:7168
	global_load_lds_dwordx4 v[216:217], off
	v_lshl_add_u64 v[216:217], s[36:37], 0, v[140:141]
	s_add_i32 m0, s48, 0xe000
	s_nop 0
	global_load_lds_dwordx4 v[216:217], off
	s_waitcnt vmcnt(8) lgkmcnt(0)
	s_barrier
	s_setprio 1
	v_mfma_f32_16x16x32_bf16 v[122:125], v[148:151], v[184:187], v[122:125]
	v_mfma_f32_16x16x32_bf16 v[126:129], v[160:163], v[184:187], v[126:129]
	v_mfma_f32_16x16x32_bf16 v[110:113], v[148:151], v[192:195], v[110:113]
	v_mfma_f32_16x16x32_bf16 v[106:109], v[160:163], v[192:195], v[106:109]
	v_mfma_f32_16x16x32_bf16 v[94:97], v[148:151], v[200:203], v[94:97]
	v_mfma_f32_16x16x32_bf16 v[90:93], v[160:163], v[200:203], v[90:93]
	v_mfma_f32_16x16x32_bf16 v[78:81], v[148:151], v[208:211], v[78:81]
	v_mfma_f32_16x16x32_bf16 v[74:77], v[160:163], v[208:211], v[74:77]
	v_mfma_f32_16x16x32_bf16 v[122:125], v[152:155], v[188:191], v[122:125]
	v_mfma_f32_16x16x32_bf16 v[126:129], v[164:167], v[188:191], v[126:129]
	v_mfma_f32_16x16x32_bf16 v[110:113], v[152:155], v[196:199], v[110:113]
	v_mfma_f32_16x16x32_bf16 v[106:109], v[164:167], v[196:199], v[106:109]
	v_mfma_f32_16x16x32_bf16 v[94:97], v[152:155], v[204:207], v[94:97]
	v_mfma_f32_16x16x32_bf16 v[90:93], v[164:167], v[204:207], v[90:93]
	v_mfma_f32_16x16x32_bf16 v[78:81], v[152:155], v[212:215], v[78:81]
	v_mfma_f32_16x16x32_bf16 v[74:77], v[164:167], v[212:215], v[74:77]
	v_mfma_f32_16x16x32_bf16 v[118:121], v[168:171], v[184:187], v[118:121]
	v_mfma_f32_16x16x32_bf16 v[114:117], v[176:179], v[184:187], v[114:117]
	v_mfma_f32_16x16x32_bf16 v[102:105], v[168:171], v[192:195], v[102:105]
	v_mfma_f32_16x16x32_bf16 v[98:101], v[176:179], v[192:195], v[98:101]
	v_mfma_f32_16x16x32_bf16 v[86:89], v[168:171], v[200:203], v[86:89]
	v_mfma_f32_16x16x32_bf16 v[82:85], v[176:179], v[200:203], v[82:85]
	v_mfma_f32_16x16x32_bf16 v[70:73], v[168:171], v[208:211], v[70:73]
	v_mfma_f32_16x16x32_bf16 v[66:69], v[176:179], v[208:211], v[66:69]
	v_mfma_f32_16x16x32_bf16 v[118:121], v[172:175], v[188:191], v[118:121]
	v_mfma_f32_16x16x32_bf16 v[114:117], v[180:183], v[188:191], v[114:117]
	v_mfma_f32_16x16x32_bf16 v[102:105], v[172:175], v[196:199], v[102:105]
	v_mfma_f32_16x16x32_bf16 v[98:101], v[180:183], v[196:199], v[98:101]
	v_mfma_f32_16x16x32_bf16 v[86:89], v[172:175], v[204:207], v[86:89]
	v_mfma_f32_16x16x32_bf16 v[82:85], v[180:183], v[204:207], v[82:85]
	v_mfma_f32_16x16x32_bf16 v[70:73], v[172:175], v[212:215], v[70:73]
	v_mfma_f32_16x16x32_bf16 v[66:69], v[180:183], v[212:215], v[66:69]
	s_setprio 0
	s_barrier
	s_add_i32 s72, s62, s47
	v_lshl_add_u64 v[216:217], s[70:71], 0, v[134:135]
	s_mov_b32 m0, s72
	ds_read_b128 v[184:187], v159 offset:16384
	ds_read_b128 v[188:191], v159 offset:17408
	ds_read_b128 v[192:195], v159 offset:18432
	ds_read_b128 v[196:199], v159 offset:19456
	ds_read_b128 v[200:203], v159 offset:20480
	ds_read_b128 v[204:207], v159 offset:21504
	ds_read_b128 v[208:211], v159 offset:22528
	ds_read_b128 v[212:215], v159 offset:23552
	global_load_lds_dwordx4 v[216:217], off
	s_add_i32 m0, s72, 0x2000
	v_lshl_add_u64 v[218:219], s[70:71], 0, v[138:139]
	s_add_u32 s70, s70, s8
	s_addc_u32 s71, s71, s9
	s_add_i32 s72, s63, s47
	global_load_lds_dwordx4 v[218:219], off
	v_lshl_add_u64 v[220:221], s[70:71], 0, v[134:135]
	s_mov_b32 m0, s72
	v_lshl_add_u64 v[222:223], s[70:71], 0, v[138:139]
	global_load_lds_dwordx4 v[220:221], off
	s_add_i32 m0, s72, 0x2000
	v_lshl_add_u64 v[224:225], s[38:39], 0, v[132:133]
	global_load_lds_dwordx4 v[222:223], off
	s_mov_b32 m0, s48
	v_lshl_add_u64 v[226:227], s[38:39], 0, v[136:137]
	global_load_lds_dwordx4 v[224:225], off
	s_mov_b32 m0, s49
	s_nop 0
	global_load_lds_dwordx4 v[226:227], off
	s_waitcnt vmcnt(8) lgkmcnt(0)
	s_barrier
; #define PG8_STAGE(bufoff, gbase, voff) do { _Pragma("unroll") for (int _i = 0; _i < 2; ++_i) \
;         __builtin_amdgcn_global_load_lds((const unsigned*)((const char*)(gbase) + (voff)[_i]), (PG8_LAS unsigned*)(lds + (bufoff) + ldsw + _i * 8192), 16, 0, 0); } while (0)
; #define PG8_LDA(dst, b, h) do { _Pragma("unroll") for (int m = 0; m < 4; ++m) _Pragma("unroll") for (int k = 0; k < 2; ++k) dst[m][k] = *(const PG8_LAS bf16x8*)(lds + PG8_SA(b, h) + aoff + m * 2048 + k * 1024); } while (0)
; #define PG8_LDB(dst, b, h) do { _Pragma("unroll") for (int n = 0; n < 2; ++n) _Pragma("unroll") for (int k = 0; k < 2; ++k) dst[n][k] = *(const PG8_LAS bf16x8*)(lds + PG8_SB(b, h) + boff + n * 2048 + k * 1024); } while (0)
; #define PG8_MMA(ai, bj, At, Bt) do { __builtin_amdgcn_s_setprio(1); _Pragma("unroll") for (int m = 0; m < 4; ++m) _Pragma("unroll") for (int n = 0; n < 2; ++n) _Pragma("unroll") for (int k = 0; k < 2; ++k) \
;         acc[ai][bj][m][n] = __builtin_amdgcn_mfma_f32_16x16x32_bf16(Bt[n][k], At[m][k], acc[ai][bj][m][n], 0, 0, 0); __builtin_amdgcn_s_setprio(0); } while (0)
; #define PG8_WAIT_V(n) asm volatile("s_waitcnt vmcnt(" #n ")" ::: "memory")
; #define PG8_WAIT_L(n) asm volatile("s_waitcnt lgkmcnt(" #n ")" ::: "memory")
; #define PG8_BAR __builtin_amdgcn_s_barrier()
; #define PG8_SCHED __builtin_amdgcn_sched_barrier(0)
; template <class Epi, class Sched, bool ALIGN_EPI = false, bool SP2 = false>
; __device__ __forceinline__ void gemm_phase(PG8_LAS unsigned char* lds, const Gemm g, const Sched& S, const Epi& E) {
;     ...
;             PG8_WAIT_V(8); PG8_WAIT_L(0); PG8_BAR; PG8_MMA(1, 0, At, B0); PG8_MMA(1, 1, At, B1); PG8_BAR; PG8_SCHED;
;             PG8_LDB(B0, 1, 0); PG8_LDB(B1, 1, 1); PG8_SCHED; PG8_LDA(At, 1, 0); PG8_STAGE(PG8_SA(0, 1), a2 + hstep, voffA);
;             PG8_WAIT_V(8); PG8_WAIT_L(0); PG8_BAR; PG8_MMA(0, 0, At, B0); PG8_MMA(0, 1, At, B1); PG8_BAR; PG8_SCHED;
	s_setprio 1
	v_mfma_f32_16x16x32_bf16 v[62:65], v[148:151], v[184:187], v[62:65]
	v_mfma_f32_16x16x32_bf16 v[58:61], v[160:163], v[184:187], v[58:61]
	v_mfma_f32_16x16x32_bf16 v[46:49], v[148:151], v[192:195], v[46:49]
	v_mfma_f32_16x16x32_bf16 v[42:45], v[160:163], v[192:195], v[42:45]
	v_mfma_f32_16x16x32_bf16 v[30:33], v[148:151], v[200:203], v[30:33]
	v_mfma_f32_16x16x32_bf16 v[26:29], v[160:163], v[200:203], v[26:29]
	v_mfma_f32_16x16x32_bf16 v[14:17], v[148:151], v[208:211], v[14:17]
	v_mfma_f32_16x16x32_bf16 v[10:13], v[160:163], v[208:211], v[10:13]
	v_mfma_f32_16x16x32_bf16 v[62:65], v[152:155], v[188:191], v[62:65]
	v_mfma_f32_16x16x32_bf16 v[58:61], v[164:167], v[188:191], v[58:61]
	v_mfma_f32_16x16x32_bf16 v[46:49], v[152:155], v[196:199], v[46:49]
	v_mfma_f32_16x16x32_bf16 v[42:45], v[164:167], v[196:199], v[42:45]
	v_mfma_f32_16x16x32_bf16 v[30:33], v[152:155], v[204:207], v[30:33]
	v_mfma_f32_16x16x32_bf16 v[26:29], v[164:167], v[204:207], v[26:29]
	v_mfma_f32_16x16x32_bf16 v[14:17], v[152:155], v[212:215], v[14:17]
	v_mfma_f32_16x16x32_bf16 v[10:13], v[164:167], v[212:215], v[10:13]
	v_mfma_f32_16x16x32_bf16 v[54:57], v[168:171], v[184:187], v[54:57]
	v_mfma_f32_16x16x32_bf16 v[50:53], v[176:179], v[184:187], v[50:53]
	v_mfma_f32_16x16x32_bf16 v[38:41], v[168:171], v[192:195], v[38:41]
	v_mfma_f32_16x16x32_bf16 v[34:37], v[176:179], v[192:195], v[34:37]
	v_mfma_f32_16x16x32_bf16 v[22:25], v[168:171], v[200:203], v[22:25]
	v_mfma_f32_16x16x32_bf16 v[18:21], v[176:179], v[200:203], v[18:21]
	v_mfma_f32_16x16x32_bf16 v[6:9], v[168:171], v[208:211], v[6:9]
	v_mfma_f32_16x16x32_bf16 v[2:5], v[176:179], v[208:211], v[2:5]
	v_mfma_f32_16x16x32_bf16 v[54:57], v[172:175], v[188:191], v[54:57]
	v_mfma_f32_16x16x32_bf16 v[50:53], v[180:183], v[188:191], v[50:53]
	v_mfma_f32_16x16x32_bf16 v[38:41], v[172:175], v[196:199], v[38:41]
	v_mfma_f32_16x16x32_bf16 v[34:37], v[180:183], v[196:199], v[34:37]
	v_mfma_f32_16x16x32_bf16 v[22:25], v[172:175], v[204:207], v[22:25]
	v_mfma_f32_16x16x32_bf16 v[18:21], v[180:183], v[204:207], v[18:21]
	v_mfma_f32_16x16x32_bf16 v[6:9], v[172:175], v[212:215], v[6:9]
	v_mfma_f32_16x16x32_bf16 v[2:5], v[180:183], v[212:215], v[2:5]
	s_setprio 0
	s_barrier
	s_add_i32 s70, 0, 0x18000
	s_add_i32 s71, 0, 0x1c000
	v_add_u32_e32 v164, s70, v156
	v_add_u32_e32 v180, s71, v156
	ds_read_b128 v[148:151], v164
	ds_read_b128 v[152:155], v164 offset:1024
	ds_read_b128 v[160:163], v164 offset:2048
	ds_read_b128 v[164:167], v164 offset:3072
	ds_read_b128 v[168:171], v180
	ds_read_b128 v[172:175], v180 offset:1024
	ds_read_b128 v[176:179], v180 offset:2048
	ds_read_b128 v[180:183], v180 offset:3072
	s_add_u32 s38, s38, s8
	s_addc_u32 s39, s39, s9
	s_mov_b32 m0, s52
	v_lshl_add_u64 v[228:229], s[38:39], 0, v[132:133]
	ds_read_b128 v[184:187], v159 offset:32768
	ds_read_b128 v[188:191], v159 offset:33792
	ds_read_b128 v[192:195], v159 offset:34816
	ds_read_b128 v[196:199], v159 offset:35840
	ds_read_b128 v[200:203], v159 offset:36864
	ds_read_b128 v[204:207], v159 offset:37888
	ds_read_b128 v[208:211], v159 offset:38912
	ds_read_b128 v[212:215], v159 offset:39936
	global_load_lds_dwordx4 v[228:229], off
	v_lshl_add_u64 v[228:229], s[38:39], 0, v[136:137]
	s_mov_b32 m0, s53
	s_nop 0
	global_load_lds_dwordx4 v[228:229], off
	s_waitcnt vmcnt(8) lgkmcnt(0)
	s_barrier
	s_setprio 1
	v_mfma_f32_16x16x32_bf16 v[122:125], v[148:151], v[184:187], v[122:125]
	v_mfma_f32_16x16x32_bf16 v[126:129], v[160:163], v[184:187], v[126:129]
	v_mfma_f32_16x16x32_bf16 v[110:113], v[148:151], v[192:195], v[110:113]
	v_mfma_f32_16x16x32_bf16 v[106:109], v[160:163], v[192:195], v[106:109]
	v_mfma_f32_16x16x32_bf16 v[94:97], v[148:151], v[200:203], v[94:97]
	v_mfma_f32_16x16x32_bf16 v[90:93], v[160:163], v[200:203], v[90:93]
	v_mfma_f32_16x16x32_bf16 v[78:81], v[148:151], v[208:211], v[78:81]
	v_mfma_f32_16x16x32_bf16 v[74:77], v[160:163], v[208:211], v[74:77]
	v_mfma_f32_16x16x32_bf16 v[122:125], v[152:155], v[188:191], v[122:125]
	v_mfma_f32_16x16x32_bf16 v[126:129], v[164:167], v[188:191], v[126:129]
	v_mfma_f32_16x16x32_bf16 v[110:113], v[152:155], v[196:199], v[110:113]
	v_mfma_f32_16x16x32_bf16 v[106:109], v[164:167], v[196:199], v[106:109]
	v_mfma_f32_16x16x32_bf16 v[94:97], v[152:155], v[204:207], v[94:97]
	v_mfma_f32_16x16x32_bf16 v[90:93], v[164:167], v[204:207], v[90:93]
	v_mfma_f32_16x16x32_bf16 v[78:81], v[152:155], v[212:215], v[78:81]
	v_mfma_f32_16x16x32_bf16 v[74:77], v[164:167], v[212:215], v[74:77]
	v_mfma_f32_16x16x32_bf16 v[118:121], v[168:171], v[184:187], v[118:121]
	v_mfma_f32_16x16x32_bf16 v[114:117], v[176:179], v[184:187], v[114:117]
	v_mfma_f32_16x16x32_bf16 v[102:105], v[168:171], v[192:195], v[102:105]
	v_mfma_f32_16x16x32_bf16 v[98:101], v[176:179], v[192:195], v[98:101]
	v_mfma_f32_16x16x32_bf16 v[86:89], v[168:171], v[200:203], v[86:89]
	v_mfma_f32_16x16x32_bf16 v[82:85], v[176:179], v[200:203], v[82:85]
	v_mfma_f32_16x16x32_bf16 v[70:73], v[168:171], v[208:211], v[70:73]
	v_mfma_f32_16x16x32_bf16 v[66:69], v[176:179], v[208:211], v[66:69]
	v_mfma_f32_16x16x32_bf16 v[118:121], v[172:175], v[188:191], v[118:121]
	v_mfma_f32_16x16x32_bf16 v[114:117], v[180:183], v[188:191], v[114:117]
	v_mfma_f32_16x16x32_bf16 v[102:105], v[172:175], v[196:199], v[102:105]
	v_mfma_f32_16x16x32_bf16 v[98:101], v[180:183], v[196:199], v[98:101]
	v_mfma_f32_16x16x32_bf16 v[86:89], v[172:175], v[204:207], v[86:89]
	v_mfma_f32_16x16x32_bf16 v[82:85], v[180:183], v[204:207], v[82:85]
	v_mfma_f32_16x16x32_bf16 v[70:73], v[172:175], v[212:215], v[70:73]
	v_mfma_f32_16x16x32_bf16 v[66:69], v[180:183], v[212:215], v[66:69]
	s_setprio 0
	s_barrier
; #define PG8_STAGE(bufoff, gbase, voff) do { _Pragma("unroll") for (int _i = 0; _i < 2; ++_i) \
;         __builtin_amdgcn_global_load_lds((const unsigned*)((const char*)(gbase) + (voff)[_i]), (PG8_LAS unsigned*)(lds + (bufoff) + ldsw + _i * 8192), 16, 0, 0); } while (0)
; #define PG8_LDA(dst, b, h) do { _Pragma("unroll") for (int m = 0; m < 4; ++m) _Pragma("unroll") for (int k = 0; k < 2; ++k) dst[m][k] = *(const PG8_LAS bf16x8*)(lds + PG8_SA(b, h) + aoff + m * 2048 + k * 1024); } while (0)
; #define PG8_MMA(ai, bj, At, Bt) do { __builtin_amdgcn_s_setprio(1); _Pragma("unroll") for (int m = 0; m < 4; ++m) _Pragma("unroll") for (int n = 0; n < 2; ++n) _Pragma("unroll") for (int k = 0; k < 2; ++k) \
;         acc[ai][bj][m][n] = __builtin_amdgcn_mfma_f32_16x16x32_bf16(Bt[n][k], At[m][k], acc[ai][bj][m][n], 0, 0, 0); __builtin_amdgcn_s_setprio(0); } while (0)
; #define PG8_WAIT_V(n) asm volatile("s_waitcnt vmcnt(" #n ")" ::: "memory")
; #define PG8_WAIT_L(n) asm volatile("s_waitcnt lgkmcnt(" #n ")" ::: "memory")
; #define PG8_BAR __builtin_amdgcn_s_barrier()
; #define PG8_SCHED __builtin_amdgcn_sched_barrier(0)
; template <class Epi, class Sched, bool ALIGN_EPI = false, bool SP2 = false>
; __device__ __forceinline__ void gemm_phase(PG8_LAS unsigned char* lds, const Gemm g, const Sched& S, const Epi& E) {
;     ...
;             PG8_LDA(At, 1, 1); PG8_STAGE(PG8_SB(1, 0), b3, voffB); PG8_STAGE(PG8_SB(1, 1), b3 + hstep, voffB); PG8_STAGE(PG8_SA(1, 0), a3, voffA);
;             PG8_WAIT_V(8); PG8_WAIT_L(0); PG8_BAR; PG8_MMA(1, 0, At, B0); PG8_MMA(1, 1, At, B1); PG8_BAR; PG8_SCHED;
	s_add_i32 s38, s70, s47
	v_lshl_add_u64 v[216:217], v[216:217], 0, s[24:25]
	s_mov_b32 m0, s38
	ds_read_b128 v[184:187], v159 offset:49152
	ds_read_b128 v[188:191], v159 offset:50176
	ds_read_b128 v[192:195], v159 offset:51200
	ds_read_b128 v[196:199], v159 offset:52224
	ds_read_b128 v[200:203], v159 offset:53248
	ds_read_b128 v[204:207], v159 offset:54272
	ds_read_b128 v[208:211], v159 offset:55296
	ds_read_b128 v[212:215], v159 offset:56320
	global_load_lds_dwordx4 v[216:217], off
	v_lshl_add_u64 v[216:217], v[218:219], 0, s[24:25]
	s_add_i32 m0, s38, 0x2000
	s_add_i32 s38, s71, s47
	global_load_lds_dwordx4 v[216:217], off
	v_lshl_add_u64 v[216:217], v[220:221], 0, s[24:25]
	s_mov_b32 m0, s38
	s_nop 0
	global_load_lds_dwordx4 v[216:217], off
	v_lshl_add_u64 v[216:217], v[222:223], 0, s[24:25]
	s_add_i32 m0, s38, 0x2000
	s_nop 0
	global_load_lds_dwordx4 v[216:217], off
	v_lshl_add_u64 v[216:217], v[224:225], 0, s[24:25]
	s_mov_b32 m0, s55
	s_nop 0
	global_load_lds_dwordx4 v[216:217], off
	v_lshl_add_u64 v[216:217], v[226:227], 0, s[24:25]
	s_mov_b32 m0, s56
	s_nop 0
	global_load_lds_dwordx4 v[216:217], off
	s_waitcnt vmcnt(8) lgkmcnt(0)
	s_barrier
	s_setprio 1
	v_mfma_f32_16x16x32_bf16 v[62:65], v[148:151], v[184:187], v[62:65]
	v_mfma_f32_16x16x32_bf16 v[58:61], v[160:163], v[184:187], v[58:61]
	v_mfma_f32_16x16x32_bf16 v[46:49], v[148:151], v[192:195], v[46:49]
	v_mfma_f32_16x16x32_bf16 v[42:45], v[160:163], v[192:195], v[42:45]
	v_mfma_f32_16x16x32_bf16 v[30:33], v[148:151], v[200:203], v[30:33]
	v_mfma_f32_16x16x32_bf16 v[26:29], v[160:163], v[200:203], v[26:29]
	v_mfma_f32_16x16x32_bf16 v[14:17], v[148:151], v[208:211], v[14:17]
	v_mfma_f32_16x16x32_bf16 v[10:13], v[160:163], v[208:211], v[10:13]
	v_mfma_f32_16x16x32_bf16 v[62:65], v[152:155], v[188:191], v[62:65]
	v_mfma_f32_16x16x32_bf16 v[58:61], v[164:167], v[188:191], v[58:61]
	v_mfma_f32_16x16x32_bf16 v[46:49], v[152:155], v[196:199], v[46:49]
	v_mfma_f32_16x16x32_bf16 v[42:45], v[164:167], v[196:199], v[42:45]
	v_mfma_f32_16x16x32_bf16 v[30:33], v[152:155], v[204:207], v[30:33]
	v_mfma_f32_16x16x32_bf16 v[26:29], v[164:167], v[204:207], v[26:29]
	v_mfma_f32_16x16x32_bf16 v[14:17], v[152:155], v[212:215], v[14:17]
	v_mfma_f32_16x16x32_bf16 v[10:13], v[164:167], v[212:215], v[10:13]
	v_mfma_f32_16x16x32_bf16 v[54:57], v[168:171], v[184:187], v[54:57]
	v_mfma_f32_16x16x32_bf16 v[50:53], v[176:179], v[184:187], v[50:53]
	v_mfma_f32_16x16x32_bf16 v[38:41], v[168:171], v[192:195], v[38:41]
	v_mfma_f32_16x16x32_bf16 v[34:37], v[176:179], v[192:195], v[34:37]
	v_mfma_f32_16x16x32_bf16 v[22:25], v[168:171], v[200:203], v[22:25]
	v_mfma_f32_16x16x32_bf16 v[18:21], v[176:179], v[200:203], v[18:21]
	v_mfma_f32_16x16x32_bf16 v[6:9], v[168:171], v[208:211], v[6:9]
	v_mfma_f32_16x16x32_bf16 v[2:5], v[176:179], v[208:211], v[2:5]
	v_mfma_f32_16x16x32_bf16 v[54:57], v[172:175], v[188:191], v[54:57]
	v_mfma_f32_16x16x32_bf16 v[50:53], v[180:183], v[188:191], v[50:53]
	v_mfma_f32_16x16x32_bf16 v[38:41], v[172:175], v[196:199], v[38:41]
	v_mfma_f32_16x16x32_bf16 v[34:37], v[180:183], v[196:199], v[34:37]
	v_mfma_f32_16x16x32_bf16 v[22:25], v[172:175], v[204:207], v[22:25]
	v_mfma_f32_16x16x32_bf16 v[18:21], v[180:183], v[204:207], v[18:21]
	v_mfma_f32_16x16x32_bf16 v[6:9], v[172:175], v[212:215], v[6:9]
	v_mfma_f32_16x16x32_bf16 v[2:5], v[180:183], v[212:215], v[2:5]
	s_setprio 0
	s_barrier
	s_add_u32 s44, s44, 0x100
	s_addc_u32 s45, s45, 0
	s_add_u32 s36, s36, 0x100
	s_addc_u32 s37, s37, 0
	s_cmp_ge_i32 s80, s57
	s_mov_b32 s38, s80
	s_cbranch_scc0 .LBB0_1724

; #define PG8_STAGE(bufoff, gbase, voff) do { _Pragma("unroll") for (int _i = 0; _i < 2; ++_i) \
;         __builtin_amdgcn_global_load_lds((const unsigned*)((const char*)(gbase) + (voff)[_i]), (PG8_LAS unsigned*)(lds + (bufoff) + ldsw + _i * 8192), 16, 0, 0); } while (0)
; #define PG8_LDA(dst, b, h) do { _Pragma("unroll") for (int m = 0; m < 4; ++m) _Pragma("unroll") for (int k = 0; k < 2; ++k) dst[m][k] = *(const PG8_LAS bf16x8*)(lds + PG8_SA(b, h) + aoff + m * 2048 + k * 1024); } while (0)
; #define PG8_LDB(dst, b, h) do { _Pragma("unroll") for (int n = 0; n < 2; ++n) _Pragma("unroll") for (int k = 0; k < 2; ++k) dst[n][k] = *(const PG8_LAS bf16x8*)(lds + PG8_SB(b, h) + boff + n * 2048 + k * 1024); } while (0)
; #define PG8_MMA(ai, bj, At, Bt) do { __builtin_amdgcn_s_setprio(1); _Pragma("unroll") for (int m = 0; m < 4; ++m) _Pragma("unroll") for (int n = 0; n < 2; ++n) _Pragma("unroll") for (int k = 0; k < 2; ++k) \
;         acc[ai][bj][m][n] = __builtin_amdgcn_mfma_f32_16x16x32_bf16(Bt[n][k], At[m][k], acc[ai][bj][m][n], 0, 0, 0); __builtin_amdgcn_s_setprio(0); } while (0)
; #define PG8_WAIT_V(n) asm volatile("s_waitcnt vmcnt(" #n ")" ::: "memory")
; #define PG8_WAIT_L(n) asm volatile("s_waitcnt lgkmcnt(" #n ")" ::: "memory")
; #define PG8_BAR __builtin_amdgcn_s_barrier()
; #define PG8_SCHED __builtin_amdgcn_sched_barrier(0)
; template <class Epi, class Sched, bool ALIGN_EPI = false, bool SP2 = false>
; __device__ __forceinline__ void gemm_phase(PG8_LAS unsigned char* lds, const Gemm g, const Sched& S, const Epi& E) {
;     ...
;             const bool last = (t == nt - 2);
;             const char* a1 = cA + (size_t)(t + 1) * kstep;
;             const char* a2 = last ? nA : cA + (size_t)(t + 2) * kstep; const char* b2 = last ? nB : cB + (size_t)(t + 2) * kstep;
;             const char* a3 = a2 + kstep; const char* b3 = b2 + kstep;
;             if (last && has_next) S.a_ready(nxt);
;             if constexpr (SP2) {
;             PG8_LDB(B0, 0, 0); PG8_LDB(B1, 0, 1); PG8_SCHED; PG8_LDA(At, 0, 0); PG8_STAGE(PG8_SA(1, 1), a1 + hstep, voffA);
;             PG8_WAIT_V(8); PG8_WAIT_L(0); PG8_BAR; PG8_MMA(0, 0, At, B0); PG8_MMA(0, 1, At, B1); PG8_BAR; PG8_SCHED;
;             PG8_LDA(At, 0, 1); PG8_STAGE(PG8_SB(0, 0), b2, voffB); PG8_STAGE(PG8_SB(0, 1), b2 + hstep, voffB); PG8_STAGE(PG8_SA(0, 0), a2, voffA);
.LBB0_1809:
	ds_read_b128 v[152:155], v148
	ds_read_b128 v[156:159], v148 offset:1024
	ds_read_b128 v[160:163], v148 offset:2048
	ds_read_b128 v[164:167], v148 offset:3072
	ds_read_b128 v[168:171], v149
	ds_read_b128 v[172:175], v149 offset:1024
	ds_read_b128 v[176:179], v149 offset:2048
	ds_read_b128 v[180:183], v149 offset:3072
	s_add_i32 s56, s26, 2
	s_add_u32 s57, s24, 0x80
	s_addc_u32 s27, s25, 0
	s_cmp_eq_u32 s43, s26
	s_cselect_b32 s26, s4, s57
	s_cselect_b32 s27, s5, s27
	s_cselect_b32 s59, s23, s55
	s_cselect_b32 s58, s22, s54
	v_lshl_add_u64 v[216:217], s[24:25], 0, v[140:141]
	s_add_i32 m0, s35, 0xc000
	ds_read_b128 v[184:187], v150
	ds_read_b128 v[188:191], v150 offset:1024
	ds_read_b128 v[192:195], v150 offset:2048
	ds_read_b128 v[196:199], v150 offset:3072
	ds_read_b128 v[200:203], v150 offset:4096
	ds_read_b128 v[204:207], v150 offset:5120
	ds_read_b128 v[208:211], v150 offset:6144
	ds_read_b128 v[212:215], v150 offset:7168
	global_load_lds_dwordx4 v[216:217], off
	v_lshl_add_u64 v[216:217], s[24:25], 0, v[138:139]
	s_add_i32 m0, s35, 0xe000
	s_nop 0
	global_load_lds_dwordx4 v[216:217], off
	s_waitcnt vmcnt(8) lgkmcnt(0)
	s_barrier
	s_setprio 1
	v_mfma_f32_16x16x32_bf16 v[122:125], v[152:155], v[184:187], v[122:125]
	v_mfma_f32_16x16x32_bf16 v[126:129], v[160:163], v[184:187], v[126:129]
	v_mfma_f32_16x16x32_bf16 v[110:113], v[152:155], v[192:195], v[110:113]
	v_mfma_f32_16x16x32_bf16 v[106:109], v[160:163], v[192:195], v[106:109]
	v_mfma_f32_16x16x32_bf16 v[94:97], v[152:155], v[200:203], v[94:97]
	v_mfma_f32_16x16x32_bf16 v[90:93], v[160:163], v[200:203], v[90:93]
	v_mfma_f32_16x16x32_bf16 v[78:81], v[152:155], v[208:211], v[78:81]
	v_mfma_f32_16x16x32_bf16 v[74:77], v[160:163], v[208:211], v[74:77]
	v_mfma_f32_16x16x32_bf16 v[122:125], v[156:159], v[188:191], v[122:125]
	v_mfma_f32_16x16x32_bf16 v[126:129], v[164:167], v[188:191], v[126:129]
	v_mfma_f32_16x16x32_bf16 v[110:113], v[156:159], v[196:199], v[110:113]
	v_mfma_f32_16x16x32_bf16 v[106:109], v[164:167], v[196:199], v[106:109]
	v_mfma_f32_16x16x32_bf16 v[94:97], v[156:159], v[204:207], v[94:97]
	v_mfma_f32_16x16x32_bf16 v[90:93], v[164:167], v[204:207], v[90:93]
	v_mfma_f32_16x16x32_bf16 v[78:81], v[156:159], v[212:215], v[78:81]
	v_mfma_f32_16x16x32_bf16 v[74:77], v[164:167], v[212:215], v[74:77]
	v_mfma_f32_16x16x32_bf16 v[118:121], v[168:171], v[184:187], v[118:121]
	v_mfma_f32_16x16x32_bf16 v[114:117], v[176:179], v[184:187], v[114:117]
	v_mfma_f32_16x16x32_bf16 v[102:105], v[168:171], v[192:195], v[102:105]
	v_mfma_f32_16x16x32_bf16 v[98:101], v[176:179], v[192:195], v[98:101]
	v_mfma_f32_16x16x32_bf16 v[86:89], v[168:171], v[200:203], v[86:89]
	v_mfma_f32_16x16x32_bf16 v[82:85], v[176:179], v[200:203], v[82:85]
	v_mfma_f32_16x16x32_bf16 v[70:73], v[168:171], v[208:211], v[70:73]
	v_mfma_f32_16x16x32_bf16 v[66:69], v[176:179], v[208:211], v[66:69]
	v_mfma_f32_16x16x32_bf16 v[118:121], v[172:175], v[188:191], v[118:121]
	v_mfma_f32_16x16x32_bf16 v[114:117], v[180:183], v[188:191], v[114:117]
	v_mfma_f32_16x16x32_bf16 v[102:105], v[172:175], v[196:199], v[102:105]
	v_mfma_f32_16x16x32_bf16 v[98:101], v[180:183], v[196:199], v[98:101]
	v_mfma_f32_16x16x32_bf16 v[86:89], v[172:175], v[204:207], v[86:89]
	v_mfma_f32_16x16x32_bf16 v[82:85], v[180:183], v[204:207], v[82:85]
	v_mfma_f32_16x16x32_bf16 v[70:73], v[172:175], v[212:215], v[70:73]
	v_mfma_f32_16x16x32_bf16 v[66:69], v[180:183], v[212:215], v[66:69]
	s_setprio 0
	s_barrier
	s_add_i32 s57, s46, s34
	v_lshl_add_u64 v[216:217], s[58:59], 0, v[132:133]
	s_mov_b32 m0, s57
	ds_read_b128 v[184:187], v150 offset:16384
	ds_read_b128 v[188:191], v150 offset:17408
	ds_read_b128 v[192:195], v150 offset:18432
	ds_read_b128 v[196:199], v150 offset:19456
	ds_read_b128 v[200:203], v150 offset:20480
	ds_read_b128 v[204:207], v150 offset:21504
	ds_read_b128 v[208:211], v150 offset:22528
	ds_read_b128 v[212:215], v150 offset:23552
	global_load_lds_dwordx4 v[216:217], off
	s_add_i32 m0, s57, 0x2000
	v_lshl_add_u64 v[218:219], s[58:59], 0, v[136:137]
	s_add_u32 s58, s58, s8
	s_addc_u32 s59, s59, s9
	s_add_i32 s57, s47, s34
	global_load_lds_dwordx4 v[218:219], off
	v_lshl_add_u64 v[220:221], s[58:59], 0, v[132:133]
	s_mov_b32 m0, s57
	v_lshl_add_u64 v[222:223], s[58:59], 0, v[136:137]
	global_load_lds_dwordx4 v[220:221], off
	s_add_i32 m0, s57, 0x2000
	v_lshl_add_u64 v[224:225], s[26:27], 0, v[130:131]
	global_load_lds_dwordx4 v[222:223], off
	s_mov_b32 m0, s35
	v_lshl_add_u64 v[226:227], s[26:27], 0, v[134:135]
	global_load_lds_dwordx4 v[224:225], off
	s_mov_b32 m0, s36
	s_nop 0
	global_load_lds_dwordx4 v[226:227], off
	s_waitcnt vmcnt(8) lgkmcnt(0)
	s_barrier
; #define PG8_STAGE(bufoff, gbase, voff) do { _Pragma("unroll") for (int _i = 0; _i < 2; ++_i) \
;         __builtin_amdgcn_global_load_lds((const unsigned*)((const char*)(gbase) + (voff)[_i]), (PG8_LAS unsigned*)(lds + (bufoff) + ldsw + _i * 8192), 16, 0, 0); } while (0)
; #define PG8_LDA(dst, b, h) do { _Pragma("unroll") for (int m = 0; m < 4; ++m) _Pragma("unroll") for (int k = 0; k < 2; ++k) dst[m][k] = *(const PG8_LAS bf16x8*)(lds + PG8_SA(b, h) + aoff + m * 2048 + k * 1024); } while (0)
; #define PG8_LDB(dst, b, h) do { _Pragma("unroll") for (int n = 0; n < 2; ++n) _Pragma("unroll") for (int k = 0; k < 2; ++k) dst[n][k] = *(const PG8_LAS bf16x8*)(lds + PG8_SB(b, h) + boff + n * 2048 + k * 1024); } while (0)
; #define PG8_MMA(ai, bj, At, Bt) do { __builtin_amdgcn_s_setprio(1); _Pragma("unroll") for (int m = 0; m < 4; ++m) _Pragma("unroll") for (int n = 0; n < 2; ++n) _Pragma("unroll") for (int k = 0; k < 2; ++k) \
;         acc[ai][bj][m][n] = __builtin_amdgcn_mfma_f32_16x16x32_bf16(Bt[n][k], At[m][k], acc[ai][bj][m][n], 0, 0, 0); __builtin_amdgcn_s_setprio(0); } while (0)
; #define PG8_WAIT_V(n) asm volatile("s_waitcnt vmcnt(" #n ")" ::: "memory")
; #define PG8_WAIT_L(n) asm volatile("s_waitcnt lgkmcnt(" #n ")" ::: "memory")
; #define PG8_BAR __builtin_amdgcn_s_barrier()
; #define PG8_SCHED __builtin_amdgcn_sched_barrier(0)
; template <class Epi, class Sched, bool ALIGN_EPI = false, bool SP2 = false>
; __device__ __forceinline__ void gemm_phase(PG8_LAS unsigned char* lds, const Gemm g, const Sched& S, const Epi& E) {
;     ...
;             PG8_WAIT_V(8); PG8_WAIT_L(0); PG8_BAR; PG8_MMA(1, 0, At, B0); PG8_MMA(1, 1, At, B1); PG8_BAR; PG8_SCHED;
;             PG8_LDB(B0, 1, 0); PG8_LDB(B1, 1, 1); PG8_SCHED; PG8_LDA(At, 1, 0); PG8_STAGE(PG8_SA(0, 1), a2 + hstep, voffA);
;             PG8_WAIT_V(8); PG8_WAIT_L(0); PG8_BAR; PG8_MMA(0, 0, At, B0); PG8_MMA(0, 1, At, B1); PG8_BAR; PG8_SCHED;
	s_setprio 1
	v_mfma_f32_16x16x32_bf16 v[62:65], v[152:155], v[184:187], v[62:65]
	v_mfma_f32_16x16x32_bf16 v[58:61], v[160:163], v[184:187], v[58:61]
	v_mfma_f32_16x16x32_bf16 v[46:49], v[152:155], v[192:195], v[46:49]
	v_mfma_f32_16x16x32_bf16 v[42:45], v[160:163], v[192:195], v[42:45]
	v_mfma_f32_16x16x32_bf16 v[30:33], v[152:155], v[200:203], v[30:33]
	v_mfma_f32_16x16x32_bf16 v[26:29], v[160:163], v[200:203], v[26:29]
	v_mfma_f32_16x16x32_bf16 v[14:17], v[152:155], v[208:211], v[14:17]
	v_mfma_f32_16x16x32_bf16 v[10:13], v[160:163], v[208:211], v[10:13]
	v_mfma_f32_16x16x32_bf16 v[62:65], v[156:159], v[188:191], v[62:65]
	v_mfma_f32_16x16x32_bf16 v[58:61], v[164:167], v[188:191], v[58:61]
	v_mfma_f32_16x16x32_bf16 v[46:49], v[156:159], v[196:199], v[46:49]
	v_mfma_f32_16x16x32_bf16 v[42:45], v[164:167], v[196:199], v[42:45]
	v_mfma_f32_16x16x32_bf16 v[30:33], v[156:159], v[204:207], v[30:33]
	v_mfma_f32_16x16x32_bf16 v[26:29], v[164:167], v[204:207], v[26:29]
	v_mfma_f32_16x16x32_bf16 v[14:17], v[156:159], v[212:215], v[14:17]
	v_mfma_f32_16x16x32_bf16 v[10:13], v[164:167], v[212:215], v[10:13]
	v_mfma_f32_16x16x32_bf16 v[54:57], v[168:171], v[184:187], v[54:57]
	v_mfma_f32_16x16x32_bf16 v[50:53], v[176:179], v[184:187], v[50:53]
	v_mfma_f32_16x16x32_bf16 v[38:41], v[168:171], v[192:195], v[38:41]
	v_mfma_f32_16x16x32_bf16 v[34:37], v[176:179], v[192:195], v[34:37]
	v_mfma_f32_16x16x32_bf16 v[22:25], v[168:171], v[200:203], v[22:25]
	v_mfma_f32_16x16x32_bf16 v[18:21], v[176:179], v[200:203], v[18:21]
	v_mfma_f32_16x16x32_bf16 v[6:9], v[168:171], v[208:211], v[6:9]
	v_mfma_f32_16x16x32_bf16 v[2:5], v[176:179], v[208:211], v[2:5]
	v_mfma_f32_16x16x32_bf16 v[54:57], v[172:175], v[188:191], v[54:57]
	v_mfma_f32_16x16x32_bf16 v[50:53], v[180:183], v[188:191], v[50:53]
	v_mfma_f32_16x16x32_bf16 v[38:41], v[172:175], v[196:199], v[38:41]
	v_mfma_f32_16x16x32_bf16 v[34:37], v[180:183], v[196:199], v[34:37]
	v_mfma_f32_16x16x32_bf16 v[22:25], v[172:175], v[204:207], v[22:25]
	v_mfma_f32_16x16x32_bf16 v[18:21], v[180:183], v[204:207], v[18:21]
	v_mfma_f32_16x16x32_bf16 v[6:9], v[172:175], v[212:215], v[6:9]
	v_mfma_f32_16x16x32_bf16 v[2:5], v[180:183], v[212:215], v[2:5]
	s_setprio 0
	s_barrier
	s_add_i32 s57, 0, 0x18000
	v_add_u32_e32 v151, s57, v146
	s_add_i32 s58, 0, 0x1c000
	ds_read_b128 v[152:155], v151
	ds_read_b128 v[156:159], v151 offset:1024
	ds_read_b128 v[160:163], v151 offset:2048
	ds_read_b128 v[164:167], v151 offset:3072
	v_add_u32_e32 v151, s58, v146
	ds_read_b128 v[168:171], v151
	ds_read_b128 v[172:175], v151 offset:1024
	ds_read_b128 v[176:179], v151 offset:2048
	ds_read_b128 v[180:183], v151 offset:3072
	s_add_u32 s26, s26, s8
	s_addc_u32 s27, s27, s9
	s_mov_b32 m0, s37
	v_lshl_add_u64 v[228:229], s[26:27], 0, v[130:131]
	ds_read_b128 v[184:187], v150 offset:32768
	ds_read_b128 v[188:191], v150 offset:33792
	ds_read_b128 v[192:195], v150 offset:34816
	ds_read_b128 v[196:199], v150 offset:35840
	ds_read_b128 v[200:203], v150 offset:36864
	ds_read_b128 v[204:207], v150 offset:37888
	ds_read_b128 v[208:211], v150 offset:38912
	ds_read_b128 v[212:215], v150 offset:39936
	global_load_lds_dwordx4 v[228:229], off
	v_lshl_add_u64 v[228:229], s[26:27], 0, v[134:135]
	s_mov_b32 m0, s38
	s_nop 0
	global_load_lds_dwordx4 v[228:229], off
	s_waitcnt vmcnt(8) lgkmcnt(0)
	s_barrier
	s_setprio 1
	v_mfma_f32_16x16x32_bf16 v[122:125], v[152:155], v[184:187], v[122:125]
	v_mfma_f32_16x16x32_bf16 v[126:129], v[160:163], v[184:187], v[126:129]
	v_mfma_f32_16x16x32_bf16 v[110:113], v[152:155], v[192:195], v[110:113]
	v_mfma_f32_16x16x32_bf16 v[106:109], v[160:163], v[192:195], v[106:109]
	v_mfma_f32_16x16x32_bf16 v[94:97], v[152:155], v[200:203], v[94:97]
	v_mfma_f32_16x16x32_bf16 v[90:93], v[160:163], v[200:203], v[90:93]
	v_mfma_f32_16x16x32_bf16 v[78:81], v[152:155], v[208:211], v[78:81]
	v_mfma_f32_16x16x32_bf16 v[74:77], v[160:163], v[208:211], v[74:77]
	v_mfma_f32_16x16x32_bf16 v[122:125], v[156:159], v[188:191], v[122:125]
	v_mfma_f32_16x16x32_bf16 v[126:129], v[164:167], v[188:191], v[126:129]
	v_mfma_f32_16x16x32_bf16 v[110:113], v[156:159], v[196:199], v[110:113]
	v_mfma_f32_16x16x32_bf16 v[106:109], v[164:167], v[196:199], v[106:109]
	v_mfma_f32_16x16x32_bf16 v[94:97], v[156:159], v[204:207], v[94:97]
	v_mfma_f32_16x16x32_bf16 v[90:93], v[164:167], v[204:207], v[90:93]
	v_mfma_f32_16x16x32_bf16 v[78:81], v[156:159], v[212:215], v[78:81]
	v_mfma_f32_16x16x32_bf16 v[74:77], v[164:167], v[212:215], v[74:77]
	v_mfma_f32_16x16x32_bf16 v[118:121], v[168:171], v[184:187], v[118:121]
	v_mfma_f32_16x16x32_bf16 v[114:117], v[176:179], v[184:187], v[114:117]
	v_mfma_f32_16x16x32_bf16 v[102:105], v[168:171], v[192:195], v[102:105]
	v_mfma_f32_16x16x32_bf16 v[98:101], v[176:179], v[192:195], v[98:101]
	v_mfma_f32_16x16x32_bf16 v[86:89], v[168:171], v[200:203], v[86:89]
	v_mfma_f32_16x16x32_bf16 v[82:85], v[176:179], v[200:203], v[82:85]
	v_mfma_f32_16x16x32_bf16 v[70:73], v[168:171], v[208:211], v[70:73]
	v_mfma_f32_16x16x32_bf16 v[66:69], v[176:179], v[208:211], v[66:69]
	v_mfma_f32_16x16x32_bf16 v[118:121], v[172:175], v[188:191], v[118:121]
	v_mfma_f32_16x16x32_bf16 v[114:117], v[180:183], v[188:191], v[114:117]
	v_mfma_f32_16x16x32_bf16 v[102:105], v[172:175], v[196:199], v[102:105]
	v_mfma_f32_16x16x32_bf16 v[98:101], v[180:183], v[196:199], v[98:101]
	v_mfma_f32_16x16x32_bf16 v[86:89], v[172:175], v[204:207], v[86:89]
	v_mfma_f32_16x16x32_bf16 v[82:85], v[180:183], v[204:207], v[82:85]
	v_mfma_f32_16x16x32_bf16 v[70:73], v[172:175], v[212:215], v[70:73]
	v_mfma_f32_16x16x32_bf16 v[66:69], v[180:183], v[212:215], v[66:69]
	s_setprio 0
	s_barrier
; #define PG8_STAGE(bufoff, gbase, voff) do { _Pragma("unroll") for (int _i = 0; _i < 2; ++_i) \
;         __builtin_amdgcn_global_load_lds((const unsigned*)((const char*)(gbase) + (voff)[_i]), (PG8_LAS unsigned*)(lds + (bufoff) + ldsw + _i * 8192), 16, 0, 0); } while (0)
; #define PG8_LDA(dst, b, h) do { _Pragma("unroll") for (int m = 0; m < 4; ++m) _Pragma("unroll") for (int k = 0; k < 2; ++k) dst[m][k] = *(const PG8_LAS bf16x8*)(lds + PG8_SA(b, h) + aoff + m * 2048 + k * 1024); } while (0)
; #define PG8_MMA(ai, bj, At, Bt) do { __builtin_amdgcn_s_setprio(1); _Pragma("unroll") for (int m = 0; m < 4; ++m) _Pragma("unroll") for (int n = 0; n < 2; ++n) _Pragma("unroll") for (int k = 0; k < 2; ++k) \
;         acc[ai][bj][m][n] = __builtin_amdgcn_mfma_f32_16x16x32_bf16(Bt[n][k], At[m][k], acc[ai][bj][m][n], 0, 0, 0); __builtin_amdgcn_s_setprio(0); } while (0)
; #define PG8_WAIT_V(n) asm volatile("s_waitcnt vmcnt(" #n ")" ::: "memory")
; #define PG8_WAIT_L(n) asm volatile("s_waitcnt lgkmcnt(" #n ")" ::: "memory")
; #define PG8_BAR __builtin_amdgcn_s_barrier()
; #define PG8_SCHED __builtin_amdgcn_sched_barrier(0)
; template <class Epi, class Sched, bool ALIGN_EPI = false, bool SP2 = false>
; __device__ __forceinline__ void gemm_phase(PG8_LAS unsigned char* lds, const Gemm g, const Sched& S, const Epi& E) {
;     ...
;             PG8_LDA(At, 1, 1); PG8_STAGE(PG8_SB(1, 0), b3, voffB); PG8_STAGE(PG8_SB(1, 1), b3 + hstep, voffB); PG8_STAGE(PG8_SA(1, 0), a3, voffA);
;             PG8_WAIT_V(8); PG8_WAIT_L(0); PG8_BAR; PG8_MMA(1, 0, At, B0); PG8_MMA(1, 1, At, B1); PG8_BAR; PG8_SCHED;
	s_add_i32 s26, s57, s34
	v_lshl_add_u64 v[216:217], v[216:217], 0, s[16:17]
	s_mov_b32 m0, s26
	ds_read_b128 v[184:187], v150 offset:49152
	ds_read_b128 v[188:191], v150 offset:50176
	ds_read_b128 v[192:195], v150 offset:51200
	ds_read_b128 v[196:199], v150 offset:52224
	ds_read_b128 v[200:203], v150 offset:53248
	ds_read_b128 v[204:207], v150 offset:54272
	ds_read_b128 v[208:211], v150 offset:55296
	ds_read_b128 v[212:215], v150 offset:56320
	global_load_lds_dwordx4 v[216:217], off
	v_lshl_add_u64 v[216:217], v[218:219], 0, s[16:17]
	s_add_i32 m0, s26, 0x2000
	s_add_i32 s26, s58, s34
	global_load_lds_dwordx4 v[216:217], off
	v_lshl_add_u64 v[216:217], v[220:221], 0, s[16:17]
	s_mov_b32 m0, s26
	s_nop 0
	global_load_lds_dwordx4 v[216:217], off
	v_lshl_add_u64 v[216:217], v[222:223], 0, s[16:17]
	s_add_i32 m0, s26, 0x2000
	s_nop 0
	global_load_lds_dwordx4 v[216:217], off
	v_lshl_add_u64 v[216:217], v[224:225], 0, s[16:17]
	s_mov_b32 m0, s40
	s_nop 0
	global_load_lds_dwordx4 v[216:217], off
	v_lshl_add_u64 v[216:217], v[226:227], 0, s[16:17]
	s_mov_b32 m0, s41
	s_nop 0
	global_load_lds_dwordx4 v[216:217], off
	s_waitcnt vmcnt(8) lgkmcnt(0)
	s_barrier
	s_setprio 1
	v_mfma_f32_16x16x32_bf16 v[62:65], v[152:155], v[184:187], v[62:65]
	v_mfma_f32_16x16x32_bf16 v[58:61], v[160:163], v[184:187], v[58:61]
	v_mfma_f32_16x16x32_bf16 v[46:49], v[152:155], v[192:195], v[46:49]
	v_mfma_f32_16x16x32_bf16 v[42:45], v[160:163], v[192:195], v[42:45]
	v_mfma_f32_16x16x32_bf16 v[30:33], v[152:155], v[200:203], v[30:33]
	v_mfma_f32_16x16x32_bf16 v[26:29], v[160:163], v[200:203], v[26:29]
	v_mfma_f32_16x16x32_bf16 v[14:17], v[152:155], v[208:211], v[14:17]
	v_mfma_f32_16x16x32_bf16 v[10:13], v[160:163], v[208:211], v[10:13]
	v_mfma_f32_16x16x32_bf16 v[62:65], v[156:159], v[188:191], v[62:65]
	v_mfma_f32_16x16x32_bf16 v[58:61], v[164:167], v[188:191], v[58:61]
	v_mfma_f32_16x16x32_bf16 v[46:49], v[156:159], v[196:199], v[46:49]
	v_mfma_f32_16x16x32_bf16 v[42:45], v[164:167], v[196:199], v[42:45]
	v_mfma_f32_16x16x32_bf16 v[30:33], v[156:159], v[204:207], v[30:33]
	v_mfma_f32_16x16x32_bf16 v[26:29], v[164:167], v[204:207], v[26:29]
	v_mfma_f32_16x16x32_bf16 v[14:17], v[156:159], v[212:215], v[14:17]
	v_mfma_f32_16x16x32_bf16 v[10:13], v[164:167], v[212:215], v[10:13]
	v_mfma_f32_16x16x32_bf16 v[54:57], v[168:171], v[184:187], v[54:57]
	v_mfma_f32_16x16x32_bf16 v[50:53], v[176:179], v[184:187], v[50:53]
	v_mfma_f32_16x16x32_bf16 v[38:41], v[168:171], v[192:195], v[38:41]
	v_mfma_f32_16x16x32_bf16 v[34:37], v[176:179], v[192:195], v[34:37]
	v_mfma_f32_16x16x32_bf16 v[22:25], v[168:171], v[200:203], v[22:25]
	v_mfma_f32_16x16x32_bf16 v[18:21], v[176:179], v[200:203], v[18:21]
	v_mfma_f32_16x16x32_bf16 v[6:9], v[168:171], v[208:211], v[6:9]
	v_mfma_f32_16x16x32_bf16 v[2:5], v[176:179], v[208:211], v[2:5]
	v_mfma_f32_16x16x32_bf16 v[54:57], v[172:175], v[188:191], v[54:57]
	v_mfma_f32_16x16x32_bf16 v[50:53], v[180:183], v[188:191], v[50:53]
	v_mfma_f32_16x16x32_bf16 v[38:41], v[172:175], v[196:199], v[38:41]
	v_mfma_f32_16x16x32_bf16 v[34:37], v[180:183], v[196:199], v[34:37]
	v_mfma_f32_16x16x32_bf16 v[22:25], v[172:175], v[204:207], v[22:25]
	v_mfma_f32_16x16x32_bf16 v[18:21], v[180:183], v[204:207], v[18:21]
	v_mfma_f32_16x16x32_bf16 v[6:9], v[172:175], v[212:215], v[6:9]
	v_mfma_f32_16x16x32_bf16 v[2:5], v[180:183], v[212:215], v[2:5]
	s_setprio 0
	s_barrier
	s_add_u32 s54, s54, 0x100
	s_addc_u32 s55, s55, 0
	s_add_u32 s24, s24, 0x100
	s_addc_u32 s25, s25, 0
	s_cmp_ge_i32 s56, s42
	s_mov_b32 s26, s56
	s_cbranch_scc0 .LBB0_1809

; #define PG8_STAGE(bufoff, gbase, voff) do { _Pragma("unroll") for (int _i = 0; _i < 2; ++_i) \
;         __builtin_amdgcn_global_load_lds((const unsigned*)((const char*)(gbase) + (voff)[_i]), (PG8_LAS unsigned*)(lds + (bufoff) + ldsw + _i * 8192), 16, 0, 0); } while (0)
; #define PG8_LDA(dst, b, h) do { _Pragma("unroll") for (int m = 0; m < 4; ++m) _Pragma("unroll") for (int k = 0; k < 2; ++k) dst[m][k] = *(const PG8_LAS bf16x8*)(lds + PG8_SA(b, h) + aoff + m * 2048 + k * 1024); } while (0)
; #define PG8_LDB(dst, b, h) do { _Pragma("unroll") for (int n = 0; n < 2; ++n) _Pragma("unroll") for (int k = 0; k < 2; ++k) dst[n][k] = *(const PG8_LAS bf16x8*)(lds + PG8_SB(b, h) + boff + n * 2048 + k * 1024); } while (0)
; #define PG8_MMA(ai, bj, At, Bt) do { __builtin_amdgcn_s_setprio(1); _Pragma("unroll") for (int m = 0; m < 4; ++m) _Pragma("unroll") for (int n = 0; n < 2; ++n) _Pragma("unroll") for (int k = 0; k < 2; ++k) \
;         acc[ai][bj][m][n] = __builtin_amdgcn_mfma_f32_16x16x32_bf16(Bt[n][k], At[m][k], acc[ai][bj][m][n], 0, 0, 0); __builtin_amdgcn_s_setprio(0); } while (0)
; #define PG8_WAIT_V(n) asm volatile("s_waitcnt vmcnt(" #n ")" ::: "memory")
; #define PG8_WAIT_L(n) asm volatile("s_waitcnt lgkmcnt(" #n ")" ::: "memory")
; #define PG8_BAR __builtin_amdgcn_s_barrier()
; #define PG8_SCHED __builtin_amdgcn_sched_barrier(0)
; template <class Epi, class Sched, bool ALIGN_EPI = false, bool SP2 = false>
; __device__ __forceinline__ void gemm_phase(PG8_LAS unsigned char* lds, const Gemm g, const Sched& S, const Epi& E) {
;     ...
;             const bool last = (t == nt - 2);
;             const char* a1 = cA + (size_t)(t + 1) * kstep;
;             const char* a2 = last ? nA : cA + (size_t)(t + 2) * kstep; const char* b2 = last ? nB : cB + (size_t)(t + 2) * kstep;
;             const char* a3 = a2 + kstep; const char* b3 = b2 + kstep;
;             if (last && has_next) S.a_ready(nxt);
;             if constexpr (SP2) {
;             PG8_LDB(B0, 0, 0); PG8_LDB(B1, 0, 1); PG8_SCHED; PG8_LDA(At, 0, 0); PG8_STAGE(PG8_SA(1, 1), a1 + hstep, voffA);
;             PG8_WAIT_V(8); PG8_WAIT_L(0); PG8_BAR; PG8_MMA(0, 0, At, B0); PG8_MMA(0, 1, At, B1); PG8_BAR; PG8_SCHED;
;             PG8_LDA(At, 0, 1); PG8_STAGE(PG8_SB(0, 0), b2, voffB); PG8_STAGE(PG8_SB(0, 1), b2 + hstep, voffB); PG8_STAGE(PG8_SA(0, 0), a2, voffA);
.LBB0_1976:
	ds_read_b128 v[152:155], v148
	ds_read_b128 v[156:159], v148 offset:1024
	ds_read_b128 v[160:163], v148 offset:2048
	ds_read_b128 v[164:167], v148 offset:3072
	ds_read_b128 v[168:171], v149
	ds_read_b128 v[172:175], v149 offset:1024
	ds_read_b128 v[176:179], v149 offset:2048
	ds_read_b128 v[180:183], v149 offset:3072
	s_add_i32 s58, s26, 2
	s_add_u32 s59, s24, 0x80
	s_addc_u32 s27, s25, 0
	s_cmp_eq_u32 s44, s26
	s_cselect_b32 s26, s4, s59
	s_cselect_b32 s27, s5, s27
	s_cselect_b32 s61, s23, s57
	s_cselect_b32 s60, s22, s56
	v_lshl_add_u64 v[216:217], s[24:25], 0, v[140:141]
	s_add_i32 m0, s36, 0xc000
	ds_read_b128 v[184:187], v150
	ds_read_b128 v[188:191], v150 offset:1024
	ds_read_b128 v[192:195], v150 offset:2048
	ds_read_b128 v[196:199], v150 offset:3072
	ds_read_b128 v[200:203], v150 offset:4096
	ds_read_b128 v[204:207], v150 offset:5120
	ds_read_b128 v[208:211], v150 offset:6144
	ds_read_b128 v[212:215], v150 offset:7168
	global_load_lds_dwordx4 v[216:217], off
	v_lshl_add_u64 v[216:217], s[24:25], 0, v[138:139]
	s_add_i32 m0, s36, 0xe000
	s_nop 0
	global_load_lds_dwordx4 v[216:217], off
	s_waitcnt vmcnt(8) lgkmcnt(0)
	s_barrier
	s_setprio 1
	v_mfma_f32_16x16x32_bf16 v[122:125], v[152:155], v[184:187], v[122:125]
	v_mfma_f32_16x16x32_bf16 v[118:121], v[160:163], v[184:187], v[118:121]
	v_mfma_f32_16x16x32_bf16 v[110:113], v[152:155], v[192:195], v[110:113]
	v_mfma_f32_16x16x32_bf16 v[102:105], v[160:163], v[192:195], v[102:105]
	v_mfma_f32_16x16x32_bf16 v[94:97], v[152:155], v[200:203], v[94:97]
	v_mfma_f32_16x16x32_bf16 v[86:89], v[160:163], v[200:203], v[86:89]
	v_mfma_f32_16x16x32_bf16 v[78:81], v[152:155], v[208:211], v[78:81]
	v_mfma_f32_16x16x32_bf16 v[70:73], v[160:163], v[208:211], v[70:73]
	v_mfma_f32_16x16x32_bf16 v[122:125], v[156:159], v[188:191], v[122:125]
	v_mfma_f32_16x16x32_bf16 v[118:121], v[164:167], v[188:191], v[118:121]
	v_mfma_f32_16x16x32_bf16 v[110:113], v[156:159], v[196:199], v[110:113]
	v_mfma_f32_16x16x32_bf16 v[102:105], v[164:167], v[196:199], v[102:105]
	v_mfma_f32_16x16x32_bf16 v[94:97], v[156:159], v[204:207], v[94:97]
	v_mfma_f32_16x16x32_bf16 v[86:89], v[164:167], v[204:207], v[86:89]
	v_mfma_f32_16x16x32_bf16 v[78:81], v[156:159], v[212:215], v[78:81]
	v_mfma_f32_16x16x32_bf16 v[70:73], v[164:167], v[212:215], v[70:73]
	v_mfma_f32_16x16x32_bf16 v[126:129], v[168:171], v[184:187], v[126:129]
	v_mfma_f32_16x16x32_bf16 v[114:117], v[176:179], v[184:187], v[114:117]
	v_mfma_f32_16x16x32_bf16 v[106:109], v[168:171], v[192:195], v[106:109]
	v_mfma_f32_16x16x32_bf16 v[98:101], v[176:179], v[192:195], v[98:101]
	v_mfma_f32_16x16x32_bf16 v[90:93], v[168:171], v[200:203], v[90:93]
	v_mfma_f32_16x16x32_bf16 v[82:85], v[176:179], v[200:203], v[82:85]
	v_mfma_f32_16x16x32_bf16 v[74:77], v[168:171], v[208:211], v[74:77]
	v_mfma_f32_16x16x32_bf16 v[66:69], v[176:179], v[208:211], v[66:69]
	v_mfma_f32_16x16x32_bf16 v[126:129], v[172:175], v[188:191], v[126:129]
	v_mfma_f32_16x16x32_bf16 v[114:117], v[180:183], v[188:191], v[114:117]
	v_mfma_f32_16x16x32_bf16 v[106:109], v[172:175], v[196:199], v[106:109]
	v_mfma_f32_16x16x32_bf16 v[98:101], v[180:183], v[196:199], v[98:101]
	v_mfma_f32_16x16x32_bf16 v[90:93], v[172:175], v[204:207], v[90:93]
	v_mfma_f32_16x16x32_bf16 v[82:85], v[180:183], v[204:207], v[82:85]
	v_mfma_f32_16x16x32_bf16 v[74:77], v[172:175], v[212:215], v[74:77]
	v_mfma_f32_16x16x32_bf16 v[66:69], v[180:183], v[212:215], v[66:69]
	s_setprio 0
	s_barrier
	s_add_i32 s59, s47, s31
	v_lshl_add_u64 v[216:217], s[60:61], 0, v[134:135]
	s_mov_b32 m0, s59
	ds_read_b128 v[184:187], v150 offset:16384
	ds_read_b128 v[188:191], v150 offset:17408
	ds_read_b128 v[192:195], v150 offset:18432
	ds_read_b128 v[196:199], v150 offset:19456
	ds_read_b128 v[200:203], v150 offset:20480
	ds_read_b128 v[204:207], v150 offset:21504
	ds_read_b128 v[208:211], v150 offset:22528
	ds_read_b128 v[212:215], v150 offset:23552
	global_load_lds_dwordx4 v[216:217], off
	s_add_i32 m0, s59, 0x2000
	v_lshl_add_u64 v[218:219], s[60:61], 0, v[130:131]
	s_add_u32 s60, s60, s8
	s_addc_u32 s61, s61, s9
	s_add_i32 s59, s48, s31
	global_load_lds_dwordx4 v[218:219], off
	v_lshl_add_u64 v[220:221], s[60:61], 0, v[134:135]
	s_mov_b32 m0, s59
	v_lshl_add_u64 v[222:223], s[60:61], 0, v[130:131]
	global_load_lds_dwordx4 v[220:221], off
	s_add_i32 m0, s59, 0x2000
	v_lshl_add_u64 v[224:225], s[26:27], 0, v[136:137]
	global_load_lds_dwordx4 v[222:223], off
	s_mov_b32 m0, s36
	v_lshl_add_u64 v[226:227], s[26:27], 0, v[132:133]
	global_load_lds_dwordx4 v[224:225], off
	s_mov_b32 m0, s37
	s_nop 0
	global_load_lds_dwordx4 v[226:227], off
	s_waitcnt vmcnt(8) lgkmcnt(0)
	s_barrier
; #define PG8_STAGE(bufoff, gbase, voff) do { _Pragma("unroll") for (int _i = 0; _i < 2; ++_i) \
;         __builtin_amdgcn_global_load_lds((const unsigned*)((const char*)(gbase) + (voff)[_i]), (PG8_LAS unsigned*)(lds + (bufoff) + ldsw + _i * 8192), 16, 0, 0); } while (0)
; #define PG8_LDA(dst, b, h) do { _Pragma("unroll") for (int m = 0; m < 4; ++m) _Pragma("unroll") for (int k = 0; k < 2; ++k) dst[m][k] = *(const PG8_LAS bf16x8*)(lds + PG8_SA(b, h) + aoff + m * 2048 + k * 1024); } while (0)
; #define PG8_LDB(dst, b, h) do { _Pragma("unroll") for (int n = 0; n < 2; ++n) _Pragma("unroll") for (int k = 0; k < 2; ++k) dst[n][k] = *(const PG8_LAS bf16x8*)(lds + PG8_SB(b, h) + boff + n * 2048 + k * 1024); } while (0)
; #define PG8_MMA(ai, bj, At, Bt) do { __builtin_amdgcn_s_setprio(1); _Pragma("unroll") for (int m = 0; m < 4; ++m) _Pragma("unroll") for (int n = 0; n < 2; ++n) _Pragma("unroll") for (int k = 0; k < 2; ++k) \
;         acc[ai][bj][m][n] = __builtin_amdgcn_mfma_f32_16x16x32_bf16(Bt[n][k], At[m][k], acc[ai][bj][m][n], 0, 0, 0); __builtin_amdgcn_s_setprio(0); } while (0)
; #define PG8_WAIT_V(n) asm volatile("s_waitcnt vmcnt(" #n ")" ::: "memory")
; #define PG8_WAIT_L(n) asm volatile("s_waitcnt lgkmcnt(" #n ")" ::: "memory")
; #define PG8_BAR __builtin_amdgcn_s_barrier()
; #define PG8_SCHED __builtin_amdgcn_sched_barrier(0)
; template <class Epi, class Sched, bool ALIGN_EPI = false, bool SP2 = false>
; __device__ __forceinline__ void gemm_phase(PG8_LAS unsigned char* lds, const Gemm g, const Sched& S, const Epi& E) {
;     ...
;             PG8_WAIT_V(8); PG8_WAIT_L(0); PG8_BAR; PG8_MMA(1, 0, At, B0); PG8_MMA(1, 1, At, B1); PG8_BAR; PG8_SCHED;
;             PG8_LDB(B0, 1, 0); PG8_LDB(B1, 1, 1); PG8_SCHED; PG8_LDA(At, 1, 0); PG8_STAGE(PG8_SA(0, 1), a2 + hstep, voffA);
;             PG8_WAIT_V(8); PG8_WAIT_L(0); PG8_BAR; PG8_MMA(0, 0, At, B0); PG8_MMA(0, 1, At, B1); PG8_BAR; PG8_SCHED;
	s_setprio 1
	v_mfma_f32_16x16x32_bf16 v[62:65], v[152:155], v[184:187], v[62:65]
	v_mfma_f32_16x16x32_bf16 v[54:57], v[160:163], v[184:187], v[54:57]
	v_mfma_f32_16x16x32_bf16 v[46:49], v[152:155], v[192:195], v[46:49]
	v_mfma_f32_16x16x32_bf16 v[38:41], v[160:163], v[192:195], v[38:41]
	v_mfma_f32_16x16x32_bf16 v[30:33], v[152:155], v[200:203], v[30:33]
	v_mfma_f32_16x16x32_bf16 v[22:25], v[160:163], v[200:203], v[22:25]
	v_mfma_f32_16x16x32_bf16 v[14:17], v[152:155], v[208:211], v[14:17]
	v_mfma_f32_16x16x32_bf16 v[6:9], v[160:163], v[208:211], v[6:9]
	v_mfma_f32_16x16x32_bf16 v[62:65], v[156:159], v[188:191], v[62:65]
	v_mfma_f32_16x16x32_bf16 v[54:57], v[164:167], v[188:191], v[54:57]
	v_mfma_f32_16x16x32_bf16 v[46:49], v[156:159], v[196:199], v[46:49]
	v_mfma_f32_16x16x32_bf16 v[38:41], v[164:167], v[196:199], v[38:41]
	v_mfma_f32_16x16x32_bf16 v[30:33], v[156:159], v[204:207], v[30:33]
	v_mfma_f32_16x16x32_bf16 v[22:25], v[164:167], v[204:207], v[22:25]
	v_mfma_f32_16x16x32_bf16 v[14:17], v[156:159], v[212:215], v[14:17]
	v_mfma_f32_16x16x32_bf16 v[6:9], v[164:167], v[212:215], v[6:9]
	v_mfma_f32_16x16x32_bf16 v[58:61], v[168:171], v[184:187], v[58:61]
	v_mfma_f32_16x16x32_bf16 v[50:53], v[176:179], v[184:187], v[50:53]
	v_mfma_f32_16x16x32_bf16 v[42:45], v[168:171], v[192:195], v[42:45]
	v_mfma_f32_16x16x32_bf16 v[34:37], v[176:179], v[192:195], v[34:37]
	v_mfma_f32_16x16x32_bf16 v[26:29], v[168:171], v[200:203], v[26:29]
	v_mfma_f32_16x16x32_bf16 v[18:21], v[176:179], v[200:203], v[18:21]
	v_mfma_f32_16x16x32_bf16 v[10:13], v[168:171], v[208:211], v[10:13]
	v_mfma_f32_16x16x32_bf16 v[2:5], v[176:179], v[208:211], v[2:5]
	v_mfma_f32_16x16x32_bf16 v[58:61], v[172:175], v[188:191], v[58:61]
	v_mfma_f32_16x16x32_bf16 v[50:53], v[180:183], v[188:191], v[50:53]
	v_mfma_f32_16x16x32_bf16 v[42:45], v[172:175], v[196:199], v[42:45]
	v_mfma_f32_16x16x32_bf16 v[34:37], v[180:183], v[196:199], v[34:37]
	v_mfma_f32_16x16x32_bf16 v[26:29], v[172:175], v[204:207], v[26:29]
	v_mfma_f32_16x16x32_bf16 v[18:21], v[180:183], v[204:207], v[18:21]
	v_mfma_f32_16x16x32_bf16 v[10:13], v[172:175], v[212:215], v[10:13]
	v_mfma_f32_16x16x32_bf16 v[2:5], v[180:183], v[212:215], v[2:5]
	s_setprio 0
	s_barrier
	s_add_i32 s59, 0, 0x18000
	v_add_u32_e32 v151, s59, v146
	s_add_i32 s60, 0, 0x1c000
	ds_read_b128 v[152:155], v151
	ds_read_b128 v[156:159], v151 offset:1024
	ds_read_b128 v[160:163], v151 offset:2048
	ds_read_b128 v[164:167], v151 offset:3072
	v_add_u32_e32 v151, s60, v146
	ds_read_b128 v[168:171], v151
	ds_read_b128 v[172:175], v151 offset:1024
	ds_read_b128 v[176:179], v151 offset:2048
	ds_read_b128 v[180:183], v151 offset:3072
	s_add_u32 s26, s26, s8
	s_addc_u32 s27, s27, s9
	s_mov_b32 m0, s38
	v_lshl_add_u64 v[228:229], s[26:27], 0, v[136:137]
	ds_read_b128 v[184:187], v150 offset:32768
	ds_read_b128 v[188:191], v150 offset:33792
	ds_read_b128 v[192:195], v150 offset:34816
	ds_read_b128 v[196:199], v150 offset:35840
	ds_read_b128 v[200:203], v150 offset:36864
	ds_read_b128 v[204:207], v150 offset:37888
	ds_read_b128 v[208:211], v150 offset:38912
	ds_read_b128 v[212:215], v150 offset:39936
	global_load_lds_dwordx4 v[228:229], off
	v_lshl_add_u64 v[228:229], s[26:27], 0, v[132:133]
	s_mov_b32 m0, s39
	s_nop 0
	global_load_lds_dwordx4 v[228:229], off
	s_waitcnt vmcnt(8) lgkmcnt(0)
	s_barrier
	s_setprio 1
	v_mfma_f32_16x16x32_bf16 v[122:125], v[152:155], v[184:187], v[122:125]
	v_mfma_f32_16x16x32_bf16 v[118:121], v[160:163], v[184:187], v[118:121]
	v_mfma_f32_16x16x32_bf16 v[110:113], v[152:155], v[192:195], v[110:113]
	v_mfma_f32_16x16x32_bf16 v[102:105], v[160:163], v[192:195], v[102:105]
	v_mfma_f32_16x16x32_bf16 v[94:97], v[152:155], v[200:203], v[94:97]
	v_mfma_f32_16x16x32_bf16 v[86:89], v[160:163], v[200:203], v[86:89]
	v_mfma_f32_16x16x32_bf16 v[78:81], v[152:155], v[208:211], v[78:81]
	v_mfma_f32_16x16x32_bf16 v[70:73], v[160:163], v[208:211], v[70:73]
	v_mfma_f32_16x16x32_bf16 v[122:125], v[156:159], v[188:191], v[122:125]
	v_mfma_f32_16x16x32_bf16 v[118:121], v[164:167], v[188:191], v[118:121]
	v_mfma_f32_16x16x32_bf16 v[110:113], v[156:159], v[196:199], v[110:113]
	v_mfma_f32_16x16x32_bf16 v[102:105], v[164:167], v[196:199], v[102:105]
	v_mfma_f32_16x16x32_bf16 v[94:97], v[156:159], v[204:207], v[94:97]
	v_mfma_f32_16x16x32_bf16 v[86:89], v[164:167], v[204:207], v[86:89]
	v_mfma_f32_16x16x32_bf16 v[78:81], v[156:159], v[212:215], v[78:81]
	v_mfma_f32_16x16x32_bf16 v[70:73], v[164:167], v[212:215], v[70:73]
	v_mfma_f32_16x16x32_bf16 v[126:129], v[168:171], v[184:187], v[126:129]
	v_mfma_f32_16x16x32_bf16 v[114:117], v[176:179], v[184:187], v[114:117]
	v_mfma_f32_16x16x32_bf16 v[106:109], v[168:171], v[192:195], v[106:109]
	v_mfma_f32_16x16x32_bf16 v[98:101], v[176:179], v[192:195], v[98:101]
	v_mfma_f32_16x16x32_bf16 v[90:93], v[168:171], v[200:203], v[90:93]
	v_mfma_f32_16x16x32_bf16 v[82:85], v[176:179], v[200:203], v[82:85]
	v_mfma_f32_16x16x32_bf16 v[74:77], v[168:171], v[208:211], v[74:77]
	v_mfma_f32_16x16x32_bf16 v[66:69], v[176:179], v[208:211], v[66:69]
	v_mfma_f32_16x16x32_bf16 v[126:129], v[172:175], v[188:191], v[126:129]
	v_mfma_f32_16x16x32_bf16 v[114:117], v[180:183], v[188:191], v[114:117]
	v_mfma_f32_16x16x32_bf16 v[106:109], v[172:175], v[196:199], v[106:109]
	v_mfma_f32_16x16x32_bf16 v[98:101], v[180:183], v[196:199], v[98:101]
	v_mfma_f32_16x16x32_bf16 v[90:93], v[172:175], v[204:207], v[90:93]
	v_mfma_f32_16x16x32_bf16 v[82:85], v[180:183], v[204:207], v[82:85]
	v_mfma_f32_16x16x32_bf16 v[74:77], v[172:175], v[212:215], v[74:77]
	v_mfma_f32_16x16x32_bf16 v[66:69], v[180:183], v[212:215], v[66:69]
	s_setprio 0
	s_barrier
; #define PG8_STAGE(bufoff, gbase, voff) do { _Pragma("unroll") for (int _i = 0; _i < 2; ++_i) \
;         __builtin_amdgcn_global_load_lds((const unsigned*)((const char*)(gbase) + (voff)[_i]), (PG8_LAS unsigned*)(lds + (bufoff) + ldsw + _i * 8192), 16, 0, 0); } while (0)
; #define PG8_LDA(dst, b, h) do { _Pragma("unroll") for (int m = 0; m < 4; ++m) _Pragma("unroll") for (int k = 0; k < 2; ++k) dst[m][k] = *(const PG8_LAS bf16x8*)(lds + PG8_SA(b, h) + aoff + m * 2048 + k * 1024); } while (0)
; #define PG8_MMA(ai, bj, At, Bt) do { __builtin_amdgcn_s_setprio(1); _Pragma("unroll") for (int m = 0; m < 4; ++m) _Pragma("unroll") for (int n = 0; n < 2; ++n) _Pragma("unroll") for (int k = 0; k < 2; ++k) \
;         acc[ai][bj][m][n] = __builtin_amdgcn_mfma_f32_16x16x32_bf16(Bt[n][k], At[m][k], acc[ai][bj][m][n], 0, 0, 0); __builtin_amdgcn_s_setprio(0); } while (0)
; #define PG8_WAIT_V(n) asm volatile("s_waitcnt vmcnt(" #n ")" ::: "memory")
; #define PG8_WAIT_L(n) asm volatile("s_waitcnt lgkmcnt(" #n ")" ::: "memory")
; #define PG8_BAR __builtin_amdgcn_s_barrier()
; #define PG8_SCHED __builtin_amdgcn_sched_barrier(0)
; template <class Epi, class Sched, bool ALIGN_EPI = false, bool SP2 = false>
; __device__ __forceinline__ void gemm_phase(PG8_LAS unsigned char* lds, const Gemm g, const Sched& S, const Epi& E) {
;     ...
;             PG8_LDA(At, 1, 1); PG8_STAGE(PG8_SB(1, 0), b3, voffB); PG8_STAGE(PG8_SB(1, 1), b3 + hstep, voffB); PG8_STAGE(PG8_SA(1, 0), a3, voffA);
;             PG8_WAIT_V(8); PG8_WAIT_L(0); PG8_BAR; PG8_MMA(1, 0, At, B0); PG8_MMA(1, 1, At, B1); PG8_BAR; PG8_SCHED;
	s_add_i32 s26, s59, s31
	v_lshl_add_u64 v[216:217], v[216:217], 0, s[16:17]
	s_mov_b32 m0, s26
	ds_read_b128 v[184:187], v150 offset:49152
	ds_read_b128 v[188:191], v150 offset:50176
	ds_read_b128 v[192:195], v150 offset:51200
	ds_read_b128 v[196:199], v150 offset:52224
	ds_read_b128 v[200:203], v150 offset:53248
	ds_read_b128 v[204:207], v150 offset:54272
	ds_read_b128 v[208:211], v150 offset:55296
	ds_read_b128 v[212:215], v150 offset:56320
	global_load_lds_dwordx4 v[216:217], off
	v_lshl_add_u64 v[216:217], v[218:219], 0, s[16:17]
	s_add_i32 m0, s26, 0x2000
	s_add_i32 s26, s60, s31
	global_load_lds_dwordx4 v[216:217], off
	v_lshl_add_u64 v[216:217], v[220:221], 0, s[16:17]
	s_mov_b32 m0, s26
	s_nop 0
	global_load_lds_dwordx4 v[216:217], off
	v_lshl_add_u64 v[216:217], v[222:223], 0, s[16:17]
	s_add_i32 m0, s26, 0x2000
	s_nop 0
	global_load_lds_dwordx4 v[216:217], off
	v_lshl_add_u64 v[216:217], v[224:225], 0, s[16:17]
	s_mov_b32 m0, s41
	s_nop 0
	global_load_lds_dwordx4 v[216:217], off
	v_lshl_add_u64 v[216:217], v[226:227], 0, s[16:17]
	s_mov_b32 m0, s42
	s_nop 0
	global_load_lds_dwordx4 v[216:217], off
	s_waitcnt vmcnt(8) lgkmcnt(0)
	s_barrier
	s_setprio 1
	v_mfma_f32_16x16x32_bf16 v[62:65], v[152:155], v[184:187], v[62:65]
	v_mfma_f32_16x16x32_bf16 v[54:57], v[160:163], v[184:187], v[54:57]
	v_mfma_f32_16x16x32_bf16 v[46:49], v[152:155], v[192:195], v[46:49]
	v_mfma_f32_16x16x32_bf16 v[38:41], v[160:163], v[192:195], v[38:41]
	v_mfma_f32_16x16x32_bf16 v[30:33], v[152:155], v[200:203], v[30:33]
	v_mfma_f32_16x16x32_bf16 v[22:25], v[160:163], v[200:203], v[22:25]
	v_mfma_f32_16x16x32_bf16 v[14:17], v[152:155], v[208:211], v[14:17]
	v_mfma_f32_16x16x32_bf16 v[6:9], v[160:163], v[208:211], v[6:9]
	v_mfma_f32_16x16x32_bf16 v[62:65], v[156:159], v[188:191], v[62:65]
	v_mfma_f32_16x16x32_bf16 v[54:57], v[164:167], v[188:191], v[54:57]
	v_mfma_f32_16x16x32_bf16 v[46:49], v[156:159], v[196:199], v[46:49]
	v_mfma_f32_16x16x32_bf16 v[38:41], v[164:167], v[196:199], v[38:41]
	v_mfma_f32_16x16x32_bf16 v[30:33], v[156:159], v[204:207], v[30:33]
	v_mfma_f32_16x16x32_bf16 v[22:25], v[164:167], v[204:207], v[22:25]
	v_mfma_f32_16x16x32_bf16 v[14:17], v[156:159], v[212:215], v[14:17]
	v_mfma_f32_16x16x32_bf16 v[6:9], v[164:167], v[212:215], v[6:9]
	v_mfma_f32_16x16x32_bf16 v[58:61], v[168:171], v[184:187], v[58:61]
	v_mfma_f32_16x16x32_bf16 v[50:53], v[176:179], v[184:187], v[50:53]
	v_mfma_f32_16x16x32_bf16 v[42:45], v[168:171], v[192:195], v[42:45]
	v_mfma_f32_16x16x32_bf16 v[34:37], v[176:179], v[192:195], v[34:37]
	v_mfma_f32_16x16x32_bf16 v[26:29], v[168:171], v[200:203], v[26:29]
	v_mfma_f32_16x16x32_bf16 v[18:21], v[176:179], v[200:203], v[18:21]
	v_mfma_f32_16x16x32_bf16 v[10:13], v[168:171], v[208:211], v[10:13]
	v_mfma_f32_16x16x32_bf16 v[2:5], v[176:179], v[208:211], v[2:5]
	v_mfma_f32_16x16x32_bf16 v[58:61], v[172:175], v[188:191], v[58:61]
	v_mfma_f32_16x16x32_bf16 v[50:53], v[180:183], v[188:191], v[50:53]
	v_mfma_f32_16x16x32_bf16 v[42:45], v[172:175], v[196:199], v[42:45]
	v_mfma_f32_16x16x32_bf16 v[34:37], v[180:183], v[196:199], v[34:37]
	v_mfma_f32_16x16x32_bf16 v[26:29], v[172:175], v[204:207], v[26:29]
	v_mfma_f32_16x16x32_bf16 v[18:21], v[180:183], v[204:207], v[18:21]
	v_mfma_f32_16x16x32_bf16 v[10:13], v[172:175], v[212:215], v[10:13]
	v_mfma_f32_16x16x32_bf16 v[2:5], v[180:183], v[212:215], v[2:5]
	s_setprio 0
	s_barrier
	s_add_u32 s56, s56, 0x100
	s_addc_u32 s57, s57, 0
	s_add_u32 s24, s24, 0x100
	s_addc_u32 s25, s25, 0
	s_cmp_ge_i32 s58, s43
	s_mov_b32 s26, s58
	s_cbranch_scc0 .LBB0_1976
